# K-loops: MFMA half's barrier-to-barrier path trimmed (priority raise before the opening barrier, drop after the closing barrier, redundant post-barrier lgkmcnt wait and mid-block priority flips remove
# speedup vs baseline: 1.0141x; 1.0141x over previous
; #define PG8_STAGE(bufoff, gbase, voff) do { _Pragma("unroll") for (int _i = 0; _i < 2; ++_i) \
;         __builtin_amdgcn_global_load_lds((const unsigned*)((const char*)(gbase) + (voff)[_i]), (PG8_LAS unsigned*)(lds + (bufoff) + ldsw + _i * 8192), 16, 0, 0); } while (0)
; #define PG8_LDA(dst, b, h) do { _Pragma("unroll") for (int m = 0; m < 4; ++m) _Pragma("unroll") for (int k = 0; k < 2; ++k) dst[m][k] = *(const PG8_LAS bf16x8*)(lds + PG8_SA(b, h) + aoff + m * 2048 + k * 1024); } while (0)
; #define PG8_LDB(dst, b, h) do { _Pragma("unroll") for (int n = 0; n < 2; ++n) _Pragma("unroll") for (int k = 0; k < 2; ++k) dst[n][k] = *(const PG8_LAS bf16x8*)(lds + PG8_SB(b, h) + boff + n * 2048 + k * 1024); } while (0)
; #define PG8_MMA(ai, bj, At, Bt) do { __builtin_amdgcn_s_setprio(1); _Pragma("unroll") for (int m = 0; m < 4; ++m) _Pragma("unroll") for (int n = 0; n < 2; ++n) _Pragma("unroll") for (int k = 0; k < 2; ++k) \
;         acc[ai][bj][m][n] = __builtin_amdgcn_mfma_f32_16x16x32_bf16(Bt[n][k], At[m][k], acc[ai][bj][m][n], 0, 0, 0); __builtin_amdgcn_s_setprio(0); } while (0)
; template <class Epi, class Sched, bool ALIGN_EPI = false, bool SP2 = false>
; __device__ __forceinline__ void gemm_phase(PG8_LAS unsigned char* lds, const Gemm g, const Sched& S, const Epi& E, int wave_in) {
;     ...
;         const char* nA = has_next ? (const char*)g.A + (size_t)(nxt.pm >> g.ash) * g.astride + (size_t)nxt.pm * tstep : cA; const char* nB = has_next ? (const char*)g.Bt + (size_t)(nxt.pm >> g.bsh) * g.bstride + (size_t)nxt.pn * tstep : cB;
;         for (int t = 0; t < nt; t += 2) {
;             const bool last = (t == nt - 2);
;             const char* a1 = cA + (size_t)(t + 1) * kstep;
;             const char* a2 = last ? nA : cA + (size_t)(t + 2) * kstep; const char* b2 = last ? nB : cB + (size_t)(t + 2) * kstep;
;             const char* a3 = a2 + kstep; const char* b3 = b2 + kstep;
;             if (last && has_next) S.a_ready(nxt);
;             if constexpr (SP2) {
;             PG8_LDB(B0, 0, 0); PG8_LDB(B1, 0, 1); PG8_SCHED; PG8_LDA(At, 0, 0); PG8_STAGE(PG8_SA(1, 1), a1 + hstep, voffA);
;             PG8_WAIT_V(8); PG8_WAIT_L(0); PG8_BAR; PG8_MMA(0, 0, At, B0); PG8_MMA(0, 1, At, B1); PG8_BAR; PG8_SCHED;
;             PG8_LDA(At, 0, 1); PG8_STAGE(PG8_SB(0, 0), b2, voffB); PG8_STAGE(PG8_SB(0, 1), b2 + hstep, voffB); PG8_STAGE(PG8_SA(0, 0), a2, voffA);
.LBB0_253:
	s_ashr_i32 s23, s22, 31
	s_lshl_b64 s[24:25], s[22:23], 19
	s_add_u32 s24, s62, s24
	s_addc_u32 s25, s63, s25
	s_and_b64 s[26:27], s[18:19], exec
	s_cselect_b32 s23, s25, s37
	s_cselect_b32 s29, s24, s36
	s_ashr_i32 s21, s20, 31
	s_lshl_b64 s[26:27], s[20:21], 19
	s_add_u32 s26, s64, s26
	s_addc_u32 s27, s65, s27
	s_and_b64 s[38:39], s[18:19], exec
	s_cselect_b32 s21, s27, s35
	s_cselect_b32 s31, s26, s34
	s_add_u32 s76, s34, 0x100
	s_addc_u32 s77, s35, 0
	s_add_u32 s34, s36, 0x40080
	s_addc_u32 s35, s37, 0
	s_mov_b32 s78, -2
	v_add_u32_e32 v174, s43, v160
	v_add_u32_e32 v190, s44, v160
	ds_read_b128 v[162:165], v174
	ds_read_b128 v[166:169], v174 offset:1024
	ds_read_b128 v[170:173], v174 offset:2048
	ds_read_b128 v[174:177], v174 offset:3072
	ds_read_b128 v[178:181], v190
	ds_read_b128 v[182:185], v190 offset:1024
	ds_read_b128 v[186:189], v190 offset:2048
	ds_read_b128 v[190:193], v190 offset:3072
	s_add_u32 s36, s34, 0xfffc0080
	s_addc_u32 s37, s35, -1
	s_cmp_eq_u32 s78, 12
	s_cselect_b32 s39, s23, s37
	s_cselect_b32 s38, s29, s36
	s_cselect_b32 s37, s21, s77
	s_cselect_b32 s36, s31, s76
	v_lshl_add_u64 v[226:227], s[34:35], 0, v[156:157]
	s_add_i32 m0, s67, 0xc000
	ds_read_b128 v[194:197], v161
	ds_read_b128 v[198:201], v161 offset:1024
	ds_read_b128 v[202:205], v161 offset:2048
	ds_read_b128 v[206:209], v161 offset:3072
	ds_read_b128 v[210:213], v161 offset:4096
	ds_read_b128 v[214:217], v161 offset:5120
	ds_read_b128 v[218:221], v161 offset:6144
	ds_read_b128 v[222:225], v161 offset:7168
	global_load_lds_dwordx4 v[226:227], off
	v_lshl_add_u64 v[226:227], s[34:35], 0, v[154:155]
	s_add_i32 m0, s67, 0xe000
	s_nop 0
	global_load_lds_dwordx4 v[226:227], off
	s_waitcnt vmcnt(8)
	s_waitcnt lgkmcnt(0)
	s_setprio 1
	s_barrier
	v_mfma_f32_16x16x32_bf16 v[124:127], v[162:165], v[194:197], 0
	v_mfma_f32_16x16x32_bf16 v[120:123], v[170:173], v[194:197], 0
	v_mfma_f32_16x16x32_bf16 v[116:119], v[162:165], v[202:205], 0
	v_mfma_f32_16x16x32_bf16 v[108:111], v[170:173], v[202:205], 0
	v_mfma_f32_16x16x32_bf16 v[100:103], v[162:165], v[210:213], 0
	v_mfma_f32_16x16x32_bf16 v[92:95], v[170:173], v[210:213], 0
	v_mfma_f32_16x16x32_bf16 v[84:87], v[162:165], v[218:221], 0
	v_mfma_f32_16x16x32_bf16 v[76:79], v[170:173], v[218:221], 0
	v_mfma_f32_16x16x32_bf16 v[124:127], v[166:169], v[198:201], v[124:127]
	v_mfma_f32_16x16x32_bf16 v[120:123], v[174:177], v[198:201], v[120:123]
	v_mfma_f32_16x16x32_bf16 v[116:119], v[166:169], v[206:209], v[116:119]
	v_mfma_f32_16x16x32_bf16 v[108:111], v[174:177], v[206:209], v[108:111]
	v_mfma_f32_16x16x32_bf16 v[100:103], v[166:169], v[214:217], v[100:103]
	v_mfma_f32_16x16x32_bf16 v[92:95], v[174:177], v[214:217], v[92:95]
	v_mfma_f32_16x16x32_bf16 v[84:87], v[166:169], v[222:225], v[84:87]
	v_mfma_f32_16x16x32_bf16 v[76:79], v[174:177], v[222:225], v[76:79]
	v_mfma_f32_16x16x32_bf16 v[112:115], v[178:181], v[194:197], 0
	v_mfma_f32_16x16x32_bf16 v[104:107], v[186:189], v[194:197], 0
	v_mfma_f32_16x16x32_bf16 v[96:99], v[178:181], v[202:205], 0
	v_mfma_f32_16x16x32_bf16 v[88:91], v[186:189], v[202:205], 0
	v_mfma_f32_16x16x32_bf16 v[80:83], v[178:181], v[210:213], 0
	v_mfma_f32_16x16x32_bf16 v[72:75], v[186:189], v[210:213], 0
	v_mfma_f32_16x16x32_bf16 v[68:71], v[178:181], v[218:221], 0
	v_mfma_f32_16x16x32_bf16 v[64:67], v[186:189], v[218:221], 0
	v_mfma_f32_16x16x32_bf16 v[112:115], v[182:185], v[198:201], v[112:115]
	v_mfma_f32_16x16x32_bf16 v[104:107], v[190:193], v[198:201], v[104:107]
	v_mfma_f32_16x16x32_bf16 v[96:99], v[182:185], v[206:209], v[96:99]
	v_mfma_f32_16x16x32_bf16 v[88:91], v[190:193], v[206:209], v[88:91]
	v_mfma_f32_16x16x32_bf16 v[80:83], v[182:185], v[214:217], v[80:83]
	v_mfma_f32_16x16x32_bf16 v[72:75], v[190:193], v[214:217], v[72:75]
	v_mfma_f32_16x16x32_bf16 v[68:71], v[182:185], v[222:225], v[68:71]
	v_mfma_f32_16x16x32_bf16 v[64:67], v[190:193], v[222:225], v[64:67]
	s_barrier
	s_setprio 0
	s_add_i32 s79, s43, s66
	v_lshl_add_u64 v[226:227], s[36:37], 0, v[132:133]
	s_mov_b32 m0, s79
	ds_read_b128 v[194:197], v161 offset:16384
	ds_read_b128 v[198:201], v161 offset:17408
	ds_read_b128 v[202:205], v161 offset:18432
	ds_read_b128 v[206:209], v161 offset:19456
	ds_read_b128 v[210:213], v161 offset:20480
	ds_read_b128 v[214:217], v161 offset:21504
	ds_read_b128 v[218:221], v161 offset:22528
	ds_read_b128 v[222:225], v161 offset:23552
	global_load_lds_dwordx4 v[226:227], off
	s_add_i32 m0, s79, 0x2000
	s_add_u32 s80, s36, 0x40000
	v_lshl_add_u64 v[228:229], s[36:37], 0, v[136:137]
	s_addc_u32 s81, s37, 0
	s_add_i32 s79, s44, s66
	global_load_lds_dwordx4 v[228:229], off
	v_lshl_add_u64 v[230:231], s[80:81], 0, v[132:133]
	s_mov_b32 m0, s79
	v_lshl_add_u64 v[232:233], s[38:39], 0, v[134:135]
	global_load_lds_dwordx4 v[230:231], off
	v_lshl_add_u64 v[230:231], s[80:81], 0, v[136:137]
	s_add_i32 m0, s79, 0x2000
	s_nop 0
	global_load_lds_dwordx4 v[230:231], off
	v_lshl_add_u64 v[230:231], s[38:39], 0, v[130:131]
	s_mov_b32 m0, s67
	s_nop 0
	global_load_lds_dwordx4 v[230:231], off
	s_mov_b32 m0, s68
	s_nop 0
	global_load_lds_dwordx4 v[232:233], off
	s_waitcnt vmcnt(8)
	s_waitcnt lgkmcnt(0)
	s_setprio 1
	s_barrier
; #define PG8_STAGE(bufoff, gbase, voff) do { _Pragma("unroll") for (int _i = 0; _i < 2; ++_i) \
;         __builtin_amdgcn_global_load_lds((const unsigned*)((const char*)(gbase) + (voff)[_i]), (PG8_LAS unsigned*)(lds + (bufoff) + ldsw + _i * 8192), 16, 0, 0); } while (0)
; #define PG8_LDA(dst, b, h) do { _Pragma("unroll") for (int m = 0; m < 4; ++m) _Pragma("unroll") for (int k = 0; k < 2; ++k) dst[m][k] = *(const PG8_LAS bf16x8*)(lds + PG8_SA(b, h) + aoff + m * 2048 + k * 1024); } while (0)
; #define PG8_LDB(dst, b, h) do { _Pragma("unroll") for (int n = 0; n < 2; ++n) _Pragma("unroll") for (int k = 0; k < 2; ++k) dst[n][k] = *(const PG8_LAS bf16x8*)(lds + PG8_SB(b, h) + boff + n * 2048 + k * 1024); } while (0)
; #define PG8_MMA(ai, bj, At, Bt) do { __builtin_amdgcn_s_setprio(1); _Pragma("unroll") for (int m = 0; m < 4; ++m) _Pragma("unroll") for (int n = 0; n < 2; ++n) _Pragma("unroll") for (int k = 0; k < 2; ++k) \
;         acc[ai][bj][m][n] = __builtin_amdgcn_mfma_f32_16x16x32_bf16(Bt[n][k], At[m][k], acc[ai][bj][m][n], 0, 0, 0); __builtin_amdgcn_s_setprio(0); } while (0)
; #define PG8_WAIT_V(n) asm volatile("s_waitcnt vmcnt(" #n ")" ::: "memory")
; #define PG8_WAIT_L(n) asm volatile("s_waitcnt lgkmcnt(" #n ")" ::: "memory")
; #define PG8_BAR __builtin_amdgcn_s_barrier()
; #define PG8_SCHED __builtin_amdgcn_sched_barrier(0)
; template <class Epi, class Sched, bool ALIGN_EPI = false, bool SP2 = false>
; __device__ __forceinline__ void gemm_phase(PG8_LAS unsigned char* lds, const Gemm g, const Sched& S, const Epi& E, int wave_in) {
;     ...
;             PG8_WAIT_V(8); PG8_WAIT_L(0); PG8_BAR; PG8_MMA(1, 0, At, B0); PG8_MMA(1, 1, At, B1); PG8_BAR; PG8_SCHED;
;             PG8_LDB(B0, 1, 0); PG8_LDB(B1, 1, 1); PG8_SCHED; PG8_LDA(At, 1, 0); PG8_STAGE(PG8_SA(0, 1), a2 + hstep, voffA);
;             PG8_WAIT_V(8); PG8_WAIT_L(0); PG8_BAR; PG8_MMA(0, 0, At, B0); PG8_MMA(0, 1, At, B1); PG8_BAR; PG8_SCHED;
	v_mfma_f32_16x16x32_bf16 v[60:63], v[162:165], v[194:197], 0
	v_mfma_f32_16x16x32_bf16 v[56:59], v[170:173], v[194:197], 0
	v_mfma_f32_16x16x32_bf16 v[52:55], v[162:165], v[202:205], 0
	v_mfma_f32_16x16x32_bf16 v[44:47], v[170:173], v[202:205], 0
	v_mfma_f32_16x16x32_bf16 v[36:39], v[162:165], v[210:213], 0
	v_mfma_f32_16x16x32_bf16 v[28:31], v[170:173], v[210:213], 0
	v_mfma_f32_16x16x32_bf16 v[20:23], v[162:165], v[218:221], 0
	v_mfma_f32_16x16x32_bf16 v[12:15], v[170:173], v[218:221], 0
	v_mfma_f32_16x16x32_bf16 v[60:63], v[166:169], v[198:201], v[60:63]
	v_mfma_f32_16x16x32_bf16 v[56:59], v[174:177], v[198:201], v[56:59]
	v_mfma_f32_16x16x32_bf16 v[52:55], v[166:169], v[206:209], v[52:55]
	v_mfma_f32_16x16x32_bf16 v[44:47], v[174:177], v[206:209], v[44:47]
	v_mfma_f32_16x16x32_bf16 v[36:39], v[166:169], v[214:217], v[36:39]
	v_mfma_f32_16x16x32_bf16 v[28:31], v[174:177], v[214:217], v[28:31]
	v_mfma_f32_16x16x32_bf16 v[20:23], v[166:169], v[222:225], v[20:23]
	v_mfma_f32_16x16x32_bf16 v[12:15], v[174:177], v[222:225], v[12:15]
	v_mfma_f32_16x16x32_bf16 v[48:51], v[178:181], v[194:197], 0
	v_mfma_f32_16x16x32_bf16 v[40:43], v[186:189], v[194:197], 0
	v_mfma_f32_16x16x32_bf16 v[32:35], v[178:181], v[202:205], 0
	v_mfma_f32_16x16x32_bf16 v[24:27], v[186:189], v[202:205], 0
	v_mfma_f32_16x16x32_bf16 v[16:19], v[178:181], v[210:213], 0
	v_mfma_f32_16x16x32_bf16 v[8:11], v[186:189], v[210:213], 0
	v_mfma_f32_16x16x32_bf16 v[4:7], v[178:181], v[218:221], 0
	v_mfma_f32_16x16x32_bf16 v[0:3], v[186:189], v[218:221], 0
	v_mfma_f32_16x16x32_bf16 v[48:51], v[182:185], v[198:201], v[48:51]
	v_mfma_f32_16x16x32_bf16 v[40:43], v[190:193], v[198:201], v[40:43]
	v_mfma_f32_16x16x32_bf16 v[32:35], v[182:185], v[206:209], v[32:35]
	v_mfma_f32_16x16x32_bf16 v[24:27], v[190:193], v[206:209], v[24:27]
	v_mfma_f32_16x16x32_bf16 v[16:19], v[182:185], v[214:217], v[16:19]
	v_mfma_f32_16x16x32_bf16 v[8:11], v[190:193], v[214:217], v[8:11]
	v_mfma_f32_16x16x32_bf16 v[4:7], v[182:185], v[222:225], v[4:7]
	v_mfma_f32_16x16x32_bf16 v[0:3], v[190:193], v[222:225], v[0:3]
	s_barrier
	s_setprio 0
	v_add_u32_e32 v174, s45, v160
	v_add_u32_e32 v190, s46, v160
	ds_read_b128 v[162:165], v174
	ds_read_b128 v[166:169], v174 offset:1024
	ds_read_b128 v[170:173], v174 offset:2048
	ds_read_b128 v[174:177], v174 offset:3072
	ds_read_b128 v[178:181], v190
	ds_read_b128 v[182:185], v190 offset:1024
	ds_read_b128 v[186:189], v190 offset:2048
	ds_read_b128 v[190:193], v190 offset:3072
	s_add_u32 s38, s38, 0x40000
	s_addc_u32 s39, s39, 0
	s_mov_b32 m0, s69
	v_lshl_add_u64 v[234:235], s[38:39], 0, v[130:131]
	ds_read_b128 v[194:197], v161 offset:32768
	ds_read_b128 v[198:201], v161 offset:33792
	ds_read_b128 v[202:205], v161 offset:34816
	ds_read_b128 v[206:209], v161 offset:35840
	ds_read_b128 v[210:213], v161 offset:36864
	ds_read_b128 v[214:217], v161 offset:37888
	ds_read_b128 v[218:221], v161 offset:38912
	ds_read_b128 v[222:225], v161 offset:39936
	global_load_lds_dwordx4 v[234:235], off
	v_lshl_add_u64 v[234:235], s[38:39], 0, v[134:135]
	s_mov_b32 m0, s70
	s_nop 0
	global_load_lds_dwordx4 v[234:235], off
	s_waitcnt vmcnt(8)
	s_waitcnt lgkmcnt(0)
	s_setprio 1
	s_barrier
	v_mfma_f32_16x16x32_bf16 v[124:127], v[162:165], v[194:197], v[124:127]
	v_mfma_f32_16x16x32_bf16 v[120:123], v[170:173], v[194:197], v[120:123]
	v_mfma_f32_16x16x32_bf16 v[116:119], v[162:165], v[202:205], v[116:119]
	v_mfma_f32_16x16x32_bf16 v[108:111], v[170:173], v[202:205], v[108:111]
	v_mfma_f32_16x16x32_bf16 v[100:103], v[162:165], v[210:213], v[100:103]
	v_mfma_f32_16x16x32_bf16 v[92:95], v[170:173], v[210:213], v[92:95]
	v_mfma_f32_16x16x32_bf16 v[84:87], v[162:165], v[218:221], v[84:87]
	v_mfma_f32_16x16x32_bf16 v[76:79], v[170:173], v[218:221], v[76:79]
	v_mfma_f32_16x16x32_bf16 v[124:127], v[166:169], v[198:201], v[124:127]
	v_mfma_f32_16x16x32_bf16 v[120:123], v[174:177], v[198:201], v[120:123]
	v_mfma_f32_16x16x32_bf16 v[116:119], v[166:169], v[206:209], v[116:119]
	v_mfma_f32_16x16x32_bf16 v[108:111], v[174:177], v[206:209], v[108:111]
	v_mfma_f32_16x16x32_bf16 v[100:103], v[166:169], v[214:217], v[100:103]
	v_mfma_f32_16x16x32_bf16 v[92:95], v[174:177], v[214:217], v[92:95]
	v_mfma_f32_16x16x32_bf16 v[84:87], v[166:169], v[222:225], v[84:87]
	v_mfma_f32_16x16x32_bf16 v[76:79], v[174:177], v[222:225], v[76:79]
	v_mfma_f32_16x16x32_bf16 v[112:115], v[178:181], v[194:197], v[112:115]
	v_mfma_f32_16x16x32_bf16 v[104:107], v[186:189], v[194:197], v[104:107]
	v_mfma_f32_16x16x32_bf16 v[96:99], v[178:181], v[202:205], v[96:99]
	v_mfma_f32_16x16x32_bf16 v[88:91], v[186:189], v[202:205], v[88:91]
	v_mfma_f32_16x16x32_bf16 v[80:83], v[178:181], v[210:213], v[80:83]
	v_mfma_f32_16x16x32_bf16 v[72:75], v[186:189], v[210:213], v[72:75]
	v_mfma_f32_16x16x32_bf16 v[68:71], v[178:181], v[218:221], v[68:71]
	v_mfma_f32_16x16x32_bf16 v[64:67], v[186:189], v[218:221], v[64:67]
	v_mfma_f32_16x16x32_bf16 v[112:115], v[182:185], v[198:201], v[112:115]
	v_mfma_f32_16x16x32_bf16 v[104:107], v[190:193], v[198:201], v[104:107]
	v_mfma_f32_16x16x32_bf16 v[96:99], v[182:185], v[206:209], v[96:99]
	v_mfma_f32_16x16x32_bf16 v[88:91], v[190:193], v[206:209], v[88:91]
	v_mfma_f32_16x16x32_bf16 v[80:83], v[182:185], v[214:217], v[80:83]
	v_mfma_f32_16x16x32_bf16 v[72:75], v[190:193], v[214:217], v[72:75]
	v_mfma_f32_16x16x32_bf16 v[68:71], v[182:185], v[222:225], v[68:71]
	v_mfma_f32_16x16x32_bf16 v[64:67], v[190:193], v[222:225], v[64:67]
	s_barrier
; #define PG8_STAGE(bufoff, gbase, voff) do { _Pragma("unroll") for (int _i = 0; _i < 2; ++_i) \
;         __builtin_amdgcn_global_load_lds((const unsigned*)((const char*)(gbase) + (voff)[_i]), (PG8_LAS unsigned*)(lds + (bufoff) + ldsw + _i * 8192), 16, 0, 0); } while (0)
; #define PG8_LDA(dst, b, h) do { _Pragma("unroll") for (int m = 0; m < 4; ++m) _Pragma("unroll") for (int k = 0; k < 2; ++k) dst[m][k] = *(const PG8_LAS bf16x8*)(lds + PG8_SA(b, h) + aoff + m * 2048 + k * 1024); } while (0)
; #define PG8_LDB(dst, b, h) do { _Pragma("unroll") for (int n = 0; n < 2; ++n) _Pragma("unroll") for (int k = 0; k < 2; ++k) dst[n][k] = *(const PG8_LAS bf16x8*)(lds + PG8_SB(b, h) + boff + n * 2048 + k * 1024); } while (0)
; #define PG8_MMA(ai, bj, At, Bt) do { __builtin_amdgcn_s_setprio(1); _Pragma("unroll") for (int m = 0; m < 4; ++m) _Pragma("unroll") for (int n = 0; n < 2; ++n) _Pragma("unroll") for (int k = 0; k < 2; ++k) \
;         acc[ai][bj][m][n] = __builtin_amdgcn_mfma_f32_16x16x32_bf16(Bt[n][k], At[m][k], acc[ai][bj][m][n], 0, 0, 0); __builtin_amdgcn_s_setprio(0); } while (0)
; #define PG8_WAIT_V(n) asm volatile("s_waitcnt vmcnt(" #n ")" ::: "memory")
; #define PG8_WAIT_L(n) asm volatile("s_waitcnt lgkmcnt(" #n ")" ::: "memory")
; #define PG8_BAR __builtin_amdgcn_s_barrier()
; #define PG8_SCHED __builtin_amdgcn_sched_barrier(0)
; template <class Epi, class Sched, bool ALIGN_EPI = false, bool SP2 = false>
; __device__ __forceinline__ void gemm_phase(PG8_LAS unsigned char* lds, const Gemm g, const Sched& S, const Epi& E, int wave_in) {
;     ...
;         for (int t = 0; t < nt; t += 2) {
;             const bool last = (t == nt - 2);
;             const char* a1 = cA + (size_t)(t + 1) * kstep;
;             const char* a2 = last ? nA : cA + (size_t)(t + 2) * kstep; const char* b2 = last ? nB : cB + (size_t)(t + 2) * kstep;
;             const char* a3 = a2 + kstep; const char* b3 = b2 + kstep;
;             if (last && has_next) S.a_ready(nxt);
;             if constexpr (SP2) {
;             PG8_LDB(B0, 0, 0); PG8_LDB(B1, 0, 1); PG8_SCHED; PG8_LDA(At, 0, 0); PG8_STAGE(PG8_SA(1, 1), a1 + hstep, voffA);
;     ...
;             PG8_LDA(At, 1, 1); PG8_STAGE(PG8_SB(1, 0), b3, voffB); PG8_STAGE(PG8_SB(1, 1), b3 + hstep, voffB); PG8_STAGE(PG8_SA(1, 0), a3, voffA);
;             PG8_WAIT_V(8); PG8_WAIT_L(0); PG8_BAR; PG8_MMA(1, 0, At, B0); PG8_MMA(1, 1, At, B1); PG8_BAR; PG8_SCHED;
	s_setprio 0
	s_add_i32 s38, s45, s66
	v_lshl_add_u64 v[226:227], v[226:227], 0, s[6:7]
	s_mov_b32 m0, s38
	ds_read_b128 v[194:197], v161 offset:49152
	ds_read_b128 v[198:201], v161 offset:50176
	ds_read_b128 v[202:205], v161 offset:51200
	ds_read_b128 v[206:209], v161 offset:52224
	ds_read_b128 v[210:213], v161 offset:53248
	ds_read_b128 v[214:217], v161 offset:54272
	ds_read_b128 v[218:221], v161 offset:55296
	ds_read_b128 v[222:225], v161 offset:56320
	global_load_lds_dwordx4 v[226:227], off
	s_add_i32 m0, s38, 0x2000
	s_add_u32 s36, s36, 0x40080
	v_lshl_add_u64 v[226:227], v[228:229], 0, s[6:7]
	s_addc_u32 s37, s37, 0
	s_add_i32 s38, s46, s66
	global_load_lds_dwordx4 v[226:227], off
	v_lshl_add_u64 v[226:227], s[36:37], 0, v[132:133]
	s_mov_b32 m0, s38
	s_nop 0
	global_load_lds_dwordx4 v[226:227], off
	v_lshl_add_u64 v[226:227], s[36:37], 0, v[136:137]
	s_add_i32 m0, s38, 0x2000
	s_nop 0
	global_load_lds_dwordx4 v[226:227], off
	v_lshl_add_u64 v[226:227], v[230:231], 0, s[6:7]
	s_mov_b32 m0, s73
	s_nop 0
	global_load_lds_dwordx4 v[226:227], off
	v_lshl_add_u64 v[226:227], v[232:233], 0, s[6:7]
	s_mov_b32 m0, s74
	s_nop 0
	global_load_lds_dwordx4 v[226:227], off
	s_waitcnt vmcnt(8)
	s_waitcnt lgkmcnt(0)
	s_setprio 1
	s_barrier
	v_mfma_f32_16x16x32_bf16 v[60:63], v[162:165], v[194:197], v[60:63]
	v_mfma_f32_16x16x32_bf16 v[56:59], v[170:173], v[194:197], v[56:59]
	v_mfma_f32_16x16x32_bf16 v[52:55], v[162:165], v[202:205], v[52:55]
	v_mfma_f32_16x16x32_bf16 v[44:47], v[170:173], v[202:205], v[44:47]
	v_mfma_f32_16x16x32_bf16 v[36:39], v[162:165], v[210:213], v[36:39]
	v_mfma_f32_16x16x32_bf16 v[28:31], v[170:173], v[210:213], v[28:31]
	v_mfma_f32_16x16x32_bf16 v[20:23], v[162:165], v[218:221], v[20:23]
	v_mfma_f32_16x16x32_bf16 v[12:15], v[170:173], v[218:221], v[12:15]
	v_mfma_f32_16x16x32_bf16 v[60:63], v[166:169], v[198:201], v[60:63]
	v_mfma_f32_16x16x32_bf16 v[56:59], v[174:177], v[198:201], v[56:59]
	v_mfma_f32_16x16x32_bf16 v[52:55], v[166:169], v[206:209], v[52:55]
	v_mfma_f32_16x16x32_bf16 v[44:47], v[174:177], v[206:209], v[44:47]
	v_mfma_f32_16x16x32_bf16 v[36:39], v[166:169], v[214:217], v[36:39]
	v_mfma_f32_16x16x32_bf16 v[28:31], v[174:177], v[214:217], v[28:31]
	v_mfma_f32_16x16x32_bf16 v[20:23], v[166:169], v[222:225], v[20:23]
	v_mfma_f32_16x16x32_bf16 v[12:15], v[174:177], v[222:225], v[12:15]
	v_mfma_f32_16x16x32_bf16 v[48:51], v[178:181], v[194:197], v[48:51]
	v_mfma_f32_16x16x32_bf16 v[40:43], v[186:189], v[194:197], v[40:43]
	v_mfma_f32_16x16x32_bf16 v[32:35], v[178:181], v[202:205], v[32:35]
	v_mfma_f32_16x16x32_bf16 v[24:27], v[186:189], v[202:205], v[24:27]
	v_mfma_f32_16x16x32_bf16 v[16:19], v[178:181], v[210:213], v[16:19]
	v_mfma_f32_16x16x32_bf16 v[8:11], v[186:189], v[210:213], v[8:11]
	v_mfma_f32_16x16x32_bf16 v[4:7], v[178:181], v[218:221], v[4:7]
	v_mfma_f32_16x16x32_bf16 v[0:3], v[186:189], v[218:221], v[0:3]
	v_mfma_f32_16x16x32_bf16 v[48:51], v[182:185], v[198:201], v[48:51]
	v_mfma_f32_16x16x32_bf16 v[40:43], v[190:193], v[198:201], v[40:43]
	v_mfma_f32_16x16x32_bf16 v[32:35], v[182:185], v[206:209], v[32:35]
	v_mfma_f32_16x16x32_bf16 v[24:27], v[190:193], v[206:209], v[24:27]
	v_mfma_f32_16x16x32_bf16 v[16:19], v[182:185], v[214:217], v[16:19]
	v_mfma_f32_16x16x32_bf16 v[8:11], v[190:193], v[214:217], v[8:11]
	v_mfma_f32_16x16x32_bf16 v[4:7], v[182:185], v[222:225], v[4:7]
	v_mfma_f32_16x16x32_bf16 v[0:3], v[190:193], v[222:225], v[0:3]
	s_barrier
	s_setprio 0
	s_add_i32 s78, s78, 2
	s_add_u32 s76, s76, 0x100
	s_addc_u32 s77, s77, 0
	s_add_u32 s34, s34, 0x100
	s_addc_u32 s35, s35, 0
	s_cmp_gt_u32 s78, 13
	s_cbranch_scc1 .Lkexit_0
.LBB0_254:
	v_add_u32_e32 v174, s43, v160
	v_add_u32_e32 v190, s44, v160
	ds_read_b128 v[162:165], v174
	ds_read_b128 v[166:169], v174 offset:1024
	ds_read_b128 v[170:173], v174 offset:2048
	ds_read_b128 v[174:177], v174 offset:3072
	ds_read_b128 v[178:181], v190
	ds_read_b128 v[182:185], v190 offset:1024
	ds_read_b128 v[186:189], v190 offset:2048
	ds_read_b128 v[190:193], v190 offset:3072
	s_add_u32 s36, s34, 0xfffc0080
	s_addc_u32 s37, s35, -1
	s_cmp_eq_u32 s78, 12
	s_cselect_b32 s39, s23, s37
	s_cselect_b32 s38, s29, s36
	s_cselect_b32 s37, s21, s77
	s_cselect_b32 s36, s31, s76
	v_lshl_add_u64 v[226:227], s[34:35], 0, v[156:157]
	s_add_i32 m0, s67, 0xc000
	ds_read_b128 v[194:197], v161
	ds_read_b128 v[198:201], v161 offset:1024
	ds_read_b128 v[202:205], v161 offset:2048
	ds_read_b128 v[206:209], v161 offset:3072
	ds_read_b128 v[210:213], v161 offset:4096
	ds_read_b128 v[214:217], v161 offset:5120
	ds_read_b128 v[218:221], v161 offset:6144
	ds_read_b128 v[222:225], v161 offset:7168
	global_load_lds_dwordx4 v[226:227], off
	v_lshl_add_u64 v[226:227], s[34:35], 0, v[154:155]
	s_add_i32 m0, s67, 0xe000
	s_nop 0
	global_load_lds_dwordx4 v[226:227], off
	s_waitcnt vmcnt(8)
	s_waitcnt lgkmcnt(0)
	s_setprio 1
	s_barrier
; #define PG8_STAGE(bufoff, gbase, voff) do { _Pragma("unroll") for (int _i = 0; _i < 2; ++_i) \
;         __builtin_amdgcn_global_load_lds((const unsigned*)((const char*)(gbase) + (voff)[_i]), (PG8_LAS unsigned*)(lds + (bufoff) + ldsw + _i * 8192), 16, 0, 0); } while (0)
; #define PG8_LDA(dst, b, h) do { _Pragma("unroll") for (int m = 0; m < 4; ++m) _Pragma("unroll") for (int k = 0; k < 2; ++k) dst[m][k] = *(const PG8_LAS bf16x8*)(lds + PG8_SA(b, h) + aoff + m * 2048 + k * 1024); } while (0)
; #define PG8_LDB(dst, b, h) do { _Pragma("unroll") for (int n = 0; n < 2; ++n) _Pragma("unroll") for (int k = 0; k < 2; ++k) dst[n][k] = *(const PG8_LAS bf16x8*)(lds + PG8_SB(b, h) + boff + n * 2048 + k * 1024); } while (0)
; #define PG8_MMA(ai, bj, At, Bt) do { __builtin_amdgcn_s_setprio(1); _Pragma("unroll") for (int m = 0; m < 4; ++m) _Pragma("unroll") for (int n = 0; n < 2; ++n) _Pragma("unroll") for (int k = 0; k < 2; ++k) \
;         acc[ai][bj][m][n] = __builtin_amdgcn_mfma_f32_16x16x32_bf16(Bt[n][k], At[m][k], acc[ai][bj][m][n], 0, 0, 0); __builtin_amdgcn_s_setprio(0); } while (0)
; #define PG8_WAIT_V(n) asm volatile("s_waitcnt vmcnt(" #n ")" ::: "memory")
; #define PG8_WAIT_L(n) asm volatile("s_waitcnt lgkmcnt(" #n ")" ::: "memory")
; #define PG8_BAR __builtin_amdgcn_s_barrier()
; #define PG8_SCHED __builtin_amdgcn_sched_barrier(0)
; template <class Epi, class Sched, bool ALIGN_EPI = false, bool SP2 = false>
; __device__ __forceinline__ void gemm_phase(PG8_LAS unsigned char* lds, const Gemm g, const Sched& S, const Epi& E, int wave_in) {
;     ...
;             PG8_WAIT_V(8); PG8_WAIT_L(0); PG8_BAR; PG8_MMA(0, 0, At, B0); PG8_MMA(0, 1, At, B1); PG8_BAR; PG8_SCHED;
;             PG8_LDA(At, 0, 1); PG8_STAGE(PG8_SB(0, 0), b2, voffB); PG8_STAGE(PG8_SB(0, 1), b2 + hstep, voffB); PG8_STAGE(PG8_SA(0, 0), a2, voffA);
;             PG8_WAIT_V(8); PG8_WAIT_L(0); PG8_BAR; PG8_MMA(1, 0, At, B0); PG8_MMA(1, 1, At, B1); PG8_BAR; PG8_SCHED;
;             PG8_LDB(B0, 1, 0); PG8_LDB(B1, 1, 1); PG8_SCHED; PG8_LDA(At, 1, 0); PG8_STAGE(PG8_SA(0, 1), a2 + hstep, voffA);
;             PG8_WAIT_V(8); PG8_WAIT_L(0); PG8_BAR; PG8_MMA(0, 0, At, B0); PG8_MMA(0, 1, At, B1); PG8_BAR; PG8_SCHED;
	v_mfma_f32_16x16x32_bf16 v[124:127], v[162:165], v[194:197], v[124:127]
	v_mfma_f32_16x16x32_bf16 v[120:123], v[170:173], v[194:197], v[120:123]
	v_mfma_f32_16x16x32_bf16 v[116:119], v[162:165], v[202:205], v[116:119]
	v_mfma_f32_16x16x32_bf16 v[108:111], v[170:173], v[202:205], v[108:111]
	v_mfma_f32_16x16x32_bf16 v[100:103], v[162:165], v[210:213], v[100:103]
	v_mfma_f32_16x16x32_bf16 v[92:95], v[170:173], v[210:213], v[92:95]
	v_mfma_f32_16x16x32_bf16 v[84:87], v[162:165], v[218:221], v[84:87]
	v_mfma_f32_16x16x32_bf16 v[76:79], v[170:173], v[218:221], v[76:79]
	v_mfma_f32_16x16x32_bf16 v[124:127], v[166:169], v[198:201], v[124:127]
	v_mfma_f32_16x16x32_bf16 v[120:123], v[174:177], v[198:201], v[120:123]
	v_mfma_f32_16x16x32_bf16 v[116:119], v[166:169], v[206:209], v[116:119]
	v_mfma_f32_16x16x32_bf16 v[108:111], v[174:177], v[206:209], v[108:111]
	v_mfma_f32_16x16x32_bf16 v[100:103], v[166:169], v[214:217], v[100:103]
	v_mfma_f32_16x16x32_bf16 v[92:95], v[174:177], v[214:217], v[92:95]
	v_mfma_f32_16x16x32_bf16 v[84:87], v[166:169], v[222:225], v[84:87]
	v_mfma_f32_16x16x32_bf16 v[76:79], v[174:177], v[222:225], v[76:79]
	v_mfma_f32_16x16x32_bf16 v[112:115], v[178:181], v[194:197], v[112:115]
	v_mfma_f32_16x16x32_bf16 v[104:107], v[186:189], v[194:197], v[104:107]
	v_mfma_f32_16x16x32_bf16 v[96:99], v[178:181], v[202:205], v[96:99]
	v_mfma_f32_16x16x32_bf16 v[88:91], v[186:189], v[202:205], v[88:91]
	v_mfma_f32_16x16x32_bf16 v[80:83], v[178:181], v[210:213], v[80:83]
	v_mfma_f32_16x16x32_bf16 v[72:75], v[186:189], v[210:213], v[72:75]
	v_mfma_f32_16x16x32_bf16 v[68:71], v[178:181], v[218:221], v[68:71]
	v_mfma_f32_16x16x32_bf16 v[64:67], v[186:189], v[218:221], v[64:67]
	v_mfma_f32_16x16x32_bf16 v[112:115], v[182:185], v[198:201], v[112:115]
	v_mfma_f32_16x16x32_bf16 v[104:107], v[190:193], v[198:201], v[104:107]
	v_mfma_f32_16x16x32_bf16 v[96:99], v[182:185], v[206:209], v[96:99]
	v_mfma_f32_16x16x32_bf16 v[88:91], v[190:193], v[206:209], v[88:91]
	v_mfma_f32_16x16x32_bf16 v[80:83], v[182:185], v[214:217], v[80:83]
	v_mfma_f32_16x16x32_bf16 v[72:75], v[190:193], v[214:217], v[72:75]
	v_mfma_f32_16x16x32_bf16 v[68:71], v[182:185], v[222:225], v[68:71]
	v_mfma_f32_16x16x32_bf16 v[64:67], v[190:193], v[222:225], v[64:67]
	s_barrier
	s_setprio 0
	s_add_i32 s79, s43, s66
	v_lshl_add_u64 v[226:227], s[36:37], 0, v[132:133]
	s_mov_b32 m0, s79
	ds_read_b128 v[194:197], v161 offset:16384
	ds_read_b128 v[198:201], v161 offset:17408
	ds_read_b128 v[202:205], v161 offset:18432
	ds_read_b128 v[206:209], v161 offset:19456
	ds_read_b128 v[210:213], v161 offset:20480
	ds_read_b128 v[214:217], v161 offset:21504
	ds_read_b128 v[218:221], v161 offset:22528
	ds_read_b128 v[222:225], v161 offset:23552
	global_load_lds_dwordx4 v[226:227], off
	s_add_i32 m0, s79, 0x2000
	s_add_u32 s80, s36, 0x40000
	v_lshl_add_u64 v[228:229], s[36:37], 0, v[136:137]
	s_addc_u32 s81, s37, 0
	s_add_i32 s79, s44, s66
	global_load_lds_dwordx4 v[228:229], off
	v_lshl_add_u64 v[230:231], s[80:81], 0, v[132:133]
	s_mov_b32 m0, s79
	v_lshl_add_u64 v[232:233], s[38:39], 0, v[134:135]
	global_load_lds_dwordx4 v[230:231], off
	v_lshl_add_u64 v[230:231], s[80:81], 0, v[136:137]
	s_add_i32 m0, s79, 0x2000
	s_nop 0
	global_load_lds_dwordx4 v[230:231], off
	v_lshl_add_u64 v[230:231], s[38:39], 0, v[130:131]
	s_mov_b32 m0, s67
	s_nop 0
	global_load_lds_dwordx4 v[230:231], off
	s_mov_b32 m0, s68
	s_nop 0
	global_load_lds_dwordx4 v[232:233], off
	s_waitcnt vmcnt(8)
	s_waitcnt lgkmcnt(0)
	s_setprio 1
	s_barrier
	v_mfma_f32_16x16x32_bf16 v[60:63], v[162:165], v[194:197], v[60:63]
	v_mfma_f32_16x16x32_bf16 v[56:59], v[170:173], v[194:197], v[56:59]
	v_mfma_f32_16x16x32_bf16 v[52:55], v[162:165], v[202:205], v[52:55]
	v_mfma_f32_16x16x32_bf16 v[44:47], v[170:173], v[202:205], v[44:47]
	v_mfma_f32_16x16x32_bf16 v[36:39], v[162:165], v[210:213], v[36:39]
	v_mfma_f32_16x16x32_bf16 v[28:31], v[170:173], v[210:213], v[28:31]
	v_mfma_f32_16x16x32_bf16 v[20:23], v[162:165], v[218:221], v[20:23]
	v_mfma_f32_16x16x32_bf16 v[12:15], v[170:173], v[218:221], v[12:15]
	v_mfma_f32_16x16x32_bf16 v[60:63], v[166:169], v[198:201], v[60:63]
	v_mfma_f32_16x16x32_bf16 v[56:59], v[174:177], v[198:201], v[56:59]
	v_mfma_f32_16x16x32_bf16 v[52:55], v[166:169], v[206:209], v[52:55]
	v_mfma_f32_16x16x32_bf16 v[44:47], v[174:177], v[206:209], v[44:47]
	v_mfma_f32_16x16x32_bf16 v[36:39], v[166:169], v[214:217], v[36:39]
	v_mfma_f32_16x16x32_bf16 v[28:31], v[174:177], v[214:217], v[28:31]
	v_mfma_f32_16x16x32_bf16 v[20:23], v[166:169], v[222:225], v[20:23]
	v_mfma_f32_16x16x32_bf16 v[12:15], v[174:177], v[222:225], v[12:15]
	v_mfma_f32_16x16x32_bf16 v[48:51], v[178:181], v[194:197], v[48:51]
	v_mfma_f32_16x16x32_bf16 v[40:43], v[186:189], v[194:197], v[40:43]
	v_mfma_f32_16x16x32_bf16 v[32:35], v[178:181], v[202:205], v[32:35]
	v_mfma_f32_16x16x32_bf16 v[24:27], v[186:189], v[202:205], v[24:27]
	v_mfma_f32_16x16x32_bf16 v[16:19], v[178:181], v[210:213], v[16:19]
	v_mfma_f32_16x16x32_bf16 v[8:11], v[186:189], v[210:213], v[8:11]
	v_mfma_f32_16x16x32_bf16 v[4:7], v[178:181], v[218:221], v[4:7]
	v_mfma_f32_16x16x32_bf16 v[0:3], v[186:189], v[218:221], v[0:3]
	v_mfma_f32_16x16x32_bf16 v[48:51], v[182:185], v[198:201], v[48:51]
	v_mfma_f32_16x16x32_bf16 v[40:43], v[190:193], v[198:201], v[40:43]
	v_mfma_f32_16x16x32_bf16 v[32:35], v[182:185], v[206:209], v[32:35]
	v_mfma_f32_16x16x32_bf16 v[24:27], v[190:193], v[206:209], v[24:27]
	v_mfma_f32_16x16x32_bf16 v[16:19], v[182:185], v[214:217], v[16:19]
	v_mfma_f32_16x16x32_bf16 v[8:11], v[190:193], v[214:217], v[8:11]
	v_mfma_f32_16x16x32_bf16 v[4:7], v[182:185], v[222:225], v[4:7]
	v_mfma_f32_16x16x32_bf16 v[0:3], v[190:193], v[222:225], v[0:3]
	s_barrier
; #define PG8_STAGE(bufoff, gbase, voff) do { _Pragma("unroll") for (int _i = 0; _i < 2; ++_i) \
;         __builtin_amdgcn_global_load_lds((const unsigned*)((const char*)(gbase) + (voff)[_i]), (PG8_LAS unsigned*)(lds + (bufoff) + ldsw + _i * 8192), 16, 0, 0); } while (0)
; #define PG8_LDA(dst, b, h) do { _Pragma("unroll") for (int m = 0; m < 4; ++m) _Pragma("unroll") for (int k = 0; k < 2; ++k) dst[m][k] = *(const PG8_LAS bf16x8*)(lds + PG8_SA(b, h) + aoff + m * 2048 + k * 1024); } while (0)
; #define PG8_LDB(dst, b, h) do { _Pragma("unroll") for (int n = 0; n < 2; ++n) _Pragma("unroll") for (int k = 0; k < 2; ++k) dst[n][k] = *(const PG8_LAS bf16x8*)(lds + PG8_SB(b, h) + boff + n * 2048 + k * 1024); } while (0)
; #define PG8_MMA(ai, bj, At, Bt) do { __builtin_amdgcn_s_setprio(1); _Pragma("unroll") for (int m = 0; m < 4; ++m) _Pragma("unroll") for (int n = 0; n < 2; ++n) _Pragma("unroll") for (int k = 0; k < 2; ++k) \
;         acc[ai][bj][m][n] = __builtin_amdgcn_mfma_f32_16x16x32_bf16(Bt[n][k], At[m][k], acc[ai][bj][m][n], 0, 0, 0); __builtin_amdgcn_s_setprio(0); } while (0)
; #define PG8_WAIT_V(n) asm volatile("s_waitcnt vmcnt(" #n ")" ::: "memory")
; #define PG8_WAIT_L(n) asm volatile("s_waitcnt lgkmcnt(" #n ")" ::: "memory")
; #define PG8_BAR __builtin_amdgcn_s_barrier()
; #define PG8_SCHED __builtin_amdgcn_sched_barrier(0)
; template <class Epi, class Sched, bool ALIGN_EPI = false, bool SP2 = false>
; __device__ __forceinline__ void gemm_phase(PG8_LAS unsigned char* lds, const Gemm g, const Sched& S, const Epi& E, int wave_in) {
;     ...
;             PG8_LDB(B0, 1, 0); PG8_LDB(B1, 1, 1); PG8_SCHED; PG8_LDA(At, 1, 0); PG8_STAGE(PG8_SA(0, 1), a2 + hstep, voffA);
;             PG8_WAIT_V(8); PG8_WAIT_L(0); PG8_BAR; PG8_MMA(0, 0, At, B0); PG8_MMA(0, 1, At, B1); PG8_BAR; PG8_SCHED;
;             PG8_LDA(At, 1, 1); PG8_STAGE(PG8_SB(1, 0), b3, voffB); PG8_STAGE(PG8_SB(1, 1), b3 + hstep, voffB); PG8_STAGE(PG8_SA(1, 0), a3, voffA);
;             PG8_WAIT_V(8); PG8_WAIT_L(0); PG8_BAR; PG8_MMA(1, 0, At, B0); PG8_MMA(1, 1, At, B1); PG8_BAR; PG8_SCHED;
	s_setprio 0
	v_add_u32_e32 v174, s45, v160
	v_add_u32_e32 v190, s46, v160
	ds_read_b128 v[162:165], v174
	ds_read_b128 v[166:169], v174 offset:1024
	ds_read_b128 v[170:173], v174 offset:2048
	ds_read_b128 v[174:177], v174 offset:3072
	ds_read_b128 v[178:181], v190
	ds_read_b128 v[182:185], v190 offset:1024
	ds_read_b128 v[186:189], v190 offset:2048
	ds_read_b128 v[190:193], v190 offset:3072
	s_add_u32 s38, s38, 0x40000
	s_addc_u32 s39, s39, 0
	s_mov_b32 m0, s69
	v_lshl_add_u64 v[234:235], s[38:39], 0, v[130:131]
	ds_read_b128 v[194:197], v161 offset:32768
	ds_read_b128 v[198:201], v161 offset:33792
	ds_read_b128 v[202:205], v161 offset:34816
	ds_read_b128 v[206:209], v161 offset:35840
	ds_read_b128 v[210:213], v161 offset:36864
	ds_read_b128 v[214:217], v161 offset:37888
	ds_read_b128 v[218:221], v161 offset:38912
	ds_read_b128 v[222:225], v161 offset:39936
	global_load_lds_dwordx4 v[234:235], off
	v_lshl_add_u64 v[234:235], s[38:39], 0, v[134:135]
	s_mov_b32 m0, s70
	s_nop 0
	global_load_lds_dwordx4 v[234:235], off
	s_waitcnt vmcnt(8)
	s_waitcnt lgkmcnt(0)
	s_setprio 1
	s_barrier
	v_mfma_f32_16x16x32_bf16 v[124:127], v[162:165], v[194:197], v[124:127]
	v_mfma_f32_16x16x32_bf16 v[120:123], v[170:173], v[194:197], v[120:123]
	v_mfma_f32_16x16x32_bf16 v[116:119], v[162:165], v[202:205], v[116:119]
	v_mfma_f32_16x16x32_bf16 v[108:111], v[170:173], v[202:205], v[108:111]
	v_mfma_f32_16x16x32_bf16 v[100:103], v[162:165], v[210:213], v[100:103]
	v_mfma_f32_16x16x32_bf16 v[92:95], v[170:173], v[210:213], v[92:95]
	v_mfma_f32_16x16x32_bf16 v[84:87], v[162:165], v[218:221], v[84:87]
	v_mfma_f32_16x16x32_bf16 v[76:79], v[170:173], v[218:221], v[76:79]
	v_mfma_f32_16x16x32_bf16 v[124:127], v[166:169], v[198:201], v[124:127]
	v_mfma_f32_16x16x32_bf16 v[120:123], v[174:177], v[198:201], v[120:123]
	v_mfma_f32_16x16x32_bf16 v[116:119], v[166:169], v[206:209], v[116:119]
	v_mfma_f32_16x16x32_bf16 v[108:111], v[174:177], v[206:209], v[108:111]
	v_mfma_f32_16x16x32_bf16 v[100:103], v[166:169], v[214:217], v[100:103]
	v_mfma_f32_16x16x32_bf16 v[92:95], v[174:177], v[214:217], v[92:95]
	v_mfma_f32_16x16x32_bf16 v[84:87], v[166:169], v[222:225], v[84:87]
	v_mfma_f32_16x16x32_bf16 v[76:79], v[174:177], v[222:225], v[76:79]
	v_mfma_f32_16x16x32_bf16 v[112:115], v[178:181], v[194:197], v[112:115]
	v_mfma_f32_16x16x32_bf16 v[104:107], v[186:189], v[194:197], v[104:107]
	v_mfma_f32_16x16x32_bf16 v[96:99], v[178:181], v[202:205], v[96:99]
	v_mfma_f32_16x16x32_bf16 v[88:91], v[186:189], v[202:205], v[88:91]
	v_mfma_f32_16x16x32_bf16 v[80:83], v[178:181], v[210:213], v[80:83]
	v_mfma_f32_16x16x32_bf16 v[72:75], v[186:189], v[210:213], v[72:75]
	v_mfma_f32_16x16x32_bf16 v[68:71], v[178:181], v[218:221], v[68:71]
	v_mfma_f32_16x16x32_bf16 v[64:67], v[186:189], v[218:221], v[64:67]
	v_mfma_f32_16x16x32_bf16 v[112:115], v[182:185], v[198:201], v[112:115]
	v_mfma_f32_16x16x32_bf16 v[104:107], v[190:193], v[198:201], v[104:107]
	v_mfma_f32_16x16x32_bf16 v[96:99], v[182:185], v[206:209], v[96:99]
	v_mfma_f32_16x16x32_bf16 v[88:91], v[190:193], v[206:209], v[88:91]
	v_mfma_f32_16x16x32_bf16 v[80:83], v[182:185], v[214:217], v[80:83]
	v_mfma_f32_16x16x32_bf16 v[72:75], v[190:193], v[214:217], v[72:75]
	v_mfma_f32_16x16x32_bf16 v[68:71], v[182:185], v[222:225], v[68:71]
	v_mfma_f32_16x16x32_bf16 v[64:67], v[190:193], v[222:225], v[64:67]
	s_barrier
	s_setprio 0
	s_add_i32 s38, s45, s66
	v_lshl_add_u64 v[226:227], v[226:227], 0, s[6:7]
	s_mov_b32 m0, s38
	ds_read_b128 v[194:197], v161 offset:49152
	ds_read_b128 v[198:201], v161 offset:50176
	ds_read_b128 v[202:205], v161 offset:51200
	ds_read_b128 v[206:209], v161 offset:52224
	ds_read_b128 v[210:213], v161 offset:53248
	ds_read_b128 v[214:217], v161 offset:54272
	ds_read_b128 v[218:221], v161 offset:55296
	ds_read_b128 v[222:225], v161 offset:56320
	global_load_lds_dwordx4 v[226:227], off
	s_add_i32 m0, s38, 0x2000
	s_add_u32 s36, s36, 0x40080
	v_lshl_add_u64 v[226:227], v[228:229], 0, s[6:7]
	s_addc_u32 s37, s37, 0
	s_add_i32 s38, s46, s66
	global_load_lds_dwordx4 v[226:227], off
	v_lshl_add_u64 v[226:227], s[36:37], 0, v[132:133]
	s_mov_b32 m0, s38
	s_nop 0
	global_load_lds_dwordx4 v[226:227], off
	v_lshl_add_u64 v[226:227], s[36:37], 0, v[136:137]
	s_add_i32 m0, s38, 0x2000
	s_nop 0
	global_load_lds_dwordx4 v[226:227], off
	v_lshl_add_u64 v[226:227], v[230:231], 0, s[6:7]
	s_mov_b32 m0, s73
	s_nop 0
	global_load_lds_dwordx4 v[226:227], off
	v_lshl_add_u64 v[226:227], v[232:233], 0, s[6:7]
	s_mov_b32 m0, s74
	s_nop 0
	global_load_lds_dwordx4 v[226:227], off
	s_waitcnt vmcnt(8)
	s_waitcnt lgkmcnt(0)
	s_setprio 1
	s_barrier
	v_mfma_f32_16x16x32_bf16 v[60:63], v[162:165], v[194:197], v[60:63]
	v_mfma_f32_16x16x32_bf16 v[56:59], v[170:173], v[194:197], v[56:59]
	v_mfma_f32_16x16x32_bf16 v[52:55], v[162:165], v[202:205], v[52:55]
	v_mfma_f32_16x16x32_bf16 v[44:47], v[170:173], v[202:205], v[44:47]
	v_mfma_f32_16x16x32_bf16 v[36:39], v[162:165], v[210:213], v[36:39]
	v_mfma_f32_16x16x32_bf16 v[28:31], v[170:173], v[210:213], v[28:31]
	v_mfma_f32_16x16x32_bf16 v[20:23], v[162:165], v[218:221], v[20:23]
	v_mfma_f32_16x16x32_bf16 v[12:15], v[170:173], v[218:221], v[12:15]
	v_mfma_f32_16x16x32_bf16 v[60:63], v[166:169], v[198:201], v[60:63]
	v_mfma_f32_16x16x32_bf16 v[56:59], v[174:177], v[198:201], v[56:59]
	v_mfma_f32_16x16x32_bf16 v[52:55], v[166:169], v[206:209], v[52:55]
	v_mfma_f32_16x16x32_bf16 v[44:47], v[174:177], v[206:209], v[44:47]
	v_mfma_f32_16x16x32_bf16 v[36:39], v[166:169], v[214:217], v[36:39]
	v_mfma_f32_16x16x32_bf16 v[28:31], v[174:177], v[214:217], v[28:31]
	v_mfma_f32_16x16x32_bf16 v[20:23], v[166:169], v[222:225], v[20:23]
	v_mfma_f32_16x16x32_bf16 v[12:15], v[174:177], v[222:225], v[12:15]
	v_mfma_f32_16x16x32_bf16 v[48:51], v[178:181], v[194:197], v[48:51]
	v_mfma_f32_16x16x32_bf16 v[40:43], v[186:189], v[194:197], v[40:43]
	v_mfma_f32_16x16x32_bf16 v[32:35], v[178:181], v[202:205], v[32:35]
	v_mfma_f32_16x16x32_bf16 v[24:27], v[186:189], v[202:205], v[24:27]
	v_mfma_f32_16x16x32_bf16 v[16:19], v[178:181], v[210:213], v[16:19]
	v_mfma_f32_16x16x32_bf16 v[8:11], v[186:189], v[210:213], v[8:11]
	v_mfma_f32_16x16x32_bf16 v[4:7], v[178:181], v[218:221], v[4:7]
	v_mfma_f32_16x16x32_bf16 v[0:3], v[186:189], v[218:221], v[0:3]
	v_mfma_f32_16x16x32_bf16 v[48:51], v[182:185], v[198:201], v[48:51]
	v_mfma_f32_16x16x32_bf16 v[40:43], v[190:193], v[198:201], v[40:43]
	v_mfma_f32_16x16x32_bf16 v[32:35], v[182:185], v[206:209], v[32:35]
	v_mfma_f32_16x16x32_bf16 v[24:27], v[190:193], v[206:209], v[24:27]
	v_mfma_f32_16x16x32_bf16 v[16:19], v[182:185], v[214:217], v[16:19]
	v_mfma_f32_16x16x32_bf16 v[8:11], v[190:193], v[214:217], v[8:11]
	v_mfma_f32_16x16x32_bf16 v[4:7], v[182:185], v[222:225], v[4:7]
	v_mfma_f32_16x16x32_bf16 v[0:3], v[190:193], v[222:225], v[0:3]
	s_barrier
	s_setprio 0
	s_add_i32 s78, s78, 2
	s_add_u32 s76, s76, 0x100
	s_addc_u32 s77, s77, 0
	s_add_u32 s34, s34, 0x100
	s_addc_u32 s35, s35, 0
	s_cmp_gt_u32 s78, 13
	s_cbranch_scc0 .LBB0_254

; #define PG8_STAGE(bufoff, gbase, voff) do { _Pragma("unroll") for (int _i = 0; _i < 2; ++_i) \
;         __builtin_amdgcn_global_load_lds((const unsigned*)((const char*)(gbase) + (voff)[_i]), (PG8_LAS unsigned*)(lds + (bufoff) + ldsw + _i * 8192), 16, 0, 0); } while (0)
; #define PG8_LDA(dst, b, h) do { _Pragma("unroll") for (int m = 0; m < 4; ++m) _Pragma("unroll") for (int k = 0; k < 2; ++k) dst[m][k] = *(const PG8_LAS bf16x8*)(lds + PG8_SA(b, h) + aoff + m * 2048 + k * 1024); } while (0)
; #define PG8_LDB(dst, b, h) do { _Pragma("unroll") for (int n = 0; n < 2; ++n) _Pragma("unroll") for (int k = 0; k < 2; ++k) dst[n][k] = *(const PG8_LAS bf16x8*)(lds + PG8_SB(b, h) + boff + n * 2048 + k * 1024); } while (0)
; #define PG8_MMA(ai, bj, At, Bt) do { __builtin_amdgcn_s_setprio(1); _Pragma("unroll") for (int m = 0; m < 4; ++m) _Pragma("unroll") for (int n = 0; n < 2; ++n) _Pragma("unroll") for (int k = 0; k < 2; ++k) \
;         acc[ai][bj][m][n] = __builtin_amdgcn_mfma_f32_16x16x32_bf16(Bt[n][k], At[m][k], acc[ai][bj][m][n], 0, 0, 0); __builtin_amdgcn_s_setprio(0); } while (0)
; template <class Epi, class Sched, bool ALIGN_EPI = false, bool SP2 = false>
; __device__ __forceinline__ void gemm_phase(PG8_LAS unsigned char* lds, const Gemm g, const Sched& S, const Epi& E, int wave_in) {
;     ...
;         const char* nA = has_next ? (const char*)g.A + (size_t)(nxt.pm >> g.ash) * g.astride + (size_t)nxt.pm * tstep : cA; const char* nB = has_next ? (const char*)g.Bt + (size_t)(nxt.pm >> g.bsh) * g.bstride + (size_t)nxt.pn * tstep : cB;
;         for (int t = 0; t < nt; t += 2) {
;             const bool last = (t == nt - 2);
;             const char* a1 = cA + (size_t)(t + 1) * kstep;
;             const char* a2 = last ? nA : cA + (size_t)(t + 2) * kstep; const char* b2 = last ? nB : cB + (size_t)(t + 2) * kstep;
;             const char* a3 = a2 + kstep; const char* b3 = b2 + kstep;
;             if (last && has_next) S.a_ready(nxt);
;             if constexpr (SP2) {
;             PG8_LDB(B0, 0, 0); PG8_LDB(B1, 0, 1); PG8_SCHED; PG8_LDA(At, 0, 0); PG8_STAGE(PG8_SA(1, 1), a1 + hstep, voffA);
;             PG8_WAIT_V(8); PG8_WAIT_L(0); PG8_BAR; PG8_MMA(0, 0, At, B0); PG8_MMA(0, 1, At, B1); PG8_BAR; PG8_SCHED;
;             PG8_LDA(At, 0, 1); PG8_STAGE(PG8_SB(0, 0), b2, voffB); PG8_STAGE(PG8_SB(0, 1), b2 + hstep, voffB); PG8_STAGE(PG8_SA(0, 0), a2, voffA);
.LBB0_272:
	s_ashr_i32 s77, s76, 31
	s_lshl_b64 s[8:9], s[76:77], 19
	s_add_u32 s84, s22, s8
	s_addc_u32 s85, s23, s9
	s_and_b64 s[8:9], s[40:41], exec
	s_cselect_b32 s8, s85, s5
	s_cselect_b32 s9, s84, s4
	s_ashr_i32 s95, s94, 31
	s_lshl_b64 s[10:11], s[94:95], 19
	v_readlane_b32 s16, v255, 39
	v_readlane_b32 s17, v255, 40
	s_add_u32 s24, s16, s10
	s_addc_u32 s25, s17, s11
	s_and_b64 s[10:11], s[40:41], exec
	s_cselect_b32 s16, s25, s1
	s_cselect_b32 s17, s24, s0
	s_add_u32 s31, s0, 0x100
	s_addc_u32 s33, s1, 0
	s_add_u32 s0, s4, 0x40080
	s_addc_u32 s1, s5, 0
	s_mov_b32 s34, -2
	s_waitcnt lgkmcnt(0)
	s_add_u32 s4, s0, 0xfffc0080
	s_addc_u32 s5, s1, -1
	s_add_i32 s42, s35, 0x100
	s_cmp_eq_u32 s34, 12
	s_cselect_b32 s11, s8, s5
	s_cselect_b32 s10, s9, s4
	s_cselect_b32 s5, s16, s33
	s_cselect_b32 s4, s17, s31
	s_add_i32 s44, s90, 0x100
	v_add_u32_e32 v168, s42, v177
	v_add_u32_e32 v188, s44, v177
	ds_read_b128 v[156:159], v168
	ds_read_b128 v[160:163], v168 offset:1024
	ds_read_b128 v[164:167], v168 offset:2048
	ds_read_b128 v[168:171], v168 offset:3072
	ds_read_b128 v[172:175], v188
	ds_read_b128 v[180:183], v188 offset:1024
	ds_read_b128 v[184:187], v188 offset:2048
	ds_read_b128 v[188:191], v188 offset:3072
	v_lshl_add_u64 v[230:231], s[0:1], 0, v[154:155]
	s_add_i32 m0, s67, 0xc000
	ds_read_b128 v[198:201], v179
	ds_read_b128 v[202:205], v179 offset:1024
	ds_read_b128 v[206:209], v179 offset:2048
	ds_read_b128 v[210:213], v179 offset:3072
	ds_read_b128 v[214:217], v179 offset:4096
	ds_read_b128 v[218:221], v179 offset:5120
	ds_read_b128 v[222:225], v179 offset:6144
	ds_read_b128 v[226:229], v179 offset:7168
	global_load_lds_dwordx4 v[230:231], off
	v_lshl_add_u64 v[230:231], s[0:1], 0, v[152:153]
	s_add_i32 m0, s67, 0xe000
	s_nop 0
	global_load_lds_dwordx4 v[230:231], off
	s_waitcnt vmcnt(8)
	s_waitcnt lgkmcnt(0)
	s_setprio 1
	s_barrier
	v_mfma_f32_16x16x32_bf16 v[124:127], v[156:159], v[198:201], 0
	v_mfma_f32_16x16x32_bf16 v[120:123], v[164:167], v[198:201], 0
	v_mfma_f32_16x16x32_bf16 v[108:111], v[156:159], v[206:209], 0
	v_mfma_f32_16x16x32_bf16 v[104:107], v[164:167], v[206:209], 0
	v_mfma_f32_16x16x32_bf16 v[92:95], v[156:159], v[214:217], 0
	v_mfma_f32_16x16x32_bf16 v[88:91], v[164:167], v[214:217], 0
	v_mfma_f32_16x16x32_bf16 v[76:79], v[156:159], v[222:225], 0
	v_mfma_f32_16x16x32_bf16 v[72:75], v[164:167], v[222:225], 0
	v_mfma_f32_16x16x32_bf16 v[124:127], v[160:163], v[202:205], v[124:127]
	v_mfma_f32_16x16x32_bf16 v[120:123], v[168:171], v[202:205], v[120:123]
	v_mfma_f32_16x16x32_bf16 v[108:111], v[160:163], v[210:213], v[108:111]
	v_mfma_f32_16x16x32_bf16 v[104:107], v[168:171], v[210:213], v[104:107]
	v_mfma_f32_16x16x32_bf16 v[92:95], v[160:163], v[218:221], v[92:95]
	v_mfma_f32_16x16x32_bf16 v[88:91], v[168:171], v[218:221], v[88:91]
	v_mfma_f32_16x16x32_bf16 v[76:79], v[160:163], v[226:229], v[76:79]
	v_mfma_f32_16x16x32_bf16 v[72:75], v[168:171], v[226:229], v[72:75]
	v_mfma_f32_16x16x32_bf16 v[116:119], v[172:175], v[198:201], 0
	v_mfma_f32_16x16x32_bf16 v[112:115], v[184:187], v[198:201], 0
	v_mfma_f32_16x16x32_bf16 v[100:103], v[172:175], v[206:209], 0
	v_mfma_f32_16x16x32_bf16 v[96:99], v[184:187], v[206:209], 0
	v_mfma_f32_16x16x32_bf16 v[84:87], v[172:175], v[214:217], 0
	v_mfma_f32_16x16x32_bf16 v[80:83], v[184:187], v[214:217], 0
	v_mfma_f32_16x16x32_bf16 v[68:71], v[172:175], v[222:225], 0
	v_mfma_f32_16x16x32_bf16 v[64:67], v[184:187], v[222:225], 0
	v_mfma_f32_16x16x32_bf16 v[116:119], v[180:183], v[202:205], v[116:119]
	v_mfma_f32_16x16x32_bf16 v[112:115], v[188:191], v[202:205], v[112:115]
	v_mfma_f32_16x16x32_bf16 v[100:103], v[180:183], v[210:213], v[100:103]
	v_mfma_f32_16x16x32_bf16 v[96:99], v[188:191], v[210:213], v[96:99]
	v_mfma_f32_16x16x32_bf16 v[84:87], v[180:183], v[218:221], v[84:87]
	v_mfma_f32_16x16x32_bf16 v[80:83], v[188:191], v[218:221], v[80:83]
	v_mfma_f32_16x16x32_bf16 v[68:71], v[180:183], v[226:229], v[68:71]
	v_mfma_f32_16x16x32_bf16 v[64:67], v[188:191], v[226:229], v[64:67]
	s_barrier
	s_setprio 0
	s_add_i32 s42, s42, s66
	v_lshl_add_u64 v[230:231], s[4:5], 0, v[132:133]
	s_mov_b32 m0, s42
	ds_read_b128 v[198:201], v179 offset:16384
	ds_read_b128 v[202:205], v179 offset:17408
	ds_read_b128 v[206:209], v179 offset:18432
	ds_read_b128 v[210:213], v179 offset:19456
	ds_read_b128 v[214:217], v179 offset:20480
	ds_read_b128 v[218:221], v179 offset:21504
	ds_read_b128 v[222:225], v179 offset:22528
	ds_read_b128 v[226:229], v179 offset:23552
	global_load_lds_dwordx4 v[230:231], off
	s_add_i32 m0, s42, 0x2000
	s_add_u32 s42, s4, 0x40000
	v_lshl_add_u64 v[232:233], s[4:5], 0, v[128:129]
	s_addc_u32 s43, s5, 0
	s_add_i32 s44, s44, s66
	global_load_lds_dwordx4 v[232:233], off
	v_lshl_add_u64 v[234:235], s[42:43], 0, v[132:133]
	s_mov_b32 m0, s44
	v_lshl_add_u64 v[236:237], s[10:11], 0, v[130:131]
	global_load_lds_dwordx4 v[234:235], off
	v_lshl_add_u64 v[234:235], s[42:43], 0, v[128:129]
	s_add_i32 m0, s44, 0x2000
	s_nop 0
	global_load_lds_dwordx4 v[234:235], off
	v_lshl_add_u64 v[234:235], s[10:11], 0, v[134:135]
	s_mov_b32 m0, s67
	s_nop 0
	global_load_lds_dwordx4 v[234:235], off
	s_mov_b32 m0, s78
	s_nop 0
	global_load_lds_dwordx4 v[236:237], off
	s_waitcnt vmcnt(8)
	s_waitcnt lgkmcnt(0)
	s_setprio 1
	s_barrier
; #define PG8_STAGE(bufoff, gbase, voff) do { _Pragma("unroll") for (int _i = 0; _i < 2; ++_i) \
;         __builtin_amdgcn_global_load_lds((const unsigned*)((const char*)(gbase) + (voff)[_i]), (PG8_LAS unsigned*)(lds + (bufoff) + ldsw + _i * 8192), 16, 0, 0); } while (0)
; #define PG8_LDA(dst, b, h) do { _Pragma("unroll") for (int m = 0; m < 4; ++m) _Pragma("unroll") for (int k = 0; k < 2; ++k) dst[m][k] = *(const PG8_LAS bf16x8*)(lds + PG8_SA(b, h) + aoff + m * 2048 + k * 1024); } while (0)
; #define PG8_LDB(dst, b, h) do { _Pragma("unroll") for (int n = 0; n < 2; ++n) _Pragma("unroll") for (int k = 0; k < 2; ++k) dst[n][k] = *(const PG8_LAS bf16x8*)(lds + PG8_SB(b, h) + boff + n * 2048 + k * 1024); } while (0)
; #define PG8_MMA(ai, bj, At, Bt) do { __builtin_amdgcn_s_setprio(1); _Pragma("unroll") for (int m = 0; m < 4; ++m) _Pragma("unroll") for (int n = 0; n < 2; ++n) _Pragma("unroll") for (int k = 0; k < 2; ++k) \
;         acc[ai][bj][m][n] = __builtin_amdgcn_mfma_f32_16x16x32_bf16(Bt[n][k], At[m][k], acc[ai][bj][m][n], 0, 0, 0); __builtin_amdgcn_s_setprio(0); } while (0)
; #define PG8_WAIT_V(n) asm volatile("s_waitcnt vmcnt(" #n ")" ::: "memory")
; #define PG8_WAIT_L(n) asm volatile("s_waitcnt lgkmcnt(" #n ")" ::: "memory")
; #define PG8_BAR __builtin_amdgcn_s_barrier()
; #define PG8_SCHED __builtin_amdgcn_sched_barrier(0)
; template <class Epi, class Sched, bool ALIGN_EPI = false, bool SP2 = false>
; __device__ __forceinline__ void gemm_phase(PG8_LAS unsigned char* lds, const Gemm g, const Sched& S, const Epi& E, int wave_in) {
;     ...
;             PG8_WAIT_V(8); PG8_WAIT_L(0); PG8_BAR; PG8_MMA(1, 0, At, B0); PG8_MMA(1, 1, At, B1); PG8_BAR; PG8_SCHED;
;             PG8_LDB(B0, 1, 0); PG8_LDB(B1, 1, 1); PG8_SCHED; PG8_LDA(At, 1, 0); PG8_STAGE(PG8_SA(0, 1), a2 + hstep, voffA);
;             PG8_WAIT_V(8); PG8_WAIT_L(0); PG8_BAR; PG8_MMA(0, 0, At, B0); PG8_MMA(0, 1, At, B1); PG8_BAR; PG8_SCHED;
	v_mfma_f32_16x16x32_bf16 v[60:63], v[156:159], v[198:201], 0
	v_mfma_f32_16x16x32_bf16 v[56:59], v[164:167], v[198:201], 0
	v_mfma_f32_16x16x32_bf16 v[44:47], v[156:159], v[206:209], 0
	v_mfma_f32_16x16x32_bf16 v[40:43], v[164:167], v[206:209], 0
	v_mfma_f32_16x16x32_bf16 v[28:31], v[156:159], v[214:217], 0
	v_mfma_f32_16x16x32_bf16 v[24:27], v[164:167], v[214:217], 0
	v_mfma_f32_16x16x32_bf16 v[12:15], v[156:159], v[222:225], 0
	v_mfma_f32_16x16x32_bf16 v[8:11], v[164:167], v[222:225], 0
	v_mfma_f32_16x16x32_bf16 v[60:63], v[160:163], v[202:205], v[60:63]
	v_mfma_f32_16x16x32_bf16 v[56:59], v[168:171], v[202:205], v[56:59]
	v_mfma_f32_16x16x32_bf16 v[44:47], v[160:163], v[210:213], v[44:47]
	v_mfma_f32_16x16x32_bf16 v[40:43], v[168:171], v[210:213], v[40:43]
	v_mfma_f32_16x16x32_bf16 v[28:31], v[160:163], v[218:221], v[28:31]
	v_mfma_f32_16x16x32_bf16 v[24:27], v[168:171], v[218:221], v[24:27]
	v_mfma_f32_16x16x32_bf16 v[12:15], v[160:163], v[226:229], v[12:15]
	v_mfma_f32_16x16x32_bf16 v[8:11], v[168:171], v[226:229], v[8:11]
	v_mfma_f32_16x16x32_bf16 v[52:55], v[172:175], v[198:201], 0
	v_mfma_f32_16x16x32_bf16 v[48:51], v[184:187], v[198:201], 0
	v_mfma_f32_16x16x32_bf16 v[36:39], v[172:175], v[206:209], 0
	v_mfma_f32_16x16x32_bf16 v[32:35], v[184:187], v[206:209], 0
	v_mfma_f32_16x16x32_bf16 v[20:23], v[172:175], v[214:217], 0
	v_mfma_f32_16x16x32_bf16 v[16:19], v[184:187], v[214:217], 0
	v_mfma_f32_16x16x32_bf16 v[4:7], v[172:175], v[222:225], 0
	v_mfma_f32_16x16x32_bf16 v[0:3], v[184:187], v[222:225], 0
	v_mfma_f32_16x16x32_bf16 v[52:55], v[180:183], v[202:205], v[52:55]
	v_mfma_f32_16x16x32_bf16 v[48:51], v[188:191], v[202:205], v[48:51]
	v_mfma_f32_16x16x32_bf16 v[36:39], v[180:183], v[210:213], v[36:39]
	v_mfma_f32_16x16x32_bf16 v[32:35], v[188:191], v[210:213], v[32:35]
	v_mfma_f32_16x16x32_bf16 v[20:23], v[180:183], v[218:221], v[20:23]
	v_mfma_f32_16x16x32_bf16 v[16:19], v[188:191], v[218:221], v[16:19]
	v_mfma_f32_16x16x32_bf16 v[4:7], v[180:183], v[226:229], v[4:7]
	v_mfma_f32_16x16x32_bf16 v[0:3], v[188:191], v[226:229], v[0:3]
	s_barrier
	s_setprio 0
	s_add_i32 s42, s65, 0x100
	s_add_i32 s43, s52, 0x100
	v_add_u32_e32 v168, s42, v177
	v_add_u32_e32 v188, s43, v177
	ds_read_b128 v[156:159], v168
	ds_read_b128 v[160:163], v168 offset:1024
	ds_read_b128 v[164:167], v168 offset:2048
	ds_read_b128 v[168:171], v168 offset:3072
	ds_read_b128 v[172:175], v188
	ds_read_b128 v[180:183], v188 offset:1024
	ds_read_b128 v[184:187], v188 offset:2048
	ds_read_b128 v[188:191], v188 offset:3072
	s_add_u32 s10, s10, 0x40000
	s_addc_u32 s11, s11, 0
	s_mov_b32 m0, s79
	v_lshl_add_u64 v[238:239], s[10:11], 0, v[134:135]
	ds_read_b128 v[198:201], v179 offset:32768
	ds_read_b128 v[202:205], v179 offset:33792
	ds_read_b128 v[206:209], v179 offset:34816
	ds_read_b128 v[210:213], v179 offset:35840
	ds_read_b128 v[214:217], v179 offset:36864
	ds_read_b128 v[218:221], v179 offset:37888
	ds_read_b128 v[222:225], v179 offset:38912
	ds_read_b128 v[226:229], v179 offset:39936
	global_load_lds_dwordx4 v[238:239], off
	v_lshl_add_u64 v[238:239], s[10:11], 0, v[130:131]
	s_mov_b32 m0, s82
	s_nop 0
	global_load_lds_dwordx4 v[238:239], off
	s_waitcnt vmcnt(8)
	s_waitcnt lgkmcnt(0)
	s_setprio 1
	s_barrier
	v_mfma_f32_16x16x32_bf16 v[124:127], v[156:159], v[198:201], v[124:127]
	v_mfma_f32_16x16x32_bf16 v[120:123], v[164:167], v[198:201], v[120:123]
	v_mfma_f32_16x16x32_bf16 v[108:111], v[156:159], v[206:209], v[108:111]
	v_mfma_f32_16x16x32_bf16 v[104:107], v[164:167], v[206:209], v[104:107]
	v_mfma_f32_16x16x32_bf16 v[92:95], v[156:159], v[214:217], v[92:95]
	v_mfma_f32_16x16x32_bf16 v[88:91], v[164:167], v[214:217], v[88:91]
	v_mfma_f32_16x16x32_bf16 v[76:79], v[156:159], v[222:225], v[76:79]
	v_mfma_f32_16x16x32_bf16 v[72:75], v[164:167], v[222:225], v[72:75]
	v_mfma_f32_16x16x32_bf16 v[124:127], v[160:163], v[202:205], v[124:127]
	v_mfma_f32_16x16x32_bf16 v[120:123], v[168:171], v[202:205], v[120:123]
	v_mfma_f32_16x16x32_bf16 v[108:111], v[160:163], v[210:213], v[108:111]
	v_mfma_f32_16x16x32_bf16 v[104:107], v[168:171], v[210:213], v[104:107]
	v_mfma_f32_16x16x32_bf16 v[92:95], v[160:163], v[218:221], v[92:95]
	v_mfma_f32_16x16x32_bf16 v[88:91], v[168:171], v[218:221], v[88:91]
	v_mfma_f32_16x16x32_bf16 v[76:79], v[160:163], v[226:229], v[76:79]
	v_mfma_f32_16x16x32_bf16 v[72:75], v[168:171], v[226:229], v[72:75]
	v_mfma_f32_16x16x32_bf16 v[116:119], v[172:175], v[198:201], v[116:119]
	v_mfma_f32_16x16x32_bf16 v[112:115], v[184:187], v[198:201], v[112:115]
	v_mfma_f32_16x16x32_bf16 v[100:103], v[172:175], v[206:209], v[100:103]
	v_mfma_f32_16x16x32_bf16 v[96:99], v[184:187], v[206:209], v[96:99]
	v_mfma_f32_16x16x32_bf16 v[84:87], v[172:175], v[214:217], v[84:87]
	v_mfma_f32_16x16x32_bf16 v[80:83], v[184:187], v[214:217], v[80:83]
	v_mfma_f32_16x16x32_bf16 v[68:71], v[172:175], v[222:225], v[68:71]
	v_mfma_f32_16x16x32_bf16 v[64:67], v[184:187], v[222:225], v[64:67]
	v_mfma_f32_16x16x32_bf16 v[116:119], v[180:183], v[202:205], v[116:119]
	v_mfma_f32_16x16x32_bf16 v[112:115], v[188:191], v[202:205], v[112:115]
	v_mfma_f32_16x16x32_bf16 v[100:103], v[180:183], v[210:213], v[100:103]
	v_mfma_f32_16x16x32_bf16 v[96:99], v[188:191], v[210:213], v[96:99]
	v_mfma_f32_16x16x32_bf16 v[84:87], v[180:183], v[218:221], v[84:87]
	v_mfma_f32_16x16x32_bf16 v[80:83], v[188:191], v[218:221], v[80:83]
	v_mfma_f32_16x16x32_bf16 v[68:71], v[180:183], v[226:229], v[68:71]
	v_mfma_f32_16x16x32_bf16 v[64:67], v[188:191], v[226:229], v[64:67]
	s_barrier
; #define PG8_STAGE(bufoff, gbase, voff) do { _Pragma("unroll") for (int _i = 0; _i < 2; ++_i) \
;         __builtin_amdgcn_global_load_lds((const unsigned*)((const char*)(gbase) + (voff)[_i]), (PG8_LAS unsigned*)(lds + (bufoff) + ldsw + _i * 8192), 16, 0, 0); } while (0)
; #define PG8_LDA(dst, b, h) do { _Pragma("unroll") for (int m = 0; m < 4; ++m) _Pragma("unroll") for (int k = 0; k < 2; ++k) dst[m][k] = *(const PG8_LAS bf16x8*)(lds + PG8_SA(b, h) + aoff + m * 2048 + k * 1024); } while (0)
; #define PG8_LDB(dst, b, h) do { _Pragma("unroll") for (int n = 0; n < 2; ++n) _Pragma("unroll") for (int k = 0; k < 2; ++k) dst[n][k] = *(const PG8_LAS bf16x8*)(lds + PG8_SB(b, h) + boff + n * 2048 + k * 1024); } while (0)
; #define PG8_MMA(ai, bj, At, Bt) do { __builtin_amdgcn_s_setprio(1); _Pragma("unroll") for (int m = 0; m < 4; ++m) _Pragma("unroll") for (int n = 0; n < 2; ++n) _Pragma("unroll") for (int k = 0; k < 2; ++k) \
;         acc[ai][bj][m][n] = __builtin_amdgcn_mfma_f32_16x16x32_bf16(Bt[n][k], At[m][k], acc[ai][bj][m][n], 0, 0, 0); __builtin_amdgcn_s_setprio(0); } while (0)
; #define PG8_WAIT_V(n) asm volatile("s_waitcnt vmcnt(" #n ")" ::: "memory")
; #define PG8_WAIT_L(n) asm volatile("s_waitcnt lgkmcnt(" #n ")" ::: "memory")
; #define PG8_BAR __builtin_amdgcn_s_barrier()
; #define PG8_SCHED __builtin_amdgcn_sched_barrier(0)
; template <class Epi, class Sched, bool ALIGN_EPI = false, bool SP2 = false>
; __device__ __forceinline__ void gemm_phase(PG8_LAS unsigned char* lds, const Gemm g, const Sched& S, const Epi& E, int wave_in) {
;     ...
;         for (int t = 0; t < nt; t += 2) {
;             const bool last = (t == nt - 2);
;             const char* a1 = cA + (size_t)(t + 1) * kstep;
;             const char* a2 = last ? nA : cA + (size_t)(t + 2) * kstep; const char* b2 = last ? nB : cB + (size_t)(t + 2) * kstep;
;             const char* a3 = a2 + kstep; const char* b3 = b2 + kstep;
;             if (last && has_next) S.a_ready(nxt);
;             if constexpr (SP2) {
;             PG8_LDB(B0, 0, 0); PG8_LDB(B1, 0, 1); PG8_SCHED; PG8_LDA(At, 0, 0); PG8_STAGE(PG8_SA(1, 1), a1 + hstep, voffA);
;     ...
;             PG8_LDA(At, 1, 1); PG8_STAGE(PG8_SB(1, 0), b3, voffB); PG8_STAGE(PG8_SB(1, 1), b3 + hstep, voffB); PG8_STAGE(PG8_SA(1, 0), a3, voffA);
;             PG8_WAIT_V(8); PG8_WAIT_L(0); PG8_BAR; PG8_MMA(1, 0, At, B0); PG8_MMA(1, 1, At, B1); PG8_BAR; PG8_SCHED;
	s_setprio 0
	s_add_i32 s10, s42, s66
	v_lshl_add_u64 v[230:231], v[230:231], 0, s[88:89]
	s_mov_b32 m0, s10
	ds_read_b128 v[198:201], v179 offset:49152
	ds_read_b128 v[202:205], v179 offset:50176
	ds_read_b128 v[206:209], v179 offset:51200
	ds_read_b128 v[210:213], v179 offset:52224
	ds_read_b128 v[214:217], v179 offset:53248
	ds_read_b128 v[218:221], v179 offset:54272
	ds_read_b128 v[222:225], v179 offset:55296
	ds_read_b128 v[226:229], v179 offset:56320
	global_load_lds_dwordx4 v[230:231], off
	s_add_i32 m0, s10, 0x2000
	s_add_u32 s4, s4, 0x40080
	v_lshl_add_u64 v[230:231], v[232:233], 0, s[88:89]
	s_addc_u32 s5, s5, 0
	s_add_i32 s10, s43, s66
	global_load_lds_dwordx4 v[230:231], off
	v_lshl_add_u64 v[230:231], s[4:5], 0, v[132:133]
	s_mov_b32 m0, s10
	s_nop 0
	global_load_lds_dwordx4 v[230:231], off
	v_lshl_add_u64 v[230:231], s[4:5], 0, v[128:129]
	s_add_i32 m0, s10, 0x2000
	s_nop 0
	global_load_lds_dwordx4 v[230:231], off
	v_lshl_add_u64 v[230:231], v[234:235], 0, s[88:89]
	s_mov_b32 m0, s72
	s_nop 0
	global_load_lds_dwordx4 v[230:231], off
	v_lshl_add_u64 v[230:231], v[236:237], 0, s[88:89]
	s_mov_b32 m0, s73
	s_nop 0
	global_load_lds_dwordx4 v[230:231], off
	s_waitcnt vmcnt(8)
	s_waitcnt lgkmcnt(0)
	s_setprio 1
	s_barrier
	v_mfma_f32_16x16x32_bf16 v[60:63], v[156:159], v[198:201], v[60:63]
	v_mfma_f32_16x16x32_bf16 v[56:59], v[164:167], v[198:201], v[56:59]
	v_mfma_f32_16x16x32_bf16 v[44:47], v[156:159], v[206:209], v[44:47]
	v_mfma_f32_16x16x32_bf16 v[40:43], v[164:167], v[206:209], v[40:43]
	v_mfma_f32_16x16x32_bf16 v[28:31], v[156:159], v[214:217], v[28:31]
	v_mfma_f32_16x16x32_bf16 v[24:27], v[164:167], v[214:217], v[24:27]
	v_mfma_f32_16x16x32_bf16 v[12:15], v[156:159], v[222:225], v[12:15]
	v_mfma_f32_16x16x32_bf16 v[8:11], v[164:167], v[222:225], v[8:11]
	v_mfma_f32_16x16x32_bf16 v[60:63], v[160:163], v[202:205], v[60:63]
	v_mfma_f32_16x16x32_bf16 v[56:59], v[168:171], v[202:205], v[56:59]
	v_mfma_f32_16x16x32_bf16 v[44:47], v[160:163], v[210:213], v[44:47]
	v_mfma_f32_16x16x32_bf16 v[40:43], v[168:171], v[210:213], v[40:43]
	v_mfma_f32_16x16x32_bf16 v[28:31], v[160:163], v[218:221], v[28:31]
	v_mfma_f32_16x16x32_bf16 v[24:27], v[168:171], v[218:221], v[24:27]
	v_mfma_f32_16x16x32_bf16 v[12:15], v[160:163], v[226:229], v[12:15]
	v_mfma_f32_16x16x32_bf16 v[8:11], v[168:171], v[226:229], v[8:11]
	v_mfma_f32_16x16x32_bf16 v[52:55], v[172:175], v[198:201], v[52:55]
	v_mfma_f32_16x16x32_bf16 v[48:51], v[184:187], v[198:201], v[48:51]
	v_mfma_f32_16x16x32_bf16 v[36:39], v[172:175], v[206:209], v[36:39]
	v_mfma_f32_16x16x32_bf16 v[32:35], v[184:187], v[206:209], v[32:35]
	v_mfma_f32_16x16x32_bf16 v[20:23], v[172:175], v[214:217], v[20:23]
	v_mfma_f32_16x16x32_bf16 v[16:19], v[184:187], v[214:217], v[16:19]
	v_mfma_f32_16x16x32_bf16 v[4:7], v[172:175], v[222:225], v[4:7]
	v_mfma_f32_16x16x32_bf16 v[0:3], v[184:187], v[222:225], v[0:3]
	v_mfma_f32_16x16x32_bf16 v[52:55], v[180:183], v[202:205], v[52:55]
	v_mfma_f32_16x16x32_bf16 v[48:51], v[188:191], v[202:205], v[48:51]
	v_mfma_f32_16x16x32_bf16 v[36:39], v[180:183], v[210:213], v[36:39]
	v_mfma_f32_16x16x32_bf16 v[32:35], v[188:191], v[210:213], v[32:35]
	v_mfma_f32_16x16x32_bf16 v[20:23], v[180:183], v[218:221], v[20:23]
	v_mfma_f32_16x16x32_bf16 v[16:19], v[188:191], v[218:221], v[16:19]
	v_mfma_f32_16x16x32_bf16 v[4:7], v[180:183], v[226:229], v[4:7]
	v_mfma_f32_16x16x32_bf16 v[0:3], v[188:191], v[226:229], v[0:3]
	s_barrier
	s_setprio 0
	s_add_i32 s34, s34, 2
	s_add_u32 s31, s31, 0x100
	s_addc_u32 s33, s33, 0
	s_add_u32 s0, s0, 0x100
	s_addc_u32 s1, s1, 0
	s_cmp_gt_u32 s34, 13
	s_cbranch_scc1 .Lkexit_1
.LBB0_273:
	s_add_u32 s4, s0, 0xfffc0080
	s_addc_u32 s5, s1, -1
	s_add_i32 s42, s35, 0x100
	s_cmp_eq_u32 s34, 12
	s_cselect_b32 s11, s8, s5
	s_cselect_b32 s10, s9, s4
	s_cselect_b32 s5, s16, s33
	s_cselect_b32 s4, s17, s31
	s_add_i32 s44, s90, 0x100
	v_add_u32_e32 v168, s42, v177
	v_add_u32_e32 v188, s44, v177
	ds_read_b128 v[156:159], v168
	ds_read_b128 v[160:163], v168 offset:1024
	ds_read_b128 v[164:167], v168 offset:2048
	ds_read_b128 v[168:171], v168 offset:3072
	ds_read_b128 v[172:175], v188
	ds_read_b128 v[180:183], v188 offset:1024
	ds_read_b128 v[184:187], v188 offset:2048
	ds_read_b128 v[188:191], v188 offset:3072
	v_lshl_add_u64 v[230:231], s[0:1], 0, v[154:155]
	s_add_i32 m0, s67, 0xc000
	ds_read_b128 v[198:201], v179
	ds_read_b128 v[202:205], v179 offset:1024
	ds_read_b128 v[206:209], v179 offset:2048
	ds_read_b128 v[210:213], v179 offset:3072
	ds_read_b128 v[214:217], v179 offset:4096
	ds_read_b128 v[218:221], v179 offset:5120
	ds_read_b128 v[222:225], v179 offset:6144
	ds_read_b128 v[226:229], v179 offset:7168
	global_load_lds_dwordx4 v[230:231], off
	v_lshl_add_u64 v[230:231], s[0:1], 0, v[152:153]
	s_add_i32 m0, s67, 0xe000
	s_nop 0
	global_load_lds_dwordx4 v[230:231], off
	s_waitcnt vmcnt(8)
	s_waitcnt lgkmcnt(0)
	s_setprio 1
	s_barrier
; #define PG8_STAGE(bufoff, gbase, voff) do { _Pragma("unroll") for (int _i = 0; _i < 2; ++_i) \
;         __builtin_amdgcn_global_load_lds((const unsigned*)((const char*)(gbase) + (voff)[_i]), (PG8_LAS unsigned*)(lds + (bufoff) + ldsw + _i * 8192), 16, 0, 0); } while (0)
; #define PG8_LDA(dst, b, h) do { _Pragma("unroll") for (int m = 0; m < 4; ++m) _Pragma("unroll") for (int k = 0; k < 2; ++k) dst[m][k] = *(const PG8_LAS bf16x8*)(lds + PG8_SA(b, h) + aoff + m * 2048 + k * 1024); } while (0)
; #define PG8_LDB(dst, b, h) do { _Pragma("unroll") for (int n = 0; n < 2; ++n) _Pragma("unroll") for (int k = 0; k < 2; ++k) dst[n][k] = *(const PG8_LAS bf16x8*)(lds + PG8_SB(b, h) + boff + n * 2048 + k * 1024); } while (0)
; #define PG8_MMA(ai, bj, At, Bt) do { __builtin_amdgcn_s_setprio(1); _Pragma("unroll") for (int m = 0; m < 4; ++m) _Pragma("unroll") for (int n = 0; n < 2; ++n) _Pragma("unroll") for (int k = 0; k < 2; ++k) \
;         acc[ai][bj][m][n] = __builtin_amdgcn_mfma_f32_16x16x32_bf16(Bt[n][k], At[m][k], acc[ai][bj][m][n], 0, 0, 0); __builtin_amdgcn_s_setprio(0); } while (0)
; #define PG8_WAIT_V(n) asm volatile("s_waitcnt vmcnt(" #n ")" ::: "memory")
; #define PG8_WAIT_L(n) asm volatile("s_waitcnt lgkmcnt(" #n ")" ::: "memory")
; #define PG8_BAR __builtin_amdgcn_s_barrier()
; #define PG8_SCHED __builtin_amdgcn_sched_barrier(0)
; template <class Epi, class Sched, bool ALIGN_EPI = false, bool SP2 = false>
; __device__ __forceinline__ void gemm_phase(PG8_LAS unsigned char* lds, const Gemm g, const Sched& S, const Epi& E, int wave_in) {
;     ...
;             PG8_WAIT_V(8); PG8_WAIT_L(0); PG8_BAR; PG8_MMA(0, 0, At, B0); PG8_MMA(0, 1, At, B1); PG8_BAR; PG8_SCHED;
;             PG8_LDA(At, 0, 1); PG8_STAGE(PG8_SB(0, 0), b2, voffB); PG8_STAGE(PG8_SB(0, 1), b2 + hstep, voffB); PG8_STAGE(PG8_SA(0, 0), a2, voffA);
;             PG8_WAIT_V(8); PG8_WAIT_L(0); PG8_BAR; PG8_MMA(1, 0, At, B0); PG8_MMA(1, 1, At, B1); PG8_BAR; PG8_SCHED;
;             PG8_LDB(B0, 1, 0); PG8_LDB(B1, 1, 1); PG8_SCHED; PG8_LDA(At, 1, 0); PG8_STAGE(PG8_SA(0, 1), a2 + hstep, voffA);
;             PG8_WAIT_V(8); PG8_WAIT_L(0); PG8_BAR; PG8_MMA(0, 0, At, B0); PG8_MMA(0, 1, At, B1); PG8_BAR; PG8_SCHED;
	v_mfma_f32_16x16x32_bf16 v[124:127], v[156:159], v[198:201], v[124:127]
	v_mfma_f32_16x16x32_bf16 v[120:123], v[164:167], v[198:201], v[120:123]
	v_mfma_f32_16x16x32_bf16 v[108:111], v[156:159], v[206:209], v[108:111]
	v_mfma_f32_16x16x32_bf16 v[104:107], v[164:167], v[206:209], v[104:107]
	v_mfma_f32_16x16x32_bf16 v[92:95], v[156:159], v[214:217], v[92:95]
	v_mfma_f32_16x16x32_bf16 v[88:91], v[164:167], v[214:217], v[88:91]
	v_mfma_f32_16x16x32_bf16 v[76:79], v[156:159], v[222:225], v[76:79]
	v_mfma_f32_16x16x32_bf16 v[72:75], v[164:167], v[222:225], v[72:75]
	v_mfma_f32_16x16x32_bf16 v[124:127], v[160:163], v[202:205], v[124:127]
	v_mfma_f32_16x16x32_bf16 v[120:123], v[168:171], v[202:205], v[120:123]
	v_mfma_f32_16x16x32_bf16 v[108:111], v[160:163], v[210:213], v[108:111]
	v_mfma_f32_16x16x32_bf16 v[104:107], v[168:171], v[210:213], v[104:107]
	v_mfma_f32_16x16x32_bf16 v[92:95], v[160:163], v[218:221], v[92:95]
	v_mfma_f32_16x16x32_bf16 v[88:91], v[168:171], v[218:221], v[88:91]
	v_mfma_f32_16x16x32_bf16 v[76:79], v[160:163], v[226:229], v[76:79]
	v_mfma_f32_16x16x32_bf16 v[72:75], v[168:171], v[226:229], v[72:75]
	v_mfma_f32_16x16x32_bf16 v[116:119], v[172:175], v[198:201], v[116:119]
	v_mfma_f32_16x16x32_bf16 v[112:115], v[184:187], v[198:201], v[112:115]
	v_mfma_f32_16x16x32_bf16 v[100:103], v[172:175], v[206:209], v[100:103]
	v_mfma_f32_16x16x32_bf16 v[96:99], v[184:187], v[206:209], v[96:99]
	v_mfma_f32_16x16x32_bf16 v[84:87], v[172:175], v[214:217], v[84:87]
	v_mfma_f32_16x16x32_bf16 v[80:83], v[184:187], v[214:217], v[80:83]
	v_mfma_f32_16x16x32_bf16 v[68:71], v[172:175], v[222:225], v[68:71]
	v_mfma_f32_16x16x32_bf16 v[64:67], v[184:187], v[222:225], v[64:67]
	v_mfma_f32_16x16x32_bf16 v[116:119], v[180:183], v[202:205], v[116:119]
	v_mfma_f32_16x16x32_bf16 v[112:115], v[188:191], v[202:205], v[112:115]
	v_mfma_f32_16x16x32_bf16 v[100:103], v[180:183], v[210:213], v[100:103]
	v_mfma_f32_16x16x32_bf16 v[96:99], v[188:191], v[210:213], v[96:99]
	v_mfma_f32_16x16x32_bf16 v[84:87], v[180:183], v[218:221], v[84:87]
	v_mfma_f32_16x16x32_bf16 v[80:83], v[188:191], v[218:221], v[80:83]
	v_mfma_f32_16x16x32_bf16 v[68:71], v[180:183], v[226:229], v[68:71]
	v_mfma_f32_16x16x32_bf16 v[64:67], v[188:191], v[226:229], v[64:67]
	s_barrier
	s_setprio 0
	s_add_i32 s42, s42, s66
	v_lshl_add_u64 v[230:231], s[4:5], 0, v[132:133]
	s_mov_b32 m0, s42
	ds_read_b128 v[198:201], v179 offset:16384
	ds_read_b128 v[202:205], v179 offset:17408
	ds_read_b128 v[206:209], v179 offset:18432
	ds_read_b128 v[210:213], v179 offset:19456
	ds_read_b128 v[214:217], v179 offset:20480
	ds_read_b128 v[218:221], v179 offset:21504
	ds_read_b128 v[222:225], v179 offset:22528
	ds_read_b128 v[226:229], v179 offset:23552
	global_load_lds_dwordx4 v[230:231], off
	s_add_i32 m0, s42, 0x2000
	s_add_u32 s42, s4, 0x40000
	v_lshl_add_u64 v[232:233], s[4:5], 0, v[128:129]
	s_addc_u32 s43, s5, 0
	s_add_i32 s44, s44, s66
	global_load_lds_dwordx4 v[232:233], off
	v_lshl_add_u64 v[234:235], s[42:43], 0, v[132:133]
	s_mov_b32 m0, s44
	v_lshl_add_u64 v[236:237], s[10:11], 0, v[130:131]
	global_load_lds_dwordx4 v[234:235], off
	v_lshl_add_u64 v[234:235], s[42:43], 0, v[128:129]
	s_add_i32 m0, s44, 0x2000
	s_nop 0
	global_load_lds_dwordx4 v[234:235], off
	v_lshl_add_u64 v[234:235], s[10:11], 0, v[134:135]
	s_mov_b32 m0, s67
	s_nop 0
	global_load_lds_dwordx4 v[234:235], off
	s_mov_b32 m0, s78
	s_nop 0
	global_load_lds_dwordx4 v[236:237], off
	s_waitcnt vmcnt(8)
	s_waitcnt lgkmcnt(0)
	s_setprio 1
	s_barrier
	v_mfma_f32_16x16x32_bf16 v[60:63], v[156:159], v[198:201], v[60:63]
	v_mfma_f32_16x16x32_bf16 v[56:59], v[164:167], v[198:201], v[56:59]
	v_mfma_f32_16x16x32_bf16 v[44:47], v[156:159], v[206:209], v[44:47]
	v_mfma_f32_16x16x32_bf16 v[40:43], v[164:167], v[206:209], v[40:43]
	v_mfma_f32_16x16x32_bf16 v[28:31], v[156:159], v[214:217], v[28:31]
	v_mfma_f32_16x16x32_bf16 v[24:27], v[164:167], v[214:217], v[24:27]
	v_mfma_f32_16x16x32_bf16 v[12:15], v[156:159], v[222:225], v[12:15]
	v_mfma_f32_16x16x32_bf16 v[8:11], v[164:167], v[222:225], v[8:11]
	v_mfma_f32_16x16x32_bf16 v[60:63], v[160:163], v[202:205], v[60:63]
	v_mfma_f32_16x16x32_bf16 v[56:59], v[168:171], v[202:205], v[56:59]
	v_mfma_f32_16x16x32_bf16 v[44:47], v[160:163], v[210:213], v[44:47]
	v_mfma_f32_16x16x32_bf16 v[40:43], v[168:171], v[210:213], v[40:43]
	v_mfma_f32_16x16x32_bf16 v[28:31], v[160:163], v[218:221], v[28:31]
	v_mfma_f32_16x16x32_bf16 v[24:27], v[168:171], v[218:221], v[24:27]
	v_mfma_f32_16x16x32_bf16 v[12:15], v[160:163], v[226:229], v[12:15]
	v_mfma_f32_16x16x32_bf16 v[8:11], v[168:171], v[226:229], v[8:11]
	v_mfma_f32_16x16x32_bf16 v[52:55], v[172:175], v[198:201], v[52:55]
	v_mfma_f32_16x16x32_bf16 v[48:51], v[184:187], v[198:201], v[48:51]
	v_mfma_f32_16x16x32_bf16 v[36:39], v[172:175], v[206:209], v[36:39]
	v_mfma_f32_16x16x32_bf16 v[32:35], v[184:187], v[206:209], v[32:35]
	v_mfma_f32_16x16x32_bf16 v[20:23], v[172:175], v[214:217], v[20:23]
	v_mfma_f32_16x16x32_bf16 v[16:19], v[184:187], v[214:217], v[16:19]
	v_mfma_f32_16x16x32_bf16 v[4:7], v[172:175], v[222:225], v[4:7]
	v_mfma_f32_16x16x32_bf16 v[0:3], v[184:187], v[222:225], v[0:3]
	v_mfma_f32_16x16x32_bf16 v[52:55], v[180:183], v[202:205], v[52:55]
	v_mfma_f32_16x16x32_bf16 v[48:51], v[188:191], v[202:205], v[48:51]
	v_mfma_f32_16x16x32_bf16 v[36:39], v[180:183], v[210:213], v[36:39]
	v_mfma_f32_16x16x32_bf16 v[32:35], v[188:191], v[210:213], v[32:35]
	v_mfma_f32_16x16x32_bf16 v[20:23], v[180:183], v[218:221], v[20:23]
	v_mfma_f32_16x16x32_bf16 v[16:19], v[188:191], v[218:221], v[16:19]
	v_mfma_f32_16x16x32_bf16 v[4:7], v[180:183], v[226:229], v[4:7]
	v_mfma_f32_16x16x32_bf16 v[0:3], v[188:191], v[226:229], v[0:3]
	s_barrier
; #define PG8_STAGE(bufoff, gbase, voff) do { _Pragma("unroll") for (int _i = 0; _i < 2; ++_i) \
;         __builtin_amdgcn_global_load_lds((const unsigned*)((const char*)(gbase) + (voff)[_i]), (PG8_LAS unsigned*)(lds + (bufoff) + ldsw + _i * 8192), 16, 0, 0); } while (0)
; #define PG8_LDA(dst, b, h) do { _Pragma("unroll") for (int m = 0; m < 4; ++m) _Pragma("unroll") for (int k = 0; k < 2; ++k) dst[m][k] = *(const PG8_LAS bf16x8*)(lds + PG8_SA(b, h) + aoff + m * 2048 + k * 1024); } while (0)
; #define PG8_LDB(dst, b, h) do { _Pragma("unroll") for (int n = 0; n < 2; ++n) _Pragma("unroll") for (int k = 0; k < 2; ++k) dst[n][k] = *(const PG8_LAS bf16x8*)(lds + PG8_SB(b, h) + boff + n * 2048 + k * 1024); } while (0)
; #define PG8_MMA(ai, bj, At, Bt) do { __builtin_amdgcn_s_setprio(1); _Pragma("unroll") for (int m = 0; m < 4; ++m) _Pragma("unroll") for (int n = 0; n < 2; ++n) _Pragma("unroll") for (int k = 0; k < 2; ++k) \
;         acc[ai][bj][m][n] = __builtin_amdgcn_mfma_f32_16x16x32_bf16(Bt[n][k], At[m][k], acc[ai][bj][m][n], 0, 0, 0); __builtin_amdgcn_s_setprio(0); } while (0)
; #define PG8_WAIT_V(n) asm volatile("s_waitcnt vmcnt(" #n ")" ::: "memory")
; #define PG8_WAIT_L(n) asm volatile("s_waitcnt lgkmcnt(" #n ")" ::: "memory")
; #define PG8_BAR __builtin_amdgcn_s_barrier()
; #define PG8_SCHED __builtin_amdgcn_sched_barrier(0)
; template <class Epi, class Sched, bool ALIGN_EPI = false, bool SP2 = false>
; __device__ __forceinline__ void gemm_phase(PG8_LAS unsigned char* lds, const Gemm g, const Sched& S, const Epi& E, int wave_in) {
;     ...
;             PG8_LDB(B0, 1, 0); PG8_LDB(B1, 1, 1); PG8_SCHED; PG8_LDA(At, 1, 0); PG8_STAGE(PG8_SA(0, 1), a2 + hstep, voffA);
;             PG8_WAIT_V(8); PG8_WAIT_L(0); PG8_BAR; PG8_MMA(0, 0, At, B0); PG8_MMA(0, 1, At, B1); PG8_BAR; PG8_SCHED;
	s_setprio 0
	s_add_i32 s42, s65, 0x100
	s_add_i32 s43, s52, 0x100
	v_add_u32_e32 v168, s42, v177
	v_add_u32_e32 v188, s43, v177
	ds_read_b128 v[156:159], v168
	ds_read_b128 v[160:163], v168 offset:1024
	ds_read_b128 v[164:167], v168 offset:2048
	ds_read_b128 v[168:171], v168 offset:3072
	ds_read_b128 v[172:175], v188
	ds_read_b128 v[180:183], v188 offset:1024
	ds_read_b128 v[184:187], v188 offset:2048
	ds_read_b128 v[188:191], v188 offset:3072
	s_add_u32 s10, s10, 0x40000
	s_addc_u32 s11, s11, 0
	s_mov_b32 m0, s79
	v_lshl_add_u64 v[238:239], s[10:11], 0, v[134:135]
	ds_read_b128 v[198:201], v179 offset:32768
	ds_read_b128 v[202:205], v179 offset:33792
	ds_read_b128 v[206:209], v179 offset:34816
	ds_read_b128 v[210:213], v179 offset:35840
	ds_read_b128 v[214:217], v179 offset:36864
	ds_read_b128 v[218:221], v179 offset:37888
	ds_read_b128 v[222:225], v179 offset:38912
	ds_read_b128 v[226:229], v179 offset:39936
	global_load_lds_dwordx4 v[238:239], off
	v_lshl_add_u64 v[238:239], s[10:11], 0, v[130:131]
	s_mov_b32 m0, s82
	s_nop 0
	global_load_lds_dwordx4 v[238:239], off
	s_waitcnt vmcnt(8)
	s_waitcnt lgkmcnt(0)
	s_setprio 1
	s_barrier
	v_mfma_f32_16x16x32_bf16 v[124:127], v[156:159], v[198:201], v[124:127]
	v_mfma_f32_16x16x32_bf16 v[120:123], v[164:167], v[198:201], v[120:123]
	v_mfma_f32_16x16x32_bf16 v[108:111], v[156:159], v[206:209], v[108:111]
	v_mfma_f32_16x16x32_bf16 v[104:107], v[164:167], v[206:209], v[104:107]
	v_mfma_f32_16x16x32_bf16 v[92:95], v[156:159], v[214:217], v[92:95]
	v_mfma_f32_16x16x32_bf16 v[88:91], v[164:167], v[214:217], v[88:91]
	v_mfma_f32_16x16x32_bf16 v[76:79], v[156:159], v[222:225], v[76:79]
	v_mfma_f32_16x16x32_bf16 v[72:75], v[164:167], v[222:225], v[72:75]
	v_mfma_f32_16x16x32_bf16 v[124:127], v[160:163], v[202:205], v[124:127]
	v_mfma_f32_16x16x32_bf16 v[120:123], v[168:171], v[202:205], v[120:123]
	v_mfma_f32_16x16x32_bf16 v[108:111], v[160:163], v[210:213], v[108:111]
	v_mfma_f32_16x16x32_bf16 v[104:107], v[168:171], v[210:213], v[104:107]
	v_mfma_f32_16x16x32_bf16 v[92:95], v[160:163], v[218:221], v[92:95]
	v_mfma_f32_16x16x32_bf16 v[88:91], v[168:171], v[218:221], v[88:91]
	v_mfma_f32_16x16x32_bf16 v[76:79], v[160:163], v[226:229], v[76:79]
	v_mfma_f32_16x16x32_bf16 v[72:75], v[168:171], v[226:229], v[72:75]
	v_mfma_f32_16x16x32_bf16 v[116:119], v[172:175], v[198:201], v[116:119]
	v_mfma_f32_16x16x32_bf16 v[112:115], v[184:187], v[198:201], v[112:115]
	v_mfma_f32_16x16x32_bf16 v[100:103], v[172:175], v[206:209], v[100:103]
	v_mfma_f32_16x16x32_bf16 v[96:99], v[184:187], v[206:209], v[96:99]
	v_mfma_f32_16x16x32_bf16 v[84:87], v[172:175], v[214:217], v[84:87]
	v_mfma_f32_16x16x32_bf16 v[80:83], v[184:187], v[214:217], v[80:83]
	v_mfma_f32_16x16x32_bf16 v[68:71], v[172:175], v[222:225], v[68:71]
	v_mfma_f32_16x16x32_bf16 v[64:67], v[184:187], v[222:225], v[64:67]
	v_mfma_f32_16x16x32_bf16 v[116:119], v[180:183], v[202:205], v[116:119]
	v_mfma_f32_16x16x32_bf16 v[112:115], v[188:191], v[202:205], v[112:115]
	v_mfma_f32_16x16x32_bf16 v[100:103], v[180:183], v[210:213], v[100:103]
	v_mfma_f32_16x16x32_bf16 v[96:99], v[188:191], v[210:213], v[96:99]
	v_mfma_f32_16x16x32_bf16 v[84:87], v[180:183], v[218:221], v[84:87]
	v_mfma_f32_16x16x32_bf16 v[80:83], v[188:191], v[218:221], v[80:83]
	v_mfma_f32_16x16x32_bf16 v[68:71], v[180:183], v[226:229], v[68:71]
	v_mfma_f32_16x16x32_bf16 v[64:67], v[188:191], v[226:229], v[64:67]
	s_barrier
; #define PG8_STAGE(bufoff, gbase, voff) do { _Pragma("unroll") for (int _i = 0; _i < 2; ++_i) \
;         __builtin_amdgcn_global_load_lds((const unsigned*)((const char*)(gbase) + (voff)[_i]), (PG8_LAS unsigned*)(lds + (bufoff) + ldsw + _i * 8192), 16, 0, 0); } while (0)
; #define PG8_LDA(dst, b, h) do { _Pragma("unroll") for (int m = 0; m < 4; ++m) _Pragma("unroll") for (int k = 0; k < 2; ++k) dst[m][k] = *(const PG8_LAS bf16x8*)(lds + PG8_SA(b, h) + aoff + m * 2048 + k * 1024); } while (0)
; #define PG8_MMA(ai, bj, At, Bt) do { __builtin_amdgcn_s_setprio(1); _Pragma("unroll") for (int m = 0; m < 4; ++m) _Pragma("unroll") for (int n = 0; n < 2; ++n) _Pragma("unroll") for (int k = 0; k < 2; ++k) \
;         acc[ai][bj][m][n] = __builtin_amdgcn_mfma_f32_16x16x32_bf16(Bt[n][k], At[m][k], acc[ai][bj][m][n], 0, 0, 0); __builtin_amdgcn_s_setprio(0); } while (0)
; #define PG8_WAIT_V(n) asm volatile("s_waitcnt vmcnt(" #n ")" ::: "memory")
; #define PG8_WAIT_L(n) asm volatile("s_waitcnt lgkmcnt(" #n ")" ::: "memory")
; #define PG8_BAR __builtin_amdgcn_s_barrier()
; #define PG8_SCHED __builtin_amdgcn_sched_barrier(0)
; template <class Epi, class Sched, bool ALIGN_EPI = false, bool SP2 = false>
; __device__ __forceinline__ void gemm_phase(PG8_LAS unsigned char* lds, const Gemm g, const Sched& S, const Epi& E, int wave_in) {
;     ...
;         for (int t = 0; t < nt; t += 2) {
;             const bool last = (t == nt - 2);
;     ...
;             PG8_LDA(At, 1, 1); PG8_STAGE(PG8_SB(1, 0), b3, voffB); PG8_STAGE(PG8_SB(1, 1), b3 + hstep, voffB); PG8_STAGE(PG8_SA(1, 0), a3, voffA);
;             PG8_WAIT_V(8); PG8_WAIT_L(0); PG8_BAR; PG8_MMA(1, 0, At, B0); PG8_MMA(1, 1, At, B1); PG8_BAR; PG8_SCHED;
	s_setprio 0
	s_add_i32 s10, s42, s66
	v_lshl_add_u64 v[230:231], v[230:231], 0, s[88:89]
	s_mov_b32 m0, s10
	ds_read_b128 v[198:201], v179 offset:49152
	ds_read_b128 v[202:205], v179 offset:50176
	ds_read_b128 v[206:209], v179 offset:51200
	ds_read_b128 v[210:213], v179 offset:52224
	ds_read_b128 v[214:217], v179 offset:53248
	ds_read_b128 v[218:221], v179 offset:54272
	ds_read_b128 v[222:225], v179 offset:55296
	ds_read_b128 v[226:229], v179 offset:56320
	global_load_lds_dwordx4 v[230:231], off
	s_add_i32 m0, s10, 0x2000
	s_add_u32 s4, s4, 0x40080
	v_lshl_add_u64 v[230:231], v[232:233], 0, s[88:89]
	s_addc_u32 s5, s5, 0
	s_add_i32 s10, s43, s66
	global_load_lds_dwordx4 v[230:231], off
	v_lshl_add_u64 v[230:231], s[4:5], 0, v[132:133]
	s_mov_b32 m0, s10
	s_nop 0
	global_load_lds_dwordx4 v[230:231], off
	v_lshl_add_u64 v[230:231], s[4:5], 0, v[128:129]
	s_add_i32 m0, s10, 0x2000
	s_nop 0
	global_load_lds_dwordx4 v[230:231], off
	v_lshl_add_u64 v[230:231], v[234:235], 0, s[88:89]
	s_mov_b32 m0, s72
	s_nop 0
	global_load_lds_dwordx4 v[230:231], off
	v_lshl_add_u64 v[230:231], v[236:237], 0, s[88:89]
	s_mov_b32 m0, s73
	s_nop 0
	global_load_lds_dwordx4 v[230:231], off
	s_waitcnt vmcnt(8)
	s_waitcnt lgkmcnt(0)
	s_setprio 1
	s_barrier
	v_mfma_f32_16x16x32_bf16 v[60:63], v[156:159], v[198:201], v[60:63]
	v_mfma_f32_16x16x32_bf16 v[56:59], v[164:167], v[198:201], v[56:59]
	v_mfma_f32_16x16x32_bf16 v[44:47], v[156:159], v[206:209], v[44:47]
	v_mfma_f32_16x16x32_bf16 v[40:43], v[164:167], v[206:209], v[40:43]
	v_mfma_f32_16x16x32_bf16 v[28:31], v[156:159], v[214:217], v[28:31]
	v_mfma_f32_16x16x32_bf16 v[24:27], v[164:167], v[214:217], v[24:27]
	v_mfma_f32_16x16x32_bf16 v[12:15], v[156:159], v[222:225], v[12:15]
	v_mfma_f32_16x16x32_bf16 v[8:11], v[164:167], v[222:225], v[8:11]
	v_mfma_f32_16x16x32_bf16 v[60:63], v[160:163], v[202:205], v[60:63]
	v_mfma_f32_16x16x32_bf16 v[56:59], v[168:171], v[202:205], v[56:59]
	v_mfma_f32_16x16x32_bf16 v[44:47], v[160:163], v[210:213], v[44:47]
	v_mfma_f32_16x16x32_bf16 v[40:43], v[168:171], v[210:213], v[40:43]
	v_mfma_f32_16x16x32_bf16 v[28:31], v[160:163], v[218:221], v[28:31]
	v_mfma_f32_16x16x32_bf16 v[24:27], v[168:171], v[218:221], v[24:27]
	v_mfma_f32_16x16x32_bf16 v[12:15], v[160:163], v[226:229], v[12:15]
	v_mfma_f32_16x16x32_bf16 v[8:11], v[168:171], v[226:229], v[8:11]
	v_mfma_f32_16x16x32_bf16 v[52:55], v[172:175], v[198:201], v[52:55]
	v_mfma_f32_16x16x32_bf16 v[48:51], v[184:187], v[198:201], v[48:51]
	v_mfma_f32_16x16x32_bf16 v[36:39], v[172:175], v[206:209], v[36:39]
	v_mfma_f32_16x16x32_bf16 v[32:35], v[184:187], v[206:209], v[32:35]
	v_mfma_f32_16x16x32_bf16 v[20:23], v[172:175], v[214:217], v[20:23]
	v_mfma_f32_16x16x32_bf16 v[16:19], v[184:187], v[214:217], v[16:19]
	v_mfma_f32_16x16x32_bf16 v[4:7], v[172:175], v[222:225], v[4:7]
	v_mfma_f32_16x16x32_bf16 v[0:3], v[184:187], v[222:225], v[0:3]
	v_mfma_f32_16x16x32_bf16 v[52:55], v[180:183], v[202:205], v[52:55]
	v_mfma_f32_16x16x32_bf16 v[48:51], v[188:191], v[202:205], v[48:51]
	v_mfma_f32_16x16x32_bf16 v[36:39], v[180:183], v[210:213], v[36:39]
	v_mfma_f32_16x16x32_bf16 v[32:35], v[188:191], v[210:213], v[32:35]
	v_mfma_f32_16x16x32_bf16 v[20:23], v[180:183], v[218:221], v[20:23]
	v_mfma_f32_16x16x32_bf16 v[16:19], v[188:191], v[218:221], v[16:19]
	v_mfma_f32_16x16x32_bf16 v[4:7], v[180:183], v[226:229], v[4:7]
	v_mfma_f32_16x16x32_bf16 v[0:3], v[188:191], v[226:229], v[0:3]
	s_barrier
	s_setprio 0
	s_add_i32 s34, s34, 2
	s_add_u32 s31, s31, 0x100
	s_addc_u32 s33, s33, 0
	s_add_u32 s0, s0, 0x100
	s_addc_u32 s1, s1, 0
	s_cmp_gt_u32 s34, 13
	s_cbranch_scc0 .LBB0_273

; #define PG8_STAGE(bufoff, gbase, voff) do { _Pragma("unroll") for (int _i = 0; _i < 2; ++_i) \
;         __builtin_amdgcn_global_load_lds((const unsigned*)((const char*)(gbase) + (voff)[_i]), (PG8_LAS unsigned*)(lds + (bufoff) + ldsw + _i * 8192), 16, 0, 0); } while (0)
; #define PG8_LDA(dst, b, h) do { _Pragma("unroll") for (int m = 0; m < 4; ++m) _Pragma("unroll") for (int k = 0; k < 2; ++k) dst[m][k] = *(const PG8_LAS bf16x8*)(lds + PG8_SA(b, h) + aoff + m * 2048 + k * 1024); } while (0)
; #define PG8_LDB(dst, b, h) do { _Pragma("unroll") for (int n = 0; n < 2; ++n) _Pragma("unroll") for (int k = 0; k < 2; ++k) dst[n][k] = *(const PG8_LAS bf16x8*)(lds + PG8_SB(b, h) + boff + n * 2048 + k * 1024); } while (0)
; #define PG8_MMA(ai, bj, At, Bt) do { __builtin_amdgcn_s_setprio(1); _Pragma("unroll") for (int m = 0; m < 4; ++m) _Pragma("unroll") for (int n = 0; n < 2; ++n) _Pragma("unroll") for (int k = 0; k < 2; ++k) \
;         acc[ai][bj][m][n] = __builtin_amdgcn_mfma_f32_16x16x32_bf16(Bt[n][k], At[m][k], acc[ai][bj][m][n], 0, 0, 0); __builtin_amdgcn_s_setprio(0); } while (0)
; template <class Epi, class Sched, bool ALIGN_EPI = false, bool SP2 = false>
; __device__ __forceinline__ void gemm_phase(PG8_LAS unsigned char* lds, const Gemm g, const Sched& S, const Epi& E, int wave_in) {
;     ...
;         const char* nA = has_next ? (const char*)g.A + (size_t)(nxt.pm >> g.ash) * g.astride + (size_t)nxt.pm * tstep : cA; const char* nB = has_next ? (const char*)g.Bt + (size_t)(nxt.pm >> g.bsh) * g.bstride + (size_t)nxt.pn * tstep : cB;
;         for (int t = 0; t < nt; t += 2) {
;             const bool last = (t == nt - 2);
;             const char* a1 = cA + (size_t)(t + 1) * kstep;
;             const char* a2 = last ? nA : cA + (size_t)(t + 2) * kstep; const char* b2 = last ? nB : cB + (size_t)(t + 2) * kstep;
;             const char* a3 = a2 + kstep; const char* b3 = b2 + kstep;
;             if (last && has_next) S.a_ready(nxt);
;             if constexpr (SP2) {
;             PG8_LDB(B0, 0, 0); PG8_LDB(B1, 0, 1); PG8_SCHED; PG8_LDA(At, 0, 0); PG8_STAGE(PG8_SA(1, 1), a1 + hstep, voffA);
;             PG8_WAIT_V(8); PG8_WAIT_L(0); PG8_BAR; PG8_MMA(0, 0, At, B0); PG8_MMA(0, 1, At, B1); PG8_BAR; PG8_SCHED;
;             PG8_LDA(At, 0, 1); PG8_STAGE(PG8_SB(0, 0), b2, voffB); PG8_STAGE(PG8_SB(0, 1), b2 + hstep, voffB); PG8_STAGE(PG8_SA(0, 0), a2, voffA);
.LBB0_484:
	s_ashr_i32 s15, s14, 31
	s_lshl_b64 s[16:17], s[14:15], 17
	s_add_u32 s16, s47, s16
	s_addc_u32 s17, s46, s17
	s_and_b64 s[18:19], s[10:11], exec
	s_cselect_b32 s15, s17, s25
	s_cselect_b32 s21, s16, s24
	s_ashr_i32 s13, s12, 31
	s_lshl_b64 s[18:19], s[12:13], 17
	s_add_u32 s18, s63, s18
	s_addc_u32 s19, s62, s19
	s_and_b64 s[38:39], s[10:11], exec
	s_cselect_b32 s13, s19, s23
	s_cselect_b32 s27, s18, s22
	s_mov_b32 s34, 0
	s_mov_b64 s[38:39], -1
	s_mov_b64 s[40:41], 0
	s_add_u32 s53, s24, s34
	s_addc_u32 s66, s25, 0
	s_add_u32 s44, s53, 0x100
	s_addc_u32 s45, s66, 0
	s_and_b64 s[42:43], s[40:41], exec
	s_cselect_b32 s45, s15, s45
	s_cselect_b32 s44, s21, s44
	s_add_u32 s34, s22, s34
	s_addc_u32 s42, s23, 0
	s_add_u32 s34, s34, 0x100
	s_addc_u32 s42, s42, 0
	s_add_i32 s97, s35, 0x100
	s_and_b64 s[40:41], s[40:41], exec
	s_cselect_b32 s61, s13, s42
	s_cselect_b32 s60, s27, s34
	s_add_i32 s41, s90, 0x100
	s_add_u32 s76, s53, 0x10080
	s_addc_u32 s77, s66, 0
	s_add_i32 s96, s97, s72
	s_add_i32 m0, s75, 0xc000
	s_add_i32 vcc_hi, s75, 0xe000
	s_add_i32 s81, s96, 0x2000
	s_add_u32 s66, s60, 0x10000
	v_add_u32_e32 v166, s97, v152
	v_add_u32_e32 v182, s41, v152
	s_addc_u32 s67, s61, 0
	s_add_i32 s95, s41, s72
	ds_read_b128 v[154:157], v166
	ds_read_b128 v[158:161], v166 offset:1024
	ds_read_b128 v[162:165], v166 offset:2048
	ds_read_b128 v[166:169], v166 offset:3072
	ds_read_b128 v[170:173], v182
	ds_read_b128 v[174:177], v182 offset:1024
	ds_read_b128 v[178:181], v182 offset:2048
	ds_read_b128 v[182:185], v182 offset:3072
	s_add_i32 s94, s95, 0x2000
	s_add_i32 s71, s65, 0x100
	s_add_i32 s69, s52, 0x100
	s_add_u32 s42, s44, 0x10000
	s_addc_u32 s43, s45, 0
	s_add_i32 s53, s71, s72
	s_add_i32 s34, s53, 0x2000
	s_add_u32 s40, s60, 0x10080
	s_addc_u32 s41, s61, 0
	s_add_i32 vcc_lo, s69, s72
	s_add_i32 s97, vcc_lo, 0x2000
	v_lshl_add_u64 v[190:191], s[76:77], 0, v[134:135]
	ds_read_b128 v[186:189], v153
	ds_read_b128 v[198:201], v153 offset:1024
	ds_read_b128 v[202:205], v153 offset:2048
	ds_read_b128 v[206:209], v153 offset:3072
	ds_read_b128 v[210:213], v153 offset:4096
	ds_read_b128 v[214:217], v153 offset:5120
	ds_read_b128 v[218:221], v153 offset:6144
	ds_read_b128 v[222:225], v153 offset:7168
	global_load_lds_dwordx4 v[190:191], off
	v_lshl_add_u64 v[190:191], s[76:77], 0, v[130:131]
	s_mov_b32 m0, vcc_hi
	s_nop 0
	global_load_lds_dwordx4 v[190:191], off
	s_waitcnt vmcnt(8)
	s_waitcnt lgkmcnt(0)
	s_setprio 1
	s_barrier
	v_mfma_f32_16x16x32_bf16 v[124:127], v[154:157], v[186:189], 0
	v_mfma_f32_16x16x32_bf16 v[120:123], v[162:165], v[186:189], 0
	v_mfma_f32_16x16x32_bf16 v[116:119], v[154:157], v[202:205], 0
	v_mfma_f32_16x16x32_bf16 v[108:111], v[162:165], v[202:205], 0
	v_mfma_f32_16x16x32_bf16 v[100:103], v[154:157], v[210:213], 0
	v_mfma_f32_16x16x32_bf16 v[92:95], v[162:165], v[210:213], 0
	v_mfma_f32_16x16x32_bf16 v[84:87], v[154:157], v[218:221], 0
	v_mfma_f32_16x16x32_bf16 v[76:79], v[162:165], v[218:221], 0
	v_mfma_f32_16x16x32_bf16 v[124:127], v[158:161], v[198:201], v[124:127]
	v_mfma_f32_16x16x32_bf16 v[120:123], v[166:169], v[198:201], v[120:123]
	v_mfma_f32_16x16x32_bf16 v[116:119], v[158:161], v[206:209], v[116:119]
	v_mfma_f32_16x16x32_bf16 v[108:111], v[166:169], v[206:209], v[108:111]
	v_mfma_f32_16x16x32_bf16 v[100:103], v[158:161], v[214:217], v[100:103]
	v_mfma_f32_16x16x32_bf16 v[92:95], v[166:169], v[214:217], v[92:95]
	v_mfma_f32_16x16x32_bf16 v[84:87], v[158:161], v[222:225], v[84:87]
	v_mfma_f32_16x16x32_bf16 v[76:79], v[166:169], v[222:225], v[76:79]
	v_mfma_f32_16x16x32_bf16 v[112:115], v[170:173], v[186:189], 0
	v_mfma_f32_16x16x32_bf16 v[104:107], v[178:181], v[186:189], 0
	v_mfma_f32_16x16x32_bf16 v[96:99], v[170:173], v[202:205], 0
	v_mfma_f32_16x16x32_bf16 v[88:91], v[178:181], v[202:205], 0
	v_mfma_f32_16x16x32_bf16 v[80:83], v[170:173], v[210:213], 0
	v_mfma_f32_16x16x32_bf16 v[72:75], v[178:181], v[210:213], 0
	v_mfma_f32_16x16x32_bf16 v[68:71], v[170:173], v[218:221], 0
	v_mfma_f32_16x16x32_bf16 v[64:67], v[178:181], v[218:221], 0
	v_mfma_f32_16x16x32_bf16 v[112:115], v[174:177], v[198:201], v[112:115]
	v_mfma_f32_16x16x32_bf16 v[104:107], v[182:185], v[198:201], v[104:107]
	v_mfma_f32_16x16x32_bf16 v[96:99], v[174:177], v[206:209], v[96:99]
	v_mfma_f32_16x16x32_bf16 v[88:91], v[182:185], v[206:209], v[88:91]
	v_mfma_f32_16x16x32_bf16 v[80:83], v[174:177], v[214:217], v[80:83]
	v_mfma_f32_16x16x32_bf16 v[72:75], v[182:185], v[214:217], v[72:75]
	v_mfma_f32_16x16x32_bf16 v[68:71], v[174:177], v[222:225], v[68:71]
	v_mfma_f32_16x16x32_bf16 v[64:67], v[182:185], v[222:225], v[64:67]
	s_barrier
	s_setprio 0
	s_mov_b32 m0, s96
	v_lshl_add_u64 v[190:191], s[60:61], 0, v[132:133]
	ds_read_b128 v[186:189], v153 offset:16384
	ds_read_b128 v[198:201], v153 offset:17408
	ds_read_b128 v[202:205], v153 offset:18432
	ds_read_b128 v[206:209], v153 offset:19456
	ds_read_b128 v[210:213], v153 offset:20480
	ds_read_b128 v[214:217], v153 offset:21504
	ds_read_b128 v[218:221], v153 offset:22528
	ds_read_b128 v[222:225], v153 offset:23552
	global_load_lds_dwordx4 v[190:191], off
	v_lshl_add_u64 v[226:227], s[60:61], 0, v[128:129]
	s_mov_b32 m0, s81
	v_lshl_add_u64 v[228:229], s[66:67], 0, v[132:133]
	global_load_lds_dwordx4 v[226:227], off
	s_mov_b32 m0, s95
	v_lshl_add_u64 v[230:231], s[44:45], 0, v[130:131]
	global_load_lds_dwordx4 v[228:229], off
	v_lshl_add_u64 v[228:229], s[66:67], 0, v[128:129]
	s_mov_b32 m0, s94
	s_nop 0
	global_load_lds_dwordx4 v[228:229], off
	v_lshl_add_u64 v[228:229], s[44:45], 0, v[134:135]
	s_mov_b32 m0, s75
	s_nop 0
	global_load_lds_dwordx4 v[228:229], off
	s_mov_b32 m0, s78
	s_nop 0
	global_load_lds_dwordx4 v[230:231], off
	s_waitcnt vmcnt(8)
	s_waitcnt lgkmcnt(0)
	s_setprio 1
	s_barrier
; #define PG8_STAGE(bufoff, gbase, voff) do { _Pragma("unroll") for (int _i = 0; _i < 2; ++_i) \
;         __builtin_amdgcn_global_load_lds((const unsigned*)((const char*)(gbase) + (voff)[_i]), (PG8_LAS unsigned*)(lds + (bufoff) + ldsw + _i * 8192), 16, 0, 0); } while (0)
; #define PG8_LDA(dst, b, h) do { _Pragma("unroll") for (int m = 0; m < 4; ++m) _Pragma("unroll") for (int k = 0; k < 2; ++k) dst[m][k] = *(const PG8_LAS bf16x8*)(lds + PG8_SA(b, h) + aoff + m * 2048 + k * 1024); } while (0)
; #define PG8_LDB(dst, b, h) do { _Pragma("unroll") for (int n = 0; n < 2; ++n) _Pragma("unroll") for (int k = 0; k < 2; ++k) dst[n][k] = *(const PG8_LAS bf16x8*)(lds + PG8_SB(b, h) + boff + n * 2048 + k * 1024); } while (0)
; #define PG8_MMA(ai, bj, At, Bt) do { __builtin_amdgcn_s_setprio(1); _Pragma("unroll") for (int m = 0; m < 4; ++m) _Pragma("unroll") for (int n = 0; n < 2; ++n) _Pragma("unroll") for (int k = 0; k < 2; ++k) \
;         acc[ai][bj][m][n] = __builtin_amdgcn_mfma_f32_16x16x32_bf16(Bt[n][k], At[m][k], acc[ai][bj][m][n], 0, 0, 0); __builtin_amdgcn_s_setprio(0); } while (0)
; #define PG8_BAR __builtin_amdgcn_s_barrier()
; template <class Epi, class Sched, bool ALIGN_EPI = false, bool SP2 = false>
; __device__ __forceinline__ void gemm_phase(PG8_LAS unsigned char* lds, const Gemm g, const Sched& S, const Epi& E, int wave_in) {
;     ...
;             PG8_LDB(B0, 0, 0); PG8_LDB(B1, 0, 1); PG8_SCHED; PG8_LDA(At, 0, 0); PG8_STAGE(PG8_SA(1, 1), a1 + hstep, voffA);
;             PG8_WAIT_V(8); PG8_WAIT_L(0); PG8_BAR; PG8_MMA(0, 0, At, B0); PG8_MMA(0, 1, At, B1); PG8_BAR; PG8_SCHED;
;             PG8_LDA(At, 0, 1); PG8_STAGE(PG8_SB(0, 0), b2, voffB); PG8_STAGE(PG8_SB(0, 1), b2 + hstep, voffB); PG8_STAGE(PG8_SA(0, 0), a2, voffA);
;             PG8_WAIT_V(8); PG8_WAIT_L(0); PG8_BAR; PG8_MMA(1, 0, At, B0); PG8_MMA(1, 1, At, B1); PG8_BAR; PG8_SCHED;
;             PG8_LDB(B0, 1, 0); PG8_LDB(B1, 1, 1); PG8_SCHED; PG8_LDA(At, 1, 0); PG8_STAGE(PG8_SA(0, 1), a2 + hstep, voffA);
;             PG8_WAIT_V(8); PG8_WAIT_L(0); PG8_BAR; PG8_MMA(0, 0, At, B0); PG8_MMA(0, 1, At, B1); PG8_BAR; PG8_SCHED;
;             PG8_LDA(At, 1, 1); PG8_STAGE(PG8_SB(1, 0), b3, voffB); PG8_STAGE(PG8_SB(1, 1), b3 + hstep, voffB); PG8_STAGE(PG8_SA(1, 0), a3, voffA);
;             PG8_WAIT_V(8); PG8_WAIT_L(0); PG8_BAR; PG8_MMA(1, 0, At, B0); PG8_MMA(1, 1, At, B1); PG8_BAR; PG8_SCHED;
	v_mfma_f32_16x16x32_bf16 v[60:63], v[154:157], v[186:189], 0
	v_mfma_f32_16x16x32_bf16 v[56:59], v[162:165], v[186:189], 0
	v_mfma_f32_16x16x32_bf16 v[52:55], v[154:157], v[202:205], 0
	v_mfma_f32_16x16x32_bf16 v[44:47], v[162:165], v[202:205], 0
	v_mfma_f32_16x16x32_bf16 v[36:39], v[154:157], v[210:213], 0
	v_mfma_f32_16x16x32_bf16 v[28:31], v[162:165], v[210:213], 0
	v_mfma_f32_16x16x32_bf16 v[20:23], v[154:157], v[218:221], 0
	v_mfma_f32_16x16x32_bf16 v[12:15], v[162:165], v[218:221], 0
	v_mfma_f32_16x16x32_bf16 v[60:63], v[158:161], v[198:201], v[60:63]
	v_mfma_f32_16x16x32_bf16 v[56:59], v[166:169], v[198:201], v[56:59]
	v_mfma_f32_16x16x32_bf16 v[52:55], v[158:161], v[206:209], v[52:55]
	v_mfma_f32_16x16x32_bf16 v[44:47], v[166:169], v[206:209], v[44:47]
	v_mfma_f32_16x16x32_bf16 v[36:39], v[158:161], v[214:217], v[36:39]
	v_mfma_f32_16x16x32_bf16 v[28:31], v[166:169], v[214:217], v[28:31]
	v_mfma_f32_16x16x32_bf16 v[20:23], v[158:161], v[222:225], v[20:23]
	v_mfma_f32_16x16x32_bf16 v[12:15], v[166:169], v[222:225], v[12:15]
	v_mfma_f32_16x16x32_bf16 v[48:51], v[170:173], v[186:189], 0
	v_mfma_f32_16x16x32_bf16 v[40:43], v[178:181], v[186:189], 0
	v_mfma_f32_16x16x32_bf16 v[32:35], v[170:173], v[202:205], 0
	v_mfma_f32_16x16x32_bf16 v[24:27], v[178:181], v[202:205], 0
	v_mfma_f32_16x16x32_bf16 v[16:19], v[170:173], v[210:213], 0
	v_mfma_f32_16x16x32_bf16 v[8:11], v[178:181], v[210:213], 0
	v_mfma_f32_16x16x32_bf16 v[4:7], v[170:173], v[218:221], 0
	v_mfma_f32_16x16x32_bf16 v[0:3], v[178:181], v[218:221], 0
	v_mfma_f32_16x16x32_bf16 v[48:51], v[174:177], v[198:201], v[48:51]
	v_mfma_f32_16x16x32_bf16 v[40:43], v[182:185], v[198:201], v[40:43]
	v_mfma_f32_16x16x32_bf16 v[32:35], v[174:177], v[206:209], v[32:35]
	v_mfma_f32_16x16x32_bf16 v[24:27], v[182:185], v[206:209], v[24:27]
	v_mfma_f32_16x16x32_bf16 v[16:19], v[174:177], v[214:217], v[16:19]
	v_mfma_f32_16x16x32_bf16 v[8:11], v[182:185], v[214:217], v[8:11]
	v_mfma_f32_16x16x32_bf16 v[4:7], v[174:177], v[222:225], v[4:7]
	v_mfma_f32_16x16x32_bf16 v[0:3], v[182:185], v[222:225], v[0:3]
	s_barrier
	s_setprio 0
	v_add_u32_e32 v166, s71, v152
	v_add_u32_e32 v182, s69, v152
	ds_read_b128 v[154:157], v166
	ds_read_b128 v[158:161], v166 offset:1024
	ds_read_b128 v[162:165], v166 offset:2048
	ds_read_b128 v[166:169], v166 offset:3072
	ds_read_b128 v[170:173], v182
	ds_read_b128 v[174:177], v182 offset:1024
	ds_read_b128 v[178:181], v182 offset:2048
	ds_read_b128 v[182:185], v182 offset:3072
	s_mov_b32 m0, s79
	v_lshl_add_u64 v[232:233], s[42:43], 0, v[134:135]
	ds_read_b128 v[186:189], v153 offset:32768
	ds_read_b128 v[198:201], v153 offset:33792
	ds_read_b128 v[202:205], v153 offset:34816
	ds_read_b128 v[206:209], v153 offset:35840
	ds_read_b128 v[210:213], v153 offset:36864
	ds_read_b128 v[214:217], v153 offset:37888
	ds_read_b128 v[218:221], v153 offset:38912
	ds_read_b128 v[222:225], v153 offset:39936
	global_load_lds_dwordx4 v[232:233], off
	v_lshl_add_u64 v[232:233], s[42:43], 0, v[130:131]
	s_mov_b32 m0, s82
	s_nop 0
	global_load_lds_dwordx4 v[232:233], off
	s_waitcnt vmcnt(8)
	s_waitcnt lgkmcnt(0)
	s_setprio 1
	s_barrier
	v_mfma_f32_16x16x32_bf16 v[124:127], v[154:157], v[186:189], v[124:127]
	v_mfma_f32_16x16x32_bf16 v[120:123], v[162:165], v[186:189], v[120:123]
	v_mfma_f32_16x16x32_bf16 v[116:119], v[154:157], v[202:205], v[116:119]
	v_mfma_f32_16x16x32_bf16 v[108:111], v[162:165], v[202:205], v[108:111]
	v_mfma_f32_16x16x32_bf16 v[100:103], v[154:157], v[210:213], v[100:103]
	v_mfma_f32_16x16x32_bf16 v[92:95], v[162:165], v[210:213], v[92:95]
	v_mfma_f32_16x16x32_bf16 v[84:87], v[154:157], v[218:221], v[84:87]
	v_mfma_f32_16x16x32_bf16 v[76:79], v[162:165], v[218:221], v[76:79]
	v_mfma_f32_16x16x32_bf16 v[124:127], v[158:161], v[198:201], v[124:127]
	v_mfma_f32_16x16x32_bf16 v[120:123], v[166:169], v[198:201], v[120:123]
	v_mfma_f32_16x16x32_bf16 v[116:119], v[158:161], v[206:209], v[116:119]
	v_mfma_f32_16x16x32_bf16 v[108:111], v[166:169], v[206:209], v[108:111]
	v_mfma_f32_16x16x32_bf16 v[100:103], v[158:161], v[214:217], v[100:103]
	v_mfma_f32_16x16x32_bf16 v[92:95], v[166:169], v[214:217], v[92:95]
	v_mfma_f32_16x16x32_bf16 v[84:87], v[158:161], v[222:225], v[84:87]
	v_mfma_f32_16x16x32_bf16 v[76:79], v[166:169], v[222:225], v[76:79]
	v_mfma_f32_16x16x32_bf16 v[112:115], v[170:173], v[186:189], v[112:115]
	v_mfma_f32_16x16x32_bf16 v[104:107], v[178:181], v[186:189], v[104:107]
	v_mfma_f32_16x16x32_bf16 v[96:99], v[170:173], v[202:205], v[96:99]
	v_mfma_f32_16x16x32_bf16 v[88:91], v[178:181], v[202:205], v[88:91]
	v_mfma_f32_16x16x32_bf16 v[80:83], v[170:173], v[210:213], v[80:83]
	v_mfma_f32_16x16x32_bf16 v[72:75], v[178:181], v[210:213], v[72:75]
	v_mfma_f32_16x16x32_bf16 v[68:71], v[170:173], v[218:221], v[68:71]
	v_mfma_f32_16x16x32_bf16 v[64:67], v[178:181], v[218:221], v[64:67]
	v_mfma_f32_16x16x32_bf16 v[112:115], v[174:177], v[198:201], v[112:115]
	v_mfma_f32_16x16x32_bf16 v[104:107], v[182:185], v[198:201], v[104:107]
	v_mfma_f32_16x16x32_bf16 v[96:99], v[174:177], v[206:209], v[96:99]
	v_mfma_f32_16x16x32_bf16 v[88:91], v[182:185], v[206:209], v[88:91]
	v_mfma_f32_16x16x32_bf16 v[80:83], v[174:177], v[214:217], v[80:83]
	v_mfma_f32_16x16x32_bf16 v[72:75], v[182:185], v[214:217], v[72:75]
	v_mfma_f32_16x16x32_bf16 v[68:71], v[174:177], v[222:225], v[68:71]
	v_mfma_f32_16x16x32_bf16 v[64:67], v[182:185], v[222:225], v[64:67]
	s_barrier
; #define PG8_STAGE(bufoff, gbase, voff) do { _Pragma("unroll") for (int _i = 0; _i < 2; ++_i) \
;         __builtin_amdgcn_global_load_lds((const unsigned*)((const char*)(gbase) + (voff)[_i]), (PG8_LAS unsigned*)(lds + (bufoff) + ldsw + _i * 8192), 16, 0, 0); } while (0)
; #define PG8_LDA(dst, b, h) do { _Pragma("unroll") for (int m = 0; m < 4; ++m) _Pragma("unroll") for (int k = 0; k < 2; ++k) dst[m][k] = *(const PG8_LAS bf16x8*)(lds + PG8_SA(b, h) + aoff + m * 2048 + k * 1024); } while (0)
; #define PG8_WAIT_V(n) asm volatile("s_waitcnt vmcnt(" #n ")" ::: "memory")
; #define PG8_WAIT_L(n) asm volatile("s_waitcnt lgkmcnt(" #n ")" ::: "memory")
; #define PG8_BAR __builtin_amdgcn_s_barrier()
; template <class Epi, class Sched, bool ALIGN_EPI = false, bool SP2 = false>
; __device__ __forceinline__ void gemm_phase(PG8_LAS unsigned char* lds, const Gemm g, const Sched& S, const Epi& E, int wave_in) {
;     ...
;         for (int t = 0; t < nt; t += 2) {
;             const bool last = (t == nt - 2);
;             const char* a1 = cA + (size_t)(t + 1) * kstep;
;             const char* a2 = last ? nA : cA + (size_t)(t + 2) * kstep; const char* b2 = last ? nB : cB + (size_t)(t + 2) * kstep;
;             const char* a3 = a2 + kstep; const char* b3 = b2 + kstep;
;             if (last && has_next) S.a_ready(nxt);
;             if constexpr (SP2) {
;             PG8_LDB(B0, 0, 0); PG8_LDB(B1, 0, 1); PG8_SCHED; PG8_LDA(At, 0, 0); PG8_STAGE(PG8_SA(1, 1), a1 + hstep, voffA);
;             PG8_WAIT_V(8); PG8_WAIT_L(0); PG8_BAR; PG8_MMA(0, 0, At, B0); PG8_MMA(0, 1, At, B1); PG8_BAR; PG8_SCHED;
;             PG8_LDA(At, 0, 1); PG8_STAGE(PG8_SB(0, 0), b2, voffB); PG8_STAGE(PG8_SB(0, 1), b2 + hstep, voffB); PG8_STAGE(PG8_SA(0, 0), a2, voffA);
;             PG8_WAIT_V(8); PG8_WAIT_L(0); PG8_BAR; PG8_MMA(1, 0, At, B0); PG8_MMA(1, 1, At, B1); PG8_BAR; PG8_SCHED;
;             PG8_LDB(B0, 1, 0); PG8_LDB(B1, 1, 1); PG8_SCHED; PG8_LDA(At, 1, 0); PG8_STAGE(PG8_SA(0, 1), a2 + hstep, voffA);
;             PG8_WAIT_V(8); PG8_WAIT_L(0); PG8_BAR; PG8_MMA(0, 0, At, B0); PG8_MMA(0, 1, At, B1); PG8_BAR; PG8_SCHED;
;             PG8_LDA(At, 1, 1); PG8_STAGE(PG8_SB(1, 0), b3, voffB); PG8_STAGE(PG8_SB(1, 1), b3 + hstep, voffB); PG8_STAGE(PG8_SA(1, 0), a3, voffA);
;             PG8_WAIT_V(8); PG8_WAIT_L(0); PG8_BAR; PG8_MMA(1, 0, At, B0); PG8_MMA(1, 1, At, B1); PG8_BAR; PG8_SCHED;
	s_setprio 0
	s_mov_b32 m0, s53
	v_lshl_add_u64 v[190:191], v[190:191], 0, s[88:89]
	ds_read_b128 v[186:189], v153 offset:49152
	ds_read_b128 v[198:201], v153 offset:50176
	ds_read_b128 v[202:205], v153 offset:51200
	ds_read_b128 v[206:209], v153 offset:52224
	ds_read_b128 v[210:213], v153 offset:53248
	ds_read_b128 v[214:217], v153 offset:54272
	ds_read_b128 v[218:221], v153 offset:55296
	ds_read_b128 v[222:225], v153 offset:56320
	global_load_lds_dwordx4 v[190:191], off
	v_lshl_add_u64 v[190:191], v[226:227], 0, s[88:89]
	s_mov_b32 m0, s34
	s_nop 0
	global_load_lds_dwordx4 v[190:191], off
	v_lshl_add_u64 v[190:191], s[40:41], 0, v[132:133]
	s_mov_b32 m0, vcc_lo
	s_nop 0
	global_load_lds_dwordx4 v[190:191], off
	v_lshl_add_u64 v[190:191], s[40:41], 0, v[128:129]
	s_mov_b32 m0, s97
	s_nop 0
	global_load_lds_dwordx4 v[190:191], off
	v_lshl_add_u64 v[190:191], v[228:229], 0, s[88:89]
	s_mov_b32 m0, s85
	s_nop 0
	global_load_lds_dwordx4 v[190:191], off
	v_lshl_add_u64 v[190:191], v[230:231], 0, s[88:89]
	s_mov_b32 m0, s92
	s_nop 0
	global_load_lds_dwordx4 v[190:191], off
	s_waitcnt vmcnt(8)
	s_waitcnt lgkmcnt(0)
	s_setprio 1
	s_barrier
	v_mfma_f32_16x16x32_bf16 v[60:63], v[154:157], v[186:189], v[60:63]
	v_mfma_f32_16x16x32_bf16 v[56:59], v[162:165], v[186:189], v[56:59]
	v_mfma_f32_16x16x32_bf16 v[52:55], v[154:157], v[202:205], v[52:55]
	v_mfma_f32_16x16x32_bf16 v[44:47], v[162:165], v[202:205], v[44:47]
	v_mfma_f32_16x16x32_bf16 v[36:39], v[154:157], v[210:213], v[36:39]
	v_mfma_f32_16x16x32_bf16 v[28:31], v[162:165], v[210:213], v[28:31]
	v_mfma_f32_16x16x32_bf16 v[20:23], v[154:157], v[218:221], v[20:23]
	v_mfma_f32_16x16x32_bf16 v[12:15], v[162:165], v[218:221], v[12:15]
	v_mfma_f32_16x16x32_bf16 v[60:63], v[158:161], v[198:201], v[60:63]
	v_mfma_f32_16x16x32_bf16 v[56:59], v[166:169], v[198:201], v[56:59]
	v_mfma_f32_16x16x32_bf16 v[52:55], v[158:161], v[206:209], v[52:55]
	v_mfma_f32_16x16x32_bf16 v[44:47], v[166:169], v[206:209], v[44:47]
	v_mfma_f32_16x16x32_bf16 v[36:39], v[158:161], v[214:217], v[36:39]
	v_mfma_f32_16x16x32_bf16 v[28:31], v[166:169], v[214:217], v[28:31]
	v_mfma_f32_16x16x32_bf16 v[20:23], v[158:161], v[222:225], v[20:23]
	v_mfma_f32_16x16x32_bf16 v[12:15], v[166:169], v[222:225], v[12:15]
	v_mfma_f32_16x16x32_bf16 v[48:51], v[170:173], v[186:189], v[48:51]
	v_mfma_f32_16x16x32_bf16 v[40:43], v[178:181], v[186:189], v[40:43]
	v_mfma_f32_16x16x32_bf16 v[32:35], v[170:173], v[202:205], v[32:35]
	v_mfma_f32_16x16x32_bf16 v[24:27], v[178:181], v[202:205], v[24:27]
	v_mfma_f32_16x16x32_bf16 v[16:19], v[170:173], v[210:213], v[16:19]
	v_mfma_f32_16x16x32_bf16 v[8:11], v[178:181], v[210:213], v[8:11]
	v_mfma_f32_16x16x32_bf16 v[4:7], v[170:173], v[218:221], v[4:7]
	v_mfma_f32_16x16x32_bf16 v[0:3], v[178:181], v[218:221], v[0:3]
	v_mfma_f32_16x16x32_bf16 v[48:51], v[174:177], v[198:201], v[48:51]
	v_mfma_f32_16x16x32_bf16 v[40:43], v[182:185], v[198:201], v[40:43]
	v_mfma_f32_16x16x32_bf16 v[32:35], v[174:177], v[206:209], v[32:35]
	v_mfma_f32_16x16x32_bf16 v[24:27], v[182:185], v[206:209], v[24:27]
	v_mfma_f32_16x16x32_bf16 v[16:19], v[174:177], v[214:217], v[16:19]
	v_mfma_f32_16x16x32_bf16 v[8:11], v[182:185], v[214:217], v[8:11]
	v_mfma_f32_16x16x32_bf16 v[4:7], v[174:177], v[222:225], v[4:7]
	v_mfma_f32_16x16x32_bf16 v[0:3], v[182:185], v[222:225], v[0:3]
	s_barrier
	s_setprio 0
	s_movk_i32 s34, 0x100
	s_andn2_b64 vcc, exec, s[38:39]
	s_mov_b64 s[40:41], -1
	s_mov_b64 s[38:39], 0
	s_cbranch_vccnz .Lkexit_2
.LBB0_485:
	s_add_u32 s53, s24, s34
	s_addc_u32 s66, s25, 0
	s_add_u32 s44, s53, 0x100
	s_addc_u32 s45, s66, 0
	s_and_b64 s[42:43], s[40:41], exec
	s_cselect_b32 s45, s15, s45
	s_cselect_b32 s44, s21, s44
	s_add_u32 s34, s22, s34
	s_addc_u32 s42, s23, 0
	s_add_u32 s34, s34, 0x100
	s_addc_u32 s42, s42, 0
	s_add_i32 s97, s35, 0x100
	s_and_b64 s[40:41], s[40:41], exec
	s_cselect_b32 s61, s13, s42
	s_cselect_b32 s60, s27, s34
	s_add_i32 s41, s90, 0x100
	s_add_u32 s76, s53, 0x10080
	s_addc_u32 s77, s66, 0
	s_add_i32 s96, s97, s72
	s_add_i32 m0, s75, 0xc000
	s_add_i32 vcc_hi, s75, 0xe000
	s_add_i32 s81, s96, 0x2000
	s_add_u32 s66, s60, 0x10000
	v_add_u32_e32 v166, s97, v152
	v_add_u32_e32 v182, s41, v152
	s_addc_u32 s67, s61, 0
	s_add_i32 s95, s41, s72
	ds_read_b128 v[154:157], v166
	ds_read_b128 v[158:161], v166 offset:1024
	ds_read_b128 v[162:165], v166 offset:2048
	ds_read_b128 v[166:169], v166 offset:3072
	ds_read_b128 v[170:173], v182
	ds_read_b128 v[174:177], v182 offset:1024
	ds_read_b128 v[178:181], v182 offset:2048
	ds_read_b128 v[182:185], v182 offset:3072
	s_add_i32 s94, s95, 0x2000
	s_add_i32 s71, s65, 0x100
	s_add_i32 s69, s52, 0x100
	s_add_u32 s42, s44, 0x10000
	s_addc_u32 s43, s45, 0
	s_add_i32 s53, s71, s72
	s_add_i32 s34, s53, 0x2000
	s_add_u32 s40, s60, 0x10080
	s_addc_u32 s41, s61, 0
	s_add_i32 vcc_lo, s69, s72
	s_add_i32 s97, vcc_lo, 0x2000
	v_lshl_add_u64 v[190:191], s[76:77], 0, v[134:135]
	ds_read_b128 v[186:189], v153
	ds_read_b128 v[198:201], v153 offset:1024
	ds_read_b128 v[202:205], v153 offset:2048
	ds_read_b128 v[206:209], v153 offset:3072
	ds_read_b128 v[210:213], v153 offset:4096
	ds_read_b128 v[214:217], v153 offset:5120
	ds_read_b128 v[218:221], v153 offset:6144
	ds_read_b128 v[222:225], v153 offset:7168
	global_load_lds_dwordx4 v[190:191], off
	v_lshl_add_u64 v[190:191], s[76:77], 0, v[130:131]
	s_mov_b32 m0, vcc_hi
	s_nop 0
	global_load_lds_dwordx4 v[190:191], off
	s_waitcnt vmcnt(8)
	s_waitcnt lgkmcnt(0)
	s_setprio 1
	s_barrier
; #define PG8_STAGE(bufoff, gbase, voff) do { _Pragma("unroll") for (int _i = 0; _i < 2; ++_i) \
;         __builtin_amdgcn_global_load_lds((const unsigned*)((const char*)(gbase) + (voff)[_i]), (PG8_LAS unsigned*)(lds + (bufoff) + ldsw + _i * 8192), 16, 0, 0); } while (0)
; #define PG8_LDA(dst, b, h) do { _Pragma("unroll") for (int m = 0; m < 4; ++m) _Pragma("unroll") for (int k = 0; k < 2; ++k) dst[m][k] = *(const PG8_LAS bf16x8*)(lds + PG8_SA(b, h) + aoff + m * 2048 + k * 1024); } while (0)
; #define PG8_LDB(dst, b, h) do { _Pragma("unroll") for (int n = 0; n < 2; ++n) _Pragma("unroll") for (int k = 0; k < 2; ++k) dst[n][k] = *(const PG8_LAS bf16x8*)(lds + PG8_SB(b, h) + boff + n * 2048 + k * 1024); } while (0)
; #define PG8_MMA(ai, bj, At, Bt) do { __builtin_amdgcn_s_setprio(1); _Pragma("unroll") for (int m = 0; m < 4; ++m) _Pragma("unroll") for (int n = 0; n < 2; ++n) _Pragma("unroll") for (int k = 0; k < 2; ++k) \
;         acc[ai][bj][m][n] = __builtin_amdgcn_mfma_f32_16x16x32_bf16(Bt[n][k], At[m][k], acc[ai][bj][m][n], 0, 0, 0); __builtin_amdgcn_s_setprio(0); } while (0)
; #define PG8_BAR __builtin_amdgcn_s_barrier()
; template <class Epi, class Sched, bool ALIGN_EPI = false, bool SP2 = false>
; __device__ __forceinline__ void gemm_phase(PG8_LAS unsigned char* lds, const Gemm g, const Sched& S, const Epi& E, int wave_in) {
;     ...
;             PG8_LDB(B0, 0, 0); PG8_LDB(B1, 0, 1); PG8_SCHED; PG8_LDA(At, 0, 0); PG8_STAGE(PG8_SA(1, 1), a1 + hstep, voffA);
;             PG8_WAIT_V(8); PG8_WAIT_L(0); PG8_BAR; PG8_MMA(0, 0, At, B0); PG8_MMA(0, 1, At, B1); PG8_BAR; PG8_SCHED;
;             PG8_LDA(At, 0, 1); PG8_STAGE(PG8_SB(0, 0), b2, voffB); PG8_STAGE(PG8_SB(0, 1), b2 + hstep, voffB); PG8_STAGE(PG8_SA(0, 0), a2, voffA);
;             PG8_WAIT_V(8); PG8_WAIT_L(0); PG8_BAR; PG8_MMA(1, 0, At, B0); PG8_MMA(1, 1, At, B1); PG8_BAR; PG8_SCHED;
;             PG8_LDB(B0, 1, 0); PG8_LDB(B1, 1, 1); PG8_SCHED; PG8_LDA(At, 1, 0); PG8_STAGE(PG8_SA(0, 1), a2 + hstep, voffA);
;             PG8_WAIT_V(8); PG8_WAIT_L(0); PG8_BAR; PG8_MMA(0, 0, At, B0); PG8_MMA(0, 1, At, B1); PG8_BAR; PG8_SCHED;
;             PG8_LDA(At, 1, 1); PG8_STAGE(PG8_SB(1, 0), b3, voffB); PG8_STAGE(PG8_SB(1, 1), b3 + hstep, voffB); PG8_STAGE(PG8_SA(1, 0), a3, voffA);
;             PG8_WAIT_V(8); PG8_WAIT_L(0); PG8_BAR; PG8_MMA(1, 0, At, B0); PG8_MMA(1, 1, At, B1); PG8_BAR; PG8_SCHED;
	v_mfma_f32_16x16x32_bf16 v[124:127], v[154:157], v[186:189], v[124:127]
	v_mfma_f32_16x16x32_bf16 v[120:123], v[162:165], v[186:189], v[120:123]
	v_mfma_f32_16x16x32_bf16 v[116:119], v[154:157], v[202:205], v[116:119]
	v_mfma_f32_16x16x32_bf16 v[108:111], v[162:165], v[202:205], v[108:111]
	v_mfma_f32_16x16x32_bf16 v[100:103], v[154:157], v[210:213], v[100:103]
	v_mfma_f32_16x16x32_bf16 v[92:95], v[162:165], v[210:213], v[92:95]
	v_mfma_f32_16x16x32_bf16 v[84:87], v[154:157], v[218:221], v[84:87]
	v_mfma_f32_16x16x32_bf16 v[76:79], v[162:165], v[218:221], v[76:79]
	v_mfma_f32_16x16x32_bf16 v[124:127], v[158:161], v[198:201], v[124:127]
	v_mfma_f32_16x16x32_bf16 v[120:123], v[166:169], v[198:201], v[120:123]
	v_mfma_f32_16x16x32_bf16 v[116:119], v[158:161], v[206:209], v[116:119]
	v_mfma_f32_16x16x32_bf16 v[108:111], v[166:169], v[206:209], v[108:111]
	v_mfma_f32_16x16x32_bf16 v[100:103], v[158:161], v[214:217], v[100:103]
	v_mfma_f32_16x16x32_bf16 v[92:95], v[166:169], v[214:217], v[92:95]
	v_mfma_f32_16x16x32_bf16 v[84:87], v[158:161], v[222:225], v[84:87]
	v_mfma_f32_16x16x32_bf16 v[76:79], v[166:169], v[222:225], v[76:79]
	v_mfma_f32_16x16x32_bf16 v[112:115], v[170:173], v[186:189], v[112:115]
	v_mfma_f32_16x16x32_bf16 v[104:107], v[178:181], v[186:189], v[104:107]
	v_mfma_f32_16x16x32_bf16 v[96:99], v[170:173], v[202:205], v[96:99]
	v_mfma_f32_16x16x32_bf16 v[88:91], v[178:181], v[202:205], v[88:91]
	v_mfma_f32_16x16x32_bf16 v[80:83], v[170:173], v[210:213], v[80:83]
	v_mfma_f32_16x16x32_bf16 v[72:75], v[178:181], v[210:213], v[72:75]
	v_mfma_f32_16x16x32_bf16 v[68:71], v[170:173], v[218:221], v[68:71]
	v_mfma_f32_16x16x32_bf16 v[64:67], v[178:181], v[218:221], v[64:67]
	v_mfma_f32_16x16x32_bf16 v[112:115], v[174:177], v[198:201], v[112:115]
	v_mfma_f32_16x16x32_bf16 v[104:107], v[182:185], v[198:201], v[104:107]
	v_mfma_f32_16x16x32_bf16 v[96:99], v[174:177], v[206:209], v[96:99]
	v_mfma_f32_16x16x32_bf16 v[88:91], v[182:185], v[206:209], v[88:91]
	v_mfma_f32_16x16x32_bf16 v[80:83], v[174:177], v[214:217], v[80:83]
	v_mfma_f32_16x16x32_bf16 v[72:75], v[182:185], v[214:217], v[72:75]
	v_mfma_f32_16x16x32_bf16 v[68:71], v[174:177], v[222:225], v[68:71]
	v_mfma_f32_16x16x32_bf16 v[64:67], v[182:185], v[222:225], v[64:67]
	s_barrier
	s_setprio 0
	s_mov_b32 m0, s96
	v_lshl_add_u64 v[190:191], s[60:61], 0, v[132:133]
	ds_read_b128 v[186:189], v153 offset:16384
	ds_read_b128 v[198:201], v153 offset:17408
	ds_read_b128 v[202:205], v153 offset:18432
	ds_read_b128 v[206:209], v153 offset:19456
	ds_read_b128 v[210:213], v153 offset:20480
	ds_read_b128 v[214:217], v153 offset:21504
	ds_read_b128 v[218:221], v153 offset:22528
	ds_read_b128 v[222:225], v153 offset:23552
	global_load_lds_dwordx4 v[190:191], off
	v_lshl_add_u64 v[226:227], s[60:61], 0, v[128:129]
	s_mov_b32 m0, s81
	v_lshl_add_u64 v[228:229], s[66:67], 0, v[132:133]
	global_load_lds_dwordx4 v[226:227], off
	s_mov_b32 m0, s95
	v_lshl_add_u64 v[230:231], s[44:45], 0, v[130:131]
	global_load_lds_dwordx4 v[228:229], off
	v_lshl_add_u64 v[228:229], s[66:67], 0, v[128:129]
	s_mov_b32 m0, s94
	s_nop 0
	global_load_lds_dwordx4 v[228:229], off
	v_lshl_add_u64 v[228:229], s[44:45], 0, v[134:135]
	s_mov_b32 m0, s75
	s_nop 0
	global_load_lds_dwordx4 v[228:229], off
	s_mov_b32 m0, s78
	s_nop 0
	global_load_lds_dwordx4 v[230:231], off
	s_waitcnt vmcnt(8)
	s_waitcnt lgkmcnt(0)
	s_setprio 1
	s_barrier
	v_mfma_f32_16x16x32_bf16 v[60:63], v[154:157], v[186:189], v[60:63]
	v_mfma_f32_16x16x32_bf16 v[56:59], v[162:165], v[186:189], v[56:59]
	v_mfma_f32_16x16x32_bf16 v[52:55], v[154:157], v[202:205], v[52:55]
	v_mfma_f32_16x16x32_bf16 v[44:47], v[162:165], v[202:205], v[44:47]
	v_mfma_f32_16x16x32_bf16 v[36:39], v[154:157], v[210:213], v[36:39]
	v_mfma_f32_16x16x32_bf16 v[28:31], v[162:165], v[210:213], v[28:31]
	v_mfma_f32_16x16x32_bf16 v[20:23], v[154:157], v[218:221], v[20:23]
	v_mfma_f32_16x16x32_bf16 v[12:15], v[162:165], v[218:221], v[12:15]
	v_mfma_f32_16x16x32_bf16 v[60:63], v[158:161], v[198:201], v[60:63]
	v_mfma_f32_16x16x32_bf16 v[56:59], v[166:169], v[198:201], v[56:59]
	v_mfma_f32_16x16x32_bf16 v[52:55], v[158:161], v[206:209], v[52:55]
	v_mfma_f32_16x16x32_bf16 v[44:47], v[166:169], v[206:209], v[44:47]
	v_mfma_f32_16x16x32_bf16 v[36:39], v[158:161], v[214:217], v[36:39]
	v_mfma_f32_16x16x32_bf16 v[28:31], v[166:169], v[214:217], v[28:31]
	v_mfma_f32_16x16x32_bf16 v[20:23], v[158:161], v[222:225], v[20:23]
	v_mfma_f32_16x16x32_bf16 v[12:15], v[166:169], v[222:225], v[12:15]
	v_mfma_f32_16x16x32_bf16 v[48:51], v[170:173], v[186:189], v[48:51]
	v_mfma_f32_16x16x32_bf16 v[40:43], v[178:181], v[186:189], v[40:43]
	v_mfma_f32_16x16x32_bf16 v[32:35], v[170:173], v[202:205], v[32:35]
	v_mfma_f32_16x16x32_bf16 v[24:27], v[178:181], v[202:205], v[24:27]
	v_mfma_f32_16x16x32_bf16 v[16:19], v[170:173], v[210:213], v[16:19]
	v_mfma_f32_16x16x32_bf16 v[8:11], v[178:181], v[210:213], v[8:11]
	v_mfma_f32_16x16x32_bf16 v[4:7], v[170:173], v[218:221], v[4:7]
	v_mfma_f32_16x16x32_bf16 v[0:3], v[178:181], v[218:221], v[0:3]
	v_mfma_f32_16x16x32_bf16 v[48:51], v[174:177], v[198:201], v[48:51]
	v_mfma_f32_16x16x32_bf16 v[40:43], v[182:185], v[198:201], v[40:43]
	v_mfma_f32_16x16x32_bf16 v[32:35], v[174:177], v[206:209], v[32:35]
	v_mfma_f32_16x16x32_bf16 v[24:27], v[182:185], v[206:209], v[24:27]
	v_mfma_f32_16x16x32_bf16 v[16:19], v[174:177], v[214:217], v[16:19]
	v_mfma_f32_16x16x32_bf16 v[8:11], v[182:185], v[214:217], v[8:11]
	v_mfma_f32_16x16x32_bf16 v[4:7], v[174:177], v[222:225], v[4:7]
	v_mfma_f32_16x16x32_bf16 v[0:3], v[182:185], v[222:225], v[0:3]
	s_barrier
; #define PG8_STAGE(bufoff, gbase, voff) do { _Pragma("unroll") for (int _i = 0; _i < 2; ++_i) \
;         __builtin_amdgcn_global_load_lds((const unsigned*)((const char*)(gbase) + (voff)[_i]), (PG8_LAS unsigned*)(lds + (bufoff) + ldsw + _i * 8192), 16, 0, 0); } while (0)
; #define PG8_LDA(dst, b, h) do { _Pragma("unroll") for (int m = 0; m < 4; ++m) _Pragma("unroll") for (int k = 0; k < 2; ++k) dst[m][k] = *(const PG8_LAS bf16x8*)(lds + PG8_SA(b, h) + aoff + m * 2048 + k * 1024); } while (0)
; #define PG8_WAIT_V(n) asm volatile("s_waitcnt vmcnt(" #n ")" ::: "memory")
; #define PG8_WAIT_L(n) asm volatile("s_waitcnt lgkmcnt(" #n ")" ::: "memory")
; #define PG8_BAR __builtin_amdgcn_s_barrier()
; template <class Epi, class Sched, bool ALIGN_EPI = false, bool SP2 = false>
; __device__ __forceinline__ void gemm_phase(PG8_LAS unsigned char* lds, const Gemm g, const Sched& S, const Epi& E, int wave_in) {
;     ...
;         for (int t = 0; t < nt; t += 2) {
;             const bool last = (t == nt - 2);
;             const char* a1 = cA + (size_t)(t + 1) * kstep;
;             const char* a2 = last ? nA : cA + (size_t)(t + 2) * kstep; const char* b2 = last ? nB : cB + (size_t)(t + 2) * kstep;
;             const char* a3 = a2 + kstep; const char* b3 = b2 + kstep;
;             if (last && has_next) S.a_ready(nxt);
;             if constexpr (SP2) {
;             PG8_LDB(B0, 0, 0); PG8_LDB(B1, 0, 1); PG8_SCHED; PG8_LDA(At, 0, 0); PG8_STAGE(PG8_SA(1, 1), a1 + hstep, voffA);
;             PG8_WAIT_V(8); PG8_WAIT_L(0); PG8_BAR; PG8_MMA(0, 0, At, B0); PG8_MMA(0, 1, At, B1); PG8_BAR; PG8_SCHED;
;             PG8_LDA(At, 0, 1); PG8_STAGE(PG8_SB(0, 0), b2, voffB); PG8_STAGE(PG8_SB(0, 1), b2 + hstep, voffB); PG8_STAGE(PG8_SA(0, 0), a2, voffA);
;             PG8_WAIT_V(8); PG8_WAIT_L(0); PG8_BAR; PG8_MMA(1, 0, At, B0); PG8_MMA(1, 1, At, B1); PG8_BAR; PG8_SCHED;
;             PG8_LDB(B0, 1, 0); PG8_LDB(B1, 1, 1); PG8_SCHED; PG8_LDA(At, 1, 0); PG8_STAGE(PG8_SA(0, 1), a2 + hstep, voffA);
;             PG8_WAIT_V(8); PG8_WAIT_L(0); PG8_BAR; PG8_MMA(0, 0, At, B0); PG8_MMA(0, 1, At, B1); PG8_BAR; PG8_SCHED;
;             PG8_LDA(At, 1, 1); PG8_STAGE(PG8_SB(1, 0), b3, voffB); PG8_STAGE(PG8_SB(1, 1), b3 + hstep, voffB); PG8_STAGE(PG8_SA(1, 0), a3, voffA);
;             PG8_WAIT_V(8); PG8_WAIT_L(0); PG8_BAR; PG8_MMA(1, 0, At, B0); PG8_MMA(1, 1, At, B1); PG8_BAR; PG8_SCHED;
	s_setprio 0
	v_add_u32_e32 v166, s71, v152
	v_add_u32_e32 v182, s69, v152
	ds_read_b128 v[154:157], v166
	ds_read_b128 v[158:161], v166 offset:1024
	ds_read_b128 v[162:165], v166 offset:2048
	ds_read_b128 v[166:169], v166 offset:3072
	ds_read_b128 v[170:173], v182
	ds_read_b128 v[174:177], v182 offset:1024
	ds_read_b128 v[178:181], v182 offset:2048
	ds_read_b128 v[182:185], v182 offset:3072
	s_mov_b32 m0, s79
	v_lshl_add_u64 v[232:233], s[42:43], 0, v[134:135]
	ds_read_b128 v[186:189], v153 offset:32768
	ds_read_b128 v[198:201], v153 offset:33792
	ds_read_b128 v[202:205], v153 offset:34816
	ds_read_b128 v[206:209], v153 offset:35840
	ds_read_b128 v[210:213], v153 offset:36864
	ds_read_b128 v[214:217], v153 offset:37888
	ds_read_b128 v[218:221], v153 offset:38912
	ds_read_b128 v[222:225], v153 offset:39936
	global_load_lds_dwordx4 v[232:233], off
	v_lshl_add_u64 v[232:233], s[42:43], 0, v[130:131]
	s_mov_b32 m0, s82
	s_nop 0
	global_load_lds_dwordx4 v[232:233], off
	s_waitcnt vmcnt(8)
	s_waitcnt lgkmcnt(0)
	s_setprio 1
	s_barrier
	v_mfma_f32_16x16x32_bf16 v[124:127], v[154:157], v[186:189], v[124:127]
	v_mfma_f32_16x16x32_bf16 v[120:123], v[162:165], v[186:189], v[120:123]
	v_mfma_f32_16x16x32_bf16 v[116:119], v[154:157], v[202:205], v[116:119]
	v_mfma_f32_16x16x32_bf16 v[108:111], v[162:165], v[202:205], v[108:111]
	v_mfma_f32_16x16x32_bf16 v[100:103], v[154:157], v[210:213], v[100:103]
	v_mfma_f32_16x16x32_bf16 v[92:95], v[162:165], v[210:213], v[92:95]
	v_mfma_f32_16x16x32_bf16 v[84:87], v[154:157], v[218:221], v[84:87]
	v_mfma_f32_16x16x32_bf16 v[76:79], v[162:165], v[218:221], v[76:79]
	v_mfma_f32_16x16x32_bf16 v[124:127], v[158:161], v[198:201], v[124:127]
	v_mfma_f32_16x16x32_bf16 v[120:123], v[166:169], v[198:201], v[120:123]
	v_mfma_f32_16x16x32_bf16 v[116:119], v[158:161], v[206:209], v[116:119]
	v_mfma_f32_16x16x32_bf16 v[108:111], v[166:169], v[206:209], v[108:111]
	v_mfma_f32_16x16x32_bf16 v[100:103], v[158:161], v[214:217], v[100:103]
	v_mfma_f32_16x16x32_bf16 v[92:95], v[166:169], v[214:217], v[92:95]
	v_mfma_f32_16x16x32_bf16 v[84:87], v[158:161], v[222:225], v[84:87]
	v_mfma_f32_16x16x32_bf16 v[76:79], v[166:169], v[222:225], v[76:79]
	v_mfma_f32_16x16x32_bf16 v[112:115], v[170:173], v[186:189], v[112:115]
	v_mfma_f32_16x16x32_bf16 v[104:107], v[178:181], v[186:189], v[104:107]
	v_mfma_f32_16x16x32_bf16 v[96:99], v[170:173], v[202:205], v[96:99]
	v_mfma_f32_16x16x32_bf16 v[88:91], v[178:181], v[202:205], v[88:91]
	v_mfma_f32_16x16x32_bf16 v[80:83], v[170:173], v[210:213], v[80:83]
	v_mfma_f32_16x16x32_bf16 v[72:75], v[178:181], v[210:213], v[72:75]
	v_mfma_f32_16x16x32_bf16 v[68:71], v[170:173], v[218:221], v[68:71]
	v_mfma_f32_16x16x32_bf16 v[64:67], v[178:181], v[218:221], v[64:67]
	v_mfma_f32_16x16x32_bf16 v[112:115], v[174:177], v[198:201], v[112:115]
	v_mfma_f32_16x16x32_bf16 v[104:107], v[182:185], v[198:201], v[104:107]
	v_mfma_f32_16x16x32_bf16 v[96:99], v[174:177], v[206:209], v[96:99]
	v_mfma_f32_16x16x32_bf16 v[88:91], v[182:185], v[206:209], v[88:91]
	v_mfma_f32_16x16x32_bf16 v[80:83], v[174:177], v[214:217], v[80:83]
	v_mfma_f32_16x16x32_bf16 v[72:75], v[182:185], v[214:217], v[72:75]
	v_mfma_f32_16x16x32_bf16 v[68:71], v[174:177], v[222:225], v[68:71]
	v_mfma_f32_16x16x32_bf16 v[64:67], v[182:185], v[222:225], v[64:67]
	s_barrier
	s_setprio 0
	s_mov_b32 m0, s53
	v_lshl_add_u64 v[190:191], v[190:191], 0, s[88:89]
	ds_read_b128 v[186:189], v153 offset:49152
	ds_read_b128 v[198:201], v153 offset:50176
	ds_read_b128 v[202:205], v153 offset:51200
	ds_read_b128 v[206:209], v153 offset:52224
	ds_read_b128 v[210:213], v153 offset:53248
	ds_read_b128 v[214:217], v153 offset:54272
	ds_read_b128 v[218:221], v153 offset:55296
	ds_read_b128 v[222:225], v153 offset:56320
	global_load_lds_dwordx4 v[190:191], off
	v_lshl_add_u64 v[190:191], v[226:227], 0, s[88:89]
	s_mov_b32 m0, s34
	s_nop 0
	global_load_lds_dwordx4 v[190:191], off
	v_lshl_add_u64 v[190:191], s[40:41], 0, v[132:133]
	s_mov_b32 m0, vcc_lo
	s_nop 0
	global_load_lds_dwordx4 v[190:191], off
	v_lshl_add_u64 v[190:191], s[40:41], 0, v[128:129]
	s_mov_b32 m0, s97
	s_nop 0
	global_load_lds_dwordx4 v[190:191], off
	v_lshl_add_u64 v[190:191], v[228:229], 0, s[88:89]
	s_mov_b32 m0, s85
	s_nop 0
	global_load_lds_dwordx4 v[190:191], off
	v_lshl_add_u64 v[190:191], v[230:231], 0, s[88:89]
	s_mov_b32 m0, s92
	s_nop 0
	global_load_lds_dwordx4 v[190:191], off
	s_waitcnt vmcnt(8)
	s_waitcnt lgkmcnt(0)
	s_setprio 1
	s_barrier
	v_mfma_f32_16x16x32_bf16 v[60:63], v[154:157], v[186:189], v[60:63]
	v_mfma_f32_16x16x32_bf16 v[56:59], v[162:165], v[186:189], v[56:59]
	v_mfma_f32_16x16x32_bf16 v[52:55], v[154:157], v[202:205], v[52:55]
	v_mfma_f32_16x16x32_bf16 v[44:47], v[162:165], v[202:205], v[44:47]
	v_mfma_f32_16x16x32_bf16 v[36:39], v[154:157], v[210:213], v[36:39]
	v_mfma_f32_16x16x32_bf16 v[28:31], v[162:165], v[210:213], v[28:31]
	v_mfma_f32_16x16x32_bf16 v[20:23], v[154:157], v[218:221], v[20:23]
	v_mfma_f32_16x16x32_bf16 v[12:15], v[162:165], v[218:221], v[12:15]
	v_mfma_f32_16x16x32_bf16 v[60:63], v[158:161], v[198:201], v[60:63]
	v_mfma_f32_16x16x32_bf16 v[56:59], v[166:169], v[198:201], v[56:59]
	v_mfma_f32_16x16x32_bf16 v[52:55], v[158:161], v[206:209], v[52:55]
	v_mfma_f32_16x16x32_bf16 v[44:47], v[166:169], v[206:209], v[44:47]
	v_mfma_f32_16x16x32_bf16 v[36:39], v[158:161], v[214:217], v[36:39]
	v_mfma_f32_16x16x32_bf16 v[28:31], v[166:169], v[214:217], v[28:31]
	v_mfma_f32_16x16x32_bf16 v[20:23], v[158:161], v[222:225], v[20:23]
	v_mfma_f32_16x16x32_bf16 v[12:15], v[166:169], v[222:225], v[12:15]
	v_mfma_f32_16x16x32_bf16 v[48:51], v[170:173], v[186:189], v[48:51]
	v_mfma_f32_16x16x32_bf16 v[40:43], v[178:181], v[186:189], v[40:43]
	v_mfma_f32_16x16x32_bf16 v[32:35], v[170:173], v[202:205], v[32:35]
	v_mfma_f32_16x16x32_bf16 v[24:27], v[178:181], v[202:205], v[24:27]
	v_mfma_f32_16x16x32_bf16 v[16:19], v[170:173], v[210:213], v[16:19]
	v_mfma_f32_16x16x32_bf16 v[8:11], v[178:181], v[210:213], v[8:11]
	v_mfma_f32_16x16x32_bf16 v[4:7], v[170:173], v[218:221], v[4:7]
	v_mfma_f32_16x16x32_bf16 v[0:3], v[178:181], v[218:221], v[0:3]
	v_mfma_f32_16x16x32_bf16 v[48:51], v[174:177], v[198:201], v[48:51]
	v_mfma_f32_16x16x32_bf16 v[40:43], v[182:185], v[198:201], v[40:43]
	v_mfma_f32_16x16x32_bf16 v[32:35], v[174:177], v[206:209], v[32:35]
	v_mfma_f32_16x16x32_bf16 v[24:27], v[182:185], v[206:209], v[24:27]
	v_mfma_f32_16x16x32_bf16 v[16:19], v[174:177], v[214:217], v[16:19]
	v_mfma_f32_16x16x32_bf16 v[8:11], v[182:185], v[214:217], v[8:11]
	v_mfma_f32_16x16x32_bf16 v[4:7], v[174:177], v[222:225], v[4:7]
	v_mfma_f32_16x16x32_bf16 v[0:3], v[182:185], v[222:225], v[0:3]
	s_barrier
	s_setprio 0
	s_movk_i32 s34, 0x100
	s_andn2_b64 vcc, exec, s[38:39]
	s_mov_b64 s[40:41], -1
	s_mov_b64 s[38:39], 0
	s_cbranch_vccz .LBB0_485

; #define PG8_STAGE(bufoff, gbase, voff) do { _Pragma("unroll") for (int _i = 0; _i < 2; ++_i) \
;         __builtin_amdgcn_global_load_lds((const unsigned*)((const char*)(gbase) + (voff)[_i]), (PG8_LAS unsigned*)(lds + (bufoff) + ldsw + _i * 8192), 16, 0, 0); } while (0)
; #define PG8_WAIT_V(n) asm volatile("s_waitcnt vmcnt(" #n ")" ::: "memory")
; #define PG8_WAIT_L(n) asm volatile("s_waitcnt lgkmcnt(" #n ")" ::: "memory")
; #define PG8_BAR __builtin_amdgcn_s_barrier()
; template <class Epi, class Sched, bool ALIGN_EPI = false, bool SP2 = false>
; __device__ __forceinline__ void gemm_phase(PG8_LAS unsigned char* lds, const Gemm g, const Sched& S, const Epi& E, int wave_in) {
;     ...
;         const char* nA = has_next ? (const char*)g.A + (size_t)(nxt.pm >> g.ash) * g.astride + (size_t)nxt.pm * tstep : cA; const char* nB = has_next ? (const char*)g.Bt + (size_t)(nxt.pm >> g.bsh) * g.bstride + (size_t)nxt.pn * tstep : cB;
;         for (int t = 0; t < nt; t += 2) {
;             const bool last = (t == nt - 2);
;             const char* a1 = cA + (size_t)(t + 1) * kstep;
;             const char* a2 = last ? nA : cA + (size_t)(t + 2) * kstep; const char* b2 = last ? nB : cB + (size_t)(t + 2) * kstep;
;             const char* a3 = a2 + kstep; const char* b3 = b2 + kstep;
;             if (last && has_next) S.a_ready(nxt);
;             if constexpr (SP2) {
;             PG8_LDB(B0, 0, 0); PG8_LDB(B1, 0, 1); PG8_SCHED; PG8_LDA(At, 0, 0); PG8_STAGE(PG8_SA(1, 1), a1 + hstep, voffA);
;             PG8_WAIT_V(8); PG8_WAIT_L(0); PG8_BAR; PG8_MMA(0, 0, At, B0); PG8_MMA(0, 1, At, B1); PG8_BAR; PG8_SCHED;
;             PG8_LDA(At, 0, 1); PG8_STAGE(PG8_SB(0, 0), b2, voffB); PG8_STAGE(PG8_SB(0, 1), b2 + hstep, voffB); PG8_STAGE(PG8_SA(0, 0), a2, voffA);
;             PG8_WAIT_V(8); PG8_WAIT_L(0); PG8_BAR; PG8_MMA(1, 0, At, B0); PG8_MMA(1, 1, At, B1); PG8_BAR; PG8_SCHED;
;             PG8_LDB(B0, 1, 0); PG8_LDB(B1, 1, 1); PG8_SCHED; PG8_LDA(At, 1, 0); PG8_STAGE(PG8_SA(0, 1), a2 + hstep, voffA);
;             PG8_WAIT_V(8); PG8_WAIT_L(0); PG8_BAR; PG8_MMA(0, 0, At, B0); PG8_MMA(0, 1, At, B1); PG8_BAR; PG8_SCHED;
;             PG8_LDA(At, 1, 1); PG8_STAGE(PG8_SB(1, 0), b3, voffB); PG8_STAGE(PG8_SB(1, 1), b3 + hstep, voffB); PG8_STAGE(PG8_SA(1, 0), a3, voffA);
;             PG8_WAIT_V(8); PG8_WAIT_L(0); PG8_BAR; PG8_MMA(1, 0, At, B0); PG8_MMA(1, 1, At, B1); PG8_BAR; PG8_SCHED;
.LBB0_589:
	s_ashr_i32 s15, s14, 31
	s_lshl_b64 s[20:21], s[14:15], 19
	s_add_u32 s20, s31, s20
	s_addc_u32 s21, s33, s21
	s_and_b64 s[26:27], s[44:45], exec
	s_cselect_b32 s15, s21, s23
	s_cselect_b32 s17, s20, s22
	s_add_u32 s34, s22, 0x100
	s_addc_u32 s44, s23, 0
	s_add_u32 s22, s24, 0x40080
	s_addc_u32 s23, s25, 0
	s_mov_b32 s45, -2
	s_add_u32 s24, s22, 0xfffc0080
	s_addc_u32 s25, s23, -1
	s_add_i32 s53, s35, 0x100
	s_cmp_eq_u32 s45, 12
	s_cselect_b32 s27, s19, s25
	s_cselect_b32 s26, s18, s24
	s_cselect_b32 s25, s15, s44
	s_cselect_b32 s24, s17, s34
	s_add_i32 s69, s90, 0x100
	v_add_u32_e32 v128, s53, v249
	v_add_u32_e32 v156, s69, v249
	ds_read_b128 v[112:115], v128
	ds_read_b128 v[120:123], v128 offset:1024
	ds_read_b128 v[124:127], v128 offset:2048
	ds_read_b128 v[128:131], v128 offset:3072
	ds_read_b128 v[136:139], v156
	ds_read_b128 v[140:143], v156 offset:1024
	ds_read_b128 v[144:147], v156 offset:2048
	ds_read_b128 v[156:159], v156 offset:3072
	v_lshl_add_u64 v[208:209], s[22:23], 0, v[206:207]
	s_add_i32 m0, s39, 0xc000
	ds_read_b128 v[160:163], v251
	ds_read_b128 v[164:167], v251 offset:1024
	ds_read_b128 v[168:171], v251 offset:2048
	ds_read_b128 v[172:175], v251 offset:3072
	ds_read_b128 v[176:179], v251 offset:4096
	ds_read_b128 v[180:183], v251 offset:5120
	ds_read_b128 v[184:187], v251 offset:6144
	ds_read_b128 v[188:191], v251 offset:7168
	global_load_lds_dwordx4 v[208:209], off
	v_lshl_add_u64 v[208:209], s[22:23], 0, v[204:205]
	s_add_i32 m0, s39, 0xe000
	s_nop 0
	global_load_lds_dwordx4 v[208:209], off
	s_waitcnt vmcnt(8)
	s_waitcnt lgkmcnt(0)
	s_setprio 1
	s_barrier
	v_mfma_f32_16x16x32_bf16 v[152:155], v[112:115], v[160:163], 0
	v_mfma_f32_16x16x32_bf16 v[148:151], v[124:127], v[160:163], 0
	v_mfma_f32_16x16x32_bf16 v[108:111], v[112:115], v[168:171], 0
	v_mfma_f32_16x16x32_bf16 v[104:107], v[124:127], v[168:171], 0
	v_mfma_f32_16x16x32_bf16 v[92:95], v[112:115], v[176:179], 0
	v_mfma_f32_16x16x32_bf16 v[88:91], v[124:127], v[176:179], 0
	v_mfma_f32_16x16x32_bf16 v[76:79], v[112:115], v[184:187], 0
	v_mfma_f32_16x16x32_bf16 v[72:75], v[124:127], v[184:187], 0
	v_mfma_f32_16x16x32_bf16 v[152:155], v[120:123], v[164:167], v[152:155]
	v_mfma_f32_16x16x32_bf16 v[148:151], v[128:131], v[164:167], v[148:151]
	v_mfma_f32_16x16x32_bf16 v[108:111], v[120:123], v[172:175], v[108:111]
	v_mfma_f32_16x16x32_bf16 v[104:107], v[128:131], v[172:175], v[104:107]
	v_mfma_f32_16x16x32_bf16 v[92:95], v[120:123], v[180:183], v[92:95]
	v_mfma_f32_16x16x32_bf16 v[88:91], v[128:131], v[180:183], v[88:91]
	v_mfma_f32_16x16x32_bf16 v[76:79], v[120:123], v[188:191], v[76:79]
	v_mfma_f32_16x16x32_bf16 v[72:75], v[128:131], v[188:191], v[72:75]
	v_mfma_f32_16x16x32_bf16 v[132:135], v[136:139], v[160:163], 0
	v_mfma_f32_16x16x32_bf16 v[116:119], v[144:147], v[160:163], 0
	v_mfma_f32_16x16x32_bf16 v[100:103], v[136:139], v[168:171], 0
	v_mfma_f32_16x16x32_bf16 v[96:99], v[144:147], v[168:171], 0
	v_mfma_f32_16x16x32_bf16 v[84:87], v[136:139], v[176:179], 0
	v_mfma_f32_16x16x32_bf16 v[80:83], v[144:147], v[176:179], 0
	v_mfma_f32_16x16x32_bf16 v[68:71], v[136:139], v[184:187], 0
	v_mfma_f32_16x16x32_bf16 v[64:67], v[144:147], v[184:187], 0
	v_mfma_f32_16x16x32_bf16 v[132:135], v[140:143], v[164:167], v[132:135]
	v_mfma_f32_16x16x32_bf16 v[116:119], v[156:159], v[164:167], v[116:119]
	v_mfma_f32_16x16x32_bf16 v[100:103], v[140:143], v[172:175], v[100:103]
	v_mfma_f32_16x16x32_bf16 v[96:99], v[156:159], v[172:175], v[96:99]
	v_mfma_f32_16x16x32_bf16 v[84:87], v[140:143], v[180:183], v[84:87]
	v_mfma_f32_16x16x32_bf16 v[80:83], v[156:159], v[180:183], v[80:83]
	v_mfma_f32_16x16x32_bf16 v[68:71], v[140:143], v[188:191], v[68:71]
	v_mfma_f32_16x16x32_bf16 v[64:67], v[156:159], v[188:191], v[64:67]
	s_barrier
	s_setprio 0
	s_add_i32 s53, s53, s38
	v_lshl_add_u64 v[208:209], s[24:25], 0, v[192:193]
	s_mov_b32 m0, s53
	ds_read_b128 v[160:163], v251 offset:16384
	ds_read_b128 v[164:167], v251 offset:17408
	ds_read_b128 v[168:171], v251 offset:18432
	ds_read_b128 v[172:175], v251 offset:19456
	ds_read_b128 v[176:179], v251 offset:20480
	ds_read_b128 v[180:183], v251 offset:21504
	ds_read_b128 v[184:187], v251 offset:22528
	ds_read_b128 v[188:191], v251 offset:23552
	global_load_lds_dwordx4 v[208:209], off
	s_add_i32 m0, s53, 0x2000
	s_add_u32 s72, s24, 0x40000
	v_lshl_add_u64 v[210:211], s[24:25], 0, v[198:199]
	s_addc_u32 s73, s25, 0
	s_add_i32 s53, s69, s38
	global_load_lds_dwordx4 v[210:211], off
	v_lshl_add_u64 v[212:213], s[72:73], 0, v[192:193]
	s_mov_b32 m0, s53
	v_lshl_add_u64 v[214:215], s[26:27], 0, v[200:201]
	global_load_lds_dwordx4 v[212:213], off
	v_lshl_add_u64 v[212:213], s[72:73], 0, v[198:199]
	s_add_i32 m0, s53, 0x2000
	s_nop 0
	global_load_lds_dwordx4 v[212:213], off
	v_lshl_add_u64 v[212:213], s[26:27], 0, v[202:203]
	s_mov_b32 m0, s39
	s_nop 0
	global_load_lds_dwordx4 v[212:213], off
	s_mov_b32 m0, s46
	s_nop 0
	global_load_lds_dwordx4 v[214:215], off
	s_waitcnt vmcnt(8)
	s_waitcnt lgkmcnt(0)
	s_setprio 1
	s_barrier
; #define PG8_STAGE(bufoff, gbase, voff) do { _Pragma("unroll") for (int _i = 0; _i < 2; ++_i) \
;         __builtin_amdgcn_global_load_lds((const unsigned*)((const char*)(gbase) + (voff)[_i]), (PG8_LAS unsigned*)(lds + (bufoff) + ldsw + _i * 8192), 16, 0, 0); } while (0)
; #define PG8_LDA(dst, b, h) do { _Pragma("unroll") for (int m = 0; m < 4; ++m) _Pragma("unroll") for (int k = 0; k < 2; ++k) dst[m][k] = *(const PG8_LAS bf16x8*)(lds + PG8_SA(b, h) + aoff + m * 2048 + k * 1024); } while (0)
; #define PG8_LDB(dst, b, h) do { _Pragma("unroll") for (int n = 0; n < 2; ++n) _Pragma("unroll") for (int k = 0; k < 2; ++k) dst[n][k] = *(const PG8_LAS bf16x8*)(lds + PG8_SB(b, h) + boff + n * 2048 + k * 1024); } while (0)
; #define PG8_MMA(ai, bj, At, Bt) do { __builtin_amdgcn_s_setprio(1); _Pragma("unroll") for (int m = 0; m < 4; ++m) _Pragma("unroll") for (int n = 0; n < 2; ++n) _Pragma("unroll") for (int k = 0; k < 2; ++k) \
;         acc[ai][bj][m][n] = __builtin_amdgcn_mfma_f32_16x16x32_bf16(Bt[n][k], At[m][k], acc[ai][bj][m][n], 0, 0, 0); __builtin_amdgcn_s_setprio(0); } while (0)
; #define PG8_BAR __builtin_amdgcn_s_barrier()
; template <class Epi, class Sched, bool ALIGN_EPI = false, bool SP2 = false>
; __device__ __forceinline__ void gemm_phase(PG8_LAS unsigned char* lds, const Gemm g, const Sched& S, const Epi& E, int wave_in) {
;     ...
;             PG8_LDB(B0, 0, 0); PG8_LDB(B1, 0, 1); PG8_SCHED; PG8_LDA(At, 0, 0); PG8_STAGE(PG8_SA(1, 1), a1 + hstep, voffA);
;             PG8_WAIT_V(8); PG8_WAIT_L(0); PG8_BAR; PG8_MMA(0, 0, At, B0); PG8_MMA(0, 1, At, B1); PG8_BAR; PG8_SCHED;
;             PG8_LDA(At, 0, 1); PG8_STAGE(PG8_SB(0, 0), b2, voffB); PG8_STAGE(PG8_SB(0, 1), b2 + hstep, voffB); PG8_STAGE(PG8_SA(0, 0), a2, voffA);
;             PG8_WAIT_V(8); PG8_WAIT_L(0); PG8_BAR; PG8_MMA(1, 0, At, B0); PG8_MMA(1, 1, At, B1); PG8_BAR; PG8_SCHED;
;             PG8_LDB(B0, 1, 0); PG8_LDB(B1, 1, 1); PG8_SCHED; PG8_LDA(At, 1, 0); PG8_STAGE(PG8_SA(0, 1), a2 + hstep, voffA);
;             PG8_WAIT_V(8); PG8_WAIT_L(0); PG8_BAR; PG8_MMA(0, 0, At, B0); PG8_MMA(0, 1, At, B1); PG8_BAR; PG8_SCHED;
;             PG8_LDA(At, 1, 1); PG8_STAGE(PG8_SB(1, 0), b3, voffB); PG8_STAGE(PG8_SB(1, 1), b3 + hstep, voffB); PG8_STAGE(PG8_SA(1, 0), a3, voffA);
;             PG8_WAIT_V(8); PG8_WAIT_L(0); PG8_BAR; PG8_MMA(1, 0, At, B0); PG8_MMA(1, 1, At, B1); PG8_BAR; PG8_SCHED;
	v_mfma_f32_16x16x32_bf16 v[60:63], v[112:115], v[160:163], 0
	v_mfma_f32_16x16x32_bf16 v[56:59], v[124:127], v[160:163], 0
	v_mfma_f32_16x16x32_bf16 v[44:47], v[112:115], v[168:171], 0
	v_mfma_f32_16x16x32_bf16 v[40:43], v[124:127], v[168:171], 0
	v_mfma_f32_16x16x32_bf16 v[28:31], v[112:115], v[176:179], 0
	v_mfma_f32_16x16x32_bf16 v[24:27], v[124:127], v[176:179], 0
	v_mfma_f32_16x16x32_bf16 v[12:15], v[112:115], v[184:187], 0
	v_mfma_f32_16x16x32_bf16 v[8:11], v[124:127], v[184:187], 0
	v_mfma_f32_16x16x32_bf16 v[60:63], v[120:123], v[164:167], v[60:63]
	v_mfma_f32_16x16x32_bf16 v[56:59], v[128:131], v[164:167], v[56:59]
	v_mfma_f32_16x16x32_bf16 v[44:47], v[120:123], v[172:175], v[44:47]
	v_mfma_f32_16x16x32_bf16 v[40:43], v[128:131], v[172:175], v[40:43]
	v_mfma_f32_16x16x32_bf16 v[28:31], v[120:123], v[180:183], v[28:31]
	v_mfma_f32_16x16x32_bf16 v[24:27], v[128:131], v[180:183], v[24:27]
	v_mfma_f32_16x16x32_bf16 v[12:15], v[120:123], v[188:191], v[12:15]
	v_mfma_f32_16x16x32_bf16 v[8:11], v[128:131], v[188:191], v[8:11]
	v_mfma_f32_16x16x32_bf16 v[52:55], v[136:139], v[160:163], 0
	v_mfma_f32_16x16x32_bf16 v[48:51], v[144:147], v[160:163], 0
	v_mfma_f32_16x16x32_bf16 v[36:39], v[136:139], v[168:171], 0
	v_mfma_f32_16x16x32_bf16 v[32:35], v[144:147], v[168:171], 0
	v_mfma_f32_16x16x32_bf16 v[20:23], v[136:139], v[176:179], 0
	v_mfma_f32_16x16x32_bf16 v[16:19], v[144:147], v[176:179], 0
	v_mfma_f32_16x16x32_bf16 v[4:7], v[136:139], v[184:187], 0
	v_mfma_f32_16x16x32_bf16 v[0:3], v[144:147], v[184:187], 0
	v_mfma_f32_16x16x32_bf16 v[52:55], v[140:143], v[164:167], v[52:55]
	v_mfma_f32_16x16x32_bf16 v[48:51], v[156:159], v[164:167], v[48:51]
	v_mfma_f32_16x16x32_bf16 v[36:39], v[140:143], v[172:175], v[36:39]
	v_mfma_f32_16x16x32_bf16 v[32:35], v[156:159], v[172:175], v[32:35]
	v_mfma_f32_16x16x32_bf16 v[20:23], v[140:143], v[180:183], v[20:23]
	v_mfma_f32_16x16x32_bf16 v[16:19], v[156:159], v[180:183], v[16:19]
	v_mfma_f32_16x16x32_bf16 v[4:7], v[140:143], v[188:191], v[4:7]
	v_mfma_f32_16x16x32_bf16 v[0:3], v[156:159], v[188:191], v[0:3]
	s_barrier
	s_setprio 0
	s_add_i32 s53, s65, 0x100
	s_add_i32 s69, s52, 0x100
	v_add_u32_e32 v128, s53, v249
	v_add_u32_e32 v156, s69, v249
	ds_read_b128 v[112:115], v128
	ds_read_b128 v[120:123], v128 offset:1024
	ds_read_b128 v[124:127], v128 offset:2048
	ds_read_b128 v[128:131], v128 offset:3072
	ds_read_b128 v[136:139], v156
	ds_read_b128 v[140:143], v156 offset:1024
	ds_read_b128 v[144:147], v156 offset:2048
	ds_read_b128 v[156:159], v156 offset:3072
	s_add_u32 s26, s26, 0x40000
	s_addc_u32 s27, s27, 0
	s_mov_b32 m0, s47
	v_lshl_add_u64 v[216:217], s[26:27], 0, v[202:203]
	ds_read_b128 v[160:163], v251 offset:32768
	ds_read_b128 v[164:167], v251 offset:33792
	ds_read_b128 v[168:171], v251 offset:34816
	ds_read_b128 v[172:175], v251 offset:35840
	ds_read_b128 v[176:179], v251 offset:36864
	ds_read_b128 v[180:183], v251 offset:37888
	ds_read_b128 v[184:187], v251 offset:38912
	ds_read_b128 v[188:191], v251 offset:39936
	global_load_lds_dwordx4 v[216:217], off
	v_lshl_add_u64 v[216:217], s[26:27], 0, v[200:201]
	s_mov_b32 m0, s60
	s_nop 0
	global_load_lds_dwordx4 v[216:217], off
	s_waitcnt vmcnt(8)
	s_waitcnt lgkmcnt(0)
	s_setprio 1
	s_barrier
	v_mfma_f32_16x16x32_bf16 v[152:155], v[112:115], v[160:163], v[152:155]
	v_mfma_f32_16x16x32_bf16 v[148:151], v[124:127], v[160:163], v[148:151]
	v_mfma_f32_16x16x32_bf16 v[108:111], v[112:115], v[168:171], v[108:111]
	v_mfma_f32_16x16x32_bf16 v[104:107], v[124:127], v[168:171], v[104:107]
	v_mfma_f32_16x16x32_bf16 v[92:95], v[112:115], v[176:179], v[92:95]
	v_mfma_f32_16x16x32_bf16 v[88:91], v[124:127], v[176:179], v[88:91]
	v_mfma_f32_16x16x32_bf16 v[76:79], v[112:115], v[184:187], v[76:79]
	v_mfma_f32_16x16x32_bf16 v[72:75], v[124:127], v[184:187], v[72:75]
	v_mfma_f32_16x16x32_bf16 v[152:155], v[120:123], v[164:167], v[152:155]
	v_mfma_f32_16x16x32_bf16 v[148:151], v[128:131], v[164:167], v[148:151]
	v_mfma_f32_16x16x32_bf16 v[108:111], v[120:123], v[172:175], v[108:111]
	v_mfma_f32_16x16x32_bf16 v[104:107], v[128:131], v[172:175], v[104:107]
	v_mfma_f32_16x16x32_bf16 v[92:95], v[120:123], v[180:183], v[92:95]
	v_mfma_f32_16x16x32_bf16 v[88:91], v[128:131], v[180:183], v[88:91]
	v_mfma_f32_16x16x32_bf16 v[76:79], v[120:123], v[188:191], v[76:79]
	v_mfma_f32_16x16x32_bf16 v[72:75], v[128:131], v[188:191], v[72:75]
	v_mfma_f32_16x16x32_bf16 v[132:135], v[136:139], v[160:163], v[132:135]
	v_mfma_f32_16x16x32_bf16 v[116:119], v[144:147], v[160:163], v[116:119]
	v_mfma_f32_16x16x32_bf16 v[100:103], v[136:139], v[168:171], v[100:103]
	v_mfma_f32_16x16x32_bf16 v[96:99], v[144:147], v[168:171], v[96:99]
	v_mfma_f32_16x16x32_bf16 v[84:87], v[136:139], v[176:179], v[84:87]
	v_mfma_f32_16x16x32_bf16 v[80:83], v[144:147], v[176:179], v[80:83]
	v_mfma_f32_16x16x32_bf16 v[68:71], v[136:139], v[184:187], v[68:71]
	v_mfma_f32_16x16x32_bf16 v[64:67], v[144:147], v[184:187], v[64:67]
	v_mfma_f32_16x16x32_bf16 v[132:135], v[140:143], v[164:167], v[132:135]
	v_mfma_f32_16x16x32_bf16 v[116:119], v[156:159], v[164:167], v[116:119]
	v_mfma_f32_16x16x32_bf16 v[100:103], v[140:143], v[172:175], v[100:103]
	v_mfma_f32_16x16x32_bf16 v[96:99], v[156:159], v[172:175], v[96:99]
	v_mfma_f32_16x16x32_bf16 v[84:87], v[140:143], v[180:183], v[84:87]
	v_mfma_f32_16x16x32_bf16 v[80:83], v[156:159], v[180:183], v[80:83]
	v_mfma_f32_16x16x32_bf16 v[68:71], v[140:143], v[188:191], v[68:71]
	v_mfma_f32_16x16x32_bf16 v[64:67], v[156:159], v[188:191], v[64:67]
	s_barrier
; #define PG8_STAGE(bufoff, gbase, voff) do { _Pragma("unroll") for (int _i = 0; _i < 2; ++_i) \
;         __builtin_amdgcn_global_load_lds((const unsigned*)((const char*)(gbase) + (voff)[_i]), (PG8_LAS unsigned*)(lds + (bufoff) + ldsw + _i * 8192), 16, 0, 0); } while (0)
; #define PG8_LDA(dst, b, h) do { _Pragma("unroll") for (int m = 0; m < 4; ++m) _Pragma("unroll") for (int k = 0; k < 2; ++k) dst[m][k] = *(const PG8_LAS bf16x8*)(lds + PG8_SA(b, h) + aoff + m * 2048 + k * 1024); } while (0)
; #define PG8_WAIT_V(n) asm volatile("s_waitcnt vmcnt(" #n ")" ::: "memory")
; #define PG8_WAIT_L(n) asm volatile("s_waitcnt lgkmcnt(" #n ")" ::: "memory")
; #define PG8_BAR __builtin_amdgcn_s_barrier()
; template <class Epi, class Sched, bool ALIGN_EPI = false, bool SP2 = false>
; __device__ __forceinline__ void gemm_phase(PG8_LAS unsigned char* lds, const Gemm g, const Sched& S, const Epi& E, int wave_in) {
;     ...
;         for (int t = 0; t < nt; t += 2) {
;             const bool last = (t == nt - 2);
;             const char* a1 = cA + (size_t)(t + 1) * kstep;
;             const char* a2 = last ? nA : cA + (size_t)(t + 2) * kstep; const char* b2 = last ? nB : cB + (size_t)(t + 2) * kstep;
;             const char* a3 = a2 + kstep; const char* b3 = b2 + kstep;
;             if (last && has_next) S.a_ready(nxt);
;             if constexpr (SP2) {
;             PG8_LDB(B0, 0, 0); PG8_LDB(B1, 0, 1); PG8_SCHED; PG8_LDA(At, 0, 0); PG8_STAGE(PG8_SA(1, 1), a1 + hstep, voffA);
;             PG8_WAIT_V(8); PG8_WAIT_L(0); PG8_BAR; PG8_MMA(0, 0, At, B0); PG8_MMA(0, 1, At, B1); PG8_BAR; PG8_SCHED;
;             PG8_LDA(At, 0, 1); PG8_STAGE(PG8_SB(0, 0), b2, voffB); PG8_STAGE(PG8_SB(0, 1), b2 + hstep, voffB); PG8_STAGE(PG8_SA(0, 0), a2, voffA);
;             PG8_WAIT_V(8); PG8_WAIT_L(0); PG8_BAR; PG8_MMA(1, 0, At, B0); PG8_MMA(1, 1, At, B1); PG8_BAR; PG8_SCHED;
;             PG8_LDB(B0, 1, 0); PG8_LDB(B1, 1, 1); PG8_SCHED; PG8_LDA(At, 1, 0); PG8_STAGE(PG8_SA(0, 1), a2 + hstep, voffA);
;             PG8_WAIT_V(8); PG8_WAIT_L(0); PG8_BAR; PG8_MMA(0, 0, At, B0); PG8_MMA(0, 1, At, B1); PG8_BAR; PG8_SCHED;
;             PG8_LDA(At, 1, 1); PG8_STAGE(PG8_SB(1, 0), b3, voffB); PG8_STAGE(PG8_SB(1, 1), b3 + hstep, voffB); PG8_STAGE(PG8_SA(1, 0), a3, voffA);
;             PG8_WAIT_V(8); PG8_WAIT_L(0); PG8_BAR; PG8_MMA(1, 0, At, B0); PG8_MMA(1, 1, At, B1); PG8_BAR; PG8_SCHED;
	s_setprio 0
	s_add_i32 s26, s53, s38
	v_lshl_add_u64 v[208:209], v[208:209], 0, s[88:89]
	s_mov_b32 m0, s26
	ds_read_b128 v[160:163], v251 offset:49152
	ds_read_b128 v[164:167], v251 offset:50176
	ds_read_b128 v[168:171], v251 offset:51200
	ds_read_b128 v[172:175], v251 offset:52224
	ds_read_b128 v[176:179], v251 offset:53248
	ds_read_b128 v[180:183], v251 offset:54272
	ds_read_b128 v[184:187], v251 offset:55296
	ds_read_b128 v[188:191], v251 offset:56320
	global_load_lds_dwordx4 v[208:209], off
	s_add_i32 m0, s26, 0x2000
	s_add_u32 s24, s24, 0x40080
	v_lshl_add_u64 v[208:209], v[210:211], 0, s[88:89]
	s_addc_u32 s25, s25, 0
	s_add_i32 s26, s69, s38
	global_load_lds_dwordx4 v[208:209], off
	v_lshl_add_u64 v[208:209], s[24:25], 0, v[192:193]
	s_mov_b32 m0, s26
	s_nop 0
	global_load_lds_dwordx4 v[208:209], off
	v_lshl_add_u64 v[208:209], s[24:25], 0, v[198:199]
	s_add_i32 m0, s26, 0x2000
	s_nop 0
	global_load_lds_dwordx4 v[208:209], off
	v_lshl_add_u64 v[208:209], v[212:213], 0, s[88:89]
	s_mov_b32 m0, s62
	s_nop 0
	global_load_lds_dwordx4 v[208:209], off
	v_lshl_add_u64 v[208:209], v[214:215], 0, s[88:89]
	s_mov_b32 m0, s63
	s_nop 0
	global_load_lds_dwordx4 v[208:209], off
	s_waitcnt vmcnt(8)
	s_waitcnt lgkmcnt(0)
	s_setprio 1
	s_barrier
	v_mfma_f32_16x16x32_bf16 v[60:63], v[112:115], v[160:163], v[60:63]
	v_mfma_f32_16x16x32_bf16 v[56:59], v[124:127], v[160:163], v[56:59]
	v_mfma_f32_16x16x32_bf16 v[44:47], v[112:115], v[168:171], v[44:47]
	v_mfma_f32_16x16x32_bf16 v[40:43], v[124:127], v[168:171], v[40:43]
	v_mfma_f32_16x16x32_bf16 v[28:31], v[112:115], v[176:179], v[28:31]
	v_mfma_f32_16x16x32_bf16 v[24:27], v[124:127], v[176:179], v[24:27]
	v_mfma_f32_16x16x32_bf16 v[12:15], v[112:115], v[184:187], v[12:15]
	v_mfma_f32_16x16x32_bf16 v[8:11], v[124:127], v[184:187], v[8:11]
	v_mfma_f32_16x16x32_bf16 v[60:63], v[120:123], v[164:167], v[60:63]
	v_mfma_f32_16x16x32_bf16 v[56:59], v[128:131], v[164:167], v[56:59]
	v_mfma_f32_16x16x32_bf16 v[44:47], v[120:123], v[172:175], v[44:47]
	v_mfma_f32_16x16x32_bf16 v[40:43], v[128:131], v[172:175], v[40:43]
	v_mfma_f32_16x16x32_bf16 v[28:31], v[120:123], v[180:183], v[28:31]
	v_mfma_f32_16x16x32_bf16 v[24:27], v[128:131], v[180:183], v[24:27]
	v_mfma_f32_16x16x32_bf16 v[12:15], v[120:123], v[188:191], v[12:15]
	v_mfma_f32_16x16x32_bf16 v[8:11], v[128:131], v[188:191], v[8:11]
	v_mfma_f32_16x16x32_bf16 v[52:55], v[136:139], v[160:163], v[52:55]
	v_mfma_f32_16x16x32_bf16 v[48:51], v[144:147], v[160:163], v[48:51]
	v_mfma_f32_16x16x32_bf16 v[36:39], v[136:139], v[168:171], v[36:39]
	v_mfma_f32_16x16x32_bf16 v[32:35], v[144:147], v[168:171], v[32:35]
	v_mfma_f32_16x16x32_bf16 v[20:23], v[136:139], v[176:179], v[20:23]
	v_mfma_f32_16x16x32_bf16 v[16:19], v[144:147], v[176:179], v[16:19]
	v_mfma_f32_16x16x32_bf16 v[4:7], v[136:139], v[184:187], v[4:7]
	v_mfma_f32_16x16x32_bf16 v[0:3], v[144:147], v[184:187], v[0:3]
	v_mfma_f32_16x16x32_bf16 v[52:55], v[140:143], v[164:167], v[52:55]
	v_mfma_f32_16x16x32_bf16 v[48:51], v[156:159], v[164:167], v[48:51]
	v_mfma_f32_16x16x32_bf16 v[36:39], v[140:143], v[172:175], v[36:39]
	v_mfma_f32_16x16x32_bf16 v[32:35], v[156:159], v[172:175], v[32:35]
	v_mfma_f32_16x16x32_bf16 v[20:23], v[140:143], v[180:183], v[20:23]
	v_mfma_f32_16x16x32_bf16 v[16:19], v[156:159], v[180:183], v[16:19]
	v_mfma_f32_16x16x32_bf16 v[4:7], v[140:143], v[188:191], v[4:7]
	v_mfma_f32_16x16x32_bf16 v[0:3], v[156:159], v[188:191], v[0:3]
	s_barrier
	s_setprio 0
	s_add_i32 s45, s45, 2
	s_add_u32 s34, s34, 0x100
	s_addc_u32 s44, s44, 0
	s_add_u32 s22, s22, 0x100
	s_addc_u32 s23, s23, 0
	s_cmp_gt_u32 s45, 13
	s_cbranch_scc1 .Lkexit_3
.LBB0_590:
	s_add_u32 s24, s22, 0xfffc0080
	s_addc_u32 s25, s23, -1
	s_add_i32 s53, s35, 0x100
	s_cmp_eq_u32 s45, 12
	s_cselect_b32 s27, s19, s25
	s_cselect_b32 s26, s18, s24
	s_cselect_b32 s25, s15, s44
	s_cselect_b32 s24, s17, s34
	s_add_i32 s69, s90, 0x100
	v_add_u32_e32 v128, s53, v249
	v_add_u32_e32 v156, s69, v249
	ds_read_b128 v[112:115], v128
	ds_read_b128 v[120:123], v128 offset:1024
	ds_read_b128 v[124:127], v128 offset:2048
	ds_read_b128 v[128:131], v128 offset:3072
	ds_read_b128 v[136:139], v156
	ds_read_b128 v[140:143], v156 offset:1024
	ds_read_b128 v[144:147], v156 offset:2048
	ds_read_b128 v[156:159], v156 offset:3072
	v_lshl_add_u64 v[208:209], s[22:23], 0, v[206:207]
	s_add_i32 m0, s39, 0xc000
	ds_read_b128 v[160:163], v251
	ds_read_b128 v[164:167], v251 offset:1024
	ds_read_b128 v[168:171], v251 offset:2048
	ds_read_b128 v[172:175], v251 offset:3072
	ds_read_b128 v[176:179], v251 offset:4096
	ds_read_b128 v[180:183], v251 offset:5120
	ds_read_b128 v[184:187], v251 offset:6144
	ds_read_b128 v[188:191], v251 offset:7168
	global_load_lds_dwordx4 v[208:209], off
	v_lshl_add_u64 v[208:209], s[22:23], 0, v[204:205]
	s_add_i32 m0, s39, 0xe000
	s_nop 0
	global_load_lds_dwordx4 v[208:209], off
	s_waitcnt vmcnt(8)
	s_waitcnt lgkmcnt(0)
	s_setprio 1
	s_barrier
; #define PG8_STAGE(bufoff, gbase, voff) do { _Pragma("unroll") for (int _i = 0; _i < 2; ++_i) \
;         __builtin_amdgcn_global_load_lds((const unsigned*)((const char*)(gbase) + (voff)[_i]), (PG8_LAS unsigned*)(lds + (bufoff) + ldsw + _i * 8192), 16, 0, 0); } while (0)
; #define PG8_LDA(dst, b, h) do { _Pragma("unroll") for (int m = 0; m < 4; ++m) _Pragma("unroll") for (int k = 0; k < 2; ++k) dst[m][k] = *(const PG8_LAS bf16x8*)(lds + PG8_SA(b, h) + aoff + m * 2048 + k * 1024); } while (0)
; #define PG8_LDB(dst, b, h) do { _Pragma("unroll") for (int n = 0; n < 2; ++n) _Pragma("unroll") for (int k = 0; k < 2; ++k) dst[n][k] = *(const PG8_LAS bf16x8*)(lds + PG8_SB(b, h) + boff + n * 2048 + k * 1024); } while (0)
; #define PG8_MMA(ai, bj, At, Bt) do { __builtin_amdgcn_s_setprio(1); _Pragma("unroll") for (int m = 0; m < 4; ++m) _Pragma("unroll") for (int n = 0; n < 2; ++n) _Pragma("unroll") for (int k = 0; k < 2; ++k) \
;         acc[ai][bj][m][n] = __builtin_amdgcn_mfma_f32_16x16x32_bf16(Bt[n][k], At[m][k], acc[ai][bj][m][n], 0, 0, 0); __builtin_amdgcn_s_setprio(0); } while (0)
; #define PG8_BAR __builtin_amdgcn_s_barrier()
; template <class Epi, class Sched, bool ALIGN_EPI = false, bool SP2 = false>
; __device__ __forceinline__ void gemm_phase(PG8_LAS unsigned char* lds, const Gemm g, const Sched& S, const Epi& E, int wave_in) {
;     ...
;             PG8_LDB(B0, 0, 0); PG8_LDB(B1, 0, 1); PG8_SCHED; PG8_LDA(At, 0, 0); PG8_STAGE(PG8_SA(1, 1), a1 + hstep, voffA);
;             PG8_WAIT_V(8); PG8_WAIT_L(0); PG8_BAR; PG8_MMA(0, 0, At, B0); PG8_MMA(0, 1, At, B1); PG8_BAR; PG8_SCHED;
;             PG8_LDA(At, 0, 1); PG8_STAGE(PG8_SB(0, 0), b2, voffB); PG8_STAGE(PG8_SB(0, 1), b2 + hstep, voffB); PG8_STAGE(PG8_SA(0, 0), a2, voffA);
;             PG8_WAIT_V(8); PG8_WAIT_L(0); PG8_BAR; PG8_MMA(1, 0, At, B0); PG8_MMA(1, 1, At, B1); PG8_BAR; PG8_SCHED;
;             PG8_LDB(B0, 1, 0); PG8_LDB(B1, 1, 1); PG8_SCHED; PG8_LDA(At, 1, 0); PG8_STAGE(PG8_SA(0, 1), a2 + hstep, voffA);
;             PG8_WAIT_V(8); PG8_WAIT_L(0); PG8_BAR; PG8_MMA(0, 0, At, B0); PG8_MMA(0, 1, At, B1); PG8_BAR; PG8_SCHED;
;             PG8_LDA(At, 1, 1); PG8_STAGE(PG8_SB(1, 0), b3, voffB); PG8_STAGE(PG8_SB(1, 1), b3 + hstep, voffB); PG8_STAGE(PG8_SA(1, 0), a3, voffA);
;             PG8_WAIT_V(8); PG8_WAIT_L(0); PG8_BAR; PG8_MMA(1, 0, At, B0); PG8_MMA(1, 1, At, B1); PG8_BAR; PG8_SCHED;
	v_mfma_f32_16x16x32_bf16 v[152:155], v[112:115], v[160:163], v[152:155]
	v_mfma_f32_16x16x32_bf16 v[148:151], v[124:127], v[160:163], v[148:151]
	v_mfma_f32_16x16x32_bf16 v[108:111], v[112:115], v[168:171], v[108:111]
	v_mfma_f32_16x16x32_bf16 v[104:107], v[124:127], v[168:171], v[104:107]
	v_mfma_f32_16x16x32_bf16 v[92:95], v[112:115], v[176:179], v[92:95]
	v_mfma_f32_16x16x32_bf16 v[88:91], v[124:127], v[176:179], v[88:91]
	v_mfma_f32_16x16x32_bf16 v[76:79], v[112:115], v[184:187], v[76:79]
	v_mfma_f32_16x16x32_bf16 v[72:75], v[124:127], v[184:187], v[72:75]
	v_mfma_f32_16x16x32_bf16 v[152:155], v[120:123], v[164:167], v[152:155]
	v_mfma_f32_16x16x32_bf16 v[148:151], v[128:131], v[164:167], v[148:151]
	v_mfma_f32_16x16x32_bf16 v[108:111], v[120:123], v[172:175], v[108:111]
	v_mfma_f32_16x16x32_bf16 v[104:107], v[128:131], v[172:175], v[104:107]
	v_mfma_f32_16x16x32_bf16 v[92:95], v[120:123], v[180:183], v[92:95]
	v_mfma_f32_16x16x32_bf16 v[88:91], v[128:131], v[180:183], v[88:91]
	v_mfma_f32_16x16x32_bf16 v[76:79], v[120:123], v[188:191], v[76:79]
	v_mfma_f32_16x16x32_bf16 v[72:75], v[128:131], v[188:191], v[72:75]
	v_mfma_f32_16x16x32_bf16 v[132:135], v[136:139], v[160:163], v[132:135]
	v_mfma_f32_16x16x32_bf16 v[116:119], v[144:147], v[160:163], v[116:119]
	v_mfma_f32_16x16x32_bf16 v[100:103], v[136:139], v[168:171], v[100:103]
	v_mfma_f32_16x16x32_bf16 v[96:99], v[144:147], v[168:171], v[96:99]
	v_mfma_f32_16x16x32_bf16 v[84:87], v[136:139], v[176:179], v[84:87]
	v_mfma_f32_16x16x32_bf16 v[80:83], v[144:147], v[176:179], v[80:83]
	v_mfma_f32_16x16x32_bf16 v[68:71], v[136:139], v[184:187], v[68:71]
	v_mfma_f32_16x16x32_bf16 v[64:67], v[144:147], v[184:187], v[64:67]
	v_mfma_f32_16x16x32_bf16 v[132:135], v[140:143], v[164:167], v[132:135]
	v_mfma_f32_16x16x32_bf16 v[116:119], v[156:159], v[164:167], v[116:119]
	v_mfma_f32_16x16x32_bf16 v[100:103], v[140:143], v[172:175], v[100:103]
	v_mfma_f32_16x16x32_bf16 v[96:99], v[156:159], v[172:175], v[96:99]
	v_mfma_f32_16x16x32_bf16 v[84:87], v[140:143], v[180:183], v[84:87]
	v_mfma_f32_16x16x32_bf16 v[80:83], v[156:159], v[180:183], v[80:83]
	v_mfma_f32_16x16x32_bf16 v[68:71], v[140:143], v[188:191], v[68:71]
	v_mfma_f32_16x16x32_bf16 v[64:67], v[156:159], v[188:191], v[64:67]
	s_barrier
	s_setprio 0
	s_add_i32 s53, s53, s38
	v_lshl_add_u64 v[208:209], s[24:25], 0, v[192:193]
	s_mov_b32 m0, s53
	ds_read_b128 v[160:163], v251 offset:16384
	ds_read_b128 v[164:167], v251 offset:17408
	ds_read_b128 v[168:171], v251 offset:18432
	ds_read_b128 v[172:175], v251 offset:19456
	ds_read_b128 v[176:179], v251 offset:20480
	ds_read_b128 v[180:183], v251 offset:21504
	ds_read_b128 v[184:187], v251 offset:22528
	ds_read_b128 v[188:191], v251 offset:23552
	global_load_lds_dwordx4 v[208:209], off
	s_add_i32 m0, s53, 0x2000
	s_add_u32 s72, s24, 0x40000
	v_lshl_add_u64 v[210:211], s[24:25], 0, v[198:199]
	s_addc_u32 s73, s25, 0
	s_add_i32 s53, s69, s38
	global_load_lds_dwordx4 v[210:211], off
	v_lshl_add_u64 v[212:213], s[72:73], 0, v[192:193]
	s_mov_b32 m0, s53
	v_lshl_add_u64 v[214:215], s[26:27], 0, v[200:201]
	global_load_lds_dwordx4 v[212:213], off
	v_lshl_add_u64 v[212:213], s[72:73], 0, v[198:199]
	s_add_i32 m0, s53, 0x2000
	s_nop 0
	global_load_lds_dwordx4 v[212:213], off
	v_lshl_add_u64 v[212:213], s[26:27], 0, v[202:203]
	s_mov_b32 m0, s39
	s_nop 0
	global_load_lds_dwordx4 v[212:213], off
	s_mov_b32 m0, s46
	s_nop 0
	global_load_lds_dwordx4 v[214:215], off
	s_waitcnt vmcnt(8)
	s_waitcnt lgkmcnt(0)
	s_setprio 1
	s_barrier
	v_mfma_f32_16x16x32_bf16 v[60:63], v[112:115], v[160:163], v[60:63]
	v_mfma_f32_16x16x32_bf16 v[56:59], v[124:127], v[160:163], v[56:59]
	v_mfma_f32_16x16x32_bf16 v[44:47], v[112:115], v[168:171], v[44:47]
	v_mfma_f32_16x16x32_bf16 v[40:43], v[124:127], v[168:171], v[40:43]
	v_mfma_f32_16x16x32_bf16 v[28:31], v[112:115], v[176:179], v[28:31]
	v_mfma_f32_16x16x32_bf16 v[24:27], v[124:127], v[176:179], v[24:27]
	v_mfma_f32_16x16x32_bf16 v[12:15], v[112:115], v[184:187], v[12:15]
	v_mfma_f32_16x16x32_bf16 v[8:11], v[124:127], v[184:187], v[8:11]
	v_mfma_f32_16x16x32_bf16 v[60:63], v[120:123], v[164:167], v[60:63]
	v_mfma_f32_16x16x32_bf16 v[56:59], v[128:131], v[164:167], v[56:59]
	v_mfma_f32_16x16x32_bf16 v[44:47], v[120:123], v[172:175], v[44:47]
	v_mfma_f32_16x16x32_bf16 v[40:43], v[128:131], v[172:175], v[40:43]
	v_mfma_f32_16x16x32_bf16 v[28:31], v[120:123], v[180:183], v[28:31]
	v_mfma_f32_16x16x32_bf16 v[24:27], v[128:131], v[180:183], v[24:27]
	v_mfma_f32_16x16x32_bf16 v[12:15], v[120:123], v[188:191], v[12:15]
	v_mfma_f32_16x16x32_bf16 v[8:11], v[128:131], v[188:191], v[8:11]
	v_mfma_f32_16x16x32_bf16 v[52:55], v[136:139], v[160:163], v[52:55]
	v_mfma_f32_16x16x32_bf16 v[48:51], v[144:147], v[160:163], v[48:51]
	v_mfma_f32_16x16x32_bf16 v[36:39], v[136:139], v[168:171], v[36:39]
	v_mfma_f32_16x16x32_bf16 v[32:35], v[144:147], v[168:171], v[32:35]
	v_mfma_f32_16x16x32_bf16 v[20:23], v[136:139], v[176:179], v[20:23]
	v_mfma_f32_16x16x32_bf16 v[16:19], v[144:147], v[176:179], v[16:19]
	v_mfma_f32_16x16x32_bf16 v[4:7], v[136:139], v[184:187], v[4:7]
	v_mfma_f32_16x16x32_bf16 v[0:3], v[144:147], v[184:187], v[0:3]
	v_mfma_f32_16x16x32_bf16 v[52:55], v[140:143], v[164:167], v[52:55]
	v_mfma_f32_16x16x32_bf16 v[48:51], v[156:159], v[164:167], v[48:51]
	v_mfma_f32_16x16x32_bf16 v[36:39], v[140:143], v[172:175], v[36:39]
	v_mfma_f32_16x16x32_bf16 v[32:35], v[156:159], v[172:175], v[32:35]
	v_mfma_f32_16x16x32_bf16 v[20:23], v[140:143], v[180:183], v[20:23]
	v_mfma_f32_16x16x32_bf16 v[16:19], v[156:159], v[180:183], v[16:19]
	v_mfma_f32_16x16x32_bf16 v[4:7], v[140:143], v[188:191], v[4:7]
	v_mfma_f32_16x16x32_bf16 v[0:3], v[156:159], v[188:191], v[0:3]
	s_barrier
; #define PG8_STAGE(bufoff, gbase, voff) do { _Pragma("unroll") for (int _i = 0; _i < 2; ++_i) \
;         __builtin_amdgcn_global_load_lds((const unsigned*)((const char*)(gbase) + (voff)[_i]), (PG8_LAS unsigned*)(lds + (bufoff) + ldsw + _i * 8192), 16, 0, 0); } while (0)
; #define PG8_LDA(dst, b, h) do { _Pragma("unroll") for (int m = 0; m < 4; ++m) _Pragma("unroll") for (int k = 0; k < 2; ++k) dst[m][k] = *(const PG8_LAS bf16x8*)(lds + PG8_SA(b, h) + aoff + m * 2048 + k * 1024); } while (0)
; #define PG8_LDB(dst, b, h) do { _Pragma("unroll") for (int n = 0; n < 2; ++n) _Pragma("unroll") for (int k = 0; k < 2; ++k) dst[n][k] = *(const PG8_LAS bf16x8*)(lds + PG8_SB(b, h) + boff + n * 2048 + k * 1024); } while (0)
; #define PG8_MMA(ai, bj, At, Bt) do { __builtin_amdgcn_s_setprio(1); _Pragma("unroll") for (int m = 0; m < 4; ++m) _Pragma("unroll") for (int n = 0; n < 2; ++n) _Pragma("unroll") for (int k = 0; k < 2; ++k) \
;         acc[ai][bj][m][n] = __builtin_amdgcn_mfma_f32_16x16x32_bf16(Bt[n][k], At[m][k], acc[ai][bj][m][n], 0, 0, 0); __builtin_amdgcn_s_setprio(0); } while (0)
; #define PG8_BAR __builtin_amdgcn_s_barrier()
; template <class Epi, class Sched, bool ALIGN_EPI = false, bool SP2 = false>
; __device__ __forceinline__ void gemm_phase(PG8_LAS unsigned char* lds, const Gemm g, const Sched& S, const Epi& E, int wave_in) {
;     ...
;             PG8_LDB(B0, 0, 0); PG8_LDB(B1, 0, 1); PG8_SCHED; PG8_LDA(At, 0, 0); PG8_STAGE(PG8_SA(1, 1), a1 + hstep, voffA);
;             PG8_WAIT_V(8); PG8_WAIT_L(0); PG8_BAR; PG8_MMA(0, 0, At, B0); PG8_MMA(0, 1, At, B1); PG8_BAR; PG8_SCHED;
;             PG8_LDA(At, 0, 1); PG8_STAGE(PG8_SB(0, 0), b2, voffB); PG8_STAGE(PG8_SB(0, 1), b2 + hstep, voffB); PG8_STAGE(PG8_SA(0, 0), a2, voffA);
;             PG8_WAIT_V(8); PG8_WAIT_L(0); PG8_BAR; PG8_MMA(1, 0, At, B0); PG8_MMA(1, 1, At, B1); PG8_BAR; PG8_SCHED;
;             PG8_LDB(B0, 1, 0); PG8_LDB(B1, 1, 1); PG8_SCHED; PG8_LDA(At, 1, 0); PG8_STAGE(PG8_SA(0, 1), a2 + hstep, voffA);
;             PG8_WAIT_V(8); PG8_WAIT_L(0); PG8_BAR; PG8_MMA(0, 0, At, B0); PG8_MMA(0, 1, At, B1); PG8_BAR; PG8_SCHED;
;             PG8_LDA(At, 1, 1); PG8_STAGE(PG8_SB(1, 0), b3, voffB); PG8_STAGE(PG8_SB(1, 1), b3 + hstep, voffB); PG8_STAGE(PG8_SA(1, 0), a3, voffA);
;             PG8_WAIT_V(8); PG8_WAIT_L(0); PG8_BAR; PG8_MMA(1, 0, At, B0); PG8_MMA(1, 1, At, B1); PG8_BAR; PG8_SCHED;
	s_setprio 0
	s_add_i32 s53, s65, 0x100
	s_add_i32 s69, s52, 0x100
	v_add_u32_e32 v128, s53, v249
	v_add_u32_e32 v156, s69, v249
	ds_read_b128 v[112:115], v128
	ds_read_b128 v[120:123], v128 offset:1024
	ds_read_b128 v[124:127], v128 offset:2048
	ds_read_b128 v[128:131], v128 offset:3072
	ds_read_b128 v[136:139], v156
	ds_read_b128 v[140:143], v156 offset:1024
	ds_read_b128 v[144:147], v156 offset:2048
	ds_read_b128 v[156:159], v156 offset:3072
	s_add_u32 s26, s26, 0x40000
	s_addc_u32 s27, s27, 0
	s_mov_b32 m0, s47
	v_lshl_add_u64 v[216:217], s[26:27], 0, v[202:203]
	ds_read_b128 v[160:163], v251 offset:32768
	ds_read_b128 v[164:167], v251 offset:33792
	ds_read_b128 v[168:171], v251 offset:34816
	ds_read_b128 v[172:175], v251 offset:35840
	ds_read_b128 v[176:179], v251 offset:36864
	ds_read_b128 v[180:183], v251 offset:37888
	ds_read_b128 v[184:187], v251 offset:38912
	ds_read_b128 v[188:191], v251 offset:39936
	global_load_lds_dwordx4 v[216:217], off
	v_lshl_add_u64 v[216:217], s[26:27], 0, v[200:201]
	s_mov_b32 m0, s60
	s_nop 0
	global_load_lds_dwordx4 v[216:217], off
	s_waitcnt vmcnt(8)
	s_waitcnt lgkmcnt(0)
	s_setprio 1
	s_barrier
	v_mfma_f32_16x16x32_bf16 v[152:155], v[112:115], v[160:163], v[152:155]
	v_mfma_f32_16x16x32_bf16 v[148:151], v[124:127], v[160:163], v[148:151]
	v_mfma_f32_16x16x32_bf16 v[108:111], v[112:115], v[168:171], v[108:111]
	v_mfma_f32_16x16x32_bf16 v[104:107], v[124:127], v[168:171], v[104:107]
	v_mfma_f32_16x16x32_bf16 v[92:95], v[112:115], v[176:179], v[92:95]
	v_mfma_f32_16x16x32_bf16 v[88:91], v[124:127], v[176:179], v[88:91]
	v_mfma_f32_16x16x32_bf16 v[76:79], v[112:115], v[184:187], v[76:79]
	v_mfma_f32_16x16x32_bf16 v[72:75], v[124:127], v[184:187], v[72:75]
	v_mfma_f32_16x16x32_bf16 v[152:155], v[120:123], v[164:167], v[152:155]
	v_mfma_f32_16x16x32_bf16 v[148:151], v[128:131], v[164:167], v[148:151]
	v_mfma_f32_16x16x32_bf16 v[108:111], v[120:123], v[172:175], v[108:111]
	v_mfma_f32_16x16x32_bf16 v[104:107], v[128:131], v[172:175], v[104:107]
	v_mfma_f32_16x16x32_bf16 v[92:95], v[120:123], v[180:183], v[92:95]
	v_mfma_f32_16x16x32_bf16 v[88:91], v[128:131], v[180:183], v[88:91]
	v_mfma_f32_16x16x32_bf16 v[76:79], v[120:123], v[188:191], v[76:79]
	v_mfma_f32_16x16x32_bf16 v[72:75], v[128:131], v[188:191], v[72:75]
	v_mfma_f32_16x16x32_bf16 v[132:135], v[136:139], v[160:163], v[132:135]
	v_mfma_f32_16x16x32_bf16 v[116:119], v[144:147], v[160:163], v[116:119]
	v_mfma_f32_16x16x32_bf16 v[100:103], v[136:139], v[168:171], v[100:103]
	v_mfma_f32_16x16x32_bf16 v[96:99], v[144:147], v[168:171], v[96:99]
	v_mfma_f32_16x16x32_bf16 v[84:87], v[136:139], v[176:179], v[84:87]
	v_mfma_f32_16x16x32_bf16 v[80:83], v[144:147], v[176:179], v[80:83]
	v_mfma_f32_16x16x32_bf16 v[68:71], v[136:139], v[184:187], v[68:71]
	v_mfma_f32_16x16x32_bf16 v[64:67], v[144:147], v[184:187], v[64:67]
	v_mfma_f32_16x16x32_bf16 v[132:135], v[140:143], v[164:167], v[132:135]
	v_mfma_f32_16x16x32_bf16 v[116:119], v[156:159], v[164:167], v[116:119]
	v_mfma_f32_16x16x32_bf16 v[100:103], v[140:143], v[172:175], v[100:103]
	v_mfma_f32_16x16x32_bf16 v[96:99], v[156:159], v[172:175], v[96:99]
	v_mfma_f32_16x16x32_bf16 v[84:87], v[140:143], v[180:183], v[84:87]
	v_mfma_f32_16x16x32_bf16 v[80:83], v[156:159], v[180:183], v[80:83]
	v_mfma_f32_16x16x32_bf16 v[68:71], v[140:143], v[188:191], v[68:71]
	v_mfma_f32_16x16x32_bf16 v[64:67], v[156:159], v[188:191], v[64:67]
	s_barrier
; #define PG8_STAGE(bufoff, gbase, voff) do { _Pragma("unroll") for (int _i = 0; _i < 2; ++_i) \
;         __builtin_amdgcn_global_load_lds((const unsigned*)((const char*)(gbase) + (voff)[_i]), (PG8_LAS unsigned*)(lds + (bufoff) + ldsw + _i * 8192), 16, 0, 0); } while (0)
; #define PG8_LDA(dst, b, h) do { _Pragma("unroll") for (int m = 0; m < 4; ++m) _Pragma("unroll") for (int k = 0; k < 2; ++k) dst[m][k] = *(const PG8_LAS bf16x8*)(lds + PG8_SA(b, h) + aoff + m * 2048 + k * 1024); } while (0)
; #define PG8_WAIT_V(n) asm volatile("s_waitcnt vmcnt(" #n ")" ::: "memory")
; #define PG8_WAIT_L(n) asm volatile("s_waitcnt lgkmcnt(" #n ")" ::: "memory")
; #define PG8_BAR __builtin_amdgcn_s_barrier()
; template <class Epi, class Sched, bool ALIGN_EPI = false, bool SP2 = false>
; __device__ __forceinline__ void gemm_phase(PG8_LAS unsigned char* lds, const Gemm g, const Sched& S, const Epi& E, int wave_in) {
;     ...
;         for (int t = 0; t < nt; t += 2) {
;             const bool last = (t == nt - 2);
;             const char* a1 = cA + (size_t)(t + 1) * kstep;
;             const char* a2 = last ? nA : cA + (size_t)(t + 2) * kstep; const char* b2 = last ? nB : cB + (size_t)(t + 2) * kstep;
;             const char* a3 = a2 + kstep; const char* b3 = b2 + kstep;
;             if (last && has_next) S.a_ready(nxt);
;             if constexpr (SP2) {
;             PG8_LDB(B0, 0, 0); PG8_LDB(B1, 0, 1); PG8_SCHED; PG8_LDA(At, 0, 0); PG8_STAGE(PG8_SA(1, 1), a1 + hstep, voffA);
;             PG8_WAIT_V(8); PG8_WAIT_L(0); PG8_BAR; PG8_MMA(0, 0, At, B0); PG8_MMA(0, 1, At, B1); PG8_BAR; PG8_SCHED;
;             PG8_LDA(At, 0, 1); PG8_STAGE(PG8_SB(0, 0), b2, voffB); PG8_STAGE(PG8_SB(0, 1), b2 + hstep, voffB); PG8_STAGE(PG8_SA(0, 0), a2, voffA);
;             PG8_WAIT_V(8); PG8_WAIT_L(0); PG8_BAR; PG8_MMA(1, 0, At, B0); PG8_MMA(1, 1, At, B1); PG8_BAR; PG8_SCHED;
;             PG8_LDB(B0, 1, 0); PG8_LDB(B1, 1, 1); PG8_SCHED; PG8_LDA(At, 1, 0); PG8_STAGE(PG8_SA(0, 1), a2 + hstep, voffA);
;             PG8_WAIT_V(8); PG8_WAIT_L(0); PG8_BAR; PG8_MMA(0, 0, At, B0); PG8_MMA(0, 1, At, B1); PG8_BAR; PG8_SCHED;
;             PG8_LDA(At, 1, 1); PG8_STAGE(PG8_SB(1, 0), b3, voffB); PG8_STAGE(PG8_SB(1, 1), b3 + hstep, voffB); PG8_STAGE(PG8_SA(1, 0), a3, voffA);
;             PG8_WAIT_V(8); PG8_WAIT_L(0); PG8_BAR; PG8_MMA(1, 0, At, B0); PG8_MMA(1, 1, At, B1); PG8_BAR; PG8_SCHED;
	s_setprio 0
	s_add_i32 s26, s53, s38
	v_lshl_add_u64 v[208:209], v[208:209], 0, s[88:89]
	s_mov_b32 m0, s26
	ds_read_b128 v[160:163], v251 offset:49152
	ds_read_b128 v[164:167], v251 offset:50176
	ds_read_b128 v[168:171], v251 offset:51200
	ds_read_b128 v[172:175], v251 offset:52224
	ds_read_b128 v[176:179], v251 offset:53248
	ds_read_b128 v[180:183], v251 offset:54272
	ds_read_b128 v[184:187], v251 offset:55296
	ds_read_b128 v[188:191], v251 offset:56320
	global_load_lds_dwordx4 v[208:209], off
	s_add_i32 m0, s26, 0x2000
	s_add_u32 s24, s24, 0x40080
	v_lshl_add_u64 v[208:209], v[210:211], 0, s[88:89]
	s_addc_u32 s25, s25, 0
	s_add_i32 s26, s69, s38
	global_load_lds_dwordx4 v[208:209], off
	v_lshl_add_u64 v[208:209], s[24:25], 0, v[192:193]
	s_mov_b32 m0, s26
	s_nop 0
	global_load_lds_dwordx4 v[208:209], off
	v_lshl_add_u64 v[208:209], s[24:25], 0, v[198:199]
	s_add_i32 m0, s26, 0x2000
	s_nop 0
	global_load_lds_dwordx4 v[208:209], off
	v_lshl_add_u64 v[208:209], v[212:213], 0, s[88:89]
	s_mov_b32 m0, s62
	s_nop 0
	global_load_lds_dwordx4 v[208:209], off
	v_lshl_add_u64 v[208:209], v[214:215], 0, s[88:89]
	s_mov_b32 m0, s63
	s_nop 0
	global_load_lds_dwordx4 v[208:209], off
	s_waitcnt vmcnt(8)
	s_waitcnt lgkmcnt(0)
	s_setprio 1
	s_barrier
	v_mfma_f32_16x16x32_bf16 v[60:63], v[112:115], v[160:163], v[60:63]
	v_mfma_f32_16x16x32_bf16 v[56:59], v[124:127], v[160:163], v[56:59]
	v_mfma_f32_16x16x32_bf16 v[44:47], v[112:115], v[168:171], v[44:47]
	v_mfma_f32_16x16x32_bf16 v[40:43], v[124:127], v[168:171], v[40:43]
	v_mfma_f32_16x16x32_bf16 v[28:31], v[112:115], v[176:179], v[28:31]
	v_mfma_f32_16x16x32_bf16 v[24:27], v[124:127], v[176:179], v[24:27]
	v_mfma_f32_16x16x32_bf16 v[12:15], v[112:115], v[184:187], v[12:15]
	v_mfma_f32_16x16x32_bf16 v[8:11], v[124:127], v[184:187], v[8:11]
	v_mfma_f32_16x16x32_bf16 v[60:63], v[120:123], v[164:167], v[60:63]
	v_mfma_f32_16x16x32_bf16 v[56:59], v[128:131], v[164:167], v[56:59]
	v_mfma_f32_16x16x32_bf16 v[44:47], v[120:123], v[172:175], v[44:47]
	v_mfma_f32_16x16x32_bf16 v[40:43], v[128:131], v[172:175], v[40:43]
	v_mfma_f32_16x16x32_bf16 v[28:31], v[120:123], v[180:183], v[28:31]
	v_mfma_f32_16x16x32_bf16 v[24:27], v[128:131], v[180:183], v[24:27]
	v_mfma_f32_16x16x32_bf16 v[12:15], v[120:123], v[188:191], v[12:15]
	v_mfma_f32_16x16x32_bf16 v[8:11], v[128:131], v[188:191], v[8:11]
	v_mfma_f32_16x16x32_bf16 v[52:55], v[136:139], v[160:163], v[52:55]
	v_mfma_f32_16x16x32_bf16 v[48:51], v[144:147], v[160:163], v[48:51]
	v_mfma_f32_16x16x32_bf16 v[36:39], v[136:139], v[168:171], v[36:39]
	v_mfma_f32_16x16x32_bf16 v[32:35], v[144:147], v[168:171], v[32:35]
	v_mfma_f32_16x16x32_bf16 v[20:23], v[136:139], v[176:179], v[20:23]
	v_mfma_f32_16x16x32_bf16 v[16:19], v[144:147], v[176:179], v[16:19]
	v_mfma_f32_16x16x32_bf16 v[4:7], v[136:139], v[184:187], v[4:7]
	v_mfma_f32_16x16x32_bf16 v[0:3], v[144:147], v[184:187], v[0:3]
	v_mfma_f32_16x16x32_bf16 v[52:55], v[140:143], v[164:167], v[52:55]
	v_mfma_f32_16x16x32_bf16 v[48:51], v[156:159], v[164:167], v[48:51]
	v_mfma_f32_16x16x32_bf16 v[36:39], v[140:143], v[172:175], v[36:39]
	v_mfma_f32_16x16x32_bf16 v[32:35], v[156:159], v[172:175], v[32:35]
	v_mfma_f32_16x16x32_bf16 v[20:23], v[140:143], v[180:183], v[20:23]
	v_mfma_f32_16x16x32_bf16 v[16:19], v[156:159], v[180:183], v[16:19]
	v_mfma_f32_16x16x32_bf16 v[4:7], v[140:143], v[188:191], v[4:7]
	v_mfma_f32_16x16x32_bf16 v[0:3], v[156:159], v[188:191], v[0:3]
	s_barrier
	s_setprio 0
	s_add_i32 s45, s45, 2
	s_add_u32 s34, s34, 0x100
	s_addc_u32 s44, s44, 0
	s_add_u32 s22, s22, 0x100
	s_addc_u32 s23, s23, 0
	s_cmp_gt_u32 s45, 13
	s_cbranch_scc0 .LBB0_590

; #define PG8_STAGE(bufoff, gbase, voff) do { _Pragma("unroll") for (int _i = 0; _i < 2; ++_i) \
;         __builtin_amdgcn_global_load_lds((const unsigned*)((const char*)(gbase) + (voff)[_i]), (PG8_LAS unsigned*)(lds + (bufoff) + ldsw + _i * 8192), 16, 0, 0); } while (0)
; #define PG8_WAIT_V(n) asm volatile("s_waitcnt vmcnt(" #n ")" ::: "memory")
; #define PG8_WAIT_L(n) asm volatile("s_waitcnt lgkmcnt(" #n ")" ::: "memory")
; #define PG8_BAR __builtin_amdgcn_s_barrier()
; template <class Epi, class Sched, bool ALIGN_EPI = false, bool SP2 = false>
; __device__ __forceinline__ void gemm_phase(PG8_LAS unsigned char* lds, const Gemm g, const Sched& S, const Epi& E, int wave_in) {
;     ...
;         const char* nA = has_next ? (const char*)g.A + (size_t)(nxt.pm >> g.ash) * g.astride + (size_t)nxt.pm * tstep : cA; const char* nB = has_next ? (const char*)g.Bt + (size_t)(nxt.pm >> g.bsh) * g.bstride + (size_t)nxt.pn * tstep : cB;
;         for (int t = 0; t < nt; t += 2) {
;             const bool last = (t == nt - 2);
;             const char* a1 = cA + (size_t)(t + 1) * kstep;
;             const char* a2 = last ? nA : cA + (size_t)(t + 2) * kstep; const char* b2 = last ? nB : cB + (size_t)(t + 2) * kstep;
;             const char* a3 = a2 + kstep; const char* b3 = b2 + kstep;
;             if (last && has_next) S.a_ready(nxt);
;             if constexpr (SP2) {
;             PG8_LDB(B0, 0, 0); PG8_LDB(B1, 0, 1); PG8_SCHED; PG8_LDA(At, 0, 0); PG8_STAGE(PG8_SA(1, 1), a1 + hstep, voffA);
;             PG8_WAIT_V(8); PG8_WAIT_L(0); PG8_BAR; PG8_MMA(0, 0, At, B0); PG8_MMA(0, 1, At, B1); PG8_BAR; PG8_SCHED;
;             PG8_LDA(At, 0, 1); PG8_STAGE(PG8_SB(0, 0), b2, voffB); PG8_STAGE(PG8_SB(0, 1), b2 + hstep, voffB); PG8_STAGE(PG8_SA(0, 0), a2, voffA);
;             PG8_WAIT_V(8); PG8_WAIT_L(0); PG8_BAR; PG8_MMA(1, 0, At, B0); PG8_MMA(1, 1, At, B1); PG8_BAR; PG8_SCHED;
;             PG8_LDB(B0, 1, 0); PG8_LDB(B1, 1, 1); PG8_SCHED; PG8_LDA(At, 1, 0); PG8_STAGE(PG8_SA(0, 1), a2 + hstep, voffA);
;             PG8_WAIT_V(8); PG8_WAIT_L(0); PG8_BAR; PG8_MMA(0, 0, At, B0); PG8_MMA(0, 1, At, B1); PG8_BAR; PG8_SCHED;
;             PG8_LDA(At, 1, 1); PG8_STAGE(PG8_SB(1, 0), b3, voffB); PG8_STAGE(PG8_SB(1, 1), b3 + hstep, voffB); PG8_STAGE(PG8_SA(1, 0), a3, voffA);
;             PG8_WAIT_V(8); PG8_WAIT_L(0); PG8_BAR; PG8_MMA(1, 0, At, B0); PG8_MMA(1, 1, At, B1); PG8_BAR; PG8_SCHED;
.LBB0_686:
	s_ashr_i32 s17, s16, 31
	s_lshl_b64 s[18:19], s[16:17], 19
	s_add_u32 s18, s8, s18
	s_addc_u32 s19, s9, s19
	s_and_b64 s[20:21], s[42:43], exec
	s_cselect_b32 s17, s19, s25
	s_cselect_b32 s69, s18, s24
	s_ashr_i32 s20, s16, 5
	s_ashr_i32 s21, s20, 31
	s_lshl_b64 s[20:21], s[20:21], 21
	s_add_u32 s26, s31, s20
	s_addc_u32 s27, s33, s21
	s_ashr_i32 s13, s12, 31
	s_lshl_b64 s[20:21], s[12:13], 19
	s_add_u32 s20, s26, s20
	s_addc_u32 s21, s27, s21
	s_and_b64 s[26:27], s[42:43], exec
	s_cselect_b32 s13, s21, s23
	s_cselect_b32 s34, s20, s22
	s_add_u32 s53, s22, 0x100
	s_addc_u32 s71, s23, 0
	s_add_u32 s22, s24, 0x40080
	s_addc_u32 s23, s25, 0
	s_mov_b32 s72, -2
	s_add_u32 s24, s22, 0xfffc0080
	s_addc_u32 s25, s23, -1
	s_add_i32 s73, s35, 0x100
	s_cmp_eq_u32 s72, 12
	s_cselect_b32 s27, s17, s25
	s_cselect_b32 s26, s69, s24
	s_cselect_b32 s25, s13, s71
	s_cselect_b32 s24, s34, s53
	s_add_i32 s76, s90, 0x100
	v_add_u32_e32 v140, s73, v212
	v_add_u32_e32 v168, s76, v212
	ds_read_b128 v[128:131], v140
	ds_read_b128 v[132:135], v140 offset:1024
	ds_read_b128 v[136:139], v140 offset:2048
	ds_read_b128 v[140:143], v140 offset:3072
	ds_read_b128 v[156:159], v168
	ds_read_b128 v[160:163], v168 offset:1024
	ds_read_b128 v[164:167], v168 offset:2048
	ds_read_b128 v[168:171], v168 offset:3072
	v_lshl_add_u64 v[194:195], s[22:23], 0, v[154:155]
	s_add_i32 m0, s39, 0xc000
	ds_read_b128 v[172:175], v227
	ds_read_b128 v[176:179], v227 offset:1024
	ds_read_b128 v[180:183], v227 offset:2048
	ds_read_b128 v[184:187], v227 offset:3072
	ds_read_b128 v[188:191], v227 offset:4096
	ds_read_b128 v[198:201], v227 offset:5120
	ds_read_b128 v[202:205], v227 offset:6144
	ds_read_b128 v[206:209], v227 offset:7168
	global_load_lds_dwordx4 v[194:195], off
	v_lshl_add_u64 v[194:195], s[22:23], 0, v[152:153]
	s_add_i32 m0, s39, 0xe000
	s_nop 0
	global_load_lds_dwordx4 v[194:195], off
	s_waitcnt vmcnt(8)
	s_waitcnt lgkmcnt(0)
	s_setprio 1
	s_barrier
	v_mfma_f32_16x16x32_bf16 v[124:127], v[128:131], v[172:175], 0
	v_mfma_f32_16x16x32_bf16 v[120:123], v[136:139], v[172:175], 0
	v_mfma_f32_16x16x32_bf16 v[108:111], v[128:131], v[180:183], 0
	v_mfma_f32_16x16x32_bf16 v[104:107], v[136:139], v[180:183], 0
	v_mfma_f32_16x16x32_bf16 v[96:99], v[128:131], v[188:191], 0
	v_mfma_f32_16x16x32_bf16 v[88:91], v[136:139], v[188:191], 0
	v_mfma_f32_16x16x32_bf16 v[80:83], v[128:131], v[202:205], 0
	v_mfma_f32_16x16x32_bf16 v[72:75], v[136:139], v[202:205], 0
	v_mfma_f32_16x16x32_bf16 v[124:127], v[132:135], v[176:179], v[124:127]
	v_mfma_f32_16x16x32_bf16 v[120:123], v[140:143], v[176:179], v[120:123]
	v_mfma_f32_16x16x32_bf16 v[108:111], v[132:135], v[184:187], v[108:111]
	v_mfma_f32_16x16x32_bf16 v[104:107], v[140:143], v[184:187], v[104:107]
	v_mfma_f32_16x16x32_bf16 v[96:99], v[132:135], v[198:201], v[96:99]
	v_mfma_f32_16x16x32_bf16 v[88:91], v[140:143], v[198:201], v[88:91]
	v_mfma_f32_16x16x32_bf16 v[80:83], v[132:135], v[206:209], v[80:83]
	v_mfma_f32_16x16x32_bf16 v[72:75], v[140:143], v[206:209], v[72:75]
	v_mfma_f32_16x16x32_bf16 v[116:119], v[156:159], v[172:175], 0
	v_mfma_f32_16x16x32_bf16 v[112:115], v[164:167], v[172:175], 0
	v_mfma_f32_16x16x32_bf16 v[100:103], v[156:159], v[180:183], 0
	v_mfma_f32_16x16x32_bf16 v[92:95], v[164:167], v[180:183], 0
	v_mfma_f32_16x16x32_bf16 v[84:87], v[156:159], v[188:191], 0
	v_mfma_f32_16x16x32_bf16 v[76:79], v[164:167], v[188:191], 0
	v_mfma_f32_16x16x32_bf16 v[68:71], v[156:159], v[202:205], 0
	v_mfma_f32_16x16x32_bf16 v[64:67], v[164:167], v[202:205], 0
	v_mfma_f32_16x16x32_bf16 v[116:119], v[160:163], v[176:179], v[116:119]
	v_mfma_f32_16x16x32_bf16 v[112:115], v[168:171], v[176:179], v[112:115]
	v_mfma_f32_16x16x32_bf16 v[100:103], v[160:163], v[184:187], v[100:103]
	v_mfma_f32_16x16x32_bf16 v[92:95], v[168:171], v[184:187], v[92:95]
	v_mfma_f32_16x16x32_bf16 v[84:87], v[160:163], v[198:201], v[84:87]
	v_mfma_f32_16x16x32_bf16 v[76:79], v[168:171], v[198:201], v[76:79]
	v_mfma_f32_16x16x32_bf16 v[68:71], v[160:163], v[206:209], v[68:71]
	v_mfma_f32_16x16x32_bf16 v[64:67], v[168:171], v[206:209], v[64:67]
	s_barrier
	s_setprio 0
	s_add_i32 s73, s73, s38
	v_lshl_add_u64 v[194:195], s[24:25], 0, v[148:149]
	s_mov_b32 m0, s73
	ds_read_b128 v[172:175], v227 offset:16384
	ds_read_b128 v[176:179], v227 offset:17408
	ds_read_b128 v[180:183], v227 offset:18432
	ds_read_b128 v[184:187], v227 offset:19456
	ds_read_b128 v[188:191], v227 offset:20480
	ds_read_b128 v[198:201], v227 offset:21504
	ds_read_b128 v[202:205], v227 offset:22528
	ds_read_b128 v[206:209], v227 offset:23552
	global_load_lds_dwordx4 v[194:195], off
	s_add_i32 m0, s73, 0x2000
	s_add_u32 s74, s24, 0x40000
	v_lshl_add_u64 v[196:197], s[24:25], 0, v[144:145]
	s_addc_u32 s75, s25, 0
	s_add_i32 s73, s76, s38
	global_load_lds_dwordx4 v[196:197], off
	v_lshl_add_u64 v[234:235], s[74:75], 0, v[148:149]
	s_mov_b32 m0, s73
	v_lshl_add_u64 v[236:237], s[26:27], 0, v[146:147]
	global_load_lds_dwordx4 v[234:235], off
	v_lshl_add_u64 v[234:235], s[74:75], 0, v[144:145]
	s_add_i32 m0, s73, 0x2000
	s_nop 0
	global_load_lds_dwordx4 v[234:235], off
	v_lshl_add_u64 v[234:235], s[26:27], 0, v[150:151]
	s_mov_b32 m0, s39
	s_nop 0
	global_load_lds_dwordx4 v[234:235], off
	s_mov_b32 m0, s44
	s_nop 0
	global_load_lds_dwordx4 v[236:237], off
	s_waitcnt vmcnt(8)
	s_waitcnt lgkmcnt(0)
	s_setprio 1
	s_barrier
; #define PG8_STAGE(bufoff, gbase, voff) do { _Pragma("unroll") for (int _i = 0; _i < 2; ++_i) \
;         __builtin_amdgcn_global_load_lds((const unsigned*)((const char*)(gbase) + (voff)[_i]), (PG8_LAS unsigned*)(lds + (bufoff) + ldsw + _i * 8192), 16, 0, 0); } while (0)
; #define PG8_LDA(dst, b, h) do { _Pragma("unroll") for (int m = 0; m < 4; ++m) _Pragma("unroll") for (int k = 0; k < 2; ++k) dst[m][k] = *(const PG8_LAS bf16x8*)(lds + PG8_SA(b, h) + aoff + m * 2048 + k * 1024); } while (0)
; #define PG8_LDB(dst, b, h) do { _Pragma("unroll") for (int n = 0; n < 2; ++n) _Pragma("unroll") for (int k = 0; k < 2; ++k) dst[n][k] = *(const PG8_LAS bf16x8*)(lds + PG8_SB(b, h) + boff + n * 2048 + k * 1024); } while (0)
; #define PG8_MMA(ai, bj, At, Bt) do { __builtin_amdgcn_s_setprio(1); _Pragma("unroll") for (int m = 0; m < 4; ++m) _Pragma("unroll") for (int n = 0; n < 2; ++n) _Pragma("unroll") for (int k = 0; k < 2; ++k) \
;         acc[ai][bj][m][n] = __builtin_amdgcn_mfma_f32_16x16x32_bf16(Bt[n][k], At[m][k], acc[ai][bj][m][n], 0, 0, 0); __builtin_amdgcn_s_setprio(0); } while (0)
; #define PG8_BAR __builtin_amdgcn_s_barrier()
; template <class Epi, class Sched, bool ALIGN_EPI = false, bool SP2 = false>
; __device__ __forceinline__ void gemm_phase(PG8_LAS unsigned char* lds, const Gemm g, const Sched& S, const Epi& E, int wave_in) {
;     ...
;             PG8_LDB(B0, 0, 0); PG8_LDB(B1, 0, 1); PG8_SCHED; PG8_LDA(At, 0, 0); PG8_STAGE(PG8_SA(1, 1), a1 + hstep, voffA);
;             PG8_WAIT_V(8); PG8_WAIT_L(0); PG8_BAR; PG8_MMA(0, 0, At, B0); PG8_MMA(0, 1, At, B1); PG8_BAR; PG8_SCHED;
;             PG8_LDA(At, 0, 1); PG8_STAGE(PG8_SB(0, 0), b2, voffB); PG8_STAGE(PG8_SB(0, 1), b2 + hstep, voffB); PG8_STAGE(PG8_SA(0, 0), a2, voffA);
;             PG8_WAIT_V(8); PG8_WAIT_L(0); PG8_BAR; PG8_MMA(1, 0, At, B0); PG8_MMA(1, 1, At, B1); PG8_BAR; PG8_SCHED;
;             PG8_LDB(B0, 1, 0); PG8_LDB(B1, 1, 1); PG8_SCHED; PG8_LDA(At, 1, 0); PG8_STAGE(PG8_SA(0, 1), a2 + hstep, voffA);
;             PG8_WAIT_V(8); PG8_WAIT_L(0); PG8_BAR; PG8_MMA(0, 0, At, B0); PG8_MMA(0, 1, At, B1); PG8_BAR; PG8_SCHED;
;             PG8_LDA(At, 1, 1); PG8_STAGE(PG8_SB(1, 0), b3, voffB); PG8_STAGE(PG8_SB(1, 1), b3 + hstep, voffB); PG8_STAGE(PG8_SA(1, 0), a3, voffA);
;             PG8_WAIT_V(8); PG8_WAIT_L(0); PG8_BAR; PG8_MMA(1, 0, At, B0); PG8_MMA(1, 1, At, B1); PG8_BAR; PG8_SCHED;
	v_mfma_f32_16x16x32_bf16 v[60:63], v[128:131], v[172:175], 0
	v_mfma_f32_16x16x32_bf16 v[56:59], v[136:139], v[172:175], 0
	v_mfma_f32_16x16x32_bf16 v[48:51], v[128:131], v[180:183], 0
	v_mfma_f32_16x16x32_bf16 v[40:43], v[136:139], v[180:183], 0
	v_mfma_f32_16x16x32_bf16 v[32:35], v[128:131], v[188:191], 0
	v_mfma_f32_16x16x32_bf16 v[24:27], v[136:139], v[188:191], 0
	v_mfma_f32_16x16x32_bf16 v[16:19], v[128:131], v[202:205], 0
	v_mfma_f32_16x16x32_bf16 v[8:11], v[136:139], v[202:205], 0
	v_mfma_f32_16x16x32_bf16 v[60:63], v[132:135], v[176:179], v[60:63]
	v_mfma_f32_16x16x32_bf16 v[56:59], v[140:143], v[176:179], v[56:59]
	v_mfma_f32_16x16x32_bf16 v[48:51], v[132:135], v[184:187], v[48:51]
	v_mfma_f32_16x16x32_bf16 v[40:43], v[140:143], v[184:187], v[40:43]
	v_mfma_f32_16x16x32_bf16 v[32:35], v[132:135], v[198:201], v[32:35]
	v_mfma_f32_16x16x32_bf16 v[24:27], v[140:143], v[198:201], v[24:27]
	v_mfma_f32_16x16x32_bf16 v[16:19], v[132:135], v[206:209], v[16:19]
	v_mfma_f32_16x16x32_bf16 v[8:11], v[140:143], v[206:209], v[8:11]
	v_mfma_f32_16x16x32_bf16 v[52:55], v[156:159], v[172:175], 0
	v_mfma_f32_16x16x32_bf16 v[44:47], v[164:167], v[172:175], 0
	v_mfma_f32_16x16x32_bf16 v[36:39], v[156:159], v[180:183], 0
	v_mfma_f32_16x16x32_bf16 v[28:31], v[164:167], v[180:183], 0
	v_mfma_f32_16x16x32_bf16 v[20:23], v[156:159], v[188:191], 0
	v_mfma_f32_16x16x32_bf16 v[12:15], v[164:167], v[188:191], 0
	v_mfma_f32_16x16x32_bf16 v[4:7], v[156:159], v[202:205], 0
	v_mfma_f32_16x16x32_bf16 v[0:3], v[164:167], v[202:205], 0
	v_mfma_f32_16x16x32_bf16 v[52:55], v[160:163], v[176:179], v[52:55]
	v_mfma_f32_16x16x32_bf16 v[44:47], v[168:171], v[176:179], v[44:47]
	v_mfma_f32_16x16x32_bf16 v[36:39], v[160:163], v[184:187], v[36:39]
	v_mfma_f32_16x16x32_bf16 v[28:31], v[168:171], v[184:187], v[28:31]
	v_mfma_f32_16x16x32_bf16 v[20:23], v[160:163], v[198:201], v[20:23]
	v_mfma_f32_16x16x32_bf16 v[12:15], v[168:171], v[198:201], v[12:15]
	v_mfma_f32_16x16x32_bf16 v[4:7], v[160:163], v[206:209], v[4:7]
	v_mfma_f32_16x16x32_bf16 v[0:3], v[168:171], v[206:209], v[0:3]
	s_barrier
	s_setprio 0
	s_add_i32 s73, s65, 0x100
	s_add_i32 s74, s52, 0x100
	v_add_u32_e32 v140, s73, v212
	v_add_u32_e32 v168, s74, v212
	ds_read_b128 v[128:131], v140
	ds_read_b128 v[132:135], v140 offset:1024
	ds_read_b128 v[136:139], v140 offset:2048
	ds_read_b128 v[140:143], v140 offset:3072
	ds_read_b128 v[156:159], v168
	ds_read_b128 v[160:163], v168 offset:1024
	ds_read_b128 v[164:167], v168 offset:2048
	ds_read_b128 v[168:171], v168 offset:3072
	s_add_u32 s26, s26, 0x40000
	s_addc_u32 s27, s27, 0
	s_mov_b32 m0, s45
	v_lshl_add_u64 v[238:239], s[26:27], 0, v[150:151]
	ds_read_b128 v[172:175], v227 offset:32768
	ds_read_b128 v[176:179], v227 offset:33792
	ds_read_b128 v[180:183], v227 offset:34816
	ds_read_b128 v[184:187], v227 offset:35840
	ds_read_b128 v[188:191], v227 offset:36864
	ds_read_b128 v[198:201], v227 offset:37888
	ds_read_b128 v[202:205], v227 offset:38912
	ds_read_b128 v[206:209], v227 offset:39936
	global_load_lds_dwordx4 v[238:239], off
	v_lshl_add_u64 v[238:239], s[26:27], 0, v[146:147]
	s_mov_b32 m0, s46
	s_nop 0
	global_load_lds_dwordx4 v[238:239], off
	s_waitcnt vmcnt(8)
	s_waitcnt lgkmcnt(0)
	s_setprio 1
	s_barrier
	v_mfma_f32_16x16x32_bf16 v[124:127], v[128:131], v[172:175], v[124:127]
	v_mfma_f32_16x16x32_bf16 v[120:123], v[136:139], v[172:175], v[120:123]
	v_mfma_f32_16x16x32_bf16 v[108:111], v[128:131], v[180:183], v[108:111]
	v_mfma_f32_16x16x32_bf16 v[104:107], v[136:139], v[180:183], v[104:107]
	v_mfma_f32_16x16x32_bf16 v[96:99], v[128:131], v[188:191], v[96:99]
	v_mfma_f32_16x16x32_bf16 v[88:91], v[136:139], v[188:191], v[88:91]
	v_mfma_f32_16x16x32_bf16 v[80:83], v[128:131], v[202:205], v[80:83]
	v_mfma_f32_16x16x32_bf16 v[72:75], v[136:139], v[202:205], v[72:75]
	v_mfma_f32_16x16x32_bf16 v[124:127], v[132:135], v[176:179], v[124:127]
	v_mfma_f32_16x16x32_bf16 v[120:123], v[140:143], v[176:179], v[120:123]
	v_mfma_f32_16x16x32_bf16 v[108:111], v[132:135], v[184:187], v[108:111]
	v_mfma_f32_16x16x32_bf16 v[104:107], v[140:143], v[184:187], v[104:107]
	v_mfma_f32_16x16x32_bf16 v[96:99], v[132:135], v[198:201], v[96:99]
	v_mfma_f32_16x16x32_bf16 v[88:91], v[140:143], v[198:201], v[88:91]
	v_mfma_f32_16x16x32_bf16 v[80:83], v[132:135], v[206:209], v[80:83]
	v_mfma_f32_16x16x32_bf16 v[72:75], v[140:143], v[206:209], v[72:75]
	v_mfma_f32_16x16x32_bf16 v[116:119], v[156:159], v[172:175], v[116:119]
	v_mfma_f32_16x16x32_bf16 v[112:115], v[164:167], v[172:175], v[112:115]
	v_mfma_f32_16x16x32_bf16 v[100:103], v[156:159], v[180:183], v[100:103]
	v_mfma_f32_16x16x32_bf16 v[92:95], v[164:167], v[180:183], v[92:95]
	v_mfma_f32_16x16x32_bf16 v[84:87], v[156:159], v[188:191], v[84:87]
	v_mfma_f32_16x16x32_bf16 v[76:79], v[164:167], v[188:191], v[76:79]
	v_mfma_f32_16x16x32_bf16 v[68:71], v[156:159], v[202:205], v[68:71]
	v_mfma_f32_16x16x32_bf16 v[64:67], v[164:167], v[202:205], v[64:67]
	v_mfma_f32_16x16x32_bf16 v[116:119], v[160:163], v[176:179], v[116:119]
	v_mfma_f32_16x16x32_bf16 v[112:115], v[168:171], v[176:179], v[112:115]
	v_mfma_f32_16x16x32_bf16 v[100:103], v[160:163], v[184:187], v[100:103]
	v_mfma_f32_16x16x32_bf16 v[92:95], v[168:171], v[184:187], v[92:95]
	v_mfma_f32_16x16x32_bf16 v[84:87], v[160:163], v[198:201], v[84:87]
	v_mfma_f32_16x16x32_bf16 v[76:79], v[168:171], v[198:201], v[76:79]
	v_mfma_f32_16x16x32_bf16 v[68:71], v[160:163], v[206:209], v[68:71]
	v_mfma_f32_16x16x32_bf16 v[64:67], v[168:171], v[206:209], v[64:67]
	s_barrier
; #define PG8_STAGE(bufoff, gbase, voff) do { _Pragma("unroll") for (int _i = 0; _i < 2; ++_i) \
;         __builtin_amdgcn_global_load_lds((const unsigned*)((const char*)(gbase) + (voff)[_i]), (PG8_LAS unsigned*)(lds + (bufoff) + ldsw + _i * 8192), 16, 0, 0); } while (0)
; #define PG8_LDA(dst, b, h) do { _Pragma("unroll") for (int m = 0; m < 4; ++m) _Pragma("unroll") for (int k = 0; k < 2; ++k) dst[m][k] = *(const PG8_LAS bf16x8*)(lds + PG8_SA(b, h) + aoff + m * 2048 + k * 1024); } while (0)
; #define PG8_WAIT_V(n) asm volatile("s_waitcnt vmcnt(" #n ")" ::: "memory")
; #define PG8_WAIT_L(n) asm volatile("s_waitcnt lgkmcnt(" #n ")" ::: "memory")
; #define PG8_BAR __builtin_amdgcn_s_barrier()
; template <class Epi, class Sched, bool ALIGN_EPI = false, bool SP2 = false>
; __device__ __forceinline__ void gemm_phase(PG8_LAS unsigned char* lds, const Gemm g, const Sched& S, const Epi& E, int wave_in) {
;     ...
;         for (int t = 0; t < nt; t += 2) {
;             const bool last = (t == nt - 2);
;             const char* a1 = cA + (size_t)(t + 1) * kstep;
;             const char* a2 = last ? nA : cA + (size_t)(t + 2) * kstep; const char* b2 = last ? nB : cB + (size_t)(t + 2) * kstep;
;             const char* a3 = a2 + kstep; const char* b3 = b2 + kstep;
;             if (last && has_next) S.a_ready(nxt);
;             if constexpr (SP2) {
;             PG8_LDB(B0, 0, 0); PG8_LDB(B1, 0, 1); PG8_SCHED; PG8_LDA(At, 0, 0); PG8_STAGE(PG8_SA(1, 1), a1 + hstep, voffA);
;             PG8_WAIT_V(8); PG8_WAIT_L(0); PG8_BAR; PG8_MMA(0, 0, At, B0); PG8_MMA(0, 1, At, B1); PG8_BAR; PG8_SCHED;
;             PG8_LDA(At, 0, 1); PG8_STAGE(PG8_SB(0, 0), b2, voffB); PG8_STAGE(PG8_SB(0, 1), b2 + hstep, voffB); PG8_STAGE(PG8_SA(0, 0), a2, voffA);
;             PG8_WAIT_V(8); PG8_WAIT_L(0); PG8_BAR; PG8_MMA(1, 0, At, B0); PG8_MMA(1, 1, At, B1); PG8_BAR; PG8_SCHED;
;             PG8_LDB(B0, 1, 0); PG8_LDB(B1, 1, 1); PG8_SCHED; PG8_LDA(At, 1, 0); PG8_STAGE(PG8_SA(0, 1), a2 + hstep, voffA);
;             PG8_WAIT_V(8); PG8_WAIT_L(0); PG8_BAR; PG8_MMA(0, 0, At, B0); PG8_MMA(0, 1, At, B1); PG8_BAR; PG8_SCHED;
;             PG8_LDA(At, 1, 1); PG8_STAGE(PG8_SB(1, 0), b3, voffB); PG8_STAGE(PG8_SB(1, 1), b3 + hstep, voffB); PG8_STAGE(PG8_SA(1, 0), a3, voffA);
;             PG8_WAIT_V(8); PG8_WAIT_L(0); PG8_BAR; PG8_MMA(1, 0, At, B0); PG8_MMA(1, 1, At, B1); PG8_BAR; PG8_SCHED;
	s_setprio 0
	s_add_i32 s26, s73, s38
	v_lshl_add_u64 v[194:195], v[194:195], 0, s[88:89]
	s_mov_b32 m0, s26
	ds_read_b128 v[172:175], v227 offset:49152
	ds_read_b128 v[176:179], v227 offset:50176
	ds_read_b128 v[180:183], v227 offset:51200
	ds_read_b128 v[184:187], v227 offset:52224
	ds_read_b128 v[188:191], v227 offset:53248
	ds_read_b128 v[198:201], v227 offset:54272
	ds_read_b128 v[202:205], v227 offset:55296
	ds_read_b128 v[206:209], v227 offset:56320
	global_load_lds_dwordx4 v[194:195], off
	s_add_i32 m0, s26, 0x2000
	s_add_u32 s24, s24, 0x40080
	v_lshl_add_u64 v[194:195], v[196:197], 0, s[88:89]
	s_addc_u32 s25, s25, 0
	s_add_i32 s26, s74, s38
	global_load_lds_dwordx4 v[194:195], off
	v_lshl_add_u64 v[194:195], s[24:25], 0, v[148:149]
	s_mov_b32 m0, s26
	s_nop 0
	global_load_lds_dwordx4 v[194:195], off
	v_lshl_add_u64 v[194:195], s[24:25], 0, v[144:145]
	s_add_i32 m0, s26, 0x2000
	s_nop 0
	global_load_lds_dwordx4 v[194:195], off
	v_lshl_add_u64 v[194:195], v[234:235], 0, s[88:89]
	s_mov_b32 m0, s61
	s_nop 0
	global_load_lds_dwordx4 v[194:195], off
	v_lshl_add_u64 v[194:195], v[236:237], 0, s[88:89]
	s_mov_b32 m0, s62
	s_nop 0
	global_load_lds_dwordx4 v[194:195], off
	s_waitcnt vmcnt(8)
	s_waitcnt lgkmcnt(0)
	s_setprio 1
	s_barrier
	v_mfma_f32_16x16x32_bf16 v[60:63], v[128:131], v[172:175], v[60:63]
	v_mfma_f32_16x16x32_bf16 v[56:59], v[136:139], v[172:175], v[56:59]
	v_mfma_f32_16x16x32_bf16 v[48:51], v[128:131], v[180:183], v[48:51]
	v_mfma_f32_16x16x32_bf16 v[40:43], v[136:139], v[180:183], v[40:43]
	v_mfma_f32_16x16x32_bf16 v[32:35], v[128:131], v[188:191], v[32:35]
	v_mfma_f32_16x16x32_bf16 v[24:27], v[136:139], v[188:191], v[24:27]
	v_mfma_f32_16x16x32_bf16 v[16:19], v[128:131], v[202:205], v[16:19]
	v_mfma_f32_16x16x32_bf16 v[8:11], v[136:139], v[202:205], v[8:11]
	v_mfma_f32_16x16x32_bf16 v[60:63], v[132:135], v[176:179], v[60:63]
	v_mfma_f32_16x16x32_bf16 v[56:59], v[140:143], v[176:179], v[56:59]
	v_mfma_f32_16x16x32_bf16 v[48:51], v[132:135], v[184:187], v[48:51]
	v_mfma_f32_16x16x32_bf16 v[40:43], v[140:143], v[184:187], v[40:43]
	v_mfma_f32_16x16x32_bf16 v[32:35], v[132:135], v[198:201], v[32:35]
	v_mfma_f32_16x16x32_bf16 v[24:27], v[140:143], v[198:201], v[24:27]
	v_mfma_f32_16x16x32_bf16 v[16:19], v[132:135], v[206:209], v[16:19]
	v_mfma_f32_16x16x32_bf16 v[8:11], v[140:143], v[206:209], v[8:11]
	v_mfma_f32_16x16x32_bf16 v[52:55], v[156:159], v[172:175], v[52:55]
	v_mfma_f32_16x16x32_bf16 v[44:47], v[164:167], v[172:175], v[44:47]
	v_mfma_f32_16x16x32_bf16 v[36:39], v[156:159], v[180:183], v[36:39]
	v_mfma_f32_16x16x32_bf16 v[28:31], v[164:167], v[180:183], v[28:31]
	v_mfma_f32_16x16x32_bf16 v[20:23], v[156:159], v[188:191], v[20:23]
	v_mfma_f32_16x16x32_bf16 v[12:15], v[164:167], v[188:191], v[12:15]
	v_mfma_f32_16x16x32_bf16 v[4:7], v[156:159], v[202:205], v[4:7]
	v_mfma_f32_16x16x32_bf16 v[0:3], v[164:167], v[202:205], v[0:3]
	v_mfma_f32_16x16x32_bf16 v[52:55], v[160:163], v[176:179], v[52:55]
	v_mfma_f32_16x16x32_bf16 v[44:47], v[168:171], v[176:179], v[44:47]
	v_mfma_f32_16x16x32_bf16 v[36:39], v[160:163], v[184:187], v[36:39]
	v_mfma_f32_16x16x32_bf16 v[28:31], v[168:171], v[184:187], v[28:31]
	v_mfma_f32_16x16x32_bf16 v[20:23], v[160:163], v[198:201], v[20:23]
	v_mfma_f32_16x16x32_bf16 v[12:15], v[168:171], v[198:201], v[12:15]
	v_mfma_f32_16x16x32_bf16 v[4:7], v[160:163], v[206:209], v[4:7]
	v_mfma_f32_16x16x32_bf16 v[0:3], v[168:171], v[206:209], v[0:3]
	s_barrier
	s_setprio 0
	s_add_i32 s72, s72, 2
	s_add_u32 s53, s53, 0x100
	s_addc_u32 s71, s71, 0
	s_add_u32 s22, s22, 0x100
	s_addc_u32 s23, s23, 0
	s_cmp_gt_u32 s72, 13
	s_cbranch_scc1 .Lkexit_4
.LBB0_687:
	s_add_u32 s24, s22, 0xfffc0080
	s_addc_u32 s25, s23, -1
	s_add_i32 s73, s35, 0x100
	s_cmp_eq_u32 s72, 12
	s_cselect_b32 s27, s17, s25
	s_cselect_b32 s26, s69, s24
	s_cselect_b32 s25, s13, s71
	s_cselect_b32 s24, s34, s53
	s_add_i32 s76, s90, 0x100
	v_add_u32_e32 v140, s73, v212
	v_add_u32_e32 v168, s76, v212
	ds_read_b128 v[128:131], v140
	ds_read_b128 v[132:135], v140 offset:1024
	ds_read_b128 v[136:139], v140 offset:2048
	ds_read_b128 v[140:143], v140 offset:3072
	ds_read_b128 v[156:159], v168
	ds_read_b128 v[160:163], v168 offset:1024
	ds_read_b128 v[164:167], v168 offset:2048
	ds_read_b128 v[168:171], v168 offset:3072
	v_lshl_add_u64 v[194:195], s[22:23], 0, v[154:155]
	s_add_i32 m0, s39, 0xc000
	ds_read_b128 v[172:175], v227
	ds_read_b128 v[176:179], v227 offset:1024
	ds_read_b128 v[180:183], v227 offset:2048
	ds_read_b128 v[184:187], v227 offset:3072
	ds_read_b128 v[188:191], v227 offset:4096
	ds_read_b128 v[198:201], v227 offset:5120
	ds_read_b128 v[202:205], v227 offset:6144
	ds_read_b128 v[206:209], v227 offset:7168
	global_load_lds_dwordx4 v[194:195], off
	v_lshl_add_u64 v[194:195], s[22:23], 0, v[152:153]
	s_add_i32 m0, s39, 0xe000
	s_nop 0
	global_load_lds_dwordx4 v[194:195], off
	s_waitcnt vmcnt(8)
	s_waitcnt lgkmcnt(0)
	s_setprio 1
	s_barrier
; #define PG8_STAGE(bufoff, gbase, voff) do { _Pragma("unroll") for (int _i = 0; _i < 2; ++_i) \
;         __builtin_amdgcn_global_load_lds((const unsigned*)((const char*)(gbase) + (voff)[_i]), (PG8_LAS unsigned*)(lds + (bufoff) + ldsw + _i * 8192), 16, 0, 0); } while (0)
; #define PG8_LDA(dst, b, h) do { _Pragma("unroll") for (int m = 0; m < 4; ++m) _Pragma("unroll") for (int k = 0; k < 2; ++k) dst[m][k] = *(const PG8_LAS bf16x8*)(lds + PG8_SA(b, h) + aoff + m * 2048 + k * 1024); } while (0)
; #define PG8_LDB(dst, b, h) do { _Pragma("unroll") for (int n = 0; n < 2; ++n) _Pragma("unroll") for (int k = 0; k < 2; ++k) dst[n][k] = *(const PG8_LAS bf16x8*)(lds + PG8_SB(b, h) + boff + n * 2048 + k * 1024); } while (0)
; #define PG8_MMA(ai, bj, At, Bt) do { __builtin_amdgcn_s_setprio(1); _Pragma("unroll") for (int m = 0; m < 4; ++m) _Pragma("unroll") for (int n = 0; n < 2; ++n) _Pragma("unroll") for (int k = 0; k < 2; ++k) \
;         acc[ai][bj][m][n] = __builtin_amdgcn_mfma_f32_16x16x32_bf16(Bt[n][k], At[m][k], acc[ai][bj][m][n], 0, 0, 0); __builtin_amdgcn_s_setprio(0); } while (0)
; #define PG8_BAR __builtin_amdgcn_s_barrier()
; template <class Epi, class Sched, bool ALIGN_EPI = false, bool SP2 = false>
; __device__ __forceinline__ void gemm_phase(PG8_LAS unsigned char* lds, const Gemm g, const Sched& S, const Epi& E, int wave_in) {
;     ...
;             PG8_LDB(B0, 0, 0); PG8_LDB(B1, 0, 1); PG8_SCHED; PG8_LDA(At, 0, 0); PG8_STAGE(PG8_SA(1, 1), a1 + hstep, voffA);
;             PG8_WAIT_V(8); PG8_WAIT_L(0); PG8_BAR; PG8_MMA(0, 0, At, B0); PG8_MMA(0, 1, At, B1); PG8_BAR; PG8_SCHED;
;             PG8_LDA(At, 0, 1); PG8_STAGE(PG8_SB(0, 0), b2, voffB); PG8_STAGE(PG8_SB(0, 1), b2 + hstep, voffB); PG8_STAGE(PG8_SA(0, 0), a2, voffA);
;             PG8_WAIT_V(8); PG8_WAIT_L(0); PG8_BAR; PG8_MMA(1, 0, At, B0); PG8_MMA(1, 1, At, B1); PG8_BAR; PG8_SCHED;
;             PG8_LDB(B0, 1, 0); PG8_LDB(B1, 1, 1); PG8_SCHED; PG8_LDA(At, 1, 0); PG8_STAGE(PG8_SA(0, 1), a2 + hstep, voffA);
;             PG8_WAIT_V(8); PG8_WAIT_L(0); PG8_BAR; PG8_MMA(0, 0, At, B0); PG8_MMA(0, 1, At, B1); PG8_BAR; PG8_SCHED;
;             PG8_LDA(At, 1, 1); PG8_STAGE(PG8_SB(1, 0), b3, voffB); PG8_STAGE(PG8_SB(1, 1), b3 + hstep, voffB); PG8_STAGE(PG8_SA(1, 0), a3, voffA);
;             PG8_WAIT_V(8); PG8_WAIT_L(0); PG8_BAR; PG8_MMA(1, 0, At, B0); PG8_MMA(1, 1, At, B1); PG8_BAR; PG8_SCHED;
	v_mfma_f32_16x16x32_bf16 v[124:127], v[128:131], v[172:175], v[124:127]
	v_mfma_f32_16x16x32_bf16 v[120:123], v[136:139], v[172:175], v[120:123]
	v_mfma_f32_16x16x32_bf16 v[108:111], v[128:131], v[180:183], v[108:111]
	v_mfma_f32_16x16x32_bf16 v[104:107], v[136:139], v[180:183], v[104:107]
	v_mfma_f32_16x16x32_bf16 v[96:99], v[128:131], v[188:191], v[96:99]
	v_mfma_f32_16x16x32_bf16 v[88:91], v[136:139], v[188:191], v[88:91]
	v_mfma_f32_16x16x32_bf16 v[80:83], v[128:131], v[202:205], v[80:83]
	v_mfma_f32_16x16x32_bf16 v[72:75], v[136:139], v[202:205], v[72:75]
	v_mfma_f32_16x16x32_bf16 v[124:127], v[132:135], v[176:179], v[124:127]
	v_mfma_f32_16x16x32_bf16 v[120:123], v[140:143], v[176:179], v[120:123]
	v_mfma_f32_16x16x32_bf16 v[108:111], v[132:135], v[184:187], v[108:111]
	v_mfma_f32_16x16x32_bf16 v[104:107], v[140:143], v[184:187], v[104:107]
	v_mfma_f32_16x16x32_bf16 v[96:99], v[132:135], v[198:201], v[96:99]
	v_mfma_f32_16x16x32_bf16 v[88:91], v[140:143], v[198:201], v[88:91]
	v_mfma_f32_16x16x32_bf16 v[80:83], v[132:135], v[206:209], v[80:83]
	v_mfma_f32_16x16x32_bf16 v[72:75], v[140:143], v[206:209], v[72:75]
	v_mfma_f32_16x16x32_bf16 v[116:119], v[156:159], v[172:175], v[116:119]
	v_mfma_f32_16x16x32_bf16 v[112:115], v[164:167], v[172:175], v[112:115]
	v_mfma_f32_16x16x32_bf16 v[100:103], v[156:159], v[180:183], v[100:103]
	v_mfma_f32_16x16x32_bf16 v[92:95], v[164:167], v[180:183], v[92:95]
	v_mfma_f32_16x16x32_bf16 v[84:87], v[156:159], v[188:191], v[84:87]
	v_mfma_f32_16x16x32_bf16 v[76:79], v[164:167], v[188:191], v[76:79]
	v_mfma_f32_16x16x32_bf16 v[68:71], v[156:159], v[202:205], v[68:71]
	v_mfma_f32_16x16x32_bf16 v[64:67], v[164:167], v[202:205], v[64:67]
	v_mfma_f32_16x16x32_bf16 v[116:119], v[160:163], v[176:179], v[116:119]
	v_mfma_f32_16x16x32_bf16 v[112:115], v[168:171], v[176:179], v[112:115]
	v_mfma_f32_16x16x32_bf16 v[100:103], v[160:163], v[184:187], v[100:103]
	v_mfma_f32_16x16x32_bf16 v[92:95], v[168:171], v[184:187], v[92:95]
	v_mfma_f32_16x16x32_bf16 v[84:87], v[160:163], v[198:201], v[84:87]
	v_mfma_f32_16x16x32_bf16 v[76:79], v[168:171], v[198:201], v[76:79]
	v_mfma_f32_16x16x32_bf16 v[68:71], v[160:163], v[206:209], v[68:71]
	v_mfma_f32_16x16x32_bf16 v[64:67], v[168:171], v[206:209], v[64:67]
	s_barrier
	s_setprio 0
	s_add_i32 s73, s73, s38
	v_lshl_add_u64 v[194:195], s[24:25], 0, v[148:149]
	s_mov_b32 m0, s73
	ds_read_b128 v[172:175], v227 offset:16384
	ds_read_b128 v[176:179], v227 offset:17408
	ds_read_b128 v[180:183], v227 offset:18432
	ds_read_b128 v[184:187], v227 offset:19456
	ds_read_b128 v[188:191], v227 offset:20480
	ds_read_b128 v[198:201], v227 offset:21504
	ds_read_b128 v[202:205], v227 offset:22528
	ds_read_b128 v[206:209], v227 offset:23552
	global_load_lds_dwordx4 v[194:195], off
	s_add_i32 m0, s73, 0x2000
	s_add_u32 s74, s24, 0x40000
	v_lshl_add_u64 v[196:197], s[24:25], 0, v[144:145]
	s_addc_u32 s75, s25, 0
	s_add_i32 s73, s76, s38
	global_load_lds_dwordx4 v[196:197], off
	v_lshl_add_u64 v[234:235], s[74:75], 0, v[148:149]
	s_mov_b32 m0, s73
	v_lshl_add_u64 v[236:237], s[26:27], 0, v[146:147]
	global_load_lds_dwordx4 v[234:235], off
	v_lshl_add_u64 v[234:235], s[74:75], 0, v[144:145]
	s_add_i32 m0, s73, 0x2000
	s_nop 0
	global_load_lds_dwordx4 v[234:235], off
	v_lshl_add_u64 v[234:235], s[26:27], 0, v[150:151]
	s_mov_b32 m0, s39
	s_nop 0
	global_load_lds_dwordx4 v[234:235], off
	s_mov_b32 m0, s44
	s_nop 0
	global_load_lds_dwordx4 v[236:237], off
	s_waitcnt vmcnt(8)
	s_waitcnt lgkmcnt(0)
	s_setprio 1
	s_barrier
	v_mfma_f32_16x16x32_bf16 v[60:63], v[128:131], v[172:175], v[60:63]
	v_mfma_f32_16x16x32_bf16 v[56:59], v[136:139], v[172:175], v[56:59]
	v_mfma_f32_16x16x32_bf16 v[48:51], v[128:131], v[180:183], v[48:51]
	v_mfma_f32_16x16x32_bf16 v[40:43], v[136:139], v[180:183], v[40:43]
	v_mfma_f32_16x16x32_bf16 v[32:35], v[128:131], v[188:191], v[32:35]
	v_mfma_f32_16x16x32_bf16 v[24:27], v[136:139], v[188:191], v[24:27]
	v_mfma_f32_16x16x32_bf16 v[16:19], v[128:131], v[202:205], v[16:19]
	v_mfma_f32_16x16x32_bf16 v[8:11], v[136:139], v[202:205], v[8:11]
	v_mfma_f32_16x16x32_bf16 v[60:63], v[132:135], v[176:179], v[60:63]
	v_mfma_f32_16x16x32_bf16 v[56:59], v[140:143], v[176:179], v[56:59]
	v_mfma_f32_16x16x32_bf16 v[48:51], v[132:135], v[184:187], v[48:51]
	v_mfma_f32_16x16x32_bf16 v[40:43], v[140:143], v[184:187], v[40:43]
	v_mfma_f32_16x16x32_bf16 v[32:35], v[132:135], v[198:201], v[32:35]
	v_mfma_f32_16x16x32_bf16 v[24:27], v[140:143], v[198:201], v[24:27]
	v_mfma_f32_16x16x32_bf16 v[16:19], v[132:135], v[206:209], v[16:19]
	v_mfma_f32_16x16x32_bf16 v[8:11], v[140:143], v[206:209], v[8:11]
	v_mfma_f32_16x16x32_bf16 v[52:55], v[156:159], v[172:175], v[52:55]
	v_mfma_f32_16x16x32_bf16 v[44:47], v[164:167], v[172:175], v[44:47]
	v_mfma_f32_16x16x32_bf16 v[36:39], v[156:159], v[180:183], v[36:39]
	v_mfma_f32_16x16x32_bf16 v[28:31], v[164:167], v[180:183], v[28:31]
	v_mfma_f32_16x16x32_bf16 v[20:23], v[156:159], v[188:191], v[20:23]
	v_mfma_f32_16x16x32_bf16 v[12:15], v[164:167], v[188:191], v[12:15]
	v_mfma_f32_16x16x32_bf16 v[4:7], v[156:159], v[202:205], v[4:7]
	v_mfma_f32_16x16x32_bf16 v[0:3], v[164:167], v[202:205], v[0:3]
	v_mfma_f32_16x16x32_bf16 v[52:55], v[160:163], v[176:179], v[52:55]
	v_mfma_f32_16x16x32_bf16 v[44:47], v[168:171], v[176:179], v[44:47]
	v_mfma_f32_16x16x32_bf16 v[36:39], v[160:163], v[184:187], v[36:39]
	v_mfma_f32_16x16x32_bf16 v[28:31], v[168:171], v[184:187], v[28:31]
	v_mfma_f32_16x16x32_bf16 v[20:23], v[160:163], v[198:201], v[20:23]
	v_mfma_f32_16x16x32_bf16 v[12:15], v[168:171], v[198:201], v[12:15]
	v_mfma_f32_16x16x32_bf16 v[4:7], v[160:163], v[206:209], v[4:7]
	v_mfma_f32_16x16x32_bf16 v[0:3], v[168:171], v[206:209], v[0:3]
	s_barrier
; #define PG8_STAGE(bufoff, gbase, voff) do { _Pragma("unroll") for (int _i = 0; _i < 2; ++_i) \
;         __builtin_amdgcn_global_load_lds((const unsigned*)((const char*)(gbase) + (voff)[_i]), (PG8_LAS unsigned*)(lds + (bufoff) + ldsw + _i * 8192), 16, 0, 0); } while (0)
; #define PG8_LDA(dst, b, h) do { _Pragma("unroll") for (int m = 0; m < 4; ++m) _Pragma("unroll") for (int k = 0; k < 2; ++k) dst[m][k] = *(const PG8_LAS bf16x8*)(lds + PG8_SA(b, h) + aoff + m * 2048 + k * 1024); } while (0)
; #define PG8_LDB(dst, b, h) do { _Pragma("unroll") for (int n = 0; n < 2; ++n) _Pragma("unroll") for (int k = 0; k < 2; ++k) dst[n][k] = *(const PG8_LAS bf16x8*)(lds + PG8_SB(b, h) + boff + n * 2048 + k * 1024); } while (0)
; #define PG8_MMA(ai, bj, At, Bt) do { __builtin_amdgcn_s_setprio(1); _Pragma("unroll") for (int m = 0; m < 4; ++m) _Pragma("unroll") for (int n = 0; n < 2; ++n) _Pragma("unroll") for (int k = 0; k < 2; ++k) \
;         acc[ai][bj][m][n] = __builtin_amdgcn_mfma_f32_16x16x32_bf16(Bt[n][k], At[m][k], acc[ai][bj][m][n], 0, 0, 0); __builtin_amdgcn_s_setprio(0); } while (0)
; #define PG8_BAR __builtin_amdgcn_s_barrier()
; template <class Epi, class Sched, bool ALIGN_EPI = false, bool SP2 = false>
; __device__ __forceinline__ void gemm_phase(PG8_LAS unsigned char* lds, const Gemm g, const Sched& S, const Epi& E, int wave_in) {
;     ...
;             PG8_LDB(B0, 0, 0); PG8_LDB(B1, 0, 1); PG8_SCHED; PG8_LDA(At, 0, 0); PG8_STAGE(PG8_SA(1, 1), a1 + hstep, voffA);
;             PG8_WAIT_V(8); PG8_WAIT_L(0); PG8_BAR; PG8_MMA(0, 0, At, B0); PG8_MMA(0, 1, At, B1); PG8_BAR; PG8_SCHED;
;             PG8_LDA(At, 0, 1); PG8_STAGE(PG8_SB(0, 0), b2, voffB); PG8_STAGE(PG8_SB(0, 1), b2 + hstep, voffB); PG8_STAGE(PG8_SA(0, 0), a2, voffA);
;             PG8_WAIT_V(8); PG8_WAIT_L(0); PG8_BAR; PG8_MMA(1, 0, At, B0); PG8_MMA(1, 1, At, B1); PG8_BAR; PG8_SCHED;
;             PG8_LDB(B0, 1, 0); PG8_LDB(B1, 1, 1); PG8_SCHED; PG8_LDA(At, 1, 0); PG8_STAGE(PG8_SA(0, 1), a2 + hstep, voffA);
;             PG8_WAIT_V(8); PG8_WAIT_L(0); PG8_BAR; PG8_MMA(0, 0, At, B0); PG8_MMA(0, 1, At, B1); PG8_BAR; PG8_SCHED;
;             PG8_LDA(At, 1, 1); PG8_STAGE(PG8_SB(1, 0), b3, voffB); PG8_STAGE(PG8_SB(1, 1), b3 + hstep, voffB); PG8_STAGE(PG8_SA(1, 0), a3, voffA);
;             PG8_WAIT_V(8); PG8_WAIT_L(0); PG8_BAR; PG8_MMA(1, 0, At, B0); PG8_MMA(1, 1, At, B1); PG8_BAR; PG8_SCHED;
	s_setprio 0
	s_add_i32 s73, s65, 0x100
	s_add_i32 s74, s52, 0x100
	v_add_u32_e32 v140, s73, v212
	v_add_u32_e32 v168, s74, v212
	ds_read_b128 v[128:131], v140
	ds_read_b128 v[132:135], v140 offset:1024
	ds_read_b128 v[136:139], v140 offset:2048
	ds_read_b128 v[140:143], v140 offset:3072
	ds_read_b128 v[156:159], v168
	ds_read_b128 v[160:163], v168 offset:1024
	ds_read_b128 v[164:167], v168 offset:2048
	ds_read_b128 v[168:171], v168 offset:3072
	s_add_u32 s26, s26, 0x40000
	s_addc_u32 s27, s27, 0
	s_mov_b32 m0, s45
	v_lshl_add_u64 v[238:239], s[26:27], 0, v[150:151]
	ds_read_b128 v[172:175], v227 offset:32768
	ds_read_b128 v[176:179], v227 offset:33792
	ds_read_b128 v[180:183], v227 offset:34816
	ds_read_b128 v[184:187], v227 offset:35840
	ds_read_b128 v[188:191], v227 offset:36864
	ds_read_b128 v[198:201], v227 offset:37888
	ds_read_b128 v[202:205], v227 offset:38912
	ds_read_b128 v[206:209], v227 offset:39936
	global_load_lds_dwordx4 v[238:239], off
	v_lshl_add_u64 v[238:239], s[26:27], 0, v[146:147]
	s_mov_b32 m0, s46
	s_nop 0
	global_load_lds_dwordx4 v[238:239], off
	s_waitcnt vmcnt(8)
	s_waitcnt lgkmcnt(0)
	s_setprio 1
	s_barrier
	v_mfma_f32_16x16x32_bf16 v[124:127], v[128:131], v[172:175], v[124:127]
	v_mfma_f32_16x16x32_bf16 v[120:123], v[136:139], v[172:175], v[120:123]
	v_mfma_f32_16x16x32_bf16 v[108:111], v[128:131], v[180:183], v[108:111]
	v_mfma_f32_16x16x32_bf16 v[104:107], v[136:139], v[180:183], v[104:107]
	v_mfma_f32_16x16x32_bf16 v[96:99], v[128:131], v[188:191], v[96:99]
	v_mfma_f32_16x16x32_bf16 v[88:91], v[136:139], v[188:191], v[88:91]
	v_mfma_f32_16x16x32_bf16 v[80:83], v[128:131], v[202:205], v[80:83]
	v_mfma_f32_16x16x32_bf16 v[72:75], v[136:139], v[202:205], v[72:75]
	v_mfma_f32_16x16x32_bf16 v[124:127], v[132:135], v[176:179], v[124:127]
	v_mfma_f32_16x16x32_bf16 v[120:123], v[140:143], v[176:179], v[120:123]
	v_mfma_f32_16x16x32_bf16 v[108:111], v[132:135], v[184:187], v[108:111]
	v_mfma_f32_16x16x32_bf16 v[104:107], v[140:143], v[184:187], v[104:107]
	v_mfma_f32_16x16x32_bf16 v[96:99], v[132:135], v[198:201], v[96:99]
	v_mfma_f32_16x16x32_bf16 v[88:91], v[140:143], v[198:201], v[88:91]
	v_mfma_f32_16x16x32_bf16 v[80:83], v[132:135], v[206:209], v[80:83]
	v_mfma_f32_16x16x32_bf16 v[72:75], v[140:143], v[206:209], v[72:75]
	v_mfma_f32_16x16x32_bf16 v[116:119], v[156:159], v[172:175], v[116:119]
	v_mfma_f32_16x16x32_bf16 v[112:115], v[164:167], v[172:175], v[112:115]
	v_mfma_f32_16x16x32_bf16 v[100:103], v[156:159], v[180:183], v[100:103]
	v_mfma_f32_16x16x32_bf16 v[92:95], v[164:167], v[180:183], v[92:95]
	v_mfma_f32_16x16x32_bf16 v[84:87], v[156:159], v[188:191], v[84:87]
	v_mfma_f32_16x16x32_bf16 v[76:79], v[164:167], v[188:191], v[76:79]
	v_mfma_f32_16x16x32_bf16 v[68:71], v[156:159], v[202:205], v[68:71]
	v_mfma_f32_16x16x32_bf16 v[64:67], v[164:167], v[202:205], v[64:67]
	v_mfma_f32_16x16x32_bf16 v[116:119], v[160:163], v[176:179], v[116:119]
	v_mfma_f32_16x16x32_bf16 v[112:115], v[168:171], v[176:179], v[112:115]
	v_mfma_f32_16x16x32_bf16 v[100:103], v[160:163], v[184:187], v[100:103]
	v_mfma_f32_16x16x32_bf16 v[92:95], v[168:171], v[184:187], v[92:95]
	v_mfma_f32_16x16x32_bf16 v[84:87], v[160:163], v[198:201], v[84:87]
	v_mfma_f32_16x16x32_bf16 v[76:79], v[168:171], v[198:201], v[76:79]
	v_mfma_f32_16x16x32_bf16 v[68:71], v[160:163], v[206:209], v[68:71]
	v_mfma_f32_16x16x32_bf16 v[64:67], v[168:171], v[206:209], v[64:67]
	s_barrier
; #define PG8_STAGE(bufoff, gbase, voff) do { _Pragma("unroll") for (int _i = 0; _i < 2; ++_i) \
;         __builtin_amdgcn_global_load_lds((const unsigned*)((const char*)(gbase) + (voff)[_i]), (PG8_LAS unsigned*)(lds + (bufoff) + ldsw + _i * 8192), 16, 0, 0); } while (0)
; #define PG8_LDA(dst, b, h) do { _Pragma("unroll") for (int m = 0; m < 4; ++m) _Pragma("unroll") for (int k = 0; k < 2; ++k) dst[m][k] = *(const PG8_LAS bf16x8*)(lds + PG8_SA(b, h) + aoff + m * 2048 + k * 1024); } while (0)
; #define PG8_WAIT_V(n) asm volatile("s_waitcnt vmcnt(" #n ")" ::: "memory")
; #define PG8_WAIT_L(n) asm volatile("s_waitcnt lgkmcnt(" #n ")" ::: "memory")
; #define PG8_BAR __builtin_amdgcn_s_barrier()
; template <class Epi, class Sched, bool ALIGN_EPI = false, bool SP2 = false>
; __device__ __forceinline__ void gemm_phase(PG8_LAS unsigned char* lds, const Gemm g, const Sched& S, const Epi& E, int wave_in) {
;     ...
;         for (int t = 0; t < nt; t += 2) {
;             const bool last = (t == nt - 2);
;             const char* a1 = cA + (size_t)(t + 1) * kstep;
;             const char* a2 = last ? nA : cA + (size_t)(t + 2) * kstep; const char* b2 = last ? nB : cB + (size_t)(t + 2) * kstep;
;             const char* a3 = a2 + kstep; const char* b3 = b2 + kstep;
;             if (last && has_next) S.a_ready(nxt);
;             if constexpr (SP2) {
;             PG8_LDB(B0, 0, 0); PG8_LDB(B1, 0, 1); PG8_SCHED; PG8_LDA(At, 0, 0); PG8_STAGE(PG8_SA(1, 1), a1 + hstep, voffA);
;             PG8_WAIT_V(8); PG8_WAIT_L(0); PG8_BAR; PG8_MMA(0, 0, At, B0); PG8_MMA(0, 1, At, B1); PG8_BAR; PG8_SCHED;
;             PG8_LDA(At, 0, 1); PG8_STAGE(PG8_SB(0, 0), b2, voffB); PG8_STAGE(PG8_SB(0, 1), b2 + hstep, voffB); PG8_STAGE(PG8_SA(0, 0), a2, voffA);
;             PG8_WAIT_V(8); PG8_WAIT_L(0); PG8_BAR; PG8_MMA(1, 0, At, B0); PG8_MMA(1, 1, At, B1); PG8_BAR; PG8_SCHED;
;             PG8_LDB(B0, 1, 0); PG8_LDB(B1, 1, 1); PG8_SCHED; PG8_LDA(At, 1, 0); PG8_STAGE(PG8_SA(0, 1), a2 + hstep, voffA);
;             PG8_WAIT_V(8); PG8_WAIT_L(0); PG8_BAR; PG8_MMA(0, 0, At, B0); PG8_MMA(0, 1, At, B1); PG8_BAR; PG8_SCHED;
;             PG8_LDA(At, 1, 1); PG8_STAGE(PG8_SB(1, 0), b3, voffB); PG8_STAGE(PG8_SB(1, 1), b3 + hstep, voffB); PG8_STAGE(PG8_SA(1, 0), a3, voffA);
;             PG8_WAIT_V(8); PG8_WAIT_L(0); PG8_BAR; PG8_MMA(1, 0, At, B0); PG8_MMA(1, 1, At, B1); PG8_BAR; PG8_SCHED;
	s_setprio 0
	s_add_i32 s26, s73, s38
	v_lshl_add_u64 v[194:195], v[194:195], 0, s[88:89]
	s_mov_b32 m0, s26
	ds_read_b128 v[172:175], v227 offset:49152
	ds_read_b128 v[176:179], v227 offset:50176
	ds_read_b128 v[180:183], v227 offset:51200
	ds_read_b128 v[184:187], v227 offset:52224
	ds_read_b128 v[188:191], v227 offset:53248
	ds_read_b128 v[198:201], v227 offset:54272
	ds_read_b128 v[202:205], v227 offset:55296
	ds_read_b128 v[206:209], v227 offset:56320
	global_load_lds_dwordx4 v[194:195], off
	s_add_i32 m0, s26, 0x2000
	s_add_u32 s24, s24, 0x40080
	v_lshl_add_u64 v[194:195], v[196:197], 0, s[88:89]
	s_addc_u32 s25, s25, 0
	s_add_i32 s26, s74, s38
	global_load_lds_dwordx4 v[194:195], off
	v_lshl_add_u64 v[194:195], s[24:25], 0, v[148:149]
	s_mov_b32 m0, s26
	s_nop 0
	global_load_lds_dwordx4 v[194:195], off
	v_lshl_add_u64 v[194:195], s[24:25], 0, v[144:145]
	s_add_i32 m0, s26, 0x2000
	s_nop 0
	global_load_lds_dwordx4 v[194:195], off
	v_lshl_add_u64 v[194:195], v[234:235], 0, s[88:89]
	s_mov_b32 m0, s61
	s_nop 0
	global_load_lds_dwordx4 v[194:195], off
	v_lshl_add_u64 v[194:195], v[236:237], 0, s[88:89]
	s_mov_b32 m0, s62
	s_nop 0
	global_load_lds_dwordx4 v[194:195], off
	s_waitcnt vmcnt(8)
	s_waitcnt lgkmcnt(0)
	s_setprio 1
	s_barrier
	v_mfma_f32_16x16x32_bf16 v[60:63], v[128:131], v[172:175], v[60:63]
	v_mfma_f32_16x16x32_bf16 v[56:59], v[136:139], v[172:175], v[56:59]
	v_mfma_f32_16x16x32_bf16 v[48:51], v[128:131], v[180:183], v[48:51]
	v_mfma_f32_16x16x32_bf16 v[40:43], v[136:139], v[180:183], v[40:43]
	v_mfma_f32_16x16x32_bf16 v[32:35], v[128:131], v[188:191], v[32:35]
	v_mfma_f32_16x16x32_bf16 v[24:27], v[136:139], v[188:191], v[24:27]
	v_mfma_f32_16x16x32_bf16 v[16:19], v[128:131], v[202:205], v[16:19]
	v_mfma_f32_16x16x32_bf16 v[8:11], v[136:139], v[202:205], v[8:11]
	v_mfma_f32_16x16x32_bf16 v[60:63], v[132:135], v[176:179], v[60:63]
	v_mfma_f32_16x16x32_bf16 v[56:59], v[140:143], v[176:179], v[56:59]
	v_mfma_f32_16x16x32_bf16 v[48:51], v[132:135], v[184:187], v[48:51]
	v_mfma_f32_16x16x32_bf16 v[40:43], v[140:143], v[184:187], v[40:43]
	v_mfma_f32_16x16x32_bf16 v[32:35], v[132:135], v[198:201], v[32:35]
	v_mfma_f32_16x16x32_bf16 v[24:27], v[140:143], v[198:201], v[24:27]
	v_mfma_f32_16x16x32_bf16 v[16:19], v[132:135], v[206:209], v[16:19]
	v_mfma_f32_16x16x32_bf16 v[8:11], v[140:143], v[206:209], v[8:11]
	v_mfma_f32_16x16x32_bf16 v[52:55], v[156:159], v[172:175], v[52:55]
	v_mfma_f32_16x16x32_bf16 v[44:47], v[164:167], v[172:175], v[44:47]
	v_mfma_f32_16x16x32_bf16 v[36:39], v[156:159], v[180:183], v[36:39]
	v_mfma_f32_16x16x32_bf16 v[28:31], v[164:167], v[180:183], v[28:31]
	v_mfma_f32_16x16x32_bf16 v[20:23], v[156:159], v[188:191], v[20:23]
	v_mfma_f32_16x16x32_bf16 v[12:15], v[164:167], v[188:191], v[12:15]
	v_mfma_f32_16x16x32_bf16 v[4:7], v[156:159], v[202:205], v[4:7]
	v_mfma_f32_16x16x32_bf16 v[0:3], v[164:167], v[202:205], v[0:3]
	v_mfma_f32_16x16x32_bf16 v[52:55], v[160:163], v[176:179], v[52:55]
	v_mfma_f32_16x16x32_bf16 v[44:47], v[168:171], v[176:179], v[44:47]
	v_mfma_f32_16x16x32_bf16 v[36:39], v[160:163], v[184:187], v[36:39]
	v_mfma_f32_16x16x32_bf16 v[28:31], v[168:171], v[184:187], v[28:31]
	v_mfma_f32_16x16x32_bf16 v[20:23], v[160:163], v[198:201], v[20:23]
	v_mfma_f32_16x16x32_bf16 v[12:15], v[168:171], v[198:201], v[12:15]
	v_mfma_f32_16x16x32_bf16 v[4:7], v[160:163], v[206:209], v[4:7]
	v_mfma_f32_16x16x32_bf16 v[0:3], v[168:171], v[206:209], v[0:3]
	s_barrier
	s_setprio 0
	s_add_i32 s72, s72, 2
	s_add_u32 s53, s53, 0x100
	s_addc_u32 s71, s71, 0
	s_add_u32 s22, s22, 0x100
	s_addc_u32 s23, s23, 0
	s_cmp_gt_u32 s72, 13
	s_cbranch_scc0 .LBB0_687

; #define PG8_STAGE(bufoff, gbase, voff) do { _Pragma("unroll") for (int _i = 0; _i < 2; ++_i) \
;         __builtin_amdgcn_global_load_lds((const unsigned*)((const char*)(gbase) + (voff)[_i]), (PG8_LAS unsigned*)(lds + (bufoff) + ldsw + _i * 8192), 16, 0, 0); } while (0)
; #define PG8_WAIT_V(n) asm volatile("s_waitcnt vmcnt(" #n ")" ::: "memory")
; #define PG8_WAIT_L(n) asm volatile("s_waitcnt lgkmcnt(" #n ")" ::: "memory")
; #define PG8_BAR __builtin_amdgcn_s_barrier()
; template <class Epi, class Sched, bool ALIGN_EPI = false, bool SP2 = false>
; __device__ __forceinline__ void gemm_phase(PG8_LAS unsigned char* lds, const Gemm g, const Sched& S, const Epi& E, int wave_in) {
;     ...
;         const char* nA = has_next ? (const char*)g.A + (size_t)(nxt.pm >> g.ash) * g.astride + (size_t)nxt.pm * tstep : cA; const char* nB = has_next ? (const char*)g.Bt + (size_t)(nxt.pm >> g.bsh) * g.bstride + (size_t)nxt.pn * tstep : cB;
;         for (int t = 0; t < nt; t += 2) {
;             const bool last = (t == nt - 2);
;             const char* a1 = cA + (size_t)(t + 1) * kstep;
;             const char* a2 = last ? nA : cA + (size_t)(t + 2) * kstep; const char* b2 = last ? nB : cB + (size_t)(t + 2) * kstep;
;             const char* a3 = a2 + kstep; const char* b3 = b2 + kstep;
;             if (last && has_next) S.a_ready(nxt);
;             if constexpr (SP2) {
;             PG8_LDB(B0, 0, 0); PG8_LDB(B1, 0, 1); PG8_SCHED; PG8_LDA(At, 0, 0); PG8_STAGE(PG8_SA(1, 1), a1 + hstep, voffA);
;             PG8_WAIT_V(8); PG8_WAIT_L(0); PG8_BAR; PG8_MMA(0, 0, At, B0); PG8_MMA(0, 1, At, B1); PG8_BAR; PG8_SCHED;
;             PG8_LDA(At, 0, 1); PG8_STAGE(PG8_SB(0, 0), b2, voffB); PG8_STAGE(PG8_SB(0, 1), b2 + hstep, voffB); PG8_STAGE(PG8_SA(0, 0), a2, voffA);
;             PG8_WAIT_V(8); PG8_WAIT_L(0); PG8_BAR; PG8_MMA(1, 0, At, B0); PG8_MMA(1, 1, At, B1); PG8_BAR; PG8_SCHED;
;             PG8_LDB(B0, 1, 0); PG8_LDB(B1, 1, 1); PG8_SCHED; PG8_LDA(At, 1, 0); PG8_STAGE(PG8_SA(0, 1), a2 + hstep, voffA);
;             PG8_WAIT_V(8); PG8_WAIT_L(0); PG8_BAR; PG8_MMA(0, 0, At, B0); PG8_MMA(0, 1, At, B1); PG8_BAR; PG8_SCHED;
;             PG8_LDA(At, 1, 1); PG8_STAGE(PG8_SB(1, 0), b3, voffB); PG8_STAGE(PG8_SB(1, 1), b3 + hstep, voffB); PG8_STAGE(PG8_SA(1, 0), a3, voffA);
;             PG8_WAIT_V(8); PG8_WAIT_L(0); PG8_BAR; PG8_MMA(1, 0, At, B0); PG8_MMA(1, 1, At, B1); PG8_BAR; PG8_SCHED;
.LBB0_803:
	s_add_u32 s15, s22, 0x100
	s_addc_u32 s17, s23, 0
	s_add_u32 s22, s24, 0x40080
	s_addc_u32 s23, s25, 0
	s_mov_b32 s34, -2
	s_add_u32 s24, s22, 0xfffc0080
	s_addc_u32 s25, s23, -1
	s_add_i32 s44, s35, 0x100
	s_cmp_eq_u32 s34, 12
	s_cselect_b32 s27, s19, s25
	s_cselect_b32 s26, s18, s24
	s_cselect_b32 s25, s21, s17
	s_cselect_b32 s24, s20, s15
	s_add_i32 s53, s90, 0x100
	v_add_u32_e32 v128, s44, v249
	v_add_u32_e32 v156, s53, v249
	ds_read_b128 v[112:115], v128
	ds_read_b128 v[120:123], v128 offset:1024
	ds_read_b128 v[124:127], v128 offset:2048
	ds_read_b128 v[128:131], v128 offset:3072
	ds_read_b128 v[136:139], v156
	ds_read_b128 v[140:143], v156 offset:1024
	ds_read_b128 v[144:147], v156 offset:2048
	ds_read_b128 v[156:159], v156 offset:3072
	v_lshl_add_u64 v[194:195], s[22:23], 0, v[206:207]
	s_add_i32 m0, s39, 0xc000
	ds_read_b128 v[160:163], v251
	ds_read_b128 v[164:167], v251 offset:1024
	ds_read_b128 v[168:171], v251 offset:2048
	ds_read_b128 v[172:175], v251 offset:3072
	ds_read_b128 v[176:179], v251 offset:4096
	ds_read_b128 v[180:183], v251 offset:5120
	ds_read_b128 v[184:187], v251 offset:6144
	ds_read_b128 v[188:191], v251 offset:7168
	global_load_lds_dwordx4 v[194:195], off
	v_lshl_add_u64 v[194:195], s[22:23], 0, v[204:205]
	s_add_i32 m0, s39, 0xe000
	s_nop 0
	global_load_lds_dwordx4 v[194:195], off
	s_waitcnt vmcnt(8)
	s_waitcnt lgkmcnt(0)
	s_setprio 1
	s_barrier
	v_mfma_f32_16x16x32_bf16 v[152:155], v[112:115], v[160:163], 0
	v_mfma_f32_16x16x32_bf16 v[148:151], v[124:127], v[160:163], 0
	v_mfma_f32_16x16x32_bf16 v[108:111], v[112:115], v[168:171], 0
	v_mfma_f32_16x16x32_bf16 v[104:107], v[124:127], v[168:171], 0
	v_mfma_f32_16x16x32_bf16 v[92:95], v[112:115], v[176:179], 0
	v_mfma_f32_16x16x32_bf16 v[88:91], v[124:127], v[176:179], 0
	v_mfma_f32_16x16x32_bf16 v[76:79], v[112:115], v[184:187], 0
	v_mfma_f32_16x16x32_bf16 v[72:75], v[124:127], v[184:187], 0
	v_mfma_f32_16x16x32_bf16 v[152:155], v[120:123], v[164:167], v[152:155]
	v_mfma_f32_16x16x32_bf16 v[148:151], v[128:131], v[164:167], v[148:151]
	v_mfma_f32_16x16x32_bf16 v[108:111], v[120:123], v[172:175], v[108:111]
	v_mfma_f32_16x16x32_bf16 v[104:107], v[128:131], v[172:175], v[104:107]
	v_mfma_f32_16x16x32_bf16 v[92:95], v[120:123], v[180:183], v[92:95]
	v_mfma_f32_16x16x32_bf16 v[88:91], v[128:131], v[180:183], v[88:91]
	v_mfma_f32_16x16x32_bf16 v[76:79], v[120:123], v[188:191], v[76:79]
	v_mfma_f32_16x16x32_bf16 v[72:75], v[128:131], v[188:191], v[72:75]
	v_mfma_f32_16x16x32_bf16 v[132:135], v[136:139], v[160:163], 0
	v_mfma_f32_16x16x32_bf16 v[116:119], v[144:147], v[160:163], 0
	v_mfma_f32_16x16x32_bf16 v[100:103], v[136:139], v[168:171], 0
	v_mfma_f32_16x16x32_bf16 v[96:99], v[144:147], v[168:171], 0
	v_mfma_f32_16x16x32_bf16 v[84:87], v[136:139], v[176:179], 0
	v_mfma_f32_16x16x32_bf16 v[80:83], v[144:147], v[176:179], 0
	v_mfma_f32_16x16x32_bf16 v[68:71], v[136:139], v[184:187], 0
	v_mfma_f32_16x16x32_bf16 v[64:67], v[144:147], v[184:187], 0
	v_mfma_f32_16x16x32_bf16 v[132:135], v[140:143], v[164:167], v[132:135]
	v_mfma_f32_16x16x32_bf16 v[116:119], v[156:159], v[164:167], v[116:119]
	v_mfma_f32_16x16x32_bf16 v[100:103], v[140:143], v[172:175], v[100:103]
	v_mfma_f32_16x16x32_bf16 v[96:99], v[156:159], v[172:175], v[96:99]
	v_mfma_f32_16x16x32_bf16 v[84:87], v[140:143], v[180:183], v[84:87]
	v_mfma_f32_16x16x32_bf16 v[80:83], v[156:159], v[180:183], v[80:83]
	v_mfma_f32_16x16x32_bf16 v[68:71], v[140:143], v[188:191], v[68:71]
	v_mfma_f32_16x16x32_bf16 v[64:67], v[156:159], v[188:191], v[64:67]
	s_barrier
	s_setprio 0
	s_add_i32 s44, s44, s38
	v_lshl_add_u64 v[194:195], s[24:25], 0, v[192:193]
	s_mov_b32 m0, s44
	ds_read_b128 v[160:163], v251 offset:16384
	ds_read_b128 v[164:167], v251 offset:17408
	ds_read_b128 v[168:171], v251 offset:18432
	ds_read_b128 v[172:175], v251 offset:19456
	ds_read_b128 v[176:179], v251 offset:20480
	ds_read_b128 v[180:183], v251 offset:21504
	ds_read_b128 v[184:187], v251 offset:22528
	ds_read_b128 v[188:191], v251 offset:23552
	global_load_lds_dwordx4 v[194:195], off
	s_add_i32 m0, s44, 0x2000
	s_add_u32 s44, s24, 0x40000
	v_lshl_add_u64 v[196:197], s[24:25], 0, v[198:199]
	s_addc_u32 s45, s25, 0
	s_add_i32 s53, s53, s38
	global_load_lds_dwordx4 v[196:197], off
	v_lshl_add_u64 v[208:209], s[44:45], 0, v[192:193]
	s_mov_b32 m0, s53
	v_lshl_add_u64 v[210:211], s[26:27], 0, v[200:201]
	global_load_lds_dwordx4 v[208:209], off
	v_lshl_add_u64 v[208:209], s[44:45], 0, v[198:199]
	s_add_i32 m0, s53, 0x2000
	s_nop 0
	global_load_lds_dwordx4 v[208:209], off
	v_lshl_add_u64 v[208:209], s[26:27], 0, v[202:203]
	s_mov_b32 m0, s39
	s_nop 0
	global_load_lds_dwordx4 v[208:209], off
	s_mov_b32 m0, s46
	s_nop 0
	global_load_lds_dwordx4 v[210:211], off
	s_waitcnt vmcnt(8)
	s_waitcnt lgkmcnt(0)
	s_setprio 1
	s_barrier
; #define PG8_STAGE(bufoff, gbase, voff) do { _Pragma("unroll") for (int _i = 0; _i < 2; ++_i) \
;         __builtin_amdgcn_global_load_lds((const unsigned*)((const char*)(gbase) + (voff)[_i]), (PG8_LAS unsigned*)(lds + (bufoff) + ldsw + _i * 8192), 16, 0, 0); } while (0)
; #define PG8_LDA(dst, b, h) do { _Pragma("unroll") for (int m = 0; m < 4; ++m) _Pragma("unroll") for (int k = 0; k < 2; ++k) dst[m][k] = *(const PG8_LAS bf16x8*)(lds + PG8_SA(b, h) + aoff + m * 2048 + k * 1024); } while (0)
; #define PG8_LDB(dst, b, h) do { _Pragma("unroll") for (int n = 0; n < 2; ++n) _Pragma("unroll") for (int k = 0; k < 2; ++k) dst[n][k] = *(const PG8_LAS bf16x8*)(lds + PG8_SB(b, h) + boff + n * 2048 + k * 1024); } while (0)
; #define PG8_MMA(ai, bj, At, Bt) do { __builtin_amdgcn_s_setprio(1); _Pragma("unroll") for (int m = 0; m < 4; ++m) _Pragma("unroll") for (int n = 0; n < 2; ++n) _Pragma("unroll") for (int k = 0; k < 2; ++k) \
;         acc[ai][bj][m][n] = __builtin_amdgcn_mfma_f32_16x16x32_bf16(Bt[n][k], At[m][k], acc[ai][bj][m][n], 0, 0, 0); __builtin_amdgcn_s_setprio(0); } while (0)
; #define PG8_BAR __builtin_amdgcn_s_barrier()
; template <class Epi, class Sched, bool ALIGN_EPI = false, bool SP2 = false>
; __device__ __forceinline__ void gemm_phase(PG8_LAS unsigned char* lds, const Gemm g, const Sched& S, const Epi& E, int wave_in) {
;     ...
;             PG8_LDB(B0, 0, 0); PG8_LDB(B1, 0, 1); PG8_SCHED; PG8_LDA(At, 0, 0); PG8_STAGE(PG8_SA(1, 1), a1 + hstep, voffA);
;             PG8_WAIT_V(8); PG8_WAIT_L(0); PG8_BAR; PG8_MMA(0, 0, At, B0); PG8_MMA(0, 1, At, B1); PG8_BAR; PG8_SCHED;
;             PG8_LDA(At, 0, 1); PG8_STAGE(PG8_SB(0, 0), b2, voffB); PG8_STAGE(PG8_SB(0, 1), b2 + hstep, voffB); PG8_STAGE(PG8_SA(0, 0), a2, voffA);
;             PG8_WAIT_V(8); PG8_WAIT_L(0); PG8_BAR; PG8_MMA(1, 0, At, B0); PG8_MMA(1, 1, At, B1); PG8_BAR; PG8_SCHED;
;             PG8_LDB(B0, 1, 0); PG8_LDB(B1, 1, 1); PG8_SCHED; PG8_LDA(At, 1, 0); PG8_STAGE(PG8_SA(0, 1), a2 + hstep, voffA);
;             PG8_WAIT_V(8); PG8_WAIT_L(0); PG8_BAR; PG8_MMA(0, 0, At, B0); PG8_MMA(0, 1, At, B1); PG8_BAR; PG8_SCHED;
;             PG8_LDA(At, 1, 1); PG8_STAGE(PG8_SB(1, 0), b3, voffB); PG8_STAGE(PG8_SB(1, 1), b3 + hstep, voffB); PG8_STAGE(PG8_SA(1, 0), a3, voffA);
;             PG8_WAIT_V(8); PG8_WAIT_L(0); PG8_BAR; PG8_MMA(1, 0, At, B0); PG8_MMA(1, 1, At, B1); PG8_BAR; PG8_SCHED;
	v_mfma_f32_16x16x32_bf16 v[60:63], v[112:115], v[160:163], 0
	v_mfma_f32_16x16x32_bf16 v[56:59], v[124:127], v[160:163], 0
	v_mfma_f32_16x16x32_bf16 v[44:47], v[112:115], v[168:171], 0
	v_mfma_f32_16x16x32_bf16 v[40:43], v[124:127], v[168:171], 0
	v_mfma_f32_16x16x32_bf16 v[28:31], v[112:115], v[176:179], 0
	v_mfma_f32_16x16x32_bf16 v[24:27], v[124:127], v[176:179], 0
	v_mfma_f32_16x16x32_bf16 v[12:15], v[112:115], v[184:187], 0
	v_mfma_f32_16x16x32_bf16 v[8:11], v[124:127], v[184:187], 0
	v_mfma_f32_16x16x32_bf16 v[60:63], v[120:123], v[164:167], v[60:63]
	v_mfma_f32_16x16x32_bf16 v[56:59], v[128:131], v[164:167], v[56:59]
	v_mfma_f32_16x16x32_bf16 v[44:47], v[120:123], v[172:175], v[44:47]
	v_mfma_f32_16x16x32_bf16 v[40:43], v[128:131], v[172:175], v[40:43]
	v_mfma_f32_16x16x32_bf16 v[28:31], v[120:123], v[180:183], v[28:31]
	v_mfma_f32_16x16x32_bf16 v[24:27], v[128:131], v[180:183], v[24:27]
	v_mfma_f32_16x16x32_bf16 v[12:15], v[120:123], v[188:191], v[12:15]
	v_mfma_f32_16x16x32_bf16 v[8:11], v[128:131], v[188:191], v[8:11]
	v_mfma_f32_16x16x32_bf16 v[52:55], v[136:139], v[160:163], 0
	v_mfma_f32_16x16x32_bf16 v[48:51], v[144:147], v[160:163], 0
	v_mfma_f32_16x16x32_bf16 v[36:39], v[136:139], v[168:171], 0
	v_mfma_f32_16x16x32_bf16 v[32:35], v[144:147], v[168:171], 0
	v_mfma_f32_16x16x32_bf16 v[20:23], v[136:139], v[176:179], 0
	v_mfma_f32_16x16x32_bf16 v[16:19], v[144:147], v[176:179], 0
	v_mfma_f32_16x16x32_bf16 v[4:7], v[136:139], v[184:187], 0
	v_mfma_f32_16x16x32_bf16 v[0:3], v[144:147], v[184:187], 0
	v_mfma_f32_16x16x32_bf16 v[52:55], v[140:143], v[164:167], v[52:55]
	v_mfma_f32_16x16x32_bf16 v[48:51], v[156:159], v[164:167], v[48:51]
	v_mfma_f32_16x16x32_bf16 v[36:39], v[140:143], v[172:175], v[36:39]
	v_mfma_f32_16x16x32_bf16 v[32:35], v[156:159], v[172:175], v[32:35]
	v_mfma_f32_16x16x32_bf16 v[20:23], v[140:143], v[180:183], v[20:23]
	v_mfma_f32_16x16x32_bf16 v[16:19], v[156:159], v[180:183], v[16:19]
	v_mfma_f32_16x16x32_bf16 v[4:7], v[140:143], v[188:191], v[4:7]
	v_mfma_f32_16x16x32_bf16 v[0:3], v[156:159], v[188:191], v[0:3]
	s_barrier
	s_setprio 0
	s_add_i32 s44, s65, 0x100
	s_add_i32 s45, s52, 0x100
	v_add_u32_e32 v128, s44, v249
	v_add_u32_e32 v156, s45, v249
	ds_read_b128 v[112:115], v128
	ds_read_b128 v[120:123], v128 offset:1024
	ds_read_b128 v[124:127], v128 offset:2048
	ds_read_b128 v[128:131], v128 offset:3072
	ds_read_b128 v[136:139], v156
	ds_read_b128 v[140:143], v156 offset:1024
	ds_read_b128 v[144:147], v156 offset:2048
	ds_read_b128 v[156:159], v156 offset:3072
	s_add_u32 s26, s26, 0x40000
	s_addc_u32 s27, s27, 0
	s_mov_b32 m0, s47
	v_lshl_add_u64 v[212:213], s[26:27], 0, v[202:203]
	ds_read_b128 v[160:163], v251 offset:32768
	ds_read_b128 v[164:167], v251 offset:33792
	ds_read_b128 v[168:171], v251 offset:34816
	ds_read_b128 v[172:175], v251 offset:35840
	ds_read_b128 v[176:179], v251 offset:36864
	ds_read_b128 v[180:183], v251 offset:37888
	ds_read_b128 v[184:187], v251 offset:38912
	ds_read_b128 v[188:191], v251 offset:39936
	global_load_lds_dwordx4 v[212:213], off
	v_lshl_add_u64 v[212:213], s[26:27], 0, v[200:201]
	s_mov_b32 m0, s60
	s_nop 0
	global_load_lds_dwordx4 v[212:213], off
	s_waitcnt vmcnt(8)
	s_waitcnt lgkmcnt(0)
	s_setprio 1
	s_barrier
	v_mfma_f32_16x16x32_bf16 v[152:155], v[112:115], v[160:163], v[152:155]
	v_mfma_f32_16x16x32_bf16 v[148:151], v[124:127], v[160:163], v[148:151]
	v_mfma_f32_16x16x32_bf16 v[108:111], v[112:115], v[168:171], v[108:111]
	v_mfma_f32_16x16x32_bf16 v[104:107], v[124:127], v[168:171], v[104:107]
	v_mfma_f32_16x16x32_bf16 v[92:95], v[112:115], v[176:179], v[92:95]
	v_mfma_f32_16x16x32_bf16 v[88:91], v[124:127], v[176:179], v[88:91]
	v_mfma_f32_16x16x32_bf16 v[76:79], v[112:115], v[184:187], v[76:79]
	v_mfma_f32_16x16x32_bf16 v[72:75], v[124:127], v[184:187], v[72:75]
	v_mfma_f32_16x16x32_bf16 v[152:155], v[120:123], v[164:167], v[152:155]
	v_mfma_f32_16x16x32_bf16 v[148:151], v[128:131], v[164:167], v[148:151]
	v_mfma_f32_16x16x32_bf16 v[108:111], v[120:123], v[172:175], v[108:111]
	v_mfma_f32_16x16x32_bf16 v[104:107], v[128:131], v[172:175], v[104:107]
	v_mfma_f32_16x16x32_bf16 v[92:95], v[120:123], v[180:183], v[92:95]
	v_mfma_f32_16x16x32_bf16 v[88:91], v[128:131], v[180:183], v[88:91]
	v_mfma_f32_16x16x32_bf16 v[76:79], v[120:123], v[188:191], v[76:79]
	v_mfma_f32_16x16x32_bf16 v[72:75], v[128:131], v[188:191], v[72:75]
	v_mfma_f32_16x16x32_bf16 v[132:135], v[136:139], v[160:163], v[132:135]
	v_mfma_f32_16x16x32_bf16 v[116:119], v[144:147], v[160:163], v[116:119]
	v_mfma_f32_16x16x32_bf16 v[100:103], v[136:139], v[168:171], v[100:103]
	v_mfma_f32_16x16x32_bf16 v[96:99], v[144:147], v[168:171], v[96:99]
	v_mfma_f32_16x16x32_bf16 v[84:87], v[136:139], v[176:179], v[84:87]
	v_mfma_f32_16x16x32_bf16 v[80:83], v[144:147], v[176:179], v[80:83]
	v_mfma_f32_16x16x32_bf16 v[68:71], v[136:139], v[184:187], v[68:71]
	v_mfma_f32_16x16x32_bf16 v[64:67], v[144:147], v[184:187], v[64:67]
	v_mfma_f32_16x16x32_bf16 v[132:135], v[140:143], v[164:167], v[132:135]
	v_mfma_f32_16x16x32_bf16 v[116:119], v[156:159], v[164:167], v[116:119]
	v_mfma_f32_16x16x32_bf16 v[100:103], v[140:143], v[172:175], v[100:103]
	v_mfma_f32_16x16x32_bf16 v[96:99], v[156:159], v[172:175], v[96:99]
	v_mfma_f32_16x16x32_bf16 v[84:87], v[140:143], v[180:183], v[84:87]
	v_mfma_f32_16x16x32_bf16 v[80:83], v[156:159], v[180:183], v[80:83]
	v_mfma_f32_16x16x32_bf16 v[68:71], v[140:143], v[188:191], v[68:71]
	v_mfma_f32_16x16x32_bf16 v[64:67], v[156:159], v[188:191], v[64:67]
	s_barrier
; #define PG8_STAGE(bufoff, gbase, voff) do { _Pragma("unroll") for (int _i = 0; _i < 2; ++_i) \
;         __builtin_amdgcn_global_load_lds((const unsigned*)((const char*)(gbase) + (voff)[_i]), (PG8_LAS unsigned*)(lds + (bufoff) + ldsw + _i * 8192), 16, 0, 0); } while (0)
; #define PG8_LDA(dst, b, h) do { _Pragma("unroll") for (int m = 0; m < 4; ++m) _Pragma("unroll") for (int k = 0; k < 2; ++k) dst[m][k] = *(const PG8_LAS bf16x8*)(lds + PG8_SA(b, h) + aoff + m * 2048 + k * 1024); } while (0)
; #define PG8_WAIT_V(n) asm volatile("s_waitcnt vmcnt(" #n ")" ::: "memory")
; #define PG8_WAIT_L(n) asm volatile("s_waitcnt lgkmcnt(" #n ")" ::: "memory")
; #define PG8_BAR __builtin_amdgcn_s_barrier()
; template <class Epi, class Sched, bool ALIGN_EPI = false, bool SP2 = false>
; __device__ __forceinline__ void gemm_phase(PG8_LAS unsigned char* lds, const Gemm g, const Sched& S, const Epi& E, int wave_in) {
;     ...
;         for (int t = 0; t < nt; t += 2) {
;             const bool last = (t == nt - 2);
;             const char* a1 = cA + (size_t)(t + 1) * kstep;
;             const char* a2 = last ? nA : cA + (size_t)(t + 2) * kstep; const char* b2 = last ? nB : cB + (size_t)(t + 2) * kstep;
;             const char* a3 = a2 + kstep; const char* b3 = b2 + kstep;
;             if (last && has_next) S.a_ready(nxt);
;             if constexpr (SP2) {
;             PG8_LDB(B0, 0, 0); PG8_LDB(B1, 0, 1); PG8_SCHED; PG8_LDA(At, 0, 0); PG8_STAGE(PG8_SA(1, 1), a1 + hstep, voffA);
;             PG8_WAIT_V(8); PG8_WAIT_L(0); PG8_BAR; PG8_MMA(0, 0, At, B0); PG8_MMA(0, 1, At, B1); PG8_BAR; PG8_SCHED;
;             PG8_LDA(At, 0, 1); PG8_STAGE(PG8_SB(0, 0), b2, voffB); PG8_STAGE(PG8_SB(0, 1), b2 + hstep, voffB); PG8_STAGE(PG8_SA(0, 0), a2, voffA);
;             PG8_WAIT_V(8); PG8_WAIT_L(0); PG8_BAR; PG8_MMA(1, 0, At, B0); PG8_MMA(1, 1, At, B1); PG8_BAR; PG8_SCHED;
;             PG8_LDB(B0, 1, 0); PG8_LDB(B1, 1, 1); PG8_SCHED; PG8_LDA(At, 1, 0); PG8_STAGE(PG8_SA(0, 1), a2 + hstep, voffA);
;             PG8_WAIT_V(8); PG8_WAIT_L(0); PG8_BAR; PG8_MMA(0, 0, At, B0); PG8_MMA(0, 1, At, B1); PG8_BAR; PG8_SCHED;
;             PG8_LDA(At, 1, 1); PG8_STAGE(PG8_SB(1, 0), b3, voffB); PG8_STAGE(PG8_SB(1, 1), b3 + hstep, voffB); PG8_STAGE(PG8_SA(1, 0), a3, voffA);
;             PG8_WAIT_V(8); PG8_WAIT_L(0); PG8_BAR; PG8_MMA(1, 0, At, B0); PG8_MMA(1, 1, At, B1); PG8_BAR; PG8_SCHED;
	s_setprio 0
	s_add_i32 s26, s44, s38
	v_lshl_add_u64 v[194:195], v[194:195], 0, s[88:89]
	s_mov_b32 m0, s26
	ds_read_b128 v[160:163], v251 offset:49152
	ds_read_b128 v[164:167], v251 offset:50176
	ds_read_b128 v[168:171], v251 offset:51200
	ds_read_b128 v[172:175], v251 offset:52224
	ds_read_b128 v[176:179], v251 offset:53248
	ds_read_b128 v[180:183], v251 offset:54272
	ds_read_b128 v[184:187], v251 offset:55296
	ds_read_b128 v[188:191], v251 offset:56320
	global_load_lds_dwordx4 v[194:195], off
	s_add_i32 m0, s26, 0x2000
	s_add_u32 s24, s24, 0x40080
	v_lshl_add_u64 v[194:195], v[196:197], 0, s[88:89]
	s_addc_u32 s25, s25, 0
	s_add_i32 s26, s45, s38
	global_load_lds_dwordx4 v[194:195], off
	v_lshl_add_u64 v[194:195], s[24:25], 0, v[192:193]
	s_mov_b32 m0, s26
	s_nop 0
	global_load_lds_dwordx4 v[194:195], off
	v_lshl_add_u64 v[194:195], s[24:25], 0, v[198:199]
	s_add_i32 m0, s26, 0x2000
	s_nop 0
	global_load_lds_dwordx4 v[194:195], off
	v_lshl_add_u64 v[194:195], v[208:209], 0, s[88:89]
	s_mov_b32 m0, s62
	s_nop 0
	global_load_lds_dwordx4 v[194:195], off
	v_lshl_add_u64 v[194:195], v[210:211], 0, s[88:89]
	s_mov_b32 m0, s63
	s_nop 0
	global_load_lds_dwordx4 v[194:195], off
	s_waitcnt vmcnt(8)
	s_waitcnt lgkmcnt(0)
	s_setprio 1
	s_barrier
	v_mfma_f32_16x16x32_bf16 v[60:63], v[112:115], v[160:163], v[60:63]
	v_mfma_f32_16x16x32_bf16 v[56:59], v[124:127], v[160:163], v[56:59]
	v_mfma_f32_16x16x32_bf16 v[44:47], v[112:115], v[168:171], v[44:47]
	v_mfma_f32_16x16x32_bf16 v[40:43], v[124:127], v[168:171], v[40:43]
	v_mfma_f32_16x16x32_bf16 v[28:31], v[112:115], v[176:179], v[28:31]
	v_mfma_f32_16x16x32_bf16 v[24:27], v[124:127], v[176:179], v[24:27]
	v_mfma_f32_16x16x32_bf16 v[12:15], v[112:115], v[184:187], v[12:15]
	v_mfma_f32_16x16x32_bf16 v[8:11], v[124:127], v[184:187], v[8:11]
	v_mfma_f32_16x16x32_bf16 v[60:63], v[120:123], v[164:167], v[60:63]
	v_mfma_f32_16x16x32_bf16 v[56:59], v[128:131], v[164:167], v[56:59]
	v_mfma_f32_16x16x32_bf16 v[44:47], v[120:123], v[172:175], v[44:47]
	v_mfma_f32_16x16x32_bf16 v[40:43], v[128:131], v[172:175], v[40:43]
	v_mfma_f32_16x16x32_bf16 v[28:31], v[120:123], v[180:183], v[28:31]
	v_mfma_f32_16x16x32_bf16 v[24:27], v[128:131], v[180:183], v[24:27]
	v_mfma_f32_16x16x32_bf16 v[12:15], v[120:123], v[188:191], v[12:15]
	v_mfma_f32_16x16x32_bf16 v[8:11], v[128:131], v[188:191], v[8:11]
	v_mfma_f32_16x16x32_bf16 v[52:55], v[136:139], v[160:163], v[52:55]
	v_mfma_f32_16x16x32_bf16 v[48:51], v[144:147], v[160:163], v[48:51]
	v_mfma_f32_16x16x32_bf16 v[36:39], v[136:139], v[168:171], v[36:39]
	v_mfma_f32_16x16x32_bf16 v[32:35], v[144:147], v[168:171], v[32:35]
	v_mfma_f32_16x16x32_bf16 v[20:23], v[136:139], v[176:179], v[20:23]
	v_mfma_f32_16x16x32_bf16 v[16:19], v[144:147], v[176:179], v[16:19]
	v_mfma_f32_16x16x32_bf16 v[4:7], v[136:139], v[184:187], v[4:7]
	v_mfma_f32_16x16x32_bf16 v[0:3], v[144:147], v[184:187], v[0:3]
	v_mfma_f32_16x16x32_bf16 v[52:55], v[140:143], v[164:167], v[52:55]
	v_mfma_f32_16x16x32_bf16 v[48:51], v[156:159], v[164:167], v[48:51]
	v_mfma_f32_16x16x32_bf16 v[36:39], v[140:143], v[172:175], v[36:39]
	v_mfma_f32_16x16x32_bf16 v[32:35], v[156:159], v[172:175], v[32:35]
	v_mfma_f32_16x16x32_bf16 v[20:23], v[140:143], v[180:183], v[20:23]
	v_mfma_f32_16x16x32_bf16 v[16:19], v[156:159], v[180:183], v[16:19]
	v_mfma_f32_16x16x32_bf16 v[4:7], v[140:143], v[188:191], v[4:7]
	v_mfma_f32_16x16x32_bf16 v[0:3], v[156:159], v[188:191], v[0:3]
	s_barrier
	s_setprio 0
	s_add_i32 s34, s34, 2
	s_add_u32 s15, s15, 0x100
	s_addc_u32 s17, s17, 0
	s_add_u32 s22, s22, 0x100
	s_addc_u32 s23, s23, 0
	s_cmp_gt_u32 s34, 13
	s_cbranch_scc1 .Lkexit_5
.LBB0_804:
	s_add_u32 s24, s22, 0xfffc0080
	s_addc_u32 s25, s23, -1
	s_add_i32 s44, s35, 0x100
	s_cmp_eq_u32 s34, 12
	s_cselect_b32 s27, s19, s25
	s_cselect_b32 s26, s18, s24
	s_cselect_b32 s25, s21, s17
	s_cselect_b32 s24, s20, s15
	s_add_i32 s53, s90, 0x100
	v_add_u32_e32 v128, s44, v249
	v_add_u32_e32 v156, s53, v249
	ds_read_b128 v[112:115], v128
	ds_read_b128 v[120:123], v128 offset:1024
	ds_read_b128 v[124:127], v128 offset:2048
	ds_read_b128 v[128:131], v128 offset:3072
	ds_read_b128 v[136:139], v156
	ds_read_b128 v[140:143], v156 offset:1024
	ds_read_b128 v[144:147], v156 offset:2048
	ds_read_b128 v[156:159], v156 offset:3072
	v_lshl_add_u64 v[194:195], s[22:23], 0, v[206:207]
	s_add_i32 m0, s39, 0xc000
	ds_read_b128 v[160:163], v251
	ds_read_b128 v[164:167], v251 offset:1024
	ds_read_b128 v[168:171], v251 offset:2048
	ds_read_b128 v[172:175], v251 offset:3072
	ds_read_b128 v[176:179], v251 offset:4096
	ds_read_b128 v[180:183], v251 offset:5120
	ds_read_b128 v[184:187], v251 offset:6144
	ds_read_b128 v[188:191], v251 offset:7168
	global_load_lds_dwordx4 v[194:195], off
	v_lshl_add_u64 v[194:195], s[22:23], 0, v[204:205]
	s_add_i32 m0, s39, 0xe000
	s_nop 0
	global_load_lds_dwordx4 v[194:195], off
	s_waitcnt vmcnt(8)
	s_waitcnt lgkmcnt(0)
	s_setprio 1
	s_barrier
; #define PG8_STAGE(bufoff, gbase, voff) do { _Pragma("unroll") for (int _i = 0; _i < 2; ++_i) \
;         __builtin_amdgcn_global_load_lds((const unsigned*)((const char*)(gbase) + (voff)[_i]), (PG8_LAS unsigned*)(lds + (bufoff) + ldsw + _i * 8192), 16, 0, 0); } while (0)
; #define PG8_LDA(dst, b, h) do { _Pragma("unroll") for (int m = 0; m < 4; ++m) _Pragma("unroll") for (int k = 0; k < 2; ++k) dst[m][k] = *(const PG8_LAS bf16x8*)(lds + PG8_SA(b, h) + aoff + m * 2048 + k * 1024); } while (0)
; #define PG8_LDB(dst, b, h) do { _Pragma("unroll") for (int n = 0; n < 2; ++n) _Pragma("unroll") for (int k = 0; k < 2; ++k) dst[n][k] = *(const PG8_LAS bf16x8*)(lds + PG8_SB(b, h) + boff + n * 2048 + k * 1024); } while (0)
; #define PG8_MMA(ai, bj, At, Bt) do { __builtin_amdgcn_s_setprio(1); _Pragma("unroll") for (int m = 0; m < 4; ++m) _Pragma("unroll") for (int n = 0; n < 2; ++n) _Pragma("unroll") for (int k = 0; k < 2; ++k) \
;         acc[ai][bj][m][n] = __builtin_amdgcn_mfma_f32_16x16x32_bf16(Bt[n][k], At[m][k], acc[ai][bj][m][n], 0, 0, 0); __builtin_amdgcn_s_setprio(0); } while (0)
; #define PG8_BAR __builtin_amdgcn_s_barrier()
; template <class Epi, class Sched, bool ALIGN_EPI = false, bool SP2 = false>
; __device__ __forceinline__ void gemm_phase(PG8_LAS unsigned char* lds, const Gemm g, const Sched& S, const Epi& E, int wave_in) {
;     ...
;             PG8_LDB(B0, 0, 0); PG8_LDB(B1, 0, 1); PG8_SCHED; PG8_LDA(At, 0, 0); PG8_STAGE(PG8_SA(1, 1), a1 + hstep, voffA);
;             PG8_WAIT_V(8); PG8_WAIT_L(0); PG8_BAR; PG8_MMA(0, 0, At, B0); PG8_MMA(0, 1, At, B1); PG8_BAR; PG8_SCHED;
;             PG8_LDA(At, 0, 1); PG8_STAGE(PG8_SB(0, 0), b2, voffB); PG8_STAGE(PG8_SB(0, 1), b2 + hstep, voffB); PG8_STAGE(PG8_SA(0, 0), a2, voffA);
;             PG8_WAIT_V(8); PG8_WAIT_L(0); PG8_BAR; PG8_MMA(1, 0, At, B0); PG8_MMA(1, 1, At, B1); PG8_BAR; PG8_SCHED;
;             PG8_LDB(B0, 1, 0); PG8_LDB(B1, 1, 1); PG8_SCHED; PG8_LDA(At, 1, 0); PG8_STAGE(PG8_SA(0, 1), a2 + hstep, voffA);
;             PG8_WAIT_V(8); PG8_WAIT_L(0); PG8_BAR; PG8_MMA(0, 0, At, B0); PG8_MMA(0, 1, At, B1); PG8_BAR; PG8_SCHED;
;             PG8_LDA(At, 1, 1); PG8_STAGE(PG8_SB(1, 0), b3, voffB); PG8_STAGE(PG8_SB(1, 1), b3 + hstep, voffB); PG8_STAGE(PG8_SA(1, 0), a3, voffA);
;             PG8_WAIT_V(8); PG8_WAIT_L(0); PG8_BAR; PG8_MMA(1, 0, At, B0); PG8_MMA(1, 1, At, B1); PG8_BAR; PG8_SCHED;
	v_mfma_f32_16x16x32_bf16 v[152:155], v[112:115], v[160:163], v[152:155]
	v_mfma_f32_16x16x32_bf16 v[148:151], v[124:127], v[160:163], v[148:151]
	v_mfma_f32_16x16x32_bf16 v[108:111], v[112:115], v[168:171], v[108:111]
	v_mfma_f32_16x16x32_bf16 v[104:107], v[124:127], v[168:171], v[104:107]
	v_mfma_f32_16x16x32_bf16 v[92:95], v[112:115], v[176:179], v[92:95]
	v_mfma_f32_16x16x32_bf16 v[88:91], v[124:127], v[176:179], v[88:91]
	v_mfma_f32_16x16x32_bf16 v[76:79], v[112:115], v[184:187], v[76:79]
	v_mfma_f32_16x16x32_bf16 v[72:75], v[124:127], v[184:187], v[72:75]
	v_mfma_f32_16x16x32_bf16 v[152:155], v[120:123], v[164:167], v[152:155]
	v_mfma_f32_16x16x32_bf16 v[148:151], v[128:131], v[164:167], v[148:151]
	v_mfma_f32_16x16x32_bf16 v[108:111], v[120:123], v[172:175], v[108:111]
	v_mfma_f32_16x16x32_bf16 v[104:107], v[128:131], v[172:175], v[104:107]
	v_mfma_f32_16x16x32_bf16 v[92:95], v[120:123], v[180:183], v[92:95]
	v_mfma_f32_16x16x32_bf16 v[88:91], v[128:131], v[180:183], v[88:91]
	v_mfma_f32_16x16x32_bf16 v[76:79], v[120:123], v[188:191], v[76:79]
	v_mfma_f32_16x16x32_bf16 v[72:75], v[128:131], v[188:191], v[72:75]
	v_mfma_f32_16x16x32_bf16 v[132:135], v[136:139], v[160:163], v[132:135]
	v_mfma_f32_16x16x32_bf16 v[116:119], v[144:147], v[160:163], v[116:119]
	v_mfma_f32_16x16x32_bf16 v[100:103], v[136:139], v[168:171], v[100:103]
	v_mfma_f32_16x16x32_bf16 v[96:99], v[144:147], v[168:171], v[96:99]
	v_mfma_f32_16x16x32_bf16 v[84:87], v[136:139], v[176:179], v[84:87]
	v_mfma_f32_16x16x32_bf16 v[80:83], v[144:147], v[176:179], v[80:83]
	v_mfma_f32_16x16x32_bf16 v[68:71], v[136:139], v[184:187], v[68:71]
	v_mfma_f32_16x16x32_bf16 v[64:67], v[144:147], v[184:187], v[64:67]
	v_mfma_f32_16x16x32_bf16 v[132:135], v[140:143], v[164:167], v[132:135]
	v_mfma_f32_16x16x32_bf16 v[116:119], v[156:159], v[164:167], v[116:119]
	v_mfma_f32_16x16x32_bf16 v[100:103], v[140:143], v[172:175], v[100:103]
	v_mfma_f32_16x16x32_bf16 v[96:99], v[156:159], v[172:175], v[96:99]
	v_mfma_f32_16x16x32_bf16 v[84:87], v[140:143], v[180:183], v[84:87]
	v_mfma_f32_16x16x32_bf16 v[80:83], v[156:159], v[180:183], v[80:83]
	v_mfma_f32_16x16x32_bf16 v[68:71], v[140:143], v[188:191], v[68:71]
	v_mfma_f32_16x16x32_bf16 v[64:67], v[156:159], v[188:191], v[64:67]
	s_barrier
	s_setprio 0
	s_add_i32 s44, s44, s38
	v_lshl_add_u64 v[194:195], s[24:25], 0, v[192:193]
	s_mov_b32 m0, s44
	ds_read_b128 v[160:163], v251 offset:16384
	ds_read_b128 v[164:167], v251 offset:17408
	ds_read_b128 v[168:171], v251 offset:18432
	ds_read_b128 v[172:175], v251 offset:19456
	ds_read_b128 v[176:179], v251 offset:20480
	ds_read_b128 v[180:183], v251 offset:21504
	ds_read_b128 v[184:187], v251 offset:22528
	ds_read_b128 v[188:191], v251 offset:23552
	global_load_lds_dwordx4 v[194:195], off
	s_add_i32 m0, s44, 0x2000
	s_add_u32 s44, s24, 0x40000
	v_lshl_add_u64 v[196:197], s[24:25], 0, v[198:199]
	s_addc_u32 s45, s25, 0
	s_add_i32 s53, s53, s38
	global_load_lds_dwordx4 v[196:197], off
	v_lshl_add_u64 v[208:209], s[44:45], 0, v[192:193]
	s_mov_b32 m0, s53
	v_lshl_add_u64 v[210:211], s[26:27], 0, v[200:201]
	global_load_lds_dwordx4 v[208:209], off
	v_lshl_add_u64 v[208:209], s[44:45], 0, v[198:199]
	s_add_i32 m0, s53, 0x2000
	s_nop 0
	global_load_lds_dwordx4 v[208:209], off
	v_lshl_add_u64 v[208:209], s[26:27], 0, v[202:203]
	s_mov_b32 m0, s39
	s_nop 0
	global_load_lds_dwordx4 v[208:209], off
	s_mov_b32 m0, s46
	s_nop 0
	global_load_lds_dwordx4 v[210:211], off
	s_waitcnt vmcnt(8)
	s_waitcnt lgkmcnt(0)
	s_setprio 1
	s_barrier
	v_mfma_f32_16x16x32_bf16 v[60:63], v[112:115], v[160:163], v[60:63]
	v_mfma_f32_16x16x32_bf16 v[56:59], v[124:127], v[160:163], v[56:59]
	v_mfma_f32_16x16x32_bf16 v[44:47], v[112:115], v[168:171], v[44:47]
	v_mfma_f32_16x16x32_bf16 v[40:43], v[124:127], v[168:171], v[40:43]
	v_mfma_f32_16x16x32_bf16 v[28:31], v[112:115], v[176:179], v[28:31]
	v_mfma_f32_16x16x32_bf16 v[24:27], v[124:127], v[176:179], v[24:27]
	v_mfma_f32_16x16x32_bf16 v[12:15], v[112:115], v[184:187], v[12:15]
	v_mfma_f32_16x16x32_bf16 v[8:11], v[124:127], v[184:187], v[8:11]
	v_mfma_f32_16x16x32_bf16 v[60:63], v[120:123], v[164:167], v[60:63]
	v_mfma_f32_16x16x32_bf16 v[56:59], v[128:131], v[164:167], v[56:59]
	v_mfma_f32_16x16x32_bf16 v[44:47], v[120:123], v[172:175], v[44:47]
	v_mfma_f32_16x16x32_bf16 v[40:43], v[128:131], v[172:175], v[40:43]
	v_mfma_f32_16x16x32_bf16 v[28:31], v[120:123], v[180:183], v[28:31]
	v_mfma_f32_16x16x32_bf16 v[24:27], v[128:131], v[180:183], v[24:27]
	v_mfma_f32_16x16x32_bf16 v[12:15], v[120:123], v[188:191], v[12:15]
	v_mfma_f32_16x16x32_bf16 v[8:11], v[128:131], v[188:191], v[8:11]
	v_mfma_f32_16x16x32_bf16 v[52:55], v[136:139], v[160:163], v[52:55]
	v_mfma_f32_16x16x32_bf16 v[48:51], v[144:147], v[160:163], v[48:51]
	v_mfma_f32_16x16x32_bf16 v[36:39], v[136:139], v[168:171], v[36:39]
	v_mfma_f32_16x16x32_bf16 v[32:35], v[144:147], v[168:171], v[32:35]
	v_mfma_f32_16x16x32_bf16 v[20:23], v[136:139], v[176:179], v[20:23]
	v_mfma_f32_16x16x32_bf16 v[16:19], v[144:147], v[176:179], v[16:19]
	v_mfma_f32_16x16x32_bf16 v[4:7], v[136:139], v[184:187], v[4:7]
	v_mfma_f32_16x16x32_bf16 v[0:3], v[144:147], v[184:187], v[0:3]
	v_mfma_f32_16x16x32_bf16 v[52:55], v[140:143], v[164:167], v[52:55]
	v_mfma_f32_16x16x32_bf16 v[48:51], v[156:159], v[164:167], v[48:51]
	v_mfma_f32_16x16x32_bf16 v[36:39], v[140:143], v[172:175], v[36:39]
	v_mfma_f32_16x16x32_bf16 v[32:35], v[156:159], v[172:175], v[32:35]
	v_mfma_f32_16x16x32_bf16 v[20:23], v[140:143], v[180:183], v[20:23]
	v_mfma_f32_16x16x32_bf16 v[16:19], v[156:159], v[180:183], v[16:19]
	v_mfma_f32_16x16x32_bf16 v[4:7], v[140:143], v[188:191], v[4:7]
	v_mfma_f32_16x16x32_bf16 v[0:3], v[156:159], v[188:191], v[0:3]
	s_barrier
; #define PG8_STAGE(bufoff, gbase, voff) do { _Pragma("unroll") for (int _i = 0; _i < 2; ++_i) \
;         __builtin_amdgcn_global_load_lds((const unsigned*)((const char*)(gbase) + (voff)[_i]), (PG8_LAS unsigned*)(lds + (bufoff) + ldsw + _i * 8192), 16, 0, 0); } while (0)
; #define PG8_LDA(dst, b, h) do { _Pragma("unroll") for (int m = 0; m < 4; ++m) _Pragma("unroll") for (int k = 0; k < 2; ++k) dst[m][k] = *(const PG8_LAS bf16x8*)(lds + PG8_SA(b, h) + aoff + m * 2048 + k * 1024); } while (0)
; #define PG8_LDB(dst, b, h) do { _Pragma("unroll") for (int n = 0; n < 2; ++n) _Pragma("unroll") for (int k = 0; k < 2; ++k) dst[n][k] = *(const PG8_LAS bf16x8*)(lds + PG8_SB(b, h) + boff + n * 2048 + k * 1024); } while (0)
; #define PG8_MMA(ai, bj, At, Bt) do { __builtin_amdgcn_s_setprio(1); _Pragma("unroll") for (int m = 0; m < 4; ++m) _Pragma("unroll") for (int n = 0; n < 2; ++n) _Pragma("unroll") for (int k = 0; k < 2; ++k) \
;         acc[ai][bj][m][n] = __builtin_amdgcn_mfma_f32_16x16x32_bf16(Bt[n][k], At[m][k], acc[ai][bj][m][n], 0, 0, 0); __builtin_amdgcn_s_setprio(0); } while (0)
; #define PG8_BAR __builtin_amdgcn_s_barrier()
; template <class Epi, class Sched, bool ALIGN_EPI = false, bool SP2 = false>
; __device__ __forceinline__ void gemm_phase(PG8_LAS unsigned char* lds, const Gemm g, const Sched& S, const Epi& E, int wave_in) {
;     ...
;             PG8_LDB(B0, 0, 0); PG8_LDB(B1, 0, 1); PG8_SCHED; PG8_LDA(At, 0, 0); PG8_STAGE(PG8_SA(1, 1), a1 + hstep, voffA);
;             PG8_WAIT_V(8); PG8_WAIT_L(0); PG8_BAR; PG8_MMA(0, 0, At, B0); PG8_MMA(0, 1, At, B1); PG8_BAR; PG8_SCHED;
;             PG8_LDA(At, 0, 1); PG8_STAGE(PG8_SB(0, 0), b2, voffB); PG8_STAGE(PG8_SB(0, 1), b2 + hstep, voffB); PG8_STAGE(PG8_SA(0, 0), a2, voffA);
;             PG8_WAIT_V(8); PG8_WAIT_L(0); PG8_BAR; PG8_MMA(1, 0, At, B0); PG8_MMA(1, 1, At, B1); PG8_BAR; PG8_SCHED;
;             PG8_LDB(B0, 1, 0); PG8_LDB(B1, 1, 1); PG8_SCHED; PG8_LDA(At, 1, 0); PG8_STAGE(PG8_SA(0, 1), a2 + hstep, voffA);
;             PG8_WAIT_V(8); PG8_WAIT_L(0); PG8_BAR; PG8_MMA(0, 0, At, B0); PG8_MMA(0, 1, At, B1); PG8_BAR; PG8_SCHED;
;             PG8_LDA(At, 1, 1); PG8_STAGE(PG8_SB(1, 0), b3, voffB); PG8_STAGE(PG8_SB(1, 1), b3 + hstep, voffB); PG8_STAGE(PG8_SA(1, 0), a3, voffA);
;             PG8_WAIT_V(8); PG8_WAIT_L(0); PG8_BAR; PG8_MMA(1, 0, At, B0); PG8_MMA(1, 1, At, B1); PG8_BAR; PG8_SCHED;
	s_setprio 0
	s_add_i32 s44, s65, 0x100
	s_add_i32 s45, s52, 0x100
	v_add_u32_e32 v128, s44, v249
	v_add_u32_e32 v156, s45, v249
	ds_read_b128 v[112:115], v128
	ds_read_b128 v[120:123], v128 offset:1024
	ds_read_b128 v[124:127], v128 offset:2048
	ds_read_b128 v[128:131], v128 offset:3072
	ds_read_b128 v[136:139], v156
	ds_read_b128 v[140:143], v156 offset:1024
	ds_read_b128 v[144:147], v156 offset:2048
	ds_read_b128 v[156:159], v156 offset:3072
	s_add_u32 s26, s26, 0x40000
	s_addc_u32 s27, s27, 0
	s_mov_b32 m0, s47
	v_lshl_add_u64 v[212:213], s[26:27], 0, v[202:203]
	ds_read_b128 v[160:163], v251 offset:32768
	ds_read_b128 v[164:167], v251 offset:33792
	ds_read_b128 v[168:171], v251 offset:34816
	ds_read_b128 v[172:175], v251 offset:35840
	ds_read_b128 v[176:179], v251 offset:36864
	ds_read_b128 v[180:183], v251 offset:37888
	ds_read_b128 v[184:187], v251 offset:38912
	ds_read_b128 v[188:191], v251 offset:39936
	global_load_lds_dwordx4 v[212:213], off
	v_lshl_add_u64 v[212:213], s[26:27], 0, v[200:201]
	s_mov_b32 m0, s60
	s_nop 0
	global_load_lds_dwordx4 v[212:213], off
	s_waitcnt vmcnt(8)
	s_waitcnt lgkmcnt(0)
	s_setprio 1
	s_barrier
	v_mfma_f32_16x16x32_bf16 v[152:155], v[112:115], v[160:163], v[152:155]
	v_mfma_f32_16x16x32_bf16 v[148:151], v[124:127], v[160:163], v[148:151]
	v_mfma_f32_16x16x32_bf16 v[108:111], v[112:115], v[168:171], v[108:111]
	v_mfma_f32_16x16x32_bf16 v[104:107], v[124:127], v[168:171], v[104:107]
	v_mfma_f32_16x16x32_bf16 v[92:95], v[112:115], v[176:179], v[92:95]
	v_mfma_f32_16x16x32_bf16 v[88:91], v[124:127], v[176:179], v[88:91]
	v_mfma_f32_16x16x32_bf16 v[76:79], v[112:115], v[184:187], v[76:79]
	v_mfma_f32_16x16x32_bf16 v[72:75], v[124:127], v[184:187], v[72:75]
	v_mfma_f32_16x16x32_bf16 v[152:155], v[120:123], v[164:167], v[152:155]
	v_mfma_f32_16x16x32_bf16 v[148:151], v[128:131], v[164:167], v[148:151]
	v_mfma_f32_16x16x32_bf16 v[108:111], v[120:123], v[172:175], v[108:111]
	v_mfma_f32_16x16x32_bf16 v[104:107], v[128:131], v[172:175], v[104:107]
	v_mfma_f32_16x16x32_bf16 v[92:95], v[120:123], v[180:183], v[92:95]
	v_mfma_f32_16x16x32_bf16 v[88:91], v[128:131], v[180:183], v[88:91]
	v_mfma_f32_16x16x32_bf16 v[76:79], v[120:123], v[188:191], v[76:79]
	v_mfma_f32_16x16x32_bf16 v[72:75], v[128:131], v[188:191], v[72:75]
	v_mfma_f32_16x16x32_bf16 v[132:135], v[136:139], v[160:163], v[132:135]
	v_mfma_f32_16x16x32_bf16 v[116:119], v[144:147], v[160:163], v[116:119]
	v_mfma_f32_16x16x32_bf16 v[100:103], v[136:139], v[168:171], v[100:103]
	v_mfma_f32_16x16x32_bf16 v[96:99], v[144:147], v[168:171], v[96:99]
	v_mfma_f32_16x16x32_bf16 v[84:87], v[136:139], v[176:179], v[84:87]
	v_mfma_f32_16x16x32_bf16 v[80:83], v[144:147], v[176:179], v[80:83]
	v_mfma_f32_16x16x32_bf16 v[68:71], v[136:139], v[184:187], v[68:71]
	v_mfma_f32_16x16x32_bf16 v[64:67], v[144:147], v[184:187], v[64:67]
	v_mfma_f32_16x16x32_bf16 v[132:135], v[140:143], v[164:167], v[132:135]
	v_mfma_f32_16x16x32_bf16 v[116:119], v[156:159], v[164:167], v[116:119]
	v_mfma_f32_16x16x32_bf16 v[100:103], v[140:143], v[172:175], v[100:103]
	v_mfma_f32_16x16x32_bf16 v[96:99], v[156:159], v[172:175], v[96:99]
	v_mfma_f32_16x16x32_bf16 v[84:87], v[140:143], v[180:183], v[84:87]
	v_mfma_f32_16x16x32_bf16 v[80:83], v[156:159], v[180:183], v[80:83]
	v_mfma_f32_16x16x32_bf16 v[68:71], v[140:143], v[188:191], v[68:71]
	v_mfma_f32_16x16x32_bf16 v[64:67], v[156:159], v[188:191], v[64:67]
	s_barrier
; #define PG8_STAGE(bufoff, gbase, voff) do { _Pragma("unroll") for (int _i = 0; _i < 2; ++_i) \
;         __builtin_amdgcn_global_load_lds((const unsigned*)((const char*)(gbase) + (voff)[_i]), (PG8_LAS unsigned*)(lds + (bufoff) + ldsw + _i * 8192), 16, 0, 0); } while (0)
; #define PG8_LDA(dst, b, h) do { _Pragma("unroll") for (int m = 0; m < 4; ++m) _Pragma("unroll") for (int k = 0; k < 2; ++k) dst[m][k] = *(const PG8_LAS bf16x8*)(lds + PG8_SA(b, h) + aoff + m * 2048 + k * 1024); } while (0)
; #define PG8_WAIT_V(n) asm volatile("s_waitcnt vmcnt(" #n ")" ::: "memory")
; #define PG8_WAIT_L(n) asm volatile("s_waitcnt lgkmcnt(" #n ")" ::: "memory")
; #define PG8_BAR __builtin_amdgcn_s_barrier()
; template <class Epi, class Sched, bool ALIGN_EPI = false, bool SP2 = false>
; __device__ __forceinline__ void gemm_phase(PG8_LAS unsigned char* lds, const Gemm g, const Sched& S, const Epi& E, int wave_in) {
;     ...
;         for (int t = 0; t < nt; t += 2) {
;             const bool last = (t == nt - 2);
;             const char* a1 = cA + (size_t)(t + 1) * kstep;
;             const char* a2 = last ? nA : cA + (size_t)(t + 2) * kstep; const char* b2 = last ? nB : cB + (size_t)(t + 2) * kstep;
;             const char* a3 = a2 + kstep; const char* b3 = b2 + kstep;
;             if (last && has_next) S.a_ready(nxt);
;             if constexpr (SP2) {
;             PG8_LDB(B0, 0, 0); PG8_LDB(B1, 0, 1); PG8_SCHED; PG8_LDA(At, 0, 0); PG8_STAGE(PG8_SA(1, 1), a1 + hstep, voffA);
;             PG8_WAIT_V(8); PG8_WAIT_L(0); PG8_BAR; PG8_MMA(0, 0, At, B0); PG8_MMA(0, 1, At, B1); PG8_BAR; PG8_SCHED;
;             PG8_LDA(At, 0, 1); PG8_STAGE(PG8_SB(0, 0), b2, voffB); PG8_STAGE(PG8_SB(0, 1), b2 + hstep, voffB); PG8_STAGE(PG8_SA(0, 0), a2, voffA);
;             PG8_WAIT_V(8); PG8_WAIT_L(0); PG8_BAR; PG8_MMA(1, 0, At, B0); PG8_MMA(1, 1, At, B1); PG8_BAR; PG8_SCHED;
;             PG8_LDB(B0, 1, 0); PG8_LDB(B1, 1, 1); PG8_SCHED; PG8_LDA(At, 1, 0); PG8_STAGE(PG8_SA(0, 1), a2 + hstep, voffA);
;             PG8_WAIT_V(8); PG8_WAIT_L(0); PG8_BAR; PG8_MMA(0, 0, At, B0); PG8_MMA(0, 1, At, B1); PG8_BAR; PG8_SCHED;
;             PG8_LDA(At, 1, 1); PG8_STAGE(PG8_SB(1, 0), b3, voffB); PG8_STAGE(PG8_SB(1, 1), b3 + hstep, voffB); PG8_STAGE(PG8_SA(1, 0), a3, voffA);
;             PG8_WAIT_V(8); PG8_WAIT_L(0); PG8_BAR; PG8_MMA(1, 0, At, B0); PG8_MMA(1, 1, At, B1); PG8_BAR; PG8_SCHED;
	s_setprio 0
	s_add_i32 s26, s44, s38
	v_lshl_add_u64 v[194:195], v[194:195], 0, s[88:89]
	s_mov_b32 m0, s26
	ds_read_b128 v[160:163], v251 offset:49152
	ds_read_b128 v[164:167], v251 offset:50176
	ds_read_b128 v[168:171], v251 offset:51200
	ds_read_b128 v[172:175], v251 offset:52224
	ds_read_b128 v[176:179], v251 offset:53248
	ds_read_b128 v[180:183], v251 offset:54272
	ds_read_b128 v[184:187], v251 offset:55296
	ds_read_b128 v[188:191], v251 offset:56320
	global_load_lds_dwordx4 v[194:195], off
	s_add_i32 m0, s26, 0x2000
	s_add_u32 s24, s24, 0x40080
	v_lshl_add_u64 v[194:195], v[196:197], 0, s[88:89]
	s_addc_u32 s25, s25, 0
	s_add_i32 s26, s45, s38
	global_load_lds_dwordx4 v[194:195], off
	v_lshl_add_u64 v[194:195], s[24:25], 0, v[192:193]
	s_mov_b32 m0, s26
	s_nop 0
	global_load_lds_dwordx4 v[194:195], off
	v_lshl_add_u64 v[194:195], s[24:25], 0, v[198:199]
	s_add_i32 m0, s26, 0x2000
	s_nop 0
	global_load_lds_dwordx4 v[194:195], off
	v_lshl_add_u64 v[194:195], v[208:209], 0, s[88:89]
	s_mov_b32 m0, s62
	s_nop 0
	global_load_lds_dwordx4 v[194:195], off
	v_lshl_add_u64 v[194:195], v[210:211], 0, s[88:89]
	s_mov_b32 m0, s63
	s_nop 0
	global_load_lds_dwordx4 v[194:195], off
	s_waitcnt vmcnt(8)
	s_waitcnt lgkmcnt(0)
	s_setprio 1
	s_barrier
	v_mfma_f32_16x16x32_bf16 v[60:63], v[112:115], v[160:163], v[60:63]
	v_mfma_f32_16x16x32_bf16 v[56:59], v[124:127], v[160:163], v[56:59]
	v_mfma_f32_16x16x32_bf16 v[44:47], v[112:115], v[168:171], v[44:47]
	v_mfma_f32_16x16x32_bf16 v[40:43], v[124:127], v[168:171], v[40:43]
	v_mfma_f32_16x16x32_bf16 v[28:31], v[112:115], v[176:179], v[28:31]
	v_mfma_f32_16x16x32_bf16 v[24:27], v[124:127], v[176:179], v[24:27]
	v_mfma_f32_16x16x32_bf16 v[12:15], v[112:115], v[184:187], v[12:15]
	v_mfma_f32_16x16x32_bf16 v[8:11], v[124:127], v[184:187], v[8:11]
	v_mfma_f32_16x16x32_bf16 v[60:63], v[120:123], v[164:167], v[60:63]
	v_mfma_f32_16x16x32_bf16 v[56:59], v[128:131], v[164:167], v[56:59]
	v_mfma_f32_16x16x32_bf16 v[44:47], v[120:123], v[172:175], v[44:47]
	v_mfma_f32_16x16x32_bf16 v[40:43], v[128:131], v[172:175], v[40:43]
	v_mfma_f32_16x16x32_bf16 v[28:31], v[120:123], v[180:183], v[28:31]
	v_mfma_f32_16x16x32_bf16 v[24:27], v[128:131], v[180:183], v[24:27]
	v_mfma_f32_16x16x32_bf16 v[12:15], v[120:123], v[188:191], v[12:15]
	v_mfma_f32_16x16x32_bf16 v[8:11], v[128:131], v[188:191], v[8:11]
	v_mfma_f32_16x16x32_bf16 v[52:55], v[136:139], v[160:163], v[52:55]
	v_mfma_f32_16x16x32_bf16 v[48:51], v[144:147], v[160:163], v[48:51]
	v_mfma_f32_16x16x32_bf16 v[36:39], v[136:139], v[168:171], v[36:39]
	v_mfma_f32_16x16x32_bf16 v[32:35], v[144:147], v[168:171], v[32:35]
	v_mfma_f32_16x16x32_bf16 v[20:23], v[136:139], v[176:179], v[20:23]
	v_mfma_f32_16x16x32_bf16 v[16:19], v[144:147], v[176:179], v[16:19]
	v_mfma_f32_16x16x32_bf16 v[4:7], v[136:139], v[184:187], v[4:7]
	v_mfma_f32_16x16x32_bf16 v[0:3], v[144:147], v[184:187], v[0:3]
	v_mfma_f32_16x16x32_bf16 v[52:55], v[140:143], v[164:167], v[52:55]
	v_mfma_f32_16x16x32_bf16 v[48:51], v[156:159], v[164:167], v[48:51]
	v_mfma_f32_16x16x32_bf16 v[36:39], v[140:143], v[172:175], v[36:39]
	v_mfma_f32_16x16x32_bf16 v[32:35], v[156:159], v[172:175], v[32:35]
	v_mfma_f32_16x16x32_bf16 v[20:23], v[140:143], v[180:183], v[20:23]
	v_mfma_f32_16x16x32_bf16 v[16:19], v[156:159], v[180:183], v[16:19]
	v_mfma_f32_16x16x32_bf16 v[4:7], v[140:143], v[188:191], v[4:7]
	v_mfma_f32_16x16x32_bf16 v[0:3], v[156:159], v[188:191], v[0:3]
	s_barrier
	s_setprio 0
	s_add_i32 s34, s34, 2
	s_add_u32 s15, s15, 0x100
	s_addc_u32 s17, s17, 0
	s_add_u32 s22, s22, 0x100
	s_addc_u32 s23, s23, 0
	s_cmp_gt_u32 s34, 13
	s_cbranch_scc0 .LBB0_804

; #define PG8_STAGE(bufoff, gbase, voff) do { _Pragma("unroll") for (int _i = 0; _i < 2; ++_i) \
;         __builtin_amdgcn_global_load_lds((const unsigned*)((const char*)(gbase) + (voff)[_i]), (PG8_LAS unsigned*)(lds + (bufoff) + ldsw + _i * 8192), 16, 0, 0); } while (0)
; #define PG8_WAIT_V(n) asm volatile("s_waitcnt vmcnt(" #n ")" ::: "memory")
; #define PG8_WAIT_L(n) asm volatile("s_waitcnt lgkmcnt(" #n ")" ::: "memory")
; #define PG8_BAR __builtin_amdgcn_s_barrier()
; template <class Epi, class Sched, bool ALIGN_EPI = false, bool SP2 = false>
; __device__ __forceinline__ void gemm_phase(PG8_LAS unsigned char* lds, const Gemm g, const Sched& S, const Epi& E, int wave_in) {
;     ...
;         const char* nA = has_next ? (const char*)g.A + (size_t)(nxt.pm >> g.ash) * g.astride + (size_t)nxt.pm * tstep : cA; const char* nB = has_next ? (const char*)g.Bt + (size_t)(nxt.pm >> g.bsh) * g.bstride + (size_t)nxt.pn * tstep : cB;
;         for (int t = 0; t < nt; t += 2) {
;             const bool last = (t == nt - 2);
;             const char* a1 = cA + (size_t)(t + 1) * kstep;
;             const char* a2 = last ? nA : cA + (size_t)(t + 2) * kstep; const char* b2 = last ? nB : cB + (size_t)(t + 2) * kstep;
;             const char* a3 = a2 + kstep; const char* b3 = b2 + kstep;
;             if (last && has_next) S.a_ready(nxt);
;             if constexpr (SP2) {
;             PG8_LDB(B0, 0, 0); PG8_LDB(B1, 0, 1); PG8_SCHED; PG8_LDA(At, 0, 0); PG8_STAGE(PG8_SA(1, 1), a1 + hstep, voffA);
;             PG8_WAIT_V(8); PG8_WAIT_L(0); PG8_BAR; PG8_MMA(0, 0, At, B0); PG8_MMA(0, 1, At, B1); PG8_BAR; PG8_SCHED;
;             PG8_LDA(At, 0, 1); PG8_STAGE(PG8_SB(0, 0), b2, voffB); PG8_STAGE(PG8_SB(0, 1), b2 + hstep, voffB); PG8_STAGE(PG8_SA(0, 0), a2, voffA);
;             PG8_WAIT_V(8); PG8_WAIT_L(0); PG8_BAR; PG8_MMA(1, 0, At, B0); PG8_MMA(1, 1, At, B1); PG8_BAR; PG8_SCHED;
;             PG8_LDB(B0, 1, 0); PG8_LDB(B1, 1, 1); PG8_SCHED; PG8_LDA(At, 1, 0); PG8_STAGE(PG8_SA(0, 1), a2 + hstep, voffA);
;             PG8_WAIT_V(8); PG8_WAIT_L(0); PG8_BAR; PG8_MMA(0, 0, At, B0); PG8_MMA(0, 1, At, B1); PG8_BAR; PG8_SCHED;
;             PG8_LDA(At, 1, 1); PG8_STAGE(PG8_SB(1, 0), b3, voffB); PG8_STAGE(PG8_SB(1, 1), b3 + hstep, voffB); PG8_STAGE(PG8_SA(1, 0), a3, voffA);
;             PG8_WAIT_V(8); PG8_WAIT_L(0); PG8_BAR; PG8_MMA(1, 0, At, B0); PG8_MMA(1, 1, At, B1); PG8_BAR; PG8_SCHED;
.LBB0_896:
	s_ashr_i32 s11, s10, 31
	s_lshl_b64 s[18:19], s[10:11], 19
	s_add_u32 s66, s6, s18
	s_addc_u32 s67, s72, s19
	s_and_b64 s[18:19], s[46:47], exec
	s_cselect_b32 s11, s67, s1
	s_cselect_b32 s34, s66, s0
	s_ashr_i32 s5, s4, 31
	s_lshl_b64 s[18:19], s[4:5], 19
	s_add_u32 s38, s73, s18
	s_addc_u32 s39, s74, s19
	s_and_b64 s[18:19], s[46:47], exec
	s_cselect_b32 s5, s39, s79
	s_cselect_b32 s53, s38, s78
	s_add_u32 s81, s78, 0x100
	s_addc_u32 s18, s79, 0
	s_add_u32 vcc_lo, s0, 0x40080
	s_addc_u32 vcc_hi, s1, 0
	s_mov_b32 s19, -2
	s_add_u32 s0, vcc_lo, 0xfffc0080
	s_addc_u32 s1, vcc_hi, -1
	s_add_i32 s76, s35, 0x100
	s_cmp_eq_u32 s19, 12
	s_cselect_b32 s79, s11, s1
	s_cselect_b32 s78, s34, s0
	s_cselect_b32 s1, s5, s18
	s_cselect_b32 s0, s53, s81
	s_add_i32 s29, s90, 0x100
	v_add_u32_e32 v140, s76, v207
	v_add_u32_e32 v156, s29, v207
	ds_read_b128 v[128:131], v140
	ds_read_b128 v[132:135], v140 offset:1024
	ds_read_b128 v[136:139], v140 offset:2048
	ds_read_b128 v[140:143], v140 offset:3072
	ds_read_b128 v[144:147], v156
	ds_read_b128 v[148:151], v156 offset:1024
	ds_read_b128 v[152:155], v156 offset:2048
	ds_read_b128 v[156:159], v156 offset:3072
	v_lshl_add_u64 v[190:191], vcc, 0, v[176:177]
	s_add_i32 m0, s33, 0xc000
	ds_read_b128 v[160:163], v219
	ds_read_b128 v[164:167], v219 offset:1024
	ds_read_b128 v[178:181], v219 offset:2048
	ds_read_b128 v[182:185], v219 offset:3072
	ds_read_b128 v[186:189], v219 offset:4096
	ds_read_b128 v[198:201], v219 offset:5120
	ds_read_b128 v[202:205], v219 offset:6144
	ds_read_b128 v[220:223], v219 offset:7168
	global_load_lds_dwordx4 v[190:191], off
	v_lshl_add_u64 v[190:191], vcc, 0, v[174:175]
	s_add_i32 m0, s33, 0xe000
	s_nop 0
	global_load_lds_dwordx4 v[190:191], off
	s_waitcnt vmcnt(8)
	s_waitcnt lgkmcnt(0)
	s_setprio 1
	s_barrier
	v_mfma_f32_16x16x32_bf16 v[124:127], v[128:131], v[160:163], 0
	v_mfma_f32_16x16x32_bf16 v[60:63], v[136:139], v[160:163], 0
	v_mfma_f32_16x16x32_bf16 v[116:119], v[128:131], v[178:181], 0
	v_mfma_f32_16x16x32_bf16 v[52:55], v[136:139], v[178:181], 0
	v_mfma_f32_16x16x32_bf16 v[108:111], v[128:131], v[186:189], 0
	v_mfma_f32_16x16x32_bf16 v[44:47], v[136:139], v[186:189], 0
	v_mfma_f32_16x16x32_bf16 v[100:103], v[128:131], v[202:205], 0
	v_mfma_f32_16x16x32_bf16 v[36:39], v[136:139], v[202:205], 0
	v_mfma_f32_16x16x32_bf16 v[124:127], v[132:135], v[164:167], v[124:127]
	v_mfma_f32_16x16x32_bf16 v[60:63], v[140:143], v[164:167], v[60:63]
	v_mfma_f32_16x16x32_bf16 v[116:119], v[132:135], v[182:185], v[116:119]
	v_mfma_f32_16x16x32_bf16 v[52:55], v[140:143], v[182:185], v[52:55]
	v_mfma_f32_16x16x32_bf16 v[108:111], v[132:135], v[198:201], v[108:111]
	v_mfma_f32_16x16x32_bf16 v[44:47], v[140:143], v[198:201], v[44:47]
	v_mfma_f32_16x16x32_bf16 v[100:103], v[132:135], v[220:223], v[100:103]
	v_mfma_f32_16x16x32_bf16 v[36:39], v[140:143], v[220:223], v[36:39]
	v_mfma_f32_16x16x32_bf16 v[120:123], v[144:147], v[160:163], 0
	v_mfma_f32_16x16x32_bf16 v[56:59], v[152:155], v[160:163], 0
	v_mfma_f32_16x16x32_bf16 v[112:115], v[144:147], v[178:181], 0
	v_mfma_f32_16x16x32_bf16 v[48:51], v[152:155], v[178:181], 0
	v_mfma_f32_16x16x32_bf16 v[104:107], v[144:147], v[186:189], 0
	v_mfma_f32_16x16x32_bf16 v[40:43], v[152:155], v[186:189], 0
	v_mfma_f32_16x16x32_bf16 v[96:99], v[144:147], v[202:205], 0
	v_mfma_f32_16x16x32_bf16 v[32:35], v[152:155], v[202:205], 0
	v_mfma_f32_16x16x32_bf16 v[120:123], v[148:151], v[164:167], v[120:123]
	v_mfma_f32_16x16x32_bf16 v[56:59], v[156:159], v[164:167], v[56:59]
	v_mfma_f32_16x16x32_bf16 v[112:115], v[148:151], v[182:185], v[112:115]
	v_mfma_f32_16x16x32_bf16 v[48:51], v[156:159], v[182:185], v[48:51]
	v_mfma_f32_16x16x32_bf16 v[104:107], v[148:151], v[198:201], v[104:107]
	v_mfma_f32_16x16x32_bf16 v[40:43], v[156:159], v[198:201], v[40:43]
	v_mfma_f32_16x16x32_bf16 v[96:99], v[148:151], v[220:223], v[96:99]
	v_mfma_f32_16x16x32_bf16 v[32:35], v[156:159], v[220:223], v[32:35]
	s_barrier
	s_setprio 0
	s_add_i32 s76, s76, s75
	v_lshl_add_u64 v[190:191], s[0:1], 0, v[192:193]
	s_mov_b32 m0, s76
	ds_read_b128 v[160:163], v219 offset:16384
	ds_read_b128 v[164:167], v219 offset:17408
	ds_read_b128 v[178:181], v219 offset:18432
	ds_read_b128 v[182:185], v219 offset:19456
	ds_read_b128 v[186:189], v219 offset:20480
	ds_read_b128 v[198:201], v219 offset:21504
	ds_read_b128 v[202:205], v219 offset:22528
	ds_read_b128 v[220:223], v219 offset:23552
	global_load_lds_dwordx4 v[190:191], off
	s_add_i32 m0, s76, 0x2000
	s_add_u32 s76, s0, 0x40000
	v_lshl_add_u64 v[194:195], s[0:1], 0, v[168:169]
	s_addc_u32 s77, s1, 0
	s_add_i32 s29, s29, s75
	global_load_lds_dwordx4 v[194:195], off
	v_lshl_add_u64 v[196:197], s[76:77], 0, v[192:193]
	s_mov_b32 m0, s29
	v_lshl_add_u64 v[224:225], s[78:79], 0, v[170:171]
	global_load_lds_dwordx4 v[196:197], off
	v_lshl_add_u64 v[196:197], s[76:77], 0, v[168:169]
	s_add_i32 m0, s29, 0x2000
	s_nop 0
	global_load_lds_dwordx4 v[196:197], off
	v_lshl_add_u64 v[196:197], s[78:79], 0, v[172:173]
	s_mov_b32 m0, s33
	s_nop 0
	global_load_lds_dwordx4 v[196:197], off
	s_mov_b32 m0, s62
	s_nop 0
	global_load_lds_dwordx4 v[224:225], off
	s_waitcnt vmcnt(8)
	s_waitcnt lgkmcnt(0)
	s_setprio 1
	s_barrier
; #define PG8_STAGE(bufoff, gbase, voff) do { _Pragma("unroll") for (int _i = 0; _i < 2; ++_i) \
;         __builtin_amdgcn_global_load_lds((const unsigned*)((const char*)(gbase) + (voff)[_i]), (PG8_LAS unsigned*)(lds + (bufoff) + ldsw + _i * 8192), 16, 0, 0); } while (0)
; #define PG8_LDA(dst, b, h) do { _Pragma("unroll") for (int m = 0; m < 4; ++m) _Pragma("unroll") for (int k = 0; k < 2; ++k) dst[m][k] = *(const PG8_LAS bf16x8*)(lds + PG8_SA(b, h) + aoff + m * 2048 + k * 1024); } while (0)
; #define PG8_LDB(dst, b, h) do { _Pragma("unroll") for (int n = 0; n < 2; ++n) _Pragma("unroll") for (int k = 0; k < 2; ++k) dst[n][k] = *(const PG8_LAS bf16x8*)(lds + PG8_SB(b, h) + boff + n * 2048 + k * 1024); } while (0)
; #define PG8_MMA(ai, bj, At, Bt) do { __builtin_amdgcn_s_setprio(1); _Pragma("unroll") for (int m = 0; m < 4; ++m) _Pragma("unroll") for (int n = 0; n < 2; ++n) _Pragma("unroll") for (int k = 0; k < 2; ++k) \
;         acc[ai][bj][m][n] = __builtin_amdgcn_mfma_f32_16x16x32_bf16(Bt[n][k], At[m][k], acc[ai][bj][m][n], 0, 0, 0); __builtin_amdgcn_s_setprio(0); } while (0)
; #define PG8_BAR __builtin_amdgcn_s_barrier()
; template <class Epi, class Sched, bool ALIGN_EPI = false, bool SP2 = false>
; __device__ __forceinline__ void gemm_phase(PG8_LAS unsigned char* lds, const Gemm g, const Sched& S, const Epi& E, int wave_in) {
;     ...
;             PG8_LDB(B0, 0, 0); PG8_LDB(B1, 0, 1); PG8_SCHED; PG8_LDA(At, 0, 0); PG8_STAGE(PG8_SA(1, 1), a1 + hstep, voffA);
;             PG8_WAIT_V(8); PG8_WAIT_L(0); PG8_BAR; PG8_MMA(0, 0, At, B0); PG8_MMA(0, 1, At, B1); PG8_BAR; PG8_SCHED;
;             PG8_LDA(At, 0, 1); PG8_STAGE(PG8_SB(0, 0), b2, voffB); PG8_STAGE(PG8_SB(0, 1), b2 + hstep, voffB); PG8_STAGE(PG8_SA(0, 0), a2, voffA);
;             PG8_WAIT_V(8); PG8_WAIT_L(0); PG8_BAR; PG8_MMA(1, 0, At, B0); PG8_MMA(1, 1, At, B1); PG8_BAR; PG8_SCHED;
;             PG8_LDB(B0, 1, 0); PG8_LDB(B1, 1, 1); PG8_SCHED; PG8_LDA(At, 1, 0); PG8_STAGE(PG8_SA(0, 1), a2 + hstep, voffA);
;             PG8_WAIT_V(8); PG8_WAIT_L(0); PG8_BAR; PG8_MMA(0, 0, At, B0); PG8_MMA(0, 1, At, B1); PG8_BAR; PG8_SCHED;
;             PG8_LDA(At, 1, 1); PG8_STAGE(PG8_SB(1, 0), b3, voffB); PG8_STAGE(PG8_SB(1, 1), b3 + hstep, voffB); PG8_STAGE(PG8_SA(1, 0), a3, voffA);
;             PG8_WAIT_V(8); PG8_WAIT_L(0); PG8_BAR; PG8_MMA(1, 0, At, B0); PG8_MMA(1, 1, At, B1); PG8_BAR; PG8_SCHED;
	v_mfma_f32_16x16x32_bf16 v[92:95], v[128:131], v[160:163], 0
	v_mfma_f32_16x16x32_bf16 v[28:31], v[136:139], v[160:163], 0
	v_mfma_f32_16x16x32_bf16 v[84:87], v[128:131], v[178:181], 0
	v_mfma_f32_16x16x32_bf16 v[20:23], v[136:139], v[178:181], 0
	v_mfma_f32_16x16x32_bf16 v[76:79], v[128:131], v[186:189], 0
	v_mfma_f32_16x16x32_bf16 v[12:15], v[136:139], v[186:189], 0
	v_mfma_f32_16x16x32_bf16 v[68:71], v[128:131], v[202:205], 0
	v_mfma_f32_16x16x32_bf16 v[4:7], v[136:139], v[202:205], 0
	v_mfma_f32_16x16x32_bf16 v[92:95], v[132:135], v[164:167], v[92:95]
	v_mfma_f32_16x16x32_bf16 v[28:31], v[140:143], v[164:167], v[28:31]
	v_mfma_f32_16x16x32_bf16 v[84:87], v[132:135], v[182:185], v[84:87]
	v_mfma_f32_16x16x32_bf16 v[20:23], v[140:143], v[182:185], v[20:23]
	v_mfma_f32_16x16x32_bf16 v[76:79], v[132:135], v[198:201], v[76:79]
	v_mfma_f32_16x16x32_bf16 v[12:15], v[140:143], v[198:201], v[12:15]
	v_mfma_f32_16x16x32_bf16 v[68:71], v[132:135], v[220:223], v[68:71]
	v_mfma_f32_16x16x32_bf16 v[4:7], v[140:143], v[220:223], v[4:7]
	v_mfma_f32_16x16x32_bf16 v[88:91], v[144:147], v[160:163], 0
	v_mfma_f32_16x16x32_bf16 v[24:27], v[152:155], v[160:163], 0
	v_mfma_f32_16x16x32_bf16 v[80:83], v[144:147], v[178:181], 0
	v_mfma_f32_16x16x32_bf16 v[16:19], v[152:155], v[178:181], 0
	v_mfma_f32_16x16x32_bf16 v[72:75], v[144:147], v[186:189], 0
	v_mfma_f32_16x16x32_bf16 v[8:11], v[152:155], v[186:189], 0
	v_mfma_f32_16x16x32_bf16 v[64:67], v[144:147], v[202:205], 0
	v_mfma_f32_16x16x32_bf16 v[0:3], v[152:155], v[202:205], 0
	v_mfma_f32_16x16x32_bf16 v[88:91], v[148:151], v[164:167], v[88:91]
	v_mfma_f32_16x16x32_bf16 v[24:27], v[156:159], v[164:167], v[24:27]
	v_mfma_f32_16x16x32_bf16 v[80:83], v[148:151], v[182:185], v[80:83]
	v_mfma_f32_16x16x32_bf16 v[16:19], v[156:159], v[182:185], v[16:19]
	v_mfma_f32_16x16x32_bf16 v[72:75], v[148:151], v[198:201], v[72:75]
	v_mfma_f32_16x16x32_bf16 v[8:11], v[156:159], v[198:201], v[8:11]
	v_mfma_f32_16x16x32_bf16 v[64:67], v[148:151], v[220:223], v[64:67]
	v_mfma_f32_16x16x32_bf16 v[0:3], v[156:159], v[220:223], v[0:3]
	s_barrier
	s_setprio 0
	s_add_i32 s29, s65, 0x100
	s_add_i32 s2, s52, 0x100
	v_add_u32_e32 v140, s29, v207
	v_add_u32_e32 v156, s2, v207
	ds_read_b128 v[128:131], v140
	ds_read_b128 v[132:135], v140 offset:1024
	ds_read_b128 v[136:139], v140 offset:2048
	ds_read_b128 v[140:143], v140 offset:3072
	ds_read_b128 v[144:147], v156
	ds_read_b128 v[148:151], v156 offset:1024
	ds_read_b128 v[152:155], v156 offset:2048
	ds_read_b128 v[156:159], v156 offset:3072
	s_add_u32 s76, s78, 0x40000
	s_addc_u32 s77, s79, 0
	s_mov_b32 m0, s63
	v_lshl_add_u64 v[226:227], s[76:77], 0, v[172:173]
	ds_read_b128 v[160:163], v219 offset:32768
	ds_read_b128 v[164:167], v219 offset:33792
	ds_read_b128 v[178:181], v219 offset:34816
	ds_read_b128 v[182:185], v219 offset:35840
	ds_read_b128 v[186:189], v219 offset:36864
	ds_read_b128 v[198:201], v219 offset:37888
	ds_read_b128 v[202:205], v219 offset:38912
	ds_read_b128 v[220:223], v219 offset:39936
	global_load_lds_dwordx4 v[226:227], off
	v_lshl_add_u64 v[226:227], s[76:77], 0, v[170:171]
	s_mov_b32 m0, s31
	s_nop 0
	global_load_lds_dwordx4 v[226:227], off
	s_waitcnt vmcnt(8)
	s_waitcnt lgkmcnt(0)
	s_setprio 1
	s_barrier
	v_mfma_f32_16x16x32_bf16 v[124:127], v[128:131], v[160:163], v[124:127]
	v_mfma_f32_16x16x32_bf16 v[60:63], v[136:139], v[160:163], v[60:63]
	v_mfma_f32_16x16x32_bf16 v[116:119], v[128:131], v[178:181], v[116:119]
	v_mfma_f32_16x16x32_bf16 v[52:55], v[136:139], v[178:181], v[52:55]
	v_mfma_f32_16x16x32_bf16 v[108:111], v[128:131], v[186:189], v[108:111]
	v_mfma_f32_16x16x32_bf16 v[44:47], v[136:139], v[186:189], v[44:47]
	v_mfma_f32_16x16x32_bf16 v[100:103], v[128:131], v[202:205], v[100:103]
	v_mfma_f32_16x16x32_bf16 v[36:39], v[136:139], v[202:205], v[36:39]
	v_mfma_f32_16x16x32_bf16 v[124:127], v[132:135], v[164:167], v[124:127]
	v_mfma_f32_16x16x32_bf16 v[60:63], v[140:143], v[164:167], v[60:63]
	v_mfma_f32_16x16x32_bf16 v[116:119], v[132:135], v[182:185], v[116:119]
	v_mfma_f32_16x16x32_bf16 v[52:55], v[140:143], v[182:185], v[52:55]
	v_mfma_f32_16x16x32_bf16 v[108:111], v[132:135], v[198:201], v[108:111]
	v_mfma_f32_16x16x32_bf16 v[44:47], v[140:143], v[198:201], v[44:47]
	v_mfma_f32_16x16x32_bf16 v[100:103], v[132:135], v[220:223], v[100:103]
	v_mfma_f32_16x16x32_bf16 v[36:39], v[140:143], v[220:223], v[36:39]
	v_mfma_f32_16x16x32_bf16 v[120:123], v[144:147], v[160:163], v[120:123]
	v_mfma_f32_16x16x32_bf16 v[56:59], v[152:155], v[160:163], v[56:59]
	v_mfma_f32_16x16x32_bf16 v[112:115], v[144:147], v[178:181], v[112:115]
	v_mfma_f32_16x16x32_bf16 v[48:51], v[152:155], v[178:181], v[48:51]
	v_mfma_f32_16x16x32_bf16 v[104:107], v[144:147], v[186:189], v[104:107]
	v_mfma_f32_16x16x32_bf16 v[40:43], v[152:155], v[186:189], v[40:43]
	v_mfma_f32_16x16x32_bf16 v[96:99], v[144:147], v[202:205], v[96:99]
	v_mfma_f32_16x16x32_bf16 v[32:35], v[152:155], v[202:205], v[32:35]
	v_mfma_f32_16x16x32_bf16 v[120:123], v[148:151], v[164:167], v[120:123]
	v_mfma_f32_16x16x32_bf16 v[56:59], v[156:159], v[164:167], v[56:59]
	v_mfma_f32_16x16x32_bf16 v[112:115], v[148:151], v[182:185], v[112:115]
	v_mfma_f32_16x16x32_bf16 v[48:51], v[156:159], v[182:185], v[48:51]
	v_mfma_f32_16x16x32_bf16 v[104:107], v[148:151], v[198:201], v[104:107]
	v_mfma_f32_16x16x32_bf16 v[40:43], v[156:159], v[198:201], v[40:43]
	v_mfma_f32_16x16x32_bf16 v[96:99], v[148:151], v[220:223], v[96:99]
	v_mfma_f32_16x16x32_bf16 v[32:35], v[156:159], v[220:223], v[32:35]
	s_barrier
; #define PG8_STAGE(bufoff, gbase, voff) do { _Pragma("unroll") for (int _i = 0; _i < 2; ++_i) \
;         __builtin_amdgcn_global_load_lds((const unsigned*)((const char*)(gbase) + (voff)[_i]), (PG8_LAS unsigned*)(lds + (bufoff) + ldsw + _i * 8192), 16, 0, 0); } while (0)
; #define PG8_LDA(dst, b, h) do { _Pragma("unroll") for (int m = 0; m < 4; ++m) _Pragma("unroll") for (int k = 0; k < 2; ++k) dst[m][k] = *(const PG8_LAS bf16x8*)(lds + PG8_SA(b, h) + aoff + m * 2048 + k * 1024); } while (0)
; #define PG8_LDB(dst, b, h) do { _Pragma("unroll") for (int n = 0; n < 2; ++n) _Pragma("unroll") for (int k = 0; k < 2; ++k) dst[n][k] = *(const PG8_LAS bf16x8*)(lds + PG8_SB(b, h) + boff + n * 2048 + k * 1024); } while (0)
; #define PG8_WAIT_V(n) asm volatile("s_waitcnt vmcnt(" #n ")" ::: "memory")
; #define PG8_BAR __builtin_amdgcn_s_barrier()
; template <class Epi, class Sched, bool ALIGN_EPI = false, bool SP2 = false>
; __device__ __forceinline__ void gemm_phase(PG8_LAS unsigned char* lds, const Gemm g, const Sched& S, const Epi& E, int wave_in) {
;     ...
;             const bool last = (t == nt - 2);
;             const char* a1 = cA + (size_t)(t + 1) * kstep;
;             const char* a2 = last ? nA : cA + (size_t)(t + 2) * kstep; const char* b2 = last ? nB : cB + (size_t)(t + 2) * kstep;
;             const char* a3 = a2 + kstep; const char* b3 = b2 + kstep;
;     ...
;             PG8_LDB(B0, 0, 0); PG8_LDB(B1, 0, 1); PG8_SCHED; PG8_LDA(At, 0, 0); PG8_STAGE(PG8_SA(1, 1), a1 + hstep, voffA);
;             PG8_WAIT_V(8); PG8_WAIT_L(0); PG8_BAR; PG8_MMA(0, 0, At, B0); PG8_MMA(0, 1, At, B1); PG8_BAR; PG8_SCHED;
;             PG8_LDA(At, 0, 1); PG8_STAGE(PG8_SB(0, 0), b2, voffB); PG8_STAGE(PG8_SB(0, 1), b2 + hstep, voffB); PG8_STAGE(PG8_SA(0, 0), a2, voffA);
;             PG8_WAIT_V(8); PG8_WAIT_L(0); PG8_BAR; PG8_MMA(1, 0, At, B0); PG8_MMA(1, 1, At, B1); PG8_BAR; PG8_SCHED;
;             PG8_LDB(B0, 1, 0); PG8_LDB(B1, 1, 1); PG8_SCHED; PG8_LDA(At, 1, 0); PG8_STAGE(PG8_SA(0, 1), a2 + hstep, voffA);
;             PG8_WAIT_V(8); PG8_WAIT_L(0); PG8_BAR; PG8_MMA(0, 0, At, B0); PG8_MMA(0, 1, At, B1); PG8_BAR; PG8_SCHED;
;             PG8_LDA(At, 1, 1); PG8_STAGE(PG8_SB(1, 0), b3, voffB); PG8_STAGE(PG8_SB(1, 1), b3 + hstep, voffB); PG8_STAGE(PG8_SA(1, 0), a3, voffA);
;             PG8_WAIT_V(8); PG8_WAIT_L(0); PG8_BAR; PG8_MMA(1, 0, At, B0); PG8_MMA(1, 1, At, B1); PG8_BAR; PG8_SCHED;
	s_setprio 0
	s_add_i32 s29, s29, s75
	v_lshl_add_u64 v[190:191], v[190:191], 0, s[88:89]
	s_mov_b32 m0, s29
	ds_read_b128 v[160:163], v219 offset:49152
	ds_read_b128 v[164:167], v219 offset:50176
	ds_read_b128 v[178:181], v219 offset:51200
	ds_read_b128 v[182:185], v219 offset:52224
	ds_read_b128 v[186:189], v219 offset:53248
	ds_read_b128 v[198:201], v219 offset:54272
	ds_read_b128 v[202:205], v219 offset:55296
	ds_read_b128 v[220:223], v219 offset:56320
	global_load_lds_dwordx4 v[190:191], off
	s_add_i32 m0, s29, 0x2000
	s_add_u32 s0, s0, 0x40080
	v_lshl_add_u64 v[190:191], v[194:195], 0, s[88:89]
	s_addc_u32 s1, s1, 0
	s_add_i32 s2, s2, s75
	global_load_lds_dwordx4 v[190:191], off
	v_lshl_add_u64 v[190:191], s[0:1], 0, v[192:193]
	s_mov_b32 m0, s2
	s_nop 0
	global_load_lds_dwordx4 v[190:191], off
	v_lshl_add_u64 v[190:191], s[0:1], 0, v[168:169]
	s_add_i32 m0, s2, 0x2000
	s_nop 0
	global_load_lds_dwordx4 v[190:191], off
	v_lshl_add_u64 v[190:191], v[196:197], 0, s[88:89]
	s_mov_b32 m0, s9
	s_nop 0
	global_load_lds_dwordx4 v[190:191], off
	v_lshl_add_u64 v[190:191], v[224:225], 0, s[88:89]
	s_mov_b32 m0, s96
	s_nop 0
	global_load_lds_dwordx4 v[190:191], off
	s_waitcnt vmcnt(8)
	s_waitcnt lgkmcnt(0)
	s_setprio 1
	s_barrier
	v_mfma_f32_16x16x32_bf16 v[92:95], v[128:131], v[160:163], v[92:95]
	v_mfma_f32_16x16x32_bf16 v[28:31], v[136:139], v[160:163], v[28:31]
	v_mfma_f32_16x16x32_bf16 v[84:87], v[128:131], v[178:181], v[84:87]
	v_mfma_f32_16x16x32_bf16 v[20:23], v[136:139], v[178:181], v[20:23]
	v_mfma_f32_16x16x32_bf16 v[76:79], v[128:131], v[186:189], v[76:79]
	v_mfma_f32_16x16x32_bf16 v[12:15], v[136:139], v[186:189], v[12:15]
	v_mfma_f32_16x16x32_bf16 v[68:71], v[128:131], v[202:205], v[68:71]
	v_mfma_f32_16x16x32_bf16 v[4:7], v[136:139], v[202:205], v[4:7]
	v_mfma_f32_16x16x32_bf16 v[92:95], v[132:135], v[164:167], v[92:95]
	v_mfma_f32_16x16x32_bf16 v[28:31], v[140:143], v[164:167], v[28:31]
	v_mfma_f32_16x16x32_bf16 v[84:87], v[132:135], v[182:185], v[84:87]
	v_mfma_f32_16x16x32_bf16 v[20:23], v[140:143], v[182:185], v[20:23]
	v_mfma_f32_16x16x32_bf16 v[76:79], v[132:135], v[198:201], v[76:79]
	v_mfma_f32_16x16x32_bf16 v[12:15], v[140:143], v[198:201], v[12:15]
	v_mfma_f32_16x16x32_bf16 v[68:71], v[132:135], v[220:223], v[68:71]
	v_mfma_f32_16x16x32_bf16 v[4:7], v[140:143], v[220:223], v[4:7]
	v_mfma_f32_16x16x32_bf16 v[88:91], v[144:147], v[160:163], v[88:91]
	v_mfma_f32_16x16x32_bf16 v[24:27], v[152:155], v[160:163], v[24:27]
	v_mfma_f32_16x16x32_bf16 v[80:83], v[144:147], v[178:181], v[80:83]
	v_mfma_f32_16x16x32_bf16 v[16:19], v[152:155], v[178:181], v[16:19]
	v_mfma_f32_16x16x32_bf16 v[72:75], v[144:147], v[186:189], v[72:75]
	v_mfma_f32_16x16x32_bf16 v[8:11], v[152:155], v[186:189], v[8:11]
	v_mfma_f32_16x16x32_bf16 v[64:67], v[144:147], v[202:205], v[64:67]
	v_mfma_f32_16x16x32_bf16 v[0:3], v[152:155], v[202:205], v[0:3]
	v_mfma_f32_16x16x32_bf16 v[88:91], v[148:151], v[164:167], v[88:91]
	v_mfma_f32_16x16x32_bf16 v[24:27], v[156:159], v[164:167], v[24:27]
	v_mfma_f32_16x16x32_bf16 v[80:83], v[148:151], v[182:185], v[80:83]
	v_mfma_f32_16x16x32_bf16 v[16:19], v[156:159], v[182:185], v[16:19]
	v_mfma_f32_16x16x32_bf16 v[72:75], v[148:151], v[198:201], v[72:75]
	v_mfma_f32_16x16x32_bf16 v[8:11], v[156:159], v[198:201], v[8:11]
	v_mfma_f32_16x16x32_bf16 v[64:67], v[148:151], v[220:223], v[64:67]
	v_mfma_f32_16x16x32_bf16 v[0:3], v[156:159], v[220:223], v[0:3]
	s_barrier
	s_setprio 0
	s_add_i32 s19, s19, 2
	s_add_u32 s81, s81, 0x100
	s_addc_u32 s18, s18, 0
	s_add_u32 vcc_lo, vcc_lo, 0x100
	s_addc_u32 vcc_hi, vcc_hi, 0
	s_cmp_gt_u32 s19, 13
	s_cbranch_scc1 .Lkexit_6
.LBB0_897:
	s_add_u32 s0, vcc_lo, 0xfffc0080
	s_addc_u32 s1, vcc_hi, -1
	s_add_i32 s76, s35, 0x100
	s_cmp_eq_u32 s19, 12
	s_cselect_b32 s79, s11, s1
	s_cselect_b32 s78, s34, s0
	s_cselect_b32 s1, s5, s18
	s_cselect_b32 s0, s53, s81
	s_add_i32 s29, s90, 0x100
	v_add_u32_e32 v140, s76, v207
	v_add_u32_e32 v156, s29, v207
	ds_read_b128 v[128:131], v140
	ds_read_b128 v[132:135], v140 offset:1024
	ds_read_b128 v[136:139], v140 offset:2048
	ds_read_b128 v[140:143], v140 offset:3072
	ds_read_b128 v[144:147], v156
	ds_read_b128 v[148:151], v156 offset:1024
	ds_read_b128 v[152:155], v156 offset:2048
	ds_read_b128 v[156:159], v156 offset:3072
	v_lshl_add_u64 v[190:191], vcc, 0, v[176:177]
	s_add_i32 m0, s33, 0xc000
	ds_read_b128 v[160:163], v219
	ds_read_b128 v[164:167], v219 offset:1024
	ds_read_b128 v[178:181], v219 offset:2048
	ds_read_b128 v[182:185], v219 offset:3072
	ds_read_b128 v[186:189], v219 offset:4096
	ds_read_b128 v[198:201], v219 offset:5120
	ds_read_b128 v[202:205], v219 offset:6144
	ds_read_b128 v[220:223], v219 offset:7168
	global_load_lds_dwordx4 v[190:191], off
	v_lshl_add_u64 v[190:191], vcc, 0, v[174:175]
	s_add_i32 m0, s33, 0xe000
	s_nop 0
	global_load_lds_dwordx4 v[190:191], off
	s_waitcnt vmcnt(8)
	s_waitcnt lgkmcnt(0)
	s_setprio 1
	s_barrier
; #define PG8_STAGE(bufoff, gbase, voff) do { _Pragma("unroll") for (int _i = 0; _i < 2; ++_i) \
;         __builtin_amdgcn_global_load_lds((const unsigned*)((const char*)(gbase) + (voff)[_i]), (PG8_LAS unsigned*)(lds + (bufoff) + ldsw + _i * 8192), 16, 0, 0); } while (0)
; #define PG8_LDA(dst, b, h) do { _Pragma("unroll") for (int m = 0; m < 4; ++m) _Pragma("unroll") for (int k = 0; k < 2; ++k) dst[m][k] = *(const PG8_LAS bf16x8*)(lds + PG8_SA(b, h) + aoff + m * 2048 + k * 1024); } while (0)
; #define PG8_LDB(dst, b, h) do { _Pragma("unroll") for (int n = 0; n < 2; ++n) _Pragma("unroll") for (int k = 0; k < 2; ++k) dst[n][k] = *(const PG8_LAS bf16x8*)(lds + PG8_SB(b, h) + boff + n * 2048 + k * 1024); } while (0)
; #define PG8_MMA(ai, bj, At, Bt) do { __builtin_amdgcn_s_setprio(1); _Pragma("unroll") for (int m = 0; m < 4; ++m) _Pragma("unroll") for (int n = 0; n < 2; ++n) _Pragma("unroll") for (int k = 0; k < 2; ++k) \
;         acc[ai][bj][m][n] = __builtin_amdgcn_mfma_f32_16x16x32_bf16(Bt[n][k], At[m][k], acc[ai][bj][m][n], 0, 0, 0); __builtin_amdgcn_s_setprio(0); } while (0)
; #define PG8_WAIT_V(n) asm volatile("s_waitcnt vmcnt(" #n ")" ::: "memory")
; #define PG8_WAIT_L(n) asm volatile("s_waitcnt lgkmcnt(" #n ")" ::: "memory")
; #define PG8_BAR __builtin_amdgcn_s_barrier()
; #define PG8_SCHED __builtin_amdgcn_sched_barrier(0)
; template <class Epi, class Sched, bool ALIGN_EPI = false, bool SP2 = false>
; __device__ __forceinline__ void gemm_phase(PG8_LAS unsigned char* lds, const Gemm g, const Sched& S, const Epi& E, int wave_in) {
;     ...
;             PG8_LDB(B0, 0, 0); PG8_LDB(B1, 0, 1); PG8_SCHED; PG8_LDA(At, 0, 0); PG8_STAGE(PG8_SA(1, 1), a1 + hstep, voffA);
;             PG8_WAIT_V(8); PG8_WAIT_L(0); PG8_BAR; PG8_MMA(0, 0, At, B0); PG8_MMA(0, 1, At, B1); PG8_BAR; PG8_SCHED;
;             PG8_LDA(At, 0, 1); PG8_STAGE(PG8_SB(0, 0), b2, voffB); PG8_STAGE(PG8_SB(0, 1), b2 + hstep, voffB); PG8_STAGE(PG8_SA(0, 0), a2, voffA);
;             PG8_WAIT_V(8); PG8_WAIT_L(0); PG8_BAR; PG8_MMA(1, 0, At, B0); PG8_MMA(1, 1, At, B1); PG8_BAR; PG8_SCHED;
	v_mfma_f32_16x16x32_bf16 v[124:127], v[128:131], v[160:163], v[124:127]
	v_mfma_f32_16x16x32_bf16 v[60:63], v[136:139], v[160:163], v[60:63]
	v_mfma_f32_16x16x32_bf16 v[116:119], v[128:131], v[178:181], v[116:119]
	v_mfma_f32_16x16x32_bf16 v[52:55], v[136:139], v[178:181], v[52:55]
	v_mfma_f32_16x16x32_bf16 v[108:111], v[128:131], v[186:189], v[108:111]
	v_mfma_f32_16x16x32_bf16 v[44:47], v[136:139], v[186:189], v[44:47]
	v_mfma_f32_16x16x32_bf16 v[100:103], v[128:131], v[202:205], v[100:103]
	v_mfma_f32_16x16x32_bf16 v[36:39], v[136:139], v[202:205], v[36:39]
	v_mfma_f32_16x16x32_bf16 v[124:127], v[132:135], v[164:167], v[124:127]
	v_mfma_f32_16x16x32_bf16 v[60:63], v[140:143], v[164:167], v[60:63]
	v_mfma_f32_16x16x32_bf16 v[116:119], v[132:135], v[182:185], v[116:119]
	v_mfma_f32_16x16x32_bf16 v[52:55], v[140:143], v[182:185], v[52:55]
	v_mfma_f32_16x16x32_bf16 v[108:111], v[132:135], v[198:201], v[108:111]
	v_mfma_f32_16x16x32_bf16 v[44:47], v[140:143], v[198:201], v[44:47]
	v_mfma_f32_16x16x32_bf16 v[100:103], v[132:135], v[220:223], v[100:103]
	v_mfma_f32_16x16x32_bf16 v[36:39], v[140:143], v[220:223], v[36:39]
	v_mfma_f32_16x16x32_bf16 v[120:123], v[144:147], v[160:163], v[120:123]
	v_mfma_f32_16x16x32_bf16 v[56:59], v[152:155], v[160:163], v[56:59]
	v_mfma_f32_16x16x32_bf16 v[112:115], v[144:147], v[178:181], v[112:115]
	v_mfma_f32_16x16x32_bf16 v[48:51], v[152:155], v[178:181], v[48:51]
	v_mfma_f32_16x16x32_bf16 v[104:107], v[144:147], v[186:189], v[104:107]
	v_mfma_f32_16x16x32_bf16 v[40:43], v[152:155], v[186:189], v[40:43]
	v_mfma_f32_16x16x32_bf16 v[96:99], v[144:147], v[202:205], v[96:99]
	v_mfma_f32_16x16x32_bf16 v[32:35], v[152:155], v[202:205], v[32:35]
	v_mfma_f32_16x16x32_bf16 v[120:123], v[148:151], v[164:167], v[120:123]
	v_mfma_f32_16x16x32_bf16 v[56:59], v[156:159], v[164:167], v[56:59]
	v_mfma_f32_16x16x32_bf16 v[112:115], v[148:151], v[182:185], v[112:115]
	v_mfma_f32_16x16x32_bf16 v[48:51], v[156:159], v[182:185], v[48:51]
	v_mfma_f32_16x16x32_bf16 v[104:107], v[148:151], v[198:201], v[104:107]
	v_mfma_f32_16x16x32_bf16 v[40:43], v[156:159], v[198:201], v[40:43]
	v_mfma_f32_16x16x32_bf16 v[96:99], v[148:151], v[220:223], v[96:99]
	v_mfma_f32_16x16x32_bf16 v[32:35], v[156:159], v[220:223], v[32:35]
	s_barrier
	s_setprio 0
	s_add_i32 s76, s76, s75
	v_lshl_add_u64 v[190:191], s[0:1], 0, v[192:193]
	s_mov_b32 m0, s76
	ds_read_b128 v[160:163], v219 offset:16384
	ds_read_b128 v[164:167], v219 offset:17408
	ds_read_b128 v[178:181], v219 offset:18432
	ds_read_b128 v[182:185], v219 offset:19456
	ds_read_b128 v[186:189], v219 offset:20480
	ds_read_b128 v[198:201], v219 offset:21504
	ds_read_b128 v[202:205], v219 offset:22528
	ds_read_b128 v[220:223], v219 offset:23552
	global_load_lds_dwordx4 v[190:191], off
	s_add_i32 m0, s76, 0x2000
	s_add_u32 s76, s0, 0x40000
	v_lshl_add_u64 v[194:195], s[0:1], 0, v[168:169]
	s_addc_u32 s77, s1, 0
	s_add_i32 s29, s29, s75
	global_load_lds_dwordx4 v[194:195], off
	v_lshl_add_u64 v[196:197], s[76:77], 0, v[192:193]
	s_mov_b32 m0, s29
	v_lshl_add_u64 v[224:225], s[78:79], 0, v[170:171]
	global_load_lds_dwordx4 v[196:197], off
	v_lshl_add_u64 v[196:197], s[76:77], 0, v[168:169]
	s_add_i32 m0, s29, 0x2000
	s_nop 0
	global_load_lds_dwordx4 v[196:197], off
	v_lshl_add_u64 v[196:197], s[78:79], 0, v[172:173]
	s_mov_b32 m0, s33
	s_nop 0
	global_load_lds_dwordx4 v[196:197], off
	s_mov_b32 m0, s62
	s_nop 0
	global_load_lds_dwordx4 v[224:225], off
	s_waitcnt vmcnt(8)
	s_waitcnt lgkmcnt(0)
	s_setprio 1
	s_barrier
	v_mfma_f32_16x16x32_bf16 v[92:95], v[128:131], v[160:163], v[92:95]
	v_mfma_f32_16x16x32_bf16 v[28:31], v[136:139], v[160:163], v[28:31]
	v_mfma_f32_16x16x32_bf16 v[84:87], v[128:131], v[178:181], v[84:87]
	v_mfma_f32_16x16x32_bf16 v[20:23], v[136:139], v[178:181], v[20:23]
	v_mfma_f32_16x16x32_bf16 v[76:79], v[128:131], v[186:189], v[76:79]
	v_mfma_f32_16x16x32_bf16 v[12:15], v[136:139], v[186:189], v[12:15]
	v_mfma_f32_16x16x32_bf16 v[68:71], v[128:131], v[202:205], v[68:71]
	v_mfma_f32_16x16x32_bf16 v[4:7], v[136:139], v[202:205], v[4:7]
	v_mfma_f32_16x16x32_bf16 v[92:95], v[132:135], v[164:167], v[92:95]
	v_mfma_f32_16x16x32_bf16 v[28:31], v[140:143], v[164:167], v[28:31]
	v_mfma_f32_16x16x32_bf16 v[84:87], v[132:135], v[182:185], v[84:87]
	v_mfma_f32_16x16x32_bf16 v[20:23], v[140:143], v[182:185], v[20:23]
	v_mfma_f32_16x16x32_bf16 v[76:79], v[132:135], v[198:201], v[76:79]
	v_mfma_f32_16x16x32_bf16 v[12:15], v[140:143], v[198:201], v[12:15]
	v_mfma_f32_16x16x32_bf16 v[68:71], v[132:135], v[220:223], v[68:71]
	v_mfma_f32_16x16x32_bf16 v[4:7], v[140:143], v[220:223], v[4:7]
	v_mfma_f32_16x16x32_bf16 v[88:91], v[144:147], v[160:163], v[88:91]
	v_mfma_f32_16x16x32_bf16 v[24:27], v[152:155], v[160:163], v[24:27]
	v_mfma_f32_16x16x32_bf16 v[80:83], v[144:147], v[178:181], v[80:83]
	v_mfma_f32_16x16x32_bf16 v[16:19], v[152:155], v[178:181], v[16:19]
	v_mfma_f32_16x16x32_bf16 v[72:75], v[144:147], v[186:189], v[72:75]
	v_mfma_f32_16x16x32_bf16 v[8:11], v[152:155], v[186:189], v[8:11]
	v_mfma_f32_16x16x32_bf16 v[64:67], v[144:147], v[202:205], v[64:67]
	v_mfma_f32_16x16x32_bf16 v[0:3], v[152:155], v[202:205], v[0:3]
	v_mfma_f32_16x16x32_bf16 v[88:91], v[148:151], v[164:167], v[88:91]
	v_mfma_f32_16x16x32_bf16 v[24:27], v[156:159], v[164:167], v[24:27]
	v_mfma_f32_16x16x32_bf16 v[80:83], v[148:151], v[182:185], v[80:83]
	v_mfma_f32_16x16x32_bf16 v[16:19], v[156:159], v[182:185], v[16:19]
	v_mfma_f32_16x16x32_bf16 v[72:75], v[148:151], v[198:201], v[72:75]
	v_mfma_f32_16x16x32_bf16 v[8:11], v[156:159], v[198:201], v[8:11]
	v_mfma_f32_16x16x32_bf16 v[64:67], v[148:151], v[220:223], v[64:67]
	v_mfma_f32_16x16x32_bf16 v[0:3], v[156:159], v[220:223], v[0:3]
	s_barrier
; #define PG8_STAGE(bufoff, gbase, voff) do { _Pragma("unroll") for (int _i = 0; _i < 2; ++_i) \
;         __builtin_amdgcn_global_load_lds((const unsigned*)((const char*)(gbase) + (voff)[_i]), (PG8_LAS unsigned*)(lds + (bufoff) + ldsw + _i * 8192), 16, 0, 0); } while (0)
; #define PG8_LDA(dst, b, h) do { _Pragma("unroll") for (int m = 0; m < 4; ++m) _Pragma("unroll") for (int k = 0; k < 2; ++k) dst[m][k] = *(const PG8_LAS bf16x8*)(lds + PG8_SA(b, h) + aoff + m * 2048 + k * 1024); } while (0)
; #define PG8_LDB(dst, b, h) do { _Pragma("unroll") for (int n = 0; n < 2; ++n) _Pragma("unroll") for (int k = 0; k < 2; ++k) dst[n][k] = *(const PG8_LAS bf16x8*)(lds + PG8_SB(b, h) + boff + n * 2048 + k * 1024); } while (0)
; #define PG8_MMA(ai, bj, At, Bt) do { __builtin_amdgcn_s_setprio(1); _Pragma("unroll") for (int m = 0; m < 4; ++m) _Pragma("unroll") for (int n = 0; n < 2; ++n) _Pragma("unroll") for (int k = 0; k < 2; ++k) \
;         acc[ai][bj][m][n] = __builtin_amdgcn_mfma_f32_16x16x32_bf16(Bt[n][k], At[m][k], acc[ai][bj][m][n], 0, 0, 0); __builtin_amdgcn_s_setprio(0); } while (0)
; #define PG8_WAIT_V(n) asm volatile("s_waitcnt vmcnt(" #n ")" ::: "memory")
; #define PG8_WAIT_L(n) asm volatile("s_waitcnt lgkmcnt(" #n ")" ::: "memory")
; #define PG8_BAR __builtin_amdgcn_s_barrier()
; #define PG8_SCHED __builtin_amdgcn_sched_barrier(0)
; template <class Epi, class Sched, bool ALIGN_EPI = false, bool SP2 = false>
; __device__ __forceinline__ void gemm_phase(PG8_LAS unsigned char* lds, const Gemm g, const Sched& S, const Epi& E, int wave_in) {
;     ...
;             PG8_LDB(B0, 1, 0); PG8_LDB(B1, 1, 1); PG8_SCHED; PG8_LDA(At, 1, 0); PG8_STAGE(PG8_SA(0, 1), a2 + hstep, voffA);
;             PG8_WAIT_V(8); PG8_WAIT_L(0); PG8_BAR; PG8_MMA(0, 0, At, B0); PG8_MMA(0, 1, At, B1); PG8_BAR; PG8_SCHED;
	s_setprio 0
	s_add_i32 s29, s65, 0x100
	s_add_i32 s2, s52, 0x100
	v_add_u32_e32 v140, s29, v207
	v_add_u32_e32 v156, s2, v207
	ds_read_b128 v[128:131], v140
	ds_read_b128 v[132:135], v140 offset:1024
	ds_read_b128 v[136:139], v140 offset:2048
	ds_read_b128 v[140:143], v140 offset:3072
	ds_read_b128 v[144:147], v156
	ds_read_b128 v[148:151], v156 offset:1024
	ds_read_b128 v[152:155], v156 offset:2048
	ds_read_b128 v[156:159], v156 offset:3072
	s_add_u32 s76, s78, 0x40000
	s_addc_u32 s77, s79, 0
	s_mov_b32 m0, s63
	v_lshl_add_u64 v[226:227], s[76:77], 0, v[172:173]
	ds_read_b128 v[160:163], v219 offset:32768
	ds_read_b128 v[164:167], v219 offset:33792
	ds_read_b128 v[178:181], v219 offset:34816
	ds_read_b128 v[182:185], v219 offset:35840
	ds_read_b128 v[186:189], v219 offset:36864
	ds_read_b128 v[198:201], v219 offset:37888
	ds_read_b128 v[202:205], v219 offset:38912
	ds_read_b128 v[220:223], v219 offset:39936
	global_load_lds_dwordx4 v[226:227], off
	v_lshl_add_u64 v[226:227], s[76:77], 0, v[170:171]
	s_mov_b32 m0, s31
	s_nop 0
	global_load_lds_dwordx4 v[226:227], off
	s_waitcnt vmcnt(8)
	s_waitcnt lgkmcnt(0)
	s_setprio 1
	s_barrier
	v_mfma_f32_16x16x32_bf16 v[124:127], v[128:131], v[160:163], v[124:127]
	v_mfma_f32_16x16x32_bf16 v[60:63], v[136:139], v[160:163], v[60:63]
	v_mfma_f32_16x16x32_bf16 v[116:119], v[128:131], v[178:181], v[116:119]
	v_mfma_f32_16x16x32_bf16 v[52:55], v[136:139], v[178:181], v[52:55]
	v_mfma_f32_16x16x32_bf16 v[108:111], v[128:131], v[186:189], v[108:111]
	v_mfma_f32_16x16x32_bf16 v[44:47], v[136:139], v[186:189], v[44:47]
	v_mfma_f32_16x16x32_bf16 v[100:103], v[128:131], v[202:205], v[100:103]
	v_mfma_f32_16x16x32_bf16 v[36:39], v[136:139], v[202:205], v[36:39]
	v_mfma_f32_16x16x32_bf16 v[124:127], v[132:135], v[164:167], v[124:127]
	v_mfma_f32_16x16x32_bf16 v[60:63], v[140:143], v[164:167], v[60:63]
	v_mfma_f32_16x16x32_bf16 v[116:119], v[132:135], v[182:185], v[116:119]
	v_mfma_f32_16x16x32_bf16 v[52:55], v[140:143], v[182:185], v[52:55]
	v_mfma_f32_16x16x32_bf16 v[108:111], v[132:135], v[198:201], v[108:111]
	v_mfma_f32_16x16x32_bf16 v[44:47], v[140:143], v[198:201], v[44:47]
	v_mfma_f32_16x16x32_bf16 v[100:103], v[132:135], v[220:223], v[100:103]
	v_mfma_f32_16x16x32_bf16 v[36:39], v[140:143], v[220:223], v[36:39]
	v_mfma_f32_16x16x32_bf16 v[120:123], v[144:147], v[160:163], v[120:123]
	v_mfma_f32_16x16x32_bf16 v[56:59], v[152:155], v[160:163], v[56:59]
	v_mfma_f32_16x16x32_bf16 v[112:115], v[144:147], v[178:181], v[112:115]
	v_mfma_f32_16x16x32_bf16 v[48:51], v[152:155], v[178:181], v[48:51]
	v_mfma_f32_16x16x32_bf16 v[104:107], v[144:147], v[186:189], v[104:107]
	v_mfma_f32_16x16x32_bf16 v[40:43], v[152:155], v[186:189], v[40:43]
	v_mfma_f32_16x16x32_bf16 v[96:99], v[144:147], v[202:205], v[96:99]
	v_mfma_f32_16x16x32_bf16 v[32:35], v[152:155], v[202:205], v[32:35]
	v_mfma_f32_16x16x32_bf16 v[120:123], v[148:151], v[164:167], v[120:123]
	v_mfma_f32_16x16x32_bf16 v[56:59], v[156:159], v[164:167], v[56:59]
	v_mfma_f32_16x16x32_bf16 v[112:115], v[148:151], v[182:185], v[112:115]
	v_mfma_f32_16x16x32_bf16 v[48:51], v[156:159], v[182:185], v[48:51]
	v_mfma_f32_16x16x32_bf16 v[104:107], v[148:151], v[198:201], v[104:107]
	v_mfma_f32_16x16x32_bf16 v[40:43], v[156:159], v[198:201], v[40:43]
	v_mfma_f32_16x16x32_bf16 v[96:99], v[148:151], v[220:223], v[96:99]
	v_mfma_f32_16x16x32_bf16 v[32:35], v[156:159], v[220:223], v[32:35]
	s_barrier
; #define PG8_STAGE(bufoff, gbase, voff) do { _Pragma("unroll") for (int _i = 0; _i < 2; ++_i) \
;         __builtin_amdgcn_global_load_lds((const unsigned*)((const char*)(gbase) + (voff)[_i]), (PG8_LAS unsigned*)(lds + (bufoff) + ldsw + _i * 8192), 16, 0, 0); } while (0)
; #define PG8_LDA(dst, b, h) do { _Pragma("unroll") for (int m = 0; m < 4; ++m) _Pragma("unroll") for (int k = 0; k < 2; ++k) dst[m][k] = *(const PG8_LAS bf16x8*)(lds + PG8_SA(b, h) + aoff + m * 2048 + k * 1024); } while (0)
; #define PG8_MMA(ai, bj, At, Bt) do { __builtin_amdgcn_s_setprio(1); _Pragma("unroll") for (int m = 0; m < 4; ++m) _Pragma("unroll") for (int n = 0; n < 2; ++n) _Pragma("unroll") for (int k = 0; k < 2; ++k) \
;         acc[ai][bj][m][n] = __builtin_amdgcn_mfma_f32_16x16x32_bf16(Bt[n][k], At[m][k], acc[ai][bj][m][n], 0, 0, 0); __builtin_amdgcn_s_setprio(0); } while (0)
; #define PG8_WAIT_V(n) asm volatile("s_waitcnt vmcnt(" #n ")" ::: "memory")
; #define PG8_WAIT_L(n) asm volatile("s_waitcnt lgkmcnt(" #n ")" ::: "memory")
; #define PG8_BAR __builtin_amdgcn_s_barrier()
; #define PG8_SCHED __builtin_amdgcn_sched_barrier(0)
; template <class Epi, class Sched, bool ALIGN_EPI = false, bool SP2 = false>
; __device__ __forceinline__ void gemm_phase(PG8_LAS unsigned char* lds, const Gemm g, const Sched& S, const Epi& E, int wave_in) {
;     ...
;         for (int t = 0; t < nt; t += 2) {
;             const bool last = (t == nt - 2);
;             const char* a1 = cA + (size_t)(t + 1) * kstep;
;             const char* a2 = last ? nA : cA + (size_t)(t + 2) * kstep; const char* b2 = last ? nB : cB + (size_t)(t + 2) * kstep;
;             const char* a3 = a2 + kstep; const char* b3 = b2 + kstep;
;     ...
;             PG8_LDA(At, 1, 1); PG8_STAGE(PG8_SB(1, 0), b3, voffB); PG8_STAGE(PG8_SB(1, 1), b3 + hstep, voffB); PG8_STAGE(PG8_SA(1, 0), a3, voffA);
;             PG8_WAIT_V(8); PG8_WAIT_L(0); PG8_BAR; PG8_MMA(1, 0, At, B0); PG8_MMA(1, 1, At, B1); PG8_BAR; PG8_SCHED;
	s_setprio 0
	s_add_i32 s29, s29, s75
	v_lshl_add_u64 v[190:191], v[190:191], 0, s[88:89]
	s_mov_b32 m0, s29
	ds_read_b128 v[160:163], v219 offset:49152
	ds_read_b128 v[164:167], v219 offset:50176
	ds_read_b128 v[178:181], v219 offset:51200
	ds_read_b128 v[182:185], v219 offset:52224
	ds_read_b128 v[186:189], v219 offset:53248
	ds_read_b128 v[198:201], v219 offset:54272
	ds_read_b128 v[202:205], v219 offset:55296
	ds_read_b128 v[220:223], v219 offset:56320
	global_load_lds_dwordx4 v[190:191], off
	s_add_i32 m0, s29, 0x2000
	s_add_u32 s0, s0, 0x40080
	v_lshl_add_u64 v[190:191], v[194:195], 0, s[88:89]
	s_addc_u32 s1, s1, 0
	s_add_i32 s2, s2, s75
	global_load_lds_dwordx4 v[190:191], off
	v_lshl_add_u64 v[190:191], s[0:1], 0, v[192:193]
	s_mov_b32 m0, s2
	s_nop 0
	global_load_lds_dwordx4 v[190:191], off
	v_lshl_add_u64 v[190:191], s[0:1], 0, v[168:169]
	s_add_i32 m0, s2, 0x2000
	s_nop 0
	global_load_lds_dwordx4 v[190:191], off
	v_lshl_add_u64 v[190:191], v[196:197], 0, s[88:89]
	s_mov_b32 m0, s9
	s_nop 0
	global_load_lds_dwordx4 v[190:191], off
	v_lshl_add_u64 v[190:191], v[224:225], 0, s[88:89]
	s_mov_b32 m0, s96
	s_nop 0
	global_load_lds_dwordx4 v[190:191], off
	s_waitcnt vmcnt(8)
	s_waitcnt lgkmcnt(0)
	s_setprio 1
	s_barrier
	v_mfma_f32_16x16x32_bf16 v[92:95], v[128:131], v[160:163], v[92:95]
	v_mfma_f32_16x16x32_bf16 v[28:31], v[136:139], v[160:163], v[28:31]
	v_mfma_f32_16x16x32_bf16 v[84:87], v[128:131], v[178:181], v[84:87]
	v_mfma_f32_16x16x32_bf16 v[20:23], v[136:139], v[178:181], v[20:23]
	v_mfma_f32_16x16x32_bf16 v[76:79], v[128:131], v[186:189], v[76:79]
	v_mfma_f32_16x16x32_bf16 v[12:15], v[136:139], v[186:189], v[12:15]
	v_mfma_f32_16x16x32_bf16 v[68:71], v[128:131], v[202:205], v[68:71]
	v_mfma_f32_16x16x32_bf16 v[4:7], v[136:139], v[202:205], v[4:7]
	v_mfma_f32_16x16x32_bf16 v[92:95], v[132:135], v[164:167], v[92:95]
	v_mfma_f32_16x16x32_bf16 v[28:31], v[140:143], v[164:167], v[28:31]
	v_mfma_f32_16x16x32_bf16 v[84:87], v[132:135], v[182:185], v[84:87]
	v_mfma_f32_16x16x32_bf16 v[20:23], v[140:143], v[182:185], v[20:23]
	v_mfma_f32_16x16x32_bf16 v[76:79], v[132:135], v[198:201], v[76:79]
	v_mfma_f32_16x16x32_bf16 v[12:15], v[140:143], v[198:201], v[12:15]
	v_mfma_f32_16x16x32_bf16 v[68:71], v[132:135], v[220:223], v[68:71]
	v_mfma_f32_16x16x32_bf16 v[4:7], v[140:143], v[220:223], v[4:7]
	v_mfma_f32_16x16x32_bf16 v[88:91], v[144:147], v[160:163], v[88:91]
	v_mfma_f32_16x16x32_bf16 v[24:27], v[152:155], v[160:163], v[24:27]
	v_mfma_f32_16x16x32_bf16 v[80:83], v[144:147], v[178:181], v[80:83]
	v_mfma_f32_16x16x32_bf16 v[16:19], v[152:155], v[178:181], v[16:19]
	v_mfma_f32_16x16x32_bf16 v[72:75], v[144:147], v[186:189], v[72:75]
	v_mfma_f32_16x16x32_bf16 v[8:11], v[152:155], v[186:189], v[8:11]
	v_mfma_f32_16x16x32_bf16 v[64:67], v[144:147], v[202:205], v[64:67]
	v_mfma_f32_16x16x32_bf16 v[0:3], v[152:155], v[202:205], v[0:3]
	v_mfma_f32_16x16x32_bf16 v[88:91], v[148:151], v[164:167], v[88:91]
	v_mfma_f32_16x16x32_bf16 v[24:27], v[156:159], v[164:167], v[24:27]
	v_mfma_f32_16x16x32_bf16 v[80:83], v[148:151], v[182:185], v[80:83]
	v_mfma_f32_16x16x32_bf16 v[16:19], v[156:159], v[182:185], v[16:19]
	v_mfma_f32_16x16x32_bf16 v[72:75], v[148:151], v[198:201], v[72:75]
	v_mfma_f32_16x16x32_bf16 v[8:11], v[156:159], v[198:201], v[8:11]
	v_mfma_f32_16x16x32_bf16 v[64:67], v[148:151], v[220:223], v[64:67]
	v_mfma_f32_16x16x32_bf16 v[0:3], v[156:159], v[220:223], v[0:3]
	s_barrier
	s_setprio 0
	s_add_i32 s19, s19, 2
	s_add_u32 s81, s81, 0x100
	s_addc_u32 s18, s18, 0
	s_add_u32 vcc_lo, vcc_lo, 0x100
	s_addc_u32 vcc_hi, vcc_hi, 0
	s_cmp_gt_u32 s19, 13
	s_cbranch_scc0 .LBB0_897

; #define PG8_STAGE(bufoff, gbase, voff) do { _Pragma("unroll") for (int _i = 0; _i < 2; ++_i) \
;         __builtin_amdgcn_global_load_lds((const unsigned*)((const char*)(gbase) + (voff)[_i]), (PG8_LAS unsigned*)(lds + (bufoff) + ldsw + _i * 8192), 16, 0, 0); } while (0)
; #define PG8_LDA(dst, b, h) do { _Pragma("unroll") for (int m = 0; m < 4; ++m) _Pragma("unroll") for (int k = 0; k < 2; ++k) dst[m][k] = *(const PG8_LAS bf16x8*)(lds + PG8_SA(b, h) + aoff + m * 2048 + k * 1024); } while (0)
; #define PG8_LDB(dst, b, h) do { _Pragma("unroll") for (int n = 0; n < 2; ++n) _Pragma("unroll") for (int k = 0; k < 2; ++k) dst[n][k] = *(const PG8_LAS bf16x8*)(lds + PG8_SB(b, h) + boff + n * 2048 + k * 1024); } while (0)
; #define PG8_MMA(ai, bj, At, Bt) do { __builtin_amdgcn_s_setprio(1); _Pragma("unroll") for (int m = 0; m < 4; ++m) _Pragma("unroll") for (int n = 0; n < 2; ++n) _Pragma("unroll") for (int k = 0; k < 2; ++k) \
;         acc[ai][bj][m][n] = __builtin_amdgcn_mfma_f32_16x16x32_bf16(Bt[n][k], At[m][k], acc[ai][bj][m][n], 0, 0, 0); __builtin_amdgcn_s_setprio(0); } while (0)
; #define PG8_WAIT_V(n) asm volatile("s_waitcnt vmcnt(" #n ")" ::: "memory")
; #define PG8_WAIT_L(n) asm volatile("s_waitcnt lgkmcnt(" #n ")" ::: "memory")
; #define PG8_BAR __builtin_amdgcn_s_barrier()
; #define PG8_SCHED __builtin_amdgcn_sched_barrier(0)
; template <class Epi, class Sched, bool ALIGN_EPI = false, bool SP2 = false>
; __device__ __forceinline__ void gemm_phase(PG8_LAS unsigned char* lds, const Gemm g, const Sched& S, const Epi& E, int wave_in) {
;     ...
;                 for (int n = 0; n < 2; ++n) acc[a][b][m][n] = (f32x4){0.f, 0.f, 0.f, 0.f};
;     ...
;             PG8_LDB(B0, 0, 0); PG8_LDB(B1, 0, 1); PG8_SCHED; PG8_LDA(At, 0, 0); PG8_STAGE(PG8_SA(1, 1), a1 + hstep, voffA);
;             PG8_WAIT_V(8); PG8_WAIT_L(0); PG8_BAR; PG8_MMA(0, 0, At, B0); PG8_MMA(0, 1, At, B1); PG8_BAR; PG8_SCHED;
;             PG8_LDA(At, 0, 1); PG8_STAGE(PG8_SB(0, 0), b2, voffB); PG8_STAGE(PG8_SB(0, 1), b2 + hstep, voffB); PG8_STAGE(PG8_SA(0, 0), a2, voffA);
;             PG8_WAIT_V(8); PG8_WAIT_L(0); PG8_BAR; PG8_MMA(1, 0, At, B0); PG8_MMA(1, 1, At, B1); PG8_BAR; PG8_SCHED;
.LBB0_1030:
	s_add_u32 s34, s20, 0x100
	s_addc_u32 s42, s21, 0
	s_mov_b32 s43, -2
	s_add_u32 s20, s16, 0x100
	s_addc_u32 s21, s17, 0
	s_add_i32 s2, s35, 0x100
	s_cmp_eq_u32 s43, 40
	s_cselect_b32 s25, s13, s21
	s_cselect_b32 s24, s12, s20
	s_cselect_b32 s23, s15, s42
	s_cselect_b32 s22, s14, s34
	s_add_i32 s29, s90, 0x100
	v_add_u32_e32 v128, s2, v249
	v_add_u32_e32 v156, s29, v249
	ds_read_b128 v[112:115], v128
	ds_read_b128 v[120:123], v128 offset:1024
	ds_read_b128 v[124:127], v128 offset:2048
	ds_read_b128 v[128:131], v128 offset:3072
	ds_read_b128 v[136:139], v156
	ds_read_b128 v[140:143], v156 offset:1024
	ds_read_b128 v[144:147], v156 offset:2048
	ds_read_b128 v[156:159], v156 offset:3072
	v_lshl_add_u64 v[194:195], s[16:17], 0, v[206:207]
	s_add_i32 m0, s45, 0xc000
	ds_read_b128 v[160:163], v251
	ds_read_b128 v[164:167], v251 offset:1024
	ds_read_b128 v[168:171], v251 offset:2048
	ds_read_b128 v[172:175], v251 offset:3072
	ds_read_b128 v[176:179], v251 offset:4096
	ds_read_b128 v[180:183], v251 offset:5120
	ds_read_b128 v[184:187], v251 offset:6144
	ds_read_b128 v[188:191], v251 offset:7168
	global_load_lds_dwordx4 v[194:195], off
	v_lshl_add_u64 v[194:195], s[16:17], 0, v[204:205]
	s_add_i32 m0, s45, 0xe000
	s_nop 0
	global_load_lds_dwordx4 v[194:195], off
	s_waitcnt vmcnt(8)
	s_waitcnt lgkmcnt(0)
	s_setprio 1
	s_barrier
	v_mfma_f32_16x16x32_bf16 v[152:155], v[112:115], v[160:163], 0
	v_mfma_f32_16x16x32_bf16 v[148:151], v[124:127], v[160:163], 0
	v_mfma_f32_16x16x32_bf16 v[108:111], v[112:115], v[168:171], 0
	v_mfma_f32_16x16x32_bf16 v[104:107], v[124:127], v[168:171], 0
	v_mfma_f32_16x16x32_bf16 v[92:95], v[112:115], v[176:179], 0
	v_mfma_f32_16x16x32_bf16 v[88:91], v[124:127], v[176:179], 0
	v_mfma_f32_16x16x32_bf16 v[76:79], v[112:115], v[184:187], 0
	v_mfma_f32_16x16x32_bf16 v[72:75], v[124:127], v[184:187], 0
	v_mfma_f32_16x16x32_bf16 v[152:155], v[120:123], v[164:167], v[152:155]
	v_mfma_f32_16x16x32_bf16 v[148:151], v[128:131], v[164:167], v[148:151]
	v_mfma_f32_16x16x32_bf16 v[108:111], v[120:123], v[172:175], v[108:111]
	v_mfma_f32_16x16x32_bf16 v[104:107], v[128:131], v[172:175], v[104:107]
	v_mfma_f32_16x16x32_bf16 v[92:95], v[120:123], v[180:183], v[92:95]
	v_mfma_f32_16x16x32_bf16 v[88:91], v[128:131], v[180:183], v[88:91]
	v_mfma_f32_16x16x32_bf16 v[76:79], v[120:123], v[188:191], v[76:79]
	v_mfma_f32_16x16x32_bf16 v[72:75], v[128:131], v[188:191], v[72:75]
	v_mfma_f32_16x16x32_bf16 v[132:135], v[136:139], v[160:163], 0
	v_mfma_f32_16x16x32_bf16 v[116:119], v[144:147], v[160:163], 0
	v_mfma_f32_16x16x32_bf16 v[100:103], v[136:139], v[168:171], 0
	v_mfma_f32_16x16x32_bf16 v[96:99], v[144:147], v[168:171], 0
	v_mfma_f32_16x16x32_bf16 v[84:87], v[136:139], v[176:179], 0
	v_mfma_f32_16x16x32_bf16 v[80:83], v[144:147], v[176:179], 0
	v_mfma_f32_16x16x32_bf16 v[68:71], v[136:139], v[184:187], 0
	v_mfma_f32_16x16x32_bf16 v[64:67], v[144:147], v[184:187], 0
	v_mfma_f32_16x16x32_bf16 v[132:135], v[140:143], v[164:167], v[132:135]
	v_mfma_f32_16x16x32_bf16 v[116:119], v[156:159], v[164:167], v[116:119]
	v_mfma_f32_16x16x32_bf16 v[100:103], v[140:143], v[172:175], v[100:103]
	v_mfma_f32_16x16x32_bf16 v[96:99], v[156:159], v[172:175], v[96:99]
	v_mfma_f32_16x16x32_bf16 v[84:87], v[140:143], v[180:183], v[84:87]
	v_mfma_f32_16x16x32_bf16 v[80:83], v[156:159], v[180:183], v[80:83]
	v_mfma_f32_16x16x32_bf16 v[68:71], v[140:143], v[188:191], v[68:71]
	v_mfma_f32_16x16x32_bf16 v[64:67], v[156:159], v[188:191], v[64:67]
	s_barrier
	s_setprio 0
	s_add_i32 s2, s2, s44
	v_lshl_add_u64 v[194:195], s[22:23], 0, v[192:193]
	s_mov_b32 m0, s2
	ds_read_b128 v[160:163], v251 offset:16384
	ds_read_b128 v[164:167], v251 offset:17408
	ds_read_b128 v[168:171], v251 offset:18432
	ds_read_b128 v[172:175], v251 offset:19456
	ds_read_b128 v[176:179], v251 offset:20480
	ds_read_b128 v[180:183], v251 offset:21504
	ds_read_b128 v[184:187], v251 offset:22528
	ds_read_b128 v[188:191], v251 offset:23552
	global_load_lds_dwordx4 v[194:195], off
	s_add_i32 m0, s2, 0x2000
	s_add_u32 s16, s22, 0xb0000
	v_lshl_add_u64 v[196:197], s[22:23], 0, v[198:199]
	s_addc_u32 s17, s23, 0
	s_add_i32 s2, s29, s44
	global_load_lds_dwordx4 v[196:197], off
	v_lshl_add_u64 v[208:209], s[16:17], 0, v[192:193]
	s_mov_b32 m0, s2
	v_lshl_add_u64 v[210:211], s[24:25], 0, v[200:201]
	global_load_lds_dwordx4 v[208:209], off
	v_lshl_add_u64 v[208:209], s[16:17], 0, v[198:199]
	s_add_i32 m0, s2, 0x2000
	s_nop 0
	global_load_lds_dwordx4 v[208:209], off
	v_lshl_add_u64 v[208:209], s[24:25], 0, v[202:203]
	s_mov_b32 m0, s45
	s_nop 0
	global_load_lds_dwordx4 v[208:209], off
	s_mov_b32 m0, s46
	s_nop 0
	global_load_lds_dwordx4 v[210:211], off
	s_waitcnt vmcnt(8)
	s_waitcnt lgkmcnt(0)
	s_setprio 1
	s_barrier
; #define PG8_STAGE(bufoff, gbase, voff) do { _Pragma("unroll") for (int _i = 0; _i < 2; ++_i) \
;         __builtin_amdgcn_global_load_lds((const unsigned*)((const char*)(gbase) + (voff)[_i]), (PG8_LAS unsigned*)(lds + (bufoff) + ldsw + _i * 8192), 16, 0, 0); } while (0)
; #define PG8_LDA(dst, b, h) do { _Pragma("unroll") for (int m = 0; m < 4; ++m) _Pragma("unroll") for (int k = 0; k < 2; ++k) dst[m][k] = *(const PG8_LAS bf16x8*)(lds + PG8_SA(b, h) + aoff + m * 2048 + k * 1024); } while (0)
; #define PG8_LDB(dst, b, h) do { _Pragma("unroll") for (int n = 0; n < 2; ++n) _Pragma("unroll") for (int k = 0; k < 2; ++k) dst[n][k] = *(const PG8_LAS bf16x8*)(lds + PG8_SB(b, h) + boff + n * 2048 + k * 1024); } while (0)
; #define PG8_MMA(ai, bj, At, Bt) do { __builtin_amdgcn_s_setprio(1); _Pragma("unroll") for (int m = 0; m < 4; ++m) _Pragma("unroll") for (int n = 0; n < 2; ++n) _Pragma("unroll") for (int k = 0; k < 2; ++k) \
;         acc[ai][bj][m][n] = __builtin_amdgcn_mfma_f32_16x16x32_bf16(Bt[n][k], At[m][k], acc[ai][bj][m][n], 0, 0, 0); __builtin_amdgcn_s_setprio(0); } while (0)
; #define PG8_WAIT_V(n) asm volatile("s_waitcnt vmcnt(" #n ")" ::: "memory")
; #define PG8_WAIT_L(n) asm volatile("s_waitcnt lgkmcnt(" #n ")" ::: "memory")
; #define PG8_BAR __builtin_amdgcn_s_barrier()
; #define PG8_SCHED __builtin_amdgcn_sched_barrier(0)
; template <class Epi, class Sched, bool ALIGN_EPI = false, bool SP2 = false>
; __device__ __forceinline__ void gemm_phase(PG8_LAS unsigned char* lds, const Gemm g, const Sched& S, const Epi& E, int wave_in) {
;     ...
;             PG8_WAIT_V(8); PG8_WAIT_L(0); PG8_BAR; PG8_MMA(1, 0, At, B0); PG8_MMA(1, 1, At, B1); PG8_BAR; PG8_SCHED;
;             PG8_LDB(B0, 1, 0); PG8_LDB(B1, 1, 1); PG8_SCHED; PG8_LDA(At, 1, 0); PG8_STAGE(PG8_SA(0, 1), a2 + hstep, voffA);
;             PG8_WAIT_V(8); PG8_WAIT_L(0); PG8_BAR; PG8_MMA(0, 0, At, B0); PG8_MMA(0, 1, At, B1); PG8_BAR; PG8_SCHED;
	v_mfma_f32_16x16x32_bf16 v[60:63], v[112:115], v[160:163], 0
	v_mfma_f32_16x16x32_bf16 v[56:59], v[124:127], v[160:163], 0
	v_mfma_f32_16x16x32_bf16 v[44:47], v[112:115], v[168:171], 0
	v_mfma_f32_16x16x32_bf16 v[40:43], v[124:127], v[168:171], 0
	v_mfma_f32_16x16x32_bf16 v[28:31], v[112:115], v[176:179], 0
	v_mfma_f32_16x16x32_bf16 v[24:27], v[124:127], v[176:179], 0
	v_mfma_f32_16x16x32_bf16 v[12:15], v[112:115], v[184:187], 0
	v_mfma_f32_16x16x32_bf16 v[8:11], v[124:127], v[184:187], 0
	v_mfma_f32_16x16x32_bf16 v[60:63], v[120:123], v[164:167], v[60:63]
	v_mfma_f32_16x16x32_bf16 v[56:59], v[128:131], v[164:167], v[56:59]
	v_mfma_f32_16x16x32_bf16 v[44:47], v[120:123], v[172:175], v[44:47]
	v_mfma_f32_16x16x32_bf16 v[40:43], v[128:131], v[172:175], v[40:43]
	v_mfma_f32_16x16x32_bf16 v[28:31], v[120:123], v[180:183], v[28:31]
	v_mfma_f32_16x16x32_bf16 v[24:27], v[128:131], v[180:183], v[24:27]
	v_mfma_f32_16x16x32_bf16 v[12:15], v[120:123], v[188:191], v[12:15]
	v_mfma_f32_16x16x32_bf16 v[8:11], v[128:131], v[188:191], v[8:11]
	v_mfma_f32_16x16x32_bf16 v[52:55], v[136:139], v[160:163], 0
	v_mfma_f32_16x16x32_bf16 v[48:51], v[144:147], v[160:163], 0
	v_mfma_f32_16x16x32_bf16 v[36:39], v[136:139], v[168:171], 0
	v_mfma_f32_16x16x32_bf16 v[32:35], v[144:147], v[168:171], 0
	v_mfma_f32_16x16x32_bf16 v[20:23], v[136:139], v[176:179], 0
	v_mfma_f32_16x16x32_bf16 v[16:19], v[144:147], v[176:179], 0
	v_mfma_f32_16x16x32_bf16 v[4:7], v[136:139], v[184:187], 0
	v_mfma_f32_16x16x32_bf16 v[0:3], v[144:147], v[184:187], 0
	v_mfma_f32_16x16x32_bf16 v[52:55], v[140:143], v[164:167], v[52:55]
	v_mfma_f32_16x16x32_bf16 v[48:51], v[156:159], v[164:167], v[48:51]
	v_mfma_f32_16x16x32_bf16 v[36:39], v[140:143], v[172:175], v[36:39]
	v_mfma_f32_16x16x32_bf16 v[32:35], v[156:159], v[172:175], v[32:35]
	v_mfma_f32_16x16x32_bf16 v[20:23], v[140:143], v[180:183], v[20:23]
	v_mfma_f32_16x16x32_bf16 v[16:19], v[156:159], v[180:183], v[16:19]
	v_mfma_f32_16x16x32_bf16 v[4:7], v[140:143], v[188:191], v[4:7]
	v_mfma_f32_16x16x32_bf16 v[0:3], v[156:159], v[188:191], v[0:3]
	s_barrier
	s_setprio 0
	s_add_i32 s2, s65, 0x100
	s_add_i32 s29, s52, 0x100
	v_add_u32_e32 v128, s2, v249
	v_add_u32_e32 v156, s29, v249
	ds_read_b128 v[112:115], v128
	ds_read_b128 v[120:123], v128 offset:1024
	ds_read_b128 v[124:127], v128 offset:2048
	ds_read_b128 v[128:131], v128 offset:3072
	ds_read_b128 v[136:139], v156
	ds_read_b128 v[140:143], v156 offset:1024
	ds_read_b128 v[144:147], v156 offset:2048
	ds_read_b128 v[156:159], v156 offset:3072
	s_add_u32 s16, s24, 0xb0000
	s_addc_u32 s17, s25, 0
	s_mov_b32 m0, s47
	v_lshl_add_u64 v[212:213], s[16:17], 0, v[202:203]
	ds_read_b128 v[160:163], v251 offset:32768
	ds_read_b128 v[164:167], v251 offset:33792
	ds_read_b128 v[168:171], v251 offset:34816
	ds_read_b128 v[172:175], v251 offset:35840
	ds_read_b128 v[176:179], v251 offset:36864
	ds_read_b128 v[180:183], v251 offset:37888
	ds_read_b128 v[184:187], v251 offset:38912
	ds_read_b128 v[188:191], v251 offset:39936
	global_load_lds_dwordx4 v[212:213], off
	v_lshl_add_u64 v[212:213], s[16:17], 0, v[200:201]
	s_mov_b32 m0, s60
	s_nop 0
	global_load_lds_dwordx4 v[212:213], off
	s_waitcnt vmcnt(8)
	s_waitcnt lgkmcnt(0)
	s_setprio 1
	s_barrier
	v_mfma_f32_16x16x32_bf16 v[152:155], v[112:115], v[160:163], v[152:155]
	v_mfma_f32_16x16x32_bf16 v[148:151], v[124:127], v[160:163], v[148:151]
	v_mfma_f32_16x16x32_bf16 v[108:111], v[112:115], v[168:171], v[108:111]
	v_mfma_f32_16x16x32_bf16 v[104:107], v[124:127], v[168:171], v[104:107]
	v_mfma_f32_16x16x32_bf16 v[92:95], v[112:115], v[176:179], v[92:95]
	v_mfma_f32_16x16x32_bf16 v[88:91], v[124:127], v[176:179], v[88:91]
	v_mfma_f32_16x16x32_bf16 v[76:79], v[112:115], v[184:187], v[76:79]
	v_mfma_f32_16x16x32_bf16 v[72:75], v[124:127], v[184:187], v[72:75]
	v_mfma_f32_16x16x32_bf16 v[152:155], v[120:123], v[164:167], v[152:155]
	v_mfma_f32_16x16x32_bf16 v[148:151], v[128:131], v[164:167], v[148:151]
	v_mfma_f32_16x16x32_bf16 v[108:111], v[120:123], v[172:175], v[108:111]
	v_mfma_f32_16x16x32_bf16 v[104:107], v[128:131], v[172:175], v[104:107]
	v_mfma_f32_16x16x32_bf16 v[92:95], v[120:123], v[180:183], v[92:95]
	v_mfma_f32_16x16x32_bf16 v[88:91], v[128:131], v[180:183], v[88:91]
	v_mfma_f32_16x16x32_bf16 v[76:79], v[120:123], v[188:191], v[76:79]
	v_mfma_f32_16x16x32_bf16 v[72:75], v[128:131], v[188:191], v[72:75]
	v_mfma_f32_16x16x32_bf16 v[132:135], v[136:139], v[160:163], v[132:135]
	v_mfma_f32_16x16x32_bf16 v[116:119], v[144:147], v[160:163], v[116:119]
	v_mfma_f32_16x16x32_bf16 v[100:103], v[136:139], v[168:171], v[100:103]
	v_mfma_f32_16x16x32_bf16 v[96:99], v[144:147], v[168:171], v[96:99]
	v_mfma_f32_16x16x32_bf16 v[84:87], v[136:139], v[176:179], v[84:87]
	v_mfma_f32_16x16x32_bf16 v[80:83], v[144:147], v[176:179], v[80:83]
	v_mfma_f32_16x16x32_bf16 v[68:71], v[136:139], v[184:187], v[68:71]
	v_mfma_f32_16x16x32_bf16 v[64:67], v[144:147], v[184:187], v[64:67]
	v_mfma_f32_16x16x32_bf16 v[132:135], v[140:143], v[164:167], v[132:135]
	v_mfma_f32_16x16x32_bf16 v[116:119], v[156:159], v[164:167], v[116:119]
	v_mfma_f32_16x16x32_bf16 v[100:103], v[140:143], v[172:175], v[100:103]
	v_mfma_f32_16x16x32_bf16 v[96:99], v[156:159], v[172:175], v[96:99]
	v_mfma_f32_16x16x32_bf16 v[84:87], v[140:143], v[180:183], v[84:87]
	v_mfma_f32_16x16x32_bf16 v[80:83], v[156:159], v[180:183], v[80:83]
	v_mfma_f32_16x16x32_bf16 v[68:71], v[140:143], v[188:191], v[68:71]
	v_mfma_f32_16x16x32_bf16 v[64:67], v[156:159], v[188:191], v[64:67]
	s_barrier
; #define PG8_STAGE(bufoff, gbase, voff) do { _Pragma("unroll") for (int _i = 0; _i < 2; ++_i) \
;         __builtin_amdgcn_global_load_lds((const unsigned*)((const char*)(gbase) + (voff)[_i]), (PG8_LAS unsigned*)(lds + (bufoff) + ldsw + _i * 8192), 16, 0, 0); } while (0)
; #define PG8_LDA(dst, b, h) do { _Pragma("unroll") for (int m = 0; m < 4; ++m) _Pragma("unroll") for (int k = 0; k < 2; ++k) dst[m][k] = *(const PG8_LAS bf16x8*)(lds + PG8_SA(b, h) + aoff + m * 2048 + k * 1024); } while (0)
; #define PG8_LDB(dst, b, h) do { _Pragma("unroll") for (int n = 0; n < 2; ++n) _Pragma("unroll") for (int k = 0; k < 2; ++k) dst[n][k] = *(const PG8_LAS bf16x8*)(lds + PG8_SB(b, h) + boff + n * 2048 + k * 1024); } while (0)
; #define PG8_MMA(ai, bj, At, Bt) do { __builtin_amdgcn_s_setprio(1); _Pragma("unroll") for (int m = 0; m < 4; ++m) _Pragma("unroll") for (int n = 0; n < 2; ++n) _Pragma("unroll") for (int k = 0; k < 2; ++k) \
;         acc[ai][bj][m][n] = __builtin_amdgcn_mfma_f32_16x16x32_bf16(Bt[n][k], At[m][k], acc[ai][bj][m][n], 0, 0, 0); __builtin_amdgcn_s_setprio(0); } while (0)
; #define PG8_WAIT_V(n) asm volatile("s_waitcnt vmcnt(" #n ")" ::: "memory")
; #define PG8_WAIT_L(n) asm volatile("s_waitcnt lgkmcnt(" #n ")" ::: "memory")
; #define PG8_BAR __builtin_amdgcn_s_barrier()
; #define PG8_SCHED __builtin_amdgcn_sched_barrier(0)
; template <class Epi, class Sched, bool ALIGN_EPI = false, bool SP2 = false>
; __device__ __forceinline__ void gemm_phase(PG8_LAS unsigned char* lds, const Gemm g, const Sched& S, const Epi& E, int wave_in) {
;     ...
;             const bool last = (t == nt - 2);
;             const char* a1 = cA + (size_t)(t + 1) * kstep;
;             const char* a2 = last ? nA : cA + (size_t)(t + 2) * kstep; const char* b2 = last ? nB : cB + (size_t)(t + 2) * kstep;
;             const char* a3 = a2 + kstep; const char* b3 = b2 + kstep;
;             if (last && has_next) S.a_ready(nxt);
;             if constexpr (SP2) {
;             PG8_LDB(B0, 0, 0); PG8_LDB(B1, 0, 1); PG8_SCHED; PG8_LDA(At, 0, 0); PG8_STAGE(PG8_SA(1, 1), a1 + hstep, voffA);
;     ...
;             PG8_LDA(At, 1, 1); PG8_STAGE(PG8_SB(1, 0), b3, voffB); PG8_STAGE(PG8_SB(1, 1), b3 + hstep, voffB); PG8_STAGE(PG8_SA(1, 0), a3, voffA);
;             PG8_WAIT_V(8); PG8_WAIT_L(0); PG8_BAR; PG8_MMA(1, 0, At, B0); PG8_MMA(1, 1, At, B1); PG8_BAR; PG8_SCHED;
	s_setprio 0
	s_add_i32 s2, s2, s44
	v_lshl_add_u64 v[194:195], v[194:195], 0, s[88:89]
	s_mov_b32 m0, s2
	ds_read_b128 v[160:163], v251 offset:49152
	ds_read_b128 v[164:167], v251 offset:50176
	ds_read_b128 v[168:171], v251 offset:51200
	ds_read_b128 v[172:175], v251 offset:52224
	ds_read_b128 v[176:179], v251 offset:53248
	ds_read_b128 v[180:183], v251 offset:54272
	ds_read_b128 v[184:187], v251 offset:55296
	ds_read_b128 v[188:191], v251 offset:56320
	global_load_lds_dwordx4 v[194:195], off
	s_add_i32 m0, s2, 0x2000
	s_add_u32 s16, s22, 0xb0080
	v_lshl_add_u64 v[194:195], v[196:197], 0, s[88:89]
	s_addc_u32 s17, s23, 0
	s_add_i32 s2, s29, s44
	global_load_lds_dwordx4 v[194:195], off
	v_lshl_add_u64 v[194:195], s[16:17], 0, v[192:193]
	s_mov_b32 m0, s2
	s_nop 0
	global_load_lds_dwordx4 v[194:195], off
	v_lshl_add_u64 v[194:195], s[16:17], 0, v[198:199]
	s_add_i32 m0, s2, 0x2000
	s_nop 0
	global_load_lds_dwordx4 v[194:195], off
	v_lshl_add_u64 v[194:195], v[208:209], 0, s[88:89]
	s_mov_b32 m0, s62
	s_nop 0
	global_load_lds_dwordx4 v[194:195], off
	v_lshl_add_u64 v[194:195], v[210:211], 0, s[88:89]
	s_mov_b32 m0, s63
	s_nop 0
	global_load_lds_dwordx4 v[194:195], off
	s_waitcnt vmcnt(8)
	s_waitcnt lgkmcnt(0)
	s_setprio 1
	s_barrier
	v_mfma_f32_16x16x32_bf16 v[60:63], v[112:115], v[160:163], v[60:63]
	v_mfma_f32_16x16x32_bf16 v[56:59], v[124:127], v[160:163], v[56:59]
	v_mfma_f32_16x16x32_bf16 v[44:47], v[112:115], v[168:171], v[44:47]
	v_mfma_f32_16x16x32_bf16 v[40:43], v[124:127], v[168:171], v[40:43]
	v_mfma_f32_16x16x32_bf16 v[28:31], v[112:115], v[176:179], v[28:31]
	v_mfma_f32_16x16x32_bf16 v[24:27], v[124:127], v[176:179], v[24:27]
	v_mfma_f32_16x16x32_bf16 v[12:15], v[112:115], v[184:187], v[12:15]
	v_mfma_f32_16x16x32_bf16 v[8:11], v[124:127], v[184:187], v[8:11]
	v_mfma_f32_16x16x32_bf16 v[60:63], v[120:123], v[164:167], v[60:63]
	v_mfma_f32_16x16x32_bf16 v[56:59], v[128:131], v[164:167], v[56:59]
	v_mfma_f32_16x16x32_bf16 v[44:47], v[120:123], v[172:175], v[44:47]
	v_mfma_f32_16x16x32_bf16 v[40:43], v[128:131], v[172:175], v[40:43]
	v_mfma_f32_16x16x32_bf16 v[28:31], v[120:123], v[180:183], v[28:31]
	v_mfma_f32_16x16x32_bf16 v[24:27], v[128:131], v[180:183], v[24:27]
	v_mfma_f32_16x16x32_bf16 v[12:15], v[120:123], v[188:191], v[12:15]
	v_mfma_f32_16x16x32_bf16 v[8:11], v[128:131], v[188:191], v[8:11]
	v_mfma_f32_16x16x32_bf16 v[52:55], v[136:139], v[160:163], v[52:55]
	v_mfma_f32_16x16x32_bf16 v[48:51], v[144:147], v[160:163], v[48:51]
	v_mfma_f32_16x16x32_bf16 v[36:39], v[136:139], v[168:171], v[36:39]
	v_mfma_f32_16x16x32_bf16 v[32:35], v[144:147], v[168:171], v[32:35]
	v_mfma_f32_16x16x32_bf16 v[20:23], v[136:139], v[176:179], v[20:23]
	v_mfma_f32_16x16x32_bf16 v[16:19], v[144:147], v[176:179], v[16:19]
	v_mfma_f32_16x16x32_bf16 v[4:7], v[136:139], v[184:187], v[4:7]
	v_mfma_f32_16x16x32_bf16 v[0:3], v[144:147], v[184:187], v[0:3]
	v_mfma_f32_16x16x32_bf16 v[52:55], v[140:143], v[164:167], v[52:55]
	v_mfma_f32_16x16x32_bf16 v[48:51], v[156:159], v[164:167], v[48:51]
	v_mfma_f32_16x16x32_bf16 v[36:39], v[140:143], v[172:175], v[36:39]
	v_mfma_f32_16x16x32_bf16 v[32:35], v[156:159], v[172:175], v[32:35]
	v_mfma_f32_16x16x32_bf16 v[20:23], v[140:143], v[180:183], v[20:23]
	v_mfma_f32_16x16x32_bf16 v[16:19], v[156:159], v[180:183], v[16:19]
	v_mfma_f32_16x16x32_bf16 v[4:7], v[140:143], v[188:191], v[4:7]
	v_mfma_f32_16x16x32_bf16 v[0:3], v[156:159], v[188:191], v[0:3]
	s_barrier
	s_setprio 0
	s_add_i32 s43, s43, 2
	s_add_u32 s34, s34, 0x100
	s_addc_u32 s42, s42, 0
	s_cmp_gt_u32 s43, 41
	s_mov_b64 s[16:17], s[20:21]
	s_cbranch_scc1 .Lkexit_7
.LBB0_1031:
	s_add_u32 s20, s16, 0x100
	s_addc_u32 s21, s17, 0
	s_add_i32 s2, s35, 0x100
	s_cmp_eq_u32 s43, 40
	s_cselect_b32 s25, s13, s21
	s_cselect_b32 s24, s12, s20
	s_cselect_b32 s23, s15, s42
	s_cselect_b32 s22, s14, s34
	s_add_i32 s29, s90, 0x100
	v_add_u32_e32 v128, s2, v249
	v_add_u32_e32 v156, s29, v249
	ds_read_b128 v[112:115], v128
	ds_read_b128 v[120:123], v128 offset:1024
	ds_read_b128 v[124:127], v128 offset:2048
	ds_read_b128 v[128:131], v128 offset:3072
	ds_read_b128 v[136:139], v156
	ds_read_b128 v[140:143], v156 offset:1024
	ds_read_b128 v[144:147], v156 offset:2048
	ds_read_b128 v[156:159], v156 offset:3072
	v_lshl_add_u64 v[194:195], s[16:17], 0, v[206:207]
	s_add_i32 m0, s45, 0xc000
	ds_read_b128 v[160:163], v251
	ds_read_b128 v[164:167], v251 offset:1024
	ds_read_b128 v[168:171], v251 offset:2048
	ds_read_b128 v[172:175], v251 offset:3072
	ds_read_b128 v[176:179], v251 offset:4096
	ds_read_b128 v[180:183], v251 offset:5120
	ds_read_b128 v[184:187], v251 offset:6144
	ds_read_b128 v[188:191], v251 offset:7168
	global_load_lds_dwordx4 v[194:195], off
	v_lshl_add_u64 v[194:195], s[16:17], 0, v[204:205]
	s_add_i32 m0, s45, 0xe000
	s_nop 0
	global_load_lds_dwordx4 v[194:195], off
	s_waitcnt vmcnt(8)
	s_waitcnt lgkmcnt(0)
	s_setprio 1
	s_barrier
; #define PG8_STAGE(bufoff, gbase, voff) do { _Pragma("unroll") for (int _i = 0; _i < 2; ++_i) \
;         __builtin_amdgcn_global_load_lds((const unsigned*)((const char*)(gbase) + (voff)[_i]), (PG8_LAS unsigned*)(lds + (bufoff) + ldsw + _i * 8192), 16, 0, 0); } while (0)
; #define PG8_LDA(dst, b, h) do { _Pragma("unroll") for (int m = 0; m < 4; ++m) _Pragma("unroll") for (int k = 0; k < 2; ++k) dst[m][k] = *(const PG8_LAS bf16x8*)(lds + PG8_SA(b, h) + aoff + m * 2048 + k * 1024); } while (0)
; #define PG8_LDB(dst, b, h) do { _Pragma("unroll") for (int n = 0; n < 2; ++n) _Pragma("unroll") for (int k = 0; k < 2; ++k) dst[n][k] = *(const PG8_LAS bf16x8*)(lds + PG8_SB(b, h) + boff + n * 2048 + k * 1024); } while (0)
; #define PG8_MMA(ai, bj, At, Bt) do { __builtin_amdgcn_s_setprio(1); _Pragma("unroll") for (int m = 0; m < 4; ++m) _Pragma("unroll") for (int n = 0; n < 2; ++n) _Pragma("unroll") for (int k = 0; k < 2; ++k) \
;         acc[ai][bj][m][n] = __builtin_amdgcn_mfma_f32_16x16x32_bf16(Bt[n][k], At[m][k], acc[ai][bj][m][n], 0, 0, 0); __builtin_amdgcn_s_setprio(0); } while (0)
; #define PG8_WAIT_V(n) asm volatile("s_waitcnt vmcnt(" #n ")" ::: "memory")
; #define PG8_WAIT_L(n) asm volatile("s_waitcnt lgkmcnt(" #n ")" ::: "memory")
; #define PG8_BAR __builtin_amdgcn_s_barrier()
; #define PG8_SCHED __builtin_amdgcn_sched_barrier(0)
; template <class Epi, class Sched, bool ALIGN_EPI = false, bool SP2 = false>
; __device__ __forceinline__ void gemm_phase(PG8_LAS unsigned char* lds, const Gemm g, const Sched& S, const Epi& E, int wave_in) {
;     ...
;             PG8_LDB(B0, 0, 0); PG8_LDB(B1, 0, 1); PG8_SCHED; PG8_LDA(At, 0, 0); PG8_STAGE(PG8_SA(1, 1), a1 + hstep, voffA);
;             PG8_WAIT_V(8); PG8_WAIT_L(0); PG8_BAR; PG8_MMA(0, 0, At, B0); PG8_MMA(0, 1, At, B1); PG8_BAR; PG8_SCHED;
;             PG8_LDA(At, 0, 1); PG8_STAGE(PG8_SB(0, 0), b2, voffB); PG8_STAGE(PG8_SB(0, 1), b2 + hstep, voffB); PG8_STAGE(PG8_SA(0, 0), a2, voffA);
;             PG8_WAIT_V(8); PG8_WAIT_L(0); PG8_BAR; PG8_MMA(1, 0, At, B0); PG8_MMA(1, 1, At, B1); PG8_BAR; PG8_SCHED;
	v_mfma_f32_16x16x32_bf16 v[152:155], v[112:115], v[160:163], v[152:155]
	v_mfma_f32_16x16x32_bf16 v[148:151], v[124:127], v[160:163], v[148:151]
	v_mfma_f32_16x16x32_bf16 v[108:111], v[112:115], v[168:171], v[108:111]
	v_mfma_f32_16x16x32_bf16 v[104:107], v[124:127], v[168:171], v[104:107]
	v_mfma_f32_16x16x32_bf16 v[92:95], v[112:115], v[176:179], v[92:95]
	v_mfma_f32_16x16x32_bf16 v[88:91], v[124:127], v[176:179], v[88:91]
	v_mfma_f32_16x16x32_bf16 v[76:79], v[112:115], v[184:187], v[76:79]
	v_mfma_f32_16x16x32_bf16 v[72:75], v[124:127], v[184:187], v[72:75]
	v_mfma_f32_16x16x32_bf16 v[152:155], v[120:123], v[164:167], v[152:155]
	v_mfma_f32_16x16x32_bf16 v[148:151], v[128:131], v[164:167], v[148:151]
	v_mfma_f32_16x16x32_bf16 v[108:111], v[120:123], v[172:175], v[108:111]
	v_mfma_f32_16x16x32_bf16 v[104:107], v[128:131], v[172:175], v[104:107]
	v_mfma_f32_16x16x32_bf16 v[92:95], v[120:123], v[180:183], v[92:95]
	v_mfma_f32_16x16x32_bf16 v[88:91], v[128:131], v[180:183], v[88:91]
	v_mfma_f32_16x16x32_bf16 v[76:79], v[120:123], v[188:191], v[76:79]
	v_mfma_f32_16x16x32_bf16 v[72:75], v[128:131], v[188:191], v[72:75]
	v_mfma_f32_16x16x32_bf16 v[132:135], v[136:139], v[160:163], v[132:135]
	v_mfma_f32_16x16x32_bf16 v[116:119], v[144:147], v[160:163], v[116:119]
	v_mfma_f32_16x16x32_bf16 v[100:103], v[136:139], v[168:171], v[100:103]
	v_mfma_f32_16x16x32_bf16 v[96:99], v[144:147], v[168:171], v[96:99]
	v_mfma_f32_16x16x32_bf16 v[84:87], v[136:139], v[176:179], v[84:87]
	v_mfma_f32_16x16x32_bf16 v[80:83], v[144:147], v[176:179], v[80:83]
	v_mfma_f32_16x16x32_bf16 v[68:71], v[136:139], v[184:187], v[68:71]
	v_mfma_f32_16x16x32_bf16 v[64:67], v[144:147], v[184:187], v[64:67]
	v_mfma_f32_16x16x32_bf16 v[132:135], v[140:143], v[164:167], v[132:135]
	v_mfma_f32_16x16x32_bf16 v[116:119], v[156:159], v[164:167], v[116:119]
	v_mfma_f32_16x16x32_bf16 v[100:103], v[140:143], v[172:175], v[100:103]
	v_mfma_f32_16x16x32_bf16 v[96:99], v[156:159], v[172:175], v[96:99]
	v_mfma_f32_16x16x32_bf16 v[84:87], v[140:143], v[180:183], v[84:87]
	v_mfma_f32_16x16x32_bf16 v[80:83], v[156:159], v[180:183], v[80:83]
	v_mfma_f32_16x16x32_bf16 v[68:71], v[140:143], v[188:191], v[68:71]
	v_mfma_f32_16x16x32_bf16 v[64:67], v[156:159], v[188:191], v[64:67]
	s_barrier
	s_setprio 0
	s_add_i32 s2, s2, s44
	v_lshl_add_u64 v[194:195], s[22:23], 0, v[192:193]
	s_mov_b32 m0, s2
	ds_read_b128 v[160:163], v251 offset:16384
	ds_read_b128 v[164:167], v251 offset:17408
	ds_read_b128 v[168:171], v251 offset:18432
	ds_read_b128 v[172:175], v251 offset:19456
	ds_read_b128 v[176:179], v251 offset:20480
	ds_read_b128 v[180:183], v251 offset:21504
	ds_read_b128 v[184:187], v251 offset:22528
	ds_read_b128 v[188:191], v251 offset:23552
	global_load_lds_dwordx4 v[194:195], off
	s_add_i32 m0, s2, 0x2000
	s_add_u32 s16, s22, 0xb0000
	v_lshl_add_u64 v[196:197], s[22:23], 0, v[198:199]
	s_addc_u32 s17, s23, 0
	s_add_i32 s2, s29, s44
	global_load_lds_dwordx4 v[196:197], off
	v_lshl_add_u64 v[208:209], s[16:17], 0, v[192:193]
	s_mov_b32 m0, s2
	v_lshl_add_u64 v[210:211], s[24:25], 0, v[200:201]
	global_load_lds_dwordx4 v[208:209], off
	v_lshl_add_u64 v[208:209], s[16:17], 0, v[198:199]
	s_add_i32 m0, s2, 0x2000
	s_nop 0
	global_load_lds_dwordx4 v[208:209], off
	v_lshl_add_u64 v[208:209], s[24:25], 0, v[202:203]
	s_mov_b32 m0, s45
	s_nop 0
	global_load_lds_dwordx4 v[208:209], off
	s_mov_b32 m0, s46
	s_nop 0
	global_load_lds_dwordx4 v[210:211], off
	s_waitcnt vmcnt(8)
	s_waitcnt lgkmcnt(0)
	s_setprio 1
	s_barrier
	v_mfma_f32_16x16x32_bf16 v[60:63], v[112:115], v[160:163], v[60:63]
	v_mfma_f32_16x16x32_bf16 v[56:59], v[124:127], v[160:163], v[56:59]
	v_mfma_f32_16x16x32_bf16 v[44:47], v[112:115], v[168:171], v[44:47]
	v_mfma_f32_16x16x32_bf16 v[40:43], v[124:127], v[168:171], v[40:43]
	v_mfma_f32_16x16x32_bf16 v[28:31], v[112:115], v[176:179], v[28:31]
	v_mfma_f32_16x16x32_bf16 v[24:27], v[124:127], v[176:179], v[24:27]
	v_mfma_f32_16x16x32_bf16 v[12:15], v[112:115], v[184:187], v[12:15]
	v_mfma_f32_16x16x32_bf16 v[8:11], v[124:127], v[184:187], v[8:11]
	v_mfma_f32_16x16x32_bf16 v[60:63], v[120:123], v[164:167], v[60:63]
	v_mfma_f32_16x16x32_bf16 v[56:59], v[128:131], v[164:167], v[56:59]
	v_mfma_f32_16x16x32_bf16 v[44:47], v[120:123], v[172:175], v[44:47]
	v_mfma_f32_16x16x32_bf16 v[40:43], v[128:131], v[172:175], v[40:43]
	v_mfma_f32_16x16x32_bf16 v[28:31], v[120:123], v[180:183], v[28:31]
	v_mfma_f32_16x16x32_bf16 v[24:27], v[128:131], v[180:183], v[24:27]
	v_mfma_f32_16x16x32_bf16 v[12:15], v[120:123], v[188:191], v[12:15]
	v_mfma_f32_16x16x32_bf16 v[8:11], v[128:131], v[188:191], v[8:11]
	v_mfma_f32_16x16x32_bf16 v[52:55], v[136:139], v[160:163], v[52:55]
	v_mfma_f32_16x16x32_bf16 v[48:51], v[144:147], v[160:163], v[48:51]
	v_mfma_f32_16x16x32_bf16 v[36:39], v[136:139], v[168:171], v[36:39]
	v_mfma_f32_16x16x32_bf16 v[32:35], v[144:147], v[168:171], v[32:35]
	v_mfma_f32_16x16x32_bf16 v[20:23], v[136:139], v[176:179], v[20:23]
	v_mfma_f32_16x16x32_bf16 v[16:19], v[144:147], v[176:179], v[16:19]
	v_mfma_f32_16x16x32_bf16 v[4:7], v[136:139], v[184:187], v[4:7]
	v_mfma_f32_16x16x32_bf16 v[0:3], v[144:147], v[184:187], v[0:3]
	v_mfma_f32_16x16x32_bf16 v[52:55], v[140:143], v[164:167], v[52:55]
	v_mfma_f32_16x16x32_bf16 v[48:51], v[156:159], v[164:167], v[48:51]
	v_mfma_f32_16x16x32_bf16 v[36:39], v[140:143], v[172:175], v[36:39]
	v_mfma_f32_16x16x32_bf16 v[32:35], v[156:159], v[172:175], v[32:35]
	v_mfma_f32_16x16x32_bf16 v[20:23], v[140:143], v[180:183], v[20:23]
	v_mfma_f32_16x16x32_bf16 v[16:19], v[156:159], v[180:183], v[16:19]
	v_mfma_f32_16x16x32_bf16 v[4:7], v[140:143], v[188:191], v[4:7]
	v_mfma_f32_16x16x32_bf16 v[0:3], v[156:159], v[188:191], v[0:3]
	s_barrier
; #define PG8_STAGE(bufoff, gbase, voff) do { _Pragma("unroll") for (int _i = 0; _i < 2; ++_i) \
;         __builtin_amdgcn_global_load_lds((const unsigned*)((const char*)(gbase) + (voff)[_i]), (PG8_LAS unsigned*)(lds + (bufoff) + ldsw + _i * 8192), 16, 0, 0); } while (0)
; #define PG8_LDA(dst, b, h) do { _Pragma("unroll") for (int m = 0; m < 4; ++m) _Pragma("unroll") for (int k = 0; k < 2; ++k) dst[m][k] = *(const PG8_LAS bf16x8*)(lds + PG8_SA(b, h) + aoff + m * 2048 + k * 1024); } while (0)
; #define PG8_LDB(dst, b, h) do { _Pragma("unroll") for (int n = 0; n < 2; ++n) _Pragma("unroll") for (int k = 0; k < 2; ++k) dst[n][k] = *(const PG8_LAS bf16x8*)(lds + PG8_SB(b, h) + boff + n * 2048 + k * 1024); } while (0)
; #define PG8_MMA(ai, bj, At, Bt) do { __builtin_amdgcn_s_setprio(1); _Pragma("unroll") for (int m = 0; m < 4; ++m) _Pragma("unroll") for (int n = 0; n < 2; ++n) _Pragma("unroll") for (int k = 0; k < 2; ++k) \
;         acc[ai][bj][m][n] = __builtin_amdgcn_mfma_f32_16x16x32_bf16(Bt[n][k], At[m][k], acc[ai][bj][m][n], 0, 0, 0); __builtin_amdgcn_s_setprio(0); } while (0)
; #define PG8_WAIT_V(n) asm volatile("s_waitcnt vmcnt(" #n ")" ::: "memory")
; #define PG8_WAIT_L(n) asm volatile("s_waitcnt lgkmcnt(" #n ")" ::: "memory")
; #define PG8_BAR __builtin_amdgcn_s_barrier()
; #define PG8_SCHED __builtin_amdgcn_sched_barrier(0)
; template <class Epi, class Sched, bool ALIGN_EPI = false, bool SP2 = false>
; __device__ __forceinline__ void gemm_phase(PG8_LAS unsigned char* lds, const Gemm g, const Sched& S, const Epi& E, int wave_in) {
;     ...
;         for (int t = 0; t < nt; t += 2) {
;     ...
;             PG8_LDB(B0, 1, 0); PG8_LDB(B1, 1, 1); PG8_SCHED; PG8_LDA(At, 1, 0); PG8_STAGE(PG8_SA(0, 1), a2 + hstep, voffA);
;             PG8_WAIT_V(8); PG8_WAIT_L(0); PG8_BAR; PG8_MMA(0, 0, At, B0); PG8_MMA(0, 1, At, B1); PG8_BAR; PG8_SCHED;
;             PG8_LDA(At, 1, 1); PG8_STAGE(PG8_SB(1, 0), b3, voffB); PG8_STAGE(PG8_SB(1, 1), b3 + hstep, voffB); PG8_STAGE(PG8_SA(1, 0), a3, voffA);
;             PG8_WAIT_V(8); PG8_WAIT_L(0); PG8_BAR; PG8_MMA(1, 0, At, B0); PG8_MMA(1, 1, At, B1); PG8_BAR; PG8_SCHED;
	s_setprio 0
	s_add_i32 s2, s65, 0x100
	s_add_i32 s29, s52, 0x100
	v_add_u32_e32 v128, s2, v249
	v_add_u32_e32 v156, s29, v249
	ds_read_b128 v[112:115], v128
	ds_read_b128 v[120:123], v128 offset:1024
	ds_read_b128 v[124:127], v128 offset:2048
	ds_read_b128 v[128:131], v128 offset:3072
	ds_read_b128 v[136:139], v156
	ds_read_b128 v[140:143], v156 offset:1024
	ds_read_b128 v[144:147], v156 offset:2048
	ds_read_b128 v[156:159], v156 offset:3072
	s_add_u32 s16, s24, 0xb0000
	s_addc_u32 s17, s25, 0
	s_mov_b32 m0, s47
	v_lshl_add_u64 v[212:213], s[16:17], 0, v[202:203]
	ds_read_b128 v[160:163], v251 offset:32768
	ds_read_b128 v[164:167], v251 offset:33792
	ds_read_b128 v[168:171], v251 offset:34816
	ds_read_b128 v[172:175], v251 offset:35840
	ds_read_b128 v[176:179], v251 offset:36864
	ds_read_b128 v[180:183], v251 offset:37888
	ds_read_b128 v[184:187], v251 offset:38912
	ds_read_b128 v[188:191], v251 offset:39936
	global_load_lds_dwordx4 v[212:213], off
	v_lshl_add_u64 v[212:213], s[16:17], 0, v[200:201]
	s_mov_b32 m0, s60
	s_nop 0
	global_load_lds_dwordx4 v[212:213], off
	s_waitcnt vmcnt(8)
	s_waitcnt lgkmcnt(0)
	s_setprio 1
	s_barrier
	v_mfma_f32_16x16x32_bf16 v[152:155], v[112:115], v[160:163], v[152:155]
	v_mfma_f32_16x16x32_bf16 v[148:151], v[124:127], v[160:163], v[148:151]
	v_mfma_f32_16x16x32_bf16 v[108:111], v[112:115], v[168:171], v[108:111]
	v_mfma_f32_16x16x32_bf16 v[104:107], v[124:127], v[168:171], v[104:107]
	v_mfma_f32_16x16x32_bf16 v[92:95], v[112:115], v[176:179], v[92:95]
	v_mfma_f32_16x16x32_bf16 v[88:91], v[124:127], v[176:179], v[88:91]
	v_mfma_f32_16x16x32_bf16 v[76:79], v[112:115], v[184:187], v[76:79]
	v_mfma_f32_16x16x32_bf16 v[72:75], v[124:127], v[184:187], v[72:75]
	v_mfma_f32_16x16x32_bf16 v[152:155], v[120:123], v[164:167], v[152:155]
	v_mfma_f32_16x16x32_bf16 v[148:151], v[128:131], v[164:167], v[148:151]
	v_mfma_f32_16x16x32_bf16 v[108:111], v[120:123], v[172:175], v[108:111]
	v_mfma_f32_16x16x32_bf16 v[104:107], v[128:131], v[172:175], v[104:107]
	v_mfma_f32_16x16x32_bf16 v[92:95], v[120:123], v[180:183], v[92:95]
	v_mfma_f32_16x16x32_bf16 v[88:91], v[128:131], v[180:183], v[88:91]
	v_mfma_f32_16x16x32_bf16 v[76:79], v[120:123], v[188:191], v[76:79]
	v_mfma_f32_16x16x32_bf16 v[72:75], v[128:131], v[188:191], v[72:75]
	v_mfma_f32_16x16x32_bf16 v[132:135], v[136:139], v[160:163], v[132:135]
	v_mfma_f32_16x16x32_bf16 v[116:119], v[144:147], v[160:163], v[116:119]
	v_mfma_f32_16x16x32_bf16 v[100:103], v[136:139], v[168:171], v[100:103]
	v_mfma_f32_16x16x32_bf16 v[96:99], v[144:147], v[168:171], v[96:99]
	v_mfma_f32_16x16x32_bf16 v[84:87], v[136:139], v[176:179], v[84:87]
	v_mfma_f32_16x16x32_bf16 v[80:83], v[144:147], v[176:179], v[80:83]
	v_mfma_f32_16x16x32_bf16 v[68:71], v[136:139], v[184:187], v[68:71]
	v_mfma_f32_16x16x32_bf16 v[64:67], v[144:147], v[184:187], v[64:67]
	v_mfma_f32_16x16x32_bf16 v[132:135], v[140:143], v[164:167], v[132:135]
	v_mfma_f32_16x16x32_bf16 v[116:119], v[156:159], v[164:167], v[116:119]
	v_mfma_f32_16x16x32_bf16 v[100:103], v[140:143], v[172:175], v[100:103]
	v_mfma_f32_16x16x32_bf16 v[96:99], v[156:159], v[172:175], v[96:99]
	v_mfma_f32_16x16x32_bf16 v[84:87], v[140:143], v[180:183], v[84:87]
	v_mfma_f32_16x16x32_bf16 v[80:83], v[156:159], v[180:183], v[80:83]
	v_mfma_f32_16x16x32_bf16 v[68:71], v[140:143], v[188:191], v[68:71]
	v_mfma_f32_16x16x32_bf16 v[64:67], v[156:159], v[188:191], v[64:67]
	s_barrier
	s_setprio 0
	s_add_i32 s2, s2, s44
	v_lshl_add_u64 v[194:195], v[194:195], 0, s[88:89]
	s_mov_b32 m0, s2
	ds_read_b128 v[160:163], v251 offset:49152
	ds_read_b128 v[164:167], v251 offset:50176
	ds_read_b128 v[168:171], v251 offset:51200
	ds_read_b128 v[172:175], v251 offset:52224
	ds_read_b128 v[176:179], v251 offset:53248
	ds_read_b128 v[180:183], v251 offset:54272
	ds_read_b128 v[184:187], v251 offset:55296
	ds_read_b128 v[188:191], v251 offset:56320
	global_load_lds_dwordx4 v[194:195], off
	s_add_i32 m0, s2, 0x2000
	s_add_u32 s16, s22, 0xb0080
	v_lshl_add_u64 v[194:195], v[196:197], 0, s[88:89]
	s_addc_u32 s17, s23, 0
	s_add_i32 s2, s29, s44
	global_load_lds_dwordx4 v[194:195], off
	v_lshl_add_u64 v[194:195], s[16:17], 0, v[192:193]
	s_mov_b32 m0, s2
	s_nop 0
	global_load_lds_dwordx4 v[194:195], off
	v_lshl_add_u64 v[194:195], s[16:17], 0, v[198:199]
	s_add_i32 m0, s2, 0x2000
	s_nop 0
	global_load_lds_dwordx4 v[194:195], off
	v_lshl_add_u64 v[194:195], v[208:209], 0, s[88:89]
	s_mov_b32 m0, s62
	s_nop 0
	global_load_lds_dwordx4 v[194:195], off
	v_lshl_add_u64 v[194:195], v[210:211], 0, s[88:89]
	s_mov_b32 m0, s63
	s_nop 0
	global_load_lds_dwordx4 v[194:195], off
	s_waitcnt vmcnt(8)
	s_waitcnt lgkmcnt(0)
	s_setprio 1
	s_barrier
	v_mfma_f32_16x16x32_bf16 v[60:63], v[112:115], v[160:163], v[60:63]
	v_mfma_f32_16x16x32_bf16 v[56:59], v[124:127], v[160:163], v[56:59]
	v_mfma_f32_16x16x32_bf16 v[44:47], v[112:115], v[168:171], v[44:47]
	v_mfma_f32_16x16x32_bf16 v[40:43], v[124:127], v[168:171], v[40:43]
	v_mfma_f32_16x16x32_bf16 v[28:31], v[112:115], v[176:179], v[28:31]
	v_mfma_f32_16x16x32_bf16 v[24:27], v[124:127], v[176:179], v[24:27]
	v_mfma_f32_16x16x32_bf16 v[12:15], v[112:115], v[184:187], v[12:15]
	v_mfma_f32_16x16x32_bf16 v[8:11], v[124:127], v[184:187], v[8:11]
	v_mfma_f32_16x16x32_bf16 v[60:63], v[120:123], v[164:167], v[60:63]
	v_mfma_f32_16x16x32_bf16 v[56:59], v[128:131], v[164:167], v[56:59]
	v_mfma_f32_16x16x32_bf16 v[44:47], v[120:123], v[172:175], v[44:47]
	v_mfma_f32_16x16x32_bf16 v[40:43], v[128:131], v[172:175], v[40:43]
	v_mfma_f32_16x16x32_bf16 v[28:31], v[120:123], v[180:183], v[28:31]
	v_mfma_f32_16x16x32_bf16 v[24:27], v[128:131], v[180:183], v[24:27]
	v_mfma_f32_16x16x32_bf16 v[12:15], v[120:123], v[188:191], v[12:15]
	v_mfma_f32_16x16x32_bf16 v[8:11], v[128:131], v[188:191], v[8:11]
	v_mfma_f32_16x16x32_bf16 v[52:55], v[136:139], v[160:163], v[52:55]
	v_mfma_f32_16x16x32_bf16 v[48:51], v[144:147], v[160:163], v[48:51]
	v_mfma_f32_16x16x32_bf16 v[36:39], v[136:139], v[168:171], v[36:39]
	v_mfma_f32_16x16x32_bf16 v[32:35], v[144:147], v[168:171], v[32:35]
	v_mfma_f32_16x16x32_bf16 v[20:23], v[136:139], v[176:179], v[20:23]
	v_mfma_f32_16x16x32_bf16 v[16:19], v[144:147], v[176:179], v[16:19]
	v_mfma_f32_16x16x32_bf16 v[4:7], v[136:139], v[184:187], v[4:7]
	v_mfma_f32_16x16x32_bf16 v[0:3], v[144:147], v[184:187], v[0:3]
	v_mfma_f32_16x16x32_bf16 v[52:55], v[140:143], v[164:167], v[52:55]
	v_mfma_f32_16x16x32_bf16 v[48:51], v[156:159], v[164:167], v[48:51]
	v_mfma_f32_16x16x32_bf16 v[36:39], v[140:143], v[172:175], v[36:39]
	v_mfma_f32_16x16x32_bf16 v[32:35], v[156:159], v[172:175], v[32:35]
	v_mfma_f32_16x16x32_bf16 v[20:23], v[140:143], v[180:183], v[20:23]
	v_mfma_f32_16x16x32_bf16 v[16:19], v[156:159], v[180:183], v[16:19]
	v_mfma_f32_16x16x32_bf16 v[4:7], v[140:143], v[188:191], v[4:7]
	v_mfma_f32_16x16x32_bf16 v[0:3], v[156:159], v[188:191], v[0:3]
	s_barrier
	s_setprio 0
	s_add_i32 s43, s43, 2
	s_add_u32 s34, s34, 0x100
	s_addc_u32 s42, s42, 0
	s_cmp_gt_u32 s43, 41
	s_mov_b64 s[16:17], s[20:21]
	s_cbranch_scc0 .LBB0_1031
